# v40 with burst-tail priority 3 instead of 2
# speedup vs baseline: 1.0057x; 1.0057x over previous
.LBB0_379:
	v_add_u32_e32 v14, s56, v140
	v_add_u32_e32 v30, s57, v140
	ds_read_b128 v[2:5], v14
	ds_read_b128 v[6:9], v14 offset:1024
	ds_read_b128 v[10:13], v14 offset:2048
	ds_read_b128 v[14:17], v14 offset:3072
	ds_read_b128 v[18:21], v30
	ds_read_b128 v[22:25], v30 offset:1024
	ds_read_b128 v[26:29], v30 offset:2048
	ds_read_b128 v[30:33], v30 offset:3072
	v_add_u32_e32 v141, 0, v1
	ds_read_b128 v[34:37], v141
	ds_read_b128 v[38:41], v141 offset:1024
	ds_read_b128 v[42:45], v141 offset:2048
	ds_read_b128 v[46:49], v141 offset:3072
	ds_read_b128 v[50:53], v141 offset:4096
	ds_read_b128 v[54:57], v141 offset:5120
	ds_read_b128 v[58:61], v141 offset:6144
	ds_read_b128 v[62:65], v141 offset:7168
	s_waitcnt vmcnt(8)
	s_waitcnt lgkmcnt(0)
	s_barrier
	s_setprio 1
	s_waitcnt lgkmcnt(0)
	v_mfma_f32_16x16x32_bf16 v[66:69], v[2:5], v[34:37], 0
	v_mfma_f32_16x16x32_bf16 v[66:69], v[6:9], v[38:41], v[66:69]
	v_mfma_f32_16x16x32_bf16 v[70:73], v[10:13], v[34:37], 0
	v_mfma_f32_16x16x32_bf16 v[70:73], v[14:17], v[38:41], v[70:73]
	v_mfma_f32_16x16x32_bf16 v[78:81], v[10:13], v[42:45], 0
	v_mfma_f32_16x16x32_bf16 v[78:81], v[14:17], v[46:49], v[78:81]
	v_mfma_f32_16x16x32_bf16 v[74:77], v[2:5], v[42:45], 0
	v_mfma_f32_16x16x32_bf16 v[74:77], v[6:9], v[46:49], v[74:77]
	v_mfma_f32_16x16x32_bf16 v[82:85], v[2:5], v[50:53], 0
	v_mfma_f32_16x16x32_bf16 v[82:85], v[6:9], v[54:57], v[82:85]
	v_mfma_f32_16x16x32_bf16 v[86:89], v[10:13], v[50:53], 0
	v_mfma_f32_16x16x32_bf16 v[86:89], v[14:17], v[54:57], v[86:89]
	v_mfma_f32_16x16x32_bf16 v[94:97], v[10:13], v[58:61], 0
	v_mfma_f32_16x16x32_bf16 v[94:97], v[14:17], v[62:65], v[94:97]
	v_mfma_f32_16x16x32_bf16 v[90:93], v[2:5], v[58:61], 0
	v_mfma_f32_16x16x32_bf16 v[90:93], v[6:9], v[62:65], v[90:93]
	s_setprio 0
	s_setprio 1
	v_mfma_f32_16x16x32_bf16 v[98:101], v[18:21], v[34:37], 0
	v_mfma_f32_16x16x32_bf16 v[34:37], v[26:29], v[34:37], 0
	v_mfma_f32_16x16x32_bf16 v[102:105], v[18:21], v[42:45], 0
	v_mfma_f32_16x16x32_bf16 v[42:45], v[26:29], v[42:45], 0
	v_mfma_f32_16x16x32_bf16 v[106:109], v[18:21], v[50:53], 0
	v_mfma_f32_16x16x32_bf16 v[50:53], v[26:29], v[50:53], 0
	v_mfma_f32_16x16x32_bf16 v[110:113], v[18:21], v[58:61], 0
	v_mfma_f32_16x16x32_bf16 v[58:61], v[26:29], v[58:61], 0
	v_mfma_f32_16x16x32_bf16 v[98:101], v[22:25], v[38:41], v[98:101]
	v_mfma_f32_16x16x32_bf16 v[38:41], v[30:33], v[38:41], v[34:37]
	v_mfma_f32_16x16x32_bf16 v[102:105], v[22:25], v[46:49], v[102:105]
	v_mfma_f32_16x16x32_bf16 v[46:49], v[30:33], v[46:49], v[42:45]
	v_mfma_f32_16x16x32_bf16 v[106:109], v[22:25], v[54:57], v[106:109]
	v_mfma_f32_16x16x32_bf16 v[54:57], v[30:33], v[54:57], v[50:53]
	s_setprio 3
	s_barrier
	v_mfma_f32_16x16x32_bf16 v[110:113], v[22:25], v[62:65], v[110:113]
	v_mfma_f32_16x16x32_bf16 v[62:65], v[30:33], v[62:65], v[58:61]
	s_setprio 0
	v_lshl_add_u64 v[136:137], s[38:39], 0, v[130:131]
	s_add_i32 s60, s56, s21
	v_mov_b32_e32 v135, v131
	v_lshl_add_u64 v[142:143], v[136:137], 0, s[10:11]
	s_mov_b32 m0, s60
	v_lshl_add_u64 v[244:245], s[38:39], 0, v[134:135]
	ds_read_b128 v[34:37], v141 offset:16384
	ds_read_b128 v[42:45], v141 offset:17408
	ds_read_b128 v[50:53], v141 offset:18432
	ds_read_b128 v[58:61], v141 offset:19456
	ds_read_b128 v[114:117], v141 offset:20480
	ds_read_b128 v[118:121], v141 offset:21504
	ds_read_b128 v[122:125], v141 offset:22528
	ds_read_b128 v[126:129], v141 offset:23552
	global_load_lds_dwordx4 v[142:143], off
	v_lshl_add_u64 v[142:143], v[244:245], 0, s[10:11]
	s_add_i32 m0, s60, 0x2000
	s_add_i32 s60, s57, s21
	global_load_lds_dwordx4 v[142:143], off
	s_mov_b32 m0, s60
	v_mov_b32_e32 v139, v131
	global_load_lds_dwordx4 v130, s[40:41]
	s_add_i32 m0, s60, 0x2000
	v_lshl_add_u64 v[246:247], s[36:37], 0, v[138:139]
	v_mov_b32_e32 v133, v131
	global_load_lds_dwordx4 v134, s[40:41]
	v_lshl_add_u64 v[142:143], v[246:247], 0, s[10:11]
	s_mov_b32 m0, s33
	v_lshl_add_u64 v[248:249], s[36:37], 0, v[132:133]
	global_load_lds_dwordx4 v[142:143], off
	v_lshl_add_u64 v[142:143], v[248:249], 0, s[10:11]
	s_mov_b32 m0, s46
	s_nop 0
	global_load_lds_dwordx4 v[142:143], off
	s_waitcnt vmcnt(8)
	s_waitcnt lgkmcnt(0)
	s_barrier
	s_setprio 1
	s_waitcnt lgkmcnt(0)
	v_mfma_f32_16x16x32_bf16 v[142:145], v[2:5], v[34:37], 0
	v_mfma_f32_16x16x32_bf16 v[148:151], v[10:13], v[34:37], 0
	v_mfma_f32_16x16x32_bf16 v[152:155], v[2:5], v[50:53], 0
	v_mfma_f32_16x16x32_bf16 v[156:159], v[10:13], v[50:53], 0
	v_mfma_f32_16x16x32_bf16 v[160:163], v[2:5], v[114:117], 0
	v_mfma_f32_16x16x32_bf16 v[164:167], v[10:13], v[114:117], 0
	v_mfma_f32_16x16x32_bf16 v[2:5], v[2:5], v[122:125], 0
	v_mfma_f32_16x16x32_bf16 v[10:13], v[10:13], v[122:125], 0
	v_mfma_f32_16x16x32_bf16 v[142:145], v[6:9], v[42:45], v[142:145]
	v_mfma_f32_16x16x32_bf16 v[148:151], v[14:17], v[42:45], v[148:151]
	v_mfma_f32_16x16x32_bf16 v[152:155], v[6:9], v[58:61], v[152:155]
	v_mfma_f32_16x16x32_bf16 v[156:159], v[14:17], v[58:61], v[156:159]
	v_mfma_f32_16x16x32_bf16 v[160:163], v[6:9], v[118:121], v[160:163]
	v_mfma_f32_16x16x32_bf16 v[164:167], v[14:17], v[118:121], v[164:167]
	v_mfma_f32_16x16x32_bf16 v[168:171], v[6:9], v[126:129], v[2:5]
	v_mfma_f32_16x16x32_bf16 v[172:175], v[14:17], v[126:129], v[10:13]
	s_setprio 0
	s_setprio 1
	v_mfma_f32_16x16x32_bf16 v[2:5], v[18:21], v[34:37], 0
	v_mfma_f32_16x16x32_bf16 v[6:9], v[26:29], v[34:37], 0
	v_mfma_f32_16x16x32_bf16 v[10:13], v[18:21], v[50:53], 0
	v_mfma_f32_16x16x32_bf16 v[14:17], v[26:29], v[50:53], 0
	v_mfma_f32_16x16x32_bf16 v[34:37], v[18:21], v[114:117], 0
	v_mfma_f32_16x16x32_bf16 v[50:53], v[26:29], v[114:117], 0
	v_mfma_f32_16x16x32_bf16 v[18:21], v[18:21], v[122:125], 0
	v_mfma_f32_16x16x32_bf16 v[26:29], v[26:29], v[122:125], 0
	v_mfma_f32_16x16x32_bf16 v[114:117], v[22:25], v[42:45], v[2:5]
	v_mfma_f32_16x16x32_bf16 v[188:191], v[22:25], v[118:121], v[34:37]
	v_mfma_f32_16x16x32_bf16 v[118:121], v[30:33], v[118:121], v[50:53]
	v_mfma_f32_16x16x32_bf16 v[176:179], v[30:33], v[42:45], v[6:9]
	v_mfma_f32_16x16x32_bf16 v[180:183], v[22:25], v[58:61], v[10:13]
	v_mfma_f32_16x16x32_bf16 v[184:187], v[30:33], v[58:61], v[14:17]
	s_setprio 3
	s_barrier
	v_mfma_f32_16x16x32_bf16 v[192:195], v[22:25], v[126:129], v[18:21]
	v_mfma_f32_16x16x32_bf16 v[196:199], v[30:33], v[126:129], v[26:29]
	s_setprio 0
	s_add_i32 s60, 0, 0x18000
	v_add_u32_e32 v2, s60, v140
	s_add_i32 s61, 0, 0x1c000
	ds_read_b128 v[200:203], v2
	ds_read_b128 v[204:207], v2 offset:1024
	ds_read_b128 v[208:211], v2 offset:2048
	ds_read_b128 v[212:215], v2 offset:3072
	v_add_u32_e32 v2, s61, v140
	ds_read_b128 v[216:219], v2
	ds_read_b128 v[220:223], v2 offset:1024
	ds_read_b128 v[224:227], v2 offset:2048
	ds_read_b128 v[228:231], v2 offset:3072
	s_mov_b32 m0, s47
	ds_read_b128 v[42:45], v141 offset:32768
	ds_read_b128 v[50:53], v141 offset:33792
	ds_read_b128 v[58:61], v141 offset:34816
	ds_read_b128 v[122:125], v141 offset:35840
	ds_read_b128 v[126:129], v141 offset:36864
	ds_read_b128 v[232:235], v141 offset:37888
	ds_read_b128 v[236:239], v141 offset:38912
	ds_read_b128 v[240:243], v141 offset:39936
	global_load_lds_dwordx4 v138, s[42:43]
	s_mov_b32 m0, s48
	s_nop 0
	global_load_lds_dwordx4 v132, s[42:43]
	s_waitcnt vmcnt(8)
	s_waitcnt lgkmcnt(0)
	s_barrier
	s_setprio 1
	s_waitcnt lgkmcnt(0)
	v_mfma_f32_16x16x32_bf16 v[2:5], v[200:203], v[42:45], v[66:69]
	v_mfma_f32_16x16x32_bf16 v[6:9], v[208:211], v[42:45], v[70:73]
	v_mfma_f32_16x16x32_bf16 v[10:13], v[200:203], v[58:61], v[74:77]
	v_mfma_f32_16x16x32_bf16 v[14:17], v[208:211], v[58:61], v[78:81]
	v_mfma_f32_16x16x32_bf16 v[18:21], v[200:203], v[126:129], v[82:85]
	v_mfma_f32_16x16x32_bf16 v[22:25], v[208:211], v[126:129], v[86:89]
	v_mfma_f32_16x16x32_bf16 v[26:29], v[200:203], v[236:239], v[90:93]
	v_mfma_f32_16x16x32_bf16 v[30:33], v[208:211], v[236:239], v[94:97]
	v_mfma_f32_16x16x32_bf16 v[2:5], v[204:207], v[50:53], v[2:5]
	v_mfma_f32_16x16x32_bf16 v[6:9], v[212:215], v[50:53], v[6:9]
	v_mfma_f32_16x16x32_bf16 v[10:13], v[204:207], v[122:125], v[10:13]
	v_mfma_f32_16x16x32_bf16 v[14:17], v[212:215], v[122:125], v[14:17]
	v_mfma_f32_16x16x32_bf16 v[18:21], v[204:207], v[232:235], v[18:21]
	v_mfma_f32_16x16x32_bf16 v[22:25], v[212:215], v[232:235], v[22:25]
	v_mfma_f32_16x16x32_bf16 v[26:29], v[204:207], v[240:243], v[26:29]
	v_mfma_f32_16x16x32_bf16 v[30:33], v[212:215], v[240:243], v[30:33]
	s_setprio 0
	s_setprio 1
	v_mfma_f32_16x16x32_bf16 v[34:37], v[216:219], v[42:45], v[98:101]
	v_mfma_f32_16x16x32_bf16 v[38:41], v[224:227], v[42:45], v[38:41]
	v_mfma_f32_16x16x32_bf16 v[34:37], v[220:223], v[50:53], v[34:37]
	v_mfma_f32_16x16x32_bf16 v[38:41], v[228:231], v[50:53], v[38:41]
	v_mfma_f32_16x16x32_bf16 v[42:45], v[216:219], v[58:61], v[102:105]
	v_mfma_f32_16x16x32_bf16 v[46:49], v[224:227], v[58:61], v[46:49]
	v_mfma_f32_16x16x32_bf16 v[50:53], v[216:219], v[126:129], v[106:109]
	v_mfma_f32_16x16x32_bf16 v[54:57], v[224:227], v[126:129], v[54:57]
	v_mfma_f32_16x16x32_bf16 v[58:61], v[216:219], v[236:239], v[110:113]
	v_mfma_f32_16x16x32_bf16 v[62:65], v[224:227], v[236:239], v[62:65]
	v_mfma_f32_16x16x32_bf16 v[42:45], v[220:223], v[122:125], v[42:45]
	v_mfma_f32_16x16x32_bf16 v[46:49], v[228:231], v[122:125], v[46:49]
	v_mfma_f32_16x16x32_bf16 v[50:53], v[220:223], v[232:235], v[50:53]
	v_mfma_f32_16x16x32_bf16 v[54:57], v[228:231], v[232:235], v[54:57]
	s_setprio 3
	s_barrier
	v_mfma_f32_16x16x32_bf16 v[58:61], v[220:223], v[240:243], v[58:61]
	v_mfma_f32_16x16x32_bf16 v[62:65], v[228:231], v[240:243], v[62:65]
	s_setprio 0
	s_add_i32 s60, s60, s21
	v_lshl_add_u64 v[66:67], v[136:137], 0, s[12:13]
	s_mov_b32 m0, s60
	ds_read_b128 v[94:97], v141 offset:49152
	ds_read_b128 v[98:101], v141 offset:50176
	ds_read_b128 v[102:105], v141 offset:51200
	ds_read_b128 v[106:109], v141 offset:52224
	ds_read_b128 v[110:113], v141 offset:53248
	ds_read_b128 v[232:235], v141 offset:54272
	ds_read_b128 v[236:239], v141 offset:55296
	ds_read_b128 v[240:243], v141 offset:56320
	global_load_lds_dwordx4 v[66:67], off
	v_lshl_add_u64 v[66:67], v[244:245], 0, s[12:13]
	s_add_i32 m0, s60, 0x2000
	s_add_i32 s60, s61, s21
	global_load_lds_dwordx4 v[66:67], off
	s_mov_b32 m0, s60
	v_lshl_add_u64 v[66:67], v[246:247], 0, s[12:13]
	global_load_lds_dwordx4 v130, s[44:45]
	s_add_i32 m0, s60, 0x2000
	s_nop 0
	global_load_lds_dwordx4 v134, s[44:45]
	s_mov_b32 m0, s52
	s_nop 0
	global_load_lds_dwordx4 v[66:67], off
	v_lshl_add_u64 v[66:67], v[248:249], 0, s[12:13]
	s_mov_b32 m0, s53
	s_nop 0
	global_load_lds_dwordx4 v[66:67], off
	s_waitcnt vmcnt(8)
	s_waitcnt lgkmcnt(0)
	s_barrier
	s_setprio 1
	s_waitcnt lgkmcnt(0)
	v_mfma_f32_16x16x32_bf16 v[66:69], v[200:203], v[94:97], v[142:145]
	v_mfma_f32_16x16x32_bf16 v[122:125], v[204:207], v[98:101], v[66:69]
	v_mfma_f32_16x16x32_bf16 v[66:69], v[208:211], v[94:97], v[148:151]
	v_mfma_f32_16x16x32_bf16 v[126:129], v[212:215], v[98:101], v[66:69]
	v_mfma_f32_16x16x32_bf16 v[66:69], v[200:203], v[102:105], v[152:155]
	v_mfma_f32_16x16x32_bf16 v[70:73], v[208:211], v[102:105], v[156:159]
	v_mfma_f32_16x16x32_bf16 v[74:77], v[200:203], v[110:113], v[160:163]
	v_mfma_f32_16x16x32_bf16 v[78:81], v[208:211], v[110:113], v[164:167]
	v_mfma_f32_16x16x32_bf16 v[82:85], v[200:203], v[236:239], v[168:171]
	v_mfma_f32_16x16x32_bf16 v[86:89], v[208:211], v[236:239], v[172:175]
	v_mfma_f32_16x16x32_bf16 v[66:69], v[204:207], v[106:109], v[66:69]
	v_mfma_f32_16x16x32_bf16 v[70:73], v[212:215], v[106:109], v[70:73]
	v_mfma_f32_16x16x32_bf16 v[74:77], v[204:207], v[232:235], v[74:77]
	v_mfma_f32_16x16x32_bf16 v[78:81], v[212:215], v[232:235], v[78:81]
	v_mfma_f32_16x16x32_bf16 v[82:85], v[204:207], v[240:243], v[82:85]
	v_mfma_f32_16x16x32_bf16 v[86:89], v[212:215], v[240:243], v[86:89]
	s_setprio 0
	s_setprio 1
	v_mfma_f32_16x16x32_bf16 v[90:93], v[216:219], v[94:97], v[114:117]
	v_mfma_f32_16x16x32_bf16 v[94:97], v[224:227], v[94:97], v[176:179]
	v_mfma_f32_16x16x32_bf16 v[90:93], v[220:223], v[98:101], v[90:93]
	v_mfma_f32_16x16x32_bf16 v[94:97], v[228:231], v[98:101], v[94:97]
	v_mfma_f32_16x16x32_bf16 v[98:101], v[216:219], v[102:105], v[180:183]
	v_mfma_f32_16x16x32_bf16 v[102:105], v[224:227], v[102:105], v[184:187]
	v_mfma_f32_16x16x32_bf16 v[98:101], v[220:223], v[106:109], v[98:101]
	v_mfma_f32_16x16x32_bf16 v[102:105], v[228:231], v[106:109], v[102:105]
	v_mfma_f32_16x16x32_bf16 v[106:109], v[216:219], v[110:113], v[188:191]
	v_mfma_f32_16x16x32_bf16 v[110:113], v[224:227], v[110:113], v[118:121]
	v_mfma_f32_16x16x32_bf16 v[114:117], v[216:219], v[236:239], v[192:195]
	v_mfma_f32_16x16x32_bf16 v[118:121], v[224:227], v[236:239], v[196:199]
	v_mfma_f32_16x16x32_bf16 v[106:109], v[220:223], v[232:235], v[106:109]
	v_mfma_f32_16x16x32_bf16 v[110:113], v[228:231], v[232:235], v[110:113]
	s_setprio 3
	s_barrier
	v_mfma_f32_16x16x32_bf16 v[114:117], v[220:223], v[240:243], v[114:117]
	v_mfma_f32_16x16x32_bf16 v[118:121], v[228:231], v[240:243], v[118:121]
	s_setprio 0
	s_add_i32 s59, s59, 2
	s_cmp_ge_i32 s59, s15
	s_cbranch_scc0 .LBB0_379
	v_mov_b32_e32 v136, v130
	s_branch .LBB0_382

.LBB0_383:
	v_add_u32_e32 v133, s56, v140
	ds_read_b128 v[142:145], v133
	ds_read_b128 v[148:151], v133 offset:1024
	ds_read_b128 v[152:155], v133 offset:2048
	ds_read_b128 v[156:159], v133 offset:3072
	v_add_u32_e32 v133, s57, v140
	ds_read_b128 v[160:163], v133
	ds_read_b128 v[164:167], v133 offset:1024
	ds_read_b128 v[168:171], v133 offset:2048
	ds_read_b128 v[172:175], v133 offset:3072
	s_add_u32 s38, s36, 0xfff80080
	s_addc_u32 s39, s37, -1
	s_cmp_eq_u32 s43, 28
	s_cselect_b32 s41, s31, s39
	s_cselect_b32 s40, s30, s38
	s_cselect_b32 s39, s35, s42
	s_cselect_b32 s38, s34, s15
	s_mov_b32 m0, s54
	v_add_u32_e32 v141, 0, v1
	ds_read_b128 v[176:179], v141
	ds_read_b128 v[180:183], v141 offset:1024
	ds_read_b128 v[184:187], v141 offset:2048
	ds_read_b128 v[188:191], v141 offset:3072
	ds_read_b128 v[192:195], v141 offset:4096
	ds_read_b128 v[196:199], v141 offset:5120
	ds_read_b128 v[200:203], v141 offset:6144
	ds_read_b128 v[204:207], v141 offset:7168
	global_load_lds_dwordx4 v130, s[36:37]
	s_mov_b32 m0, s55
	v_mov_b32_e32 v133, v131
	global_load_lds_dwordx4 v132, s[36:37]
	s_waitcnt vmcnt(8)
	s_waitcnt lgkmcnt(0)
	s_barrier
	s_setprio 1
	s_waitcnt lgkmcnt(0)
	v_mfma_f32_16x16x32_bf16 v[2:5], v[142:145], v[176:179], v[2:5]
	v_mfma_f32_16x16x32_bf16 v[2:5], v[148:151], v[180:183], v[2:5]
	v_mfma_f32_16x16x32_bf16 v[6:9], v[156:159], v[180:183], v[6:9]
	v_mfma_f32_16x16x32_bf16 v[6:9], v[152:155], v[176:179], v[6:9]
	v_mfma_f32_16x16x32_bf16 v[14:17], v[152:155], v[184:187], v[14:17]
	v_mfma_f32_16x16x32_bf16 v[14:17], v[156:159], v[188:191], v[14:17]
	v_mfma_f32_16x16x32_bf16 v[10:13], v[148:151], v[188:191], v[10:13]
	v_mfma_f32_16x16x32_bf16 v[10:13], v[142:145], v[184:187], v[10:13]
	v_mfma_f32_16x16x32_bf16 v[18:21], v[142:145], v[192:195], v[18:21]
	v_mfma_f32_16x16x32_bf16 v[18:21], v[148:151], v[196:199], v[18:21]
	v_mfma_f32_16x16x32_bf16 v[22:25], v[156:159], v[196:199], v[22:25]
	v_mfma_f32_16x16x32_bf16 v[22:25], v[152:155], v[192:195], v[22:25]
	v_mfma_f32_16x16x32_bf16 v[30:33], v[152:155], v[200:203], v[30:33]
	v_mfma_f32_16x16x32_bf16 v[30:33], v[156:159], v[204:207], v[30:33]
	v_mfma_f32_16x16x32_bf16 v[26:29], v[148:151], v[204:207], v[26:29]
	v_mfma_f32_16x16x32_bf16 v[26:29], v[142:145], v[200:203], v[26:29]
	s_setprio 0
	s_setprio 1
	v_mfma_f32_16x16x32_bf16 v[34:37], v[160:163], v[176:179], v[34:37]
	v_mfma_f32_16x16x32_bf16 v[34:37], v[164:167], v[180:183], v[34:37]
	v_mfma_f32_16x16x32_bf16 v[38:41], v[172:175], v[180:183], v[38:41]
	v_mfma_f32_16x16x32_bf16 v[38:41], v[168:171], v[176:179], v[38:41]
	v_mfma_f32_16x16x32_bf16 v[46:49], v[168:171], v[184:187], v[46:49]
	v_mfma_f32_16x16x32_bf16 v[46:49], v[172:175], v[188:191], v[46:49]
	v_mfma_f32_16x16x32_bf16 v[42:45], v[164:167], v[188:191], v[42:45]
	v_mfma_f32_16x16x32_bf16 v[42:45], v[160:163], v[184:187], v[42:45]
	v_mfma_f32_16x16x32_bf16 v[50:53], v[160:163], v[192:195], v[50:53]
	v_mfma_f32_16x16x32_bf16 v[50:53], v[164:167], v[196:199], v[50:53]
	v_mfma_f32_16x16x32_bf16 v[54:57], v[172:175], v[196:199], v[54:57]
	v_mfma_f32_16x16x32_bf16 v[54:57], v[168:171], v[192:195], v[54:57]
	v_mfma_f32_16x16x32_bf16 v[62:65], v[168:171], v[200:203], v[62:65]
	v_mfma_f32_16x16x32_bf16 v[62:65], v[172:175], v[204:207], v[62:65]
	s_setprio 3
	s_barrier
	v_mfma_f32_16x16x32_bf16 v[58:61], v[164:167], v[204:207], v[58:61]
	v_mfma_f32_16x16x32_bf16 v[58:61], v[160:163], v[200:203], v[58:61]
	s_setprio 0
	s_add_i32 s44, s56, s21
	s_mov_b32 m0, s44
	ds_read_b128 v[176:179], v141 offset:16384
	ds_read_b128 v[180:183], v141 offset:17408
	ds_read_b128 v[184:187], v141 offset:18432
	ds_read_b128 v[188:191], v141 offset:19456
	ds_read_b128 v[192:195], v141 offset:20480
	ds_read_b128 v[196:199], v141 offset:21504
	ds_read_b128 v[200:203], v141 offset:22528
	ds_read_b128 v[204:207], v141 offset:23552
	global_load_lds_dwordx4 v136, s[38:39]
	s_add_i32 m0, s44, 0x2000
	s_add_u32 s44, s38, 0x80000
	s_addc_u32 s45, s39, 0
	s_add_i32 s59, s57, s21
	global_load_lds_dwordx4 v134, s[38:39]
	s_mov_b32 m0, s59
	v_mov_b32_e32 v137, v131
	global_load_lds_dwordx4 v136, s[44:45]
	s_add_i32 m0, s59, 0x2000
	v_mov_b32_e32 v135, v131
	global_load_lds_dwordx4 v134, s[44:45]
	s_mov_b32 m0, s33
	v_lshl_add_u64 v[138:139], s[38:39], 0, v[136:137]
	global_load_lds_dwordx4 v130, s[40:41]
	s_mov_b32 m0, s46
	v_lshl_add_u64 v[208:209], s[38:39], 0, v[134:135]
	global_load_lds_dwordx4 v132, s[40:41]
	s_waitcnt vmcnt(8)
	s_waitcnt lgkmcnt(0)
	v_lshl_add_u64 v[210:211], s[40:41], 0, v[130:131]
	v_lshl_add_u64 v[212:213], s[40:41], 0, v[132:133]
	s_barrier
	s_setprio 1
	s_waitcnt lgkmcnt(0)
	v_mfma_f32_16x16x32_bf16 v[122:125], v[142:145], v[176:179], v[122:125]
	v_mfma_f32_16x16x32_bf16 v[122:125], v[148:151], v[180:183], v[122:125]
	v_mfma_f32_16x16x32_bf16 v[126:129], v[156:159], v[180:183], v[126:129]
	v_mfma_f32_16x16x32_bf16 v[126:129], v[152:155], v[176:179], v[126:129]
	v_mfma_f32_16x16x32_bf16 v[70:73], v[152:155], v[184:187], v[70:73]
	v_mfma_f32_16x16x32_bf16 v[70:73], v[156:159], v[188:191], v[70:73]
	v_mfma_f32_16x16x32_bf16 v[66:69], v[148:151], v[188:191], v[66:69]
	v_mfma_f32_16x16x32_bf16 v[66:69], v[142:145], v[184:187], v[66:69]
	v_mfma_f32_16x16x32_bf16 v[74:77], v[142:145], v[192:195], v[74:77]
	v_mfma_f32_16x16x32_bf16 v[74:77], v[148:151], v[196:199], v[74:77]
	v_mfma_f32_16x16x32_bf16 v[78:81], v[156:159], v[196:199], v[78:81]
	v_mfma_f32_16x16x32_bf16 v[78:81], v[152:155], v[192:195], v[78:81]
	v_mfma_f32_16x16x32_bf16 v[86:89], v[152:155], v[200:203], v[86:89]
	v_mfma_f32_16x16x32_bf16 v[86:89], v[156:159], v[204:207], v[86:89]
	v_mfma_f32_16x16x32_bf16 v[82:85], v[148:151], v[204:207], v[82:85]
	v_mfma_f32_16x16x32_bf16 v[82:85], v[142:145], v[200:203], v[82:85]
	s_setprio 0
	s_setprio 1
	v_mfma_f32_16x16x32_bf16 v[90:93], v[160:163], v[176:179], v[90:93]
	v_mfma_f32_16x16x32_bf16 v[90:93], v[164:167], v[180:183], v[90:93]
	v_mfma_f32_16x16x32_bf16 v[94:97], v[172:175], v[180:183], v[94:97]
	v_mfma_f32_16x16x32_bf16 v[94:97], v[168:171], v[176:179], v[94:97]
	v_mfma_f32_16x16x32_bf16 v[102:105], v[168:171], v[184:187], v[102:105]
	v_mfma_f32_16x16x32_bf16 v[102:105], v[172:175], v[188:191], v[102:105]
	v_mfma_f32_16x16x32_bf16 v[98:101], v[164:167], v[188:191], v[98:101]
	v_mfma_f32_16x16x32_bf16 v[98:101], v[160:163], v[184:187], v[98:101]
	v_mfma_f32_16x16x32_bf16 v[106:109], v[160:163], v[192:195], v[106:109]
	v_mfma_f32_16x16x32_bf16 v[106:109], v[164:167], v[196:199], v[106:109]
	v_mfma_f32_16x16x32_bf16 v[110:113], v[172:175], v[196:199], v[110:113]
	v_mfma_f32_16x16x32_bf16 v[110:113], v[168:171], v[192:195], v[110:113]
	v_mfma_f32_16x16x32_bf16 v[118:121], v[168:171], v[200:203], v[118:121]
	v_mfma_f32_16x16x32_bf16 v[118:121], v[172:175], v[204:207], v[118:121]
	s_setprio 3
	s_barrier
	v_mfma_f32_16x16x32_bf16 v[114:117], v[164:167], v[204:207], v[114:117]
	v_mfma_f32_16x16x32_bf16 v[114:117], v[160:163], v[200:203], v[114:117]
	s_setprio 0
	s_add_i32 s44, 0, 0x18000
	v_add_u32_e32 v135, s44, v140
	s_add_i32 s45, 0, 0x1c000
	ds_read_b128 v[142:145], v135
	ds_read_b128 v[148:151], v135 offset:1024
	ds_read_b128 v[152:155], v135 offset:2048
	ds_read_b128 v[156:159], v135 offset:3072
	v_add_u32_e32 v135, s45, v140
	ds_read_b128 v[160:163], v135
	ds_read_b128 v[164:167], v135 offset:1024
	ds_read_b128 v[168:171], v135 offset:2048
	ds_read_b128 v[172:175], v135 offset:3072
	s_add_u32 s40, s40, 0x80000
	s_addc_u32 s41, s41, 0
	s_mov_b32 m0, s47
	ds_read_b128 v[176:179], v141 offset:32768
	ds_read_b128 v[180:183], v141 offset:33792
	ds_read_b128 v[184:187], v141 offset:34816
	ds_read_b128 v[188:191], v141 offset:35840
	ds_read_b128 v[192:195], v141 offset:36864
	ds_read_b128 v[196:199], v141 offset:37888
	ds_read_b128 v[200:203], v141 offset:38912
	ds_read_b128 v[204:207], v141 offset:39936
	global_load_lds_dwordx4 v130, s[40:41]
	s_mov_b32 m0, s48
	s_nop 0
	global_load_lds_dwordx4 v132, s[40:41]
	s_waitcnt vmcnt(8)
	s_waitcnt lgkmcnt(0)
	s_barrier
	s_setprio 1
	s_waitcnt lgkmcnt(0)
	v_mfma_f32_16x16x32_bf16 v[2:5], v[142:145], v[176:179], v[2:5]
	v_mfma_f32_16x16x32_bf16 v[2:5], v[148:151], v[180:183], v[2:5]
	v_mfma_f32_16x16x32_bf16 v[6:9], v[156:159], v[180:183], v[6:9]
	v_mfma_f32_16x16x32_bf16 v[6:9], v[152:155], v[176:179], v[6:9]
	v_mfma_f32_16x16x32_bf16 v[14:17], v[152:155], v[184:187], v[14:17]
	v_mfma_f32_16x16x32_bf16 v[14:17], v[156:159], v[188:191], v[14:17]
	v_mfma_f32_16x16x32_bf16 v[10:13], v[148:151], v[188:191], v[10:13]
	v_mfma_f32_16x16x32_bf16 v[10:13], v[142:145], v[184:187], v[10:13]
	v_mfma_f32_16x16x32_bf16 v[18:21], v[142:145], v[192:195], v[18:21]
	v_mfma_f32_16x16x32_bf16 v[18:21], v[148:151], v[196:199], v[18:21]
	v_mfma_f32_16x16x32_bf16 v[22:25], v[156:159], v[196:199], v[22:25]
	v_mfma_f32_16x16x32_bf16 v[22:25], v[152:155], v[192:195], v[22:25]
	v_mfma_f32_16x16x32_bf16 v[30:33], v[152:155], v[200:203], v[30:33]
	v_mfma_f32_16x16x32_bf16 v[30:33], v[156:159], v[204:207], v[30:33]
	v_mfma_f32_16x16x32_bf16 v[26:29], v[148:151], v[204:207], v[26:29]
	v_mfma_f32_16x16x32_bf16 v[26:29], v[142:145], v[200:203], v[26:29]
	s_setprio 0
	s_setprio 1
	v_mfma_f32_16x16x32_bf16 v[34:37], v[160:163], v[176:179], v[34:37]
	v_mfma_f32_16x16x32_bf16 v[34:37], v[164:167], v[180:183], v[34:37]
	v_mfma_f32_16x16x32_bf16 v[38:41], v[172:175], v[180:183], v[38:41]
	v_mfma_f32_16x16x32_bf16 v[38:41], v[168:171], v[176:179], v[38:41]
	v_mfma_f32_16x16x32_bf16 v[46:49], v[168:171], v[184:187], v[46:49]
	v_mfma_f32_16x16x32_bf16 v[46:49], v[172:175], v[188:191], v[46:49]
	v_mfma_f32_16x16x32_bf16 v[42:45], v[164:167], v[188:191], v[42:45]
	v_mfma_f32_16x16x32_bf16 v[42:45], v[160:163], v[184:187], v[42:45]
	v_mfma_f32_16x16x32_bf16 v[50:53], v[160:163], v[192:195], v[50:53]
	v_mfma_f32_16x16x32_bf16 v[50:53], v[164:167], v[196:199], v[50:53]
	v_mfma_f32_16x16x32_bf16 v[54:57], v[172:175], v[196:199], v[54:57]
	v_mfma_f32_16x16x32_bf16 v[54:57], v[168:171], v[192:195], v[54:57]
	v_mfma_f32_16x16x32_bf16 v[62:65], v[168:171], v[200:203], v[62:65]
	v_mfma_f32_16x16x32_bf16 v[62:65], v[172:175], v[204:207], v[62:65]
	s_setprio 3
	s_barrier
	v_mfma_f32_16x16x32_bf16 v[58:61], v[164:167], v[204:207], v[58:61]
	v_mfma_f32_16x16x32_bf16 v[58:61], v[160:163], v[200:203], v[58:61]
	s_setprio 0
	s_add_i32 s40, s44, s21
	v_lshl_add_u64 v[138:139], v[138:139], 0, s[6:7]
	s_mov_b32 m0, s40
	ds_read_b128 v[176:179], v141 offset:49152
	ds_read_b128 v[180:183], v141 offset:50176
	ds_read_b128 v[184:187], v141 offset:51200
	ds_read_b128 v[188:191], v141 offset:52224
	ds_read_b128 v[192:195], v141 offset:53248
	ds_read_b128 v[196:199], v141 offset:54272
	ds_read_b128 v[200:203], v141 offset:55296
	ds_read_b128 v[204:207], v141 offset:56320
	global_load_lds_dwordx4 v[138:139], off
	s_add_i32 m0, s40, 0x2000
	s_add_u32 s38, s38, 0x80080
	v_lshl_add_u64 v[138:139], v[208:209], 0, s[6:7]
	s_addc_u32 s39, s39, 0
	s_add_i32 s40, s45, s21
	global_load_lds_dwordx4 v[138:139], off
	s_mov_b32 m0, s40
	v_lshl_add_u64 v[138:139], v[210:211], 0, s[6:7]
	global_load_lds_dwordx4 v136, s[38:39]
	s_add_i32 m0, s40, 0x2000
	s_nop 0
	global_load_lds_dwordx4 v134, s[38:39]
	s_mov_b32 m0, s52
	s_nop 0
	global_load_lds_dwordx4 v[138:139], off
	v_lshl_add_u64 v[138:139], v[212:213], 0, s[6:7]
	s_mov_b32 m0, s53
	s_nop 0
	global_load_lds_dwordx4 v[138:139], off
	s_waitcnt vmcnt(8)
	s_waitcnt lgkmcnt(0)
	s_barrier
	s_setprio 1
	s_waitcnt lgkmcnt(0)
	v_mfma_f32_16x16x32_bf16 v[122:125], v[142:145], v[176:179], v[122:125]
	v_mfma_f32_16x16x32_bf16 v[122:125], v[148:151], v[180:183], v[122:125]
	v_mfma_f32_16x16x32_bf16 v[126:129], v[156:159], v[180:183], v[126:129]
	v_mfma_f32_16x16x32_bf16 v[126:129], v[152:155], v[176:179], v[126:129]
	v_mfma_f32_16x16x32_bf16 v[70:73], v[152:155], v[184:187], v[70:73]
	v_mfma_f32_16x16x32_bf16 v[70:73], v[156:159], v[188:191], v[70:73]
	v_mfma_f32_16x16x32_bf16 v[66:69], v[148:151], v[188:191], v[66:69]
	v_mfma_f32_16x16x32_bf16 v[66:69], v[142:145], v[184:187], v[66:69]
	v_mfma_f32_16x16x32_bf16 v[74:77], v[142:145], v[192:195], v[74:77]
	v_mfma_f32_16x16x32_bf16 v[74:77], v[148:151], v[196:199], v[74:77]
	v_mfma_f32_16x16x32_bf16 v[78:81], v[156:159], v[196:199], v[78:81]
	v_mfma_f32_16x16x32_bf16 v[78:81], v[152:155], v[192:195], v[78:81]
	v_mfma_f32_16x16x32_bf16 v[86:89], v[152:155], v[200:203], v[86:89]
	v_mfma_f32_16x16x32_bf16 v[86:89], v[156:159], v[204:207], v[86:89]
	v_mfma_f32_16x16x32_bf16 v[82:85], v[148:151], v[204:207], v[82:85]
	v_mfma_f32_16x16x32_bf16 v[82:85], v[142:145], v[200:203], v[82:85]
	s_setprio 0
	s_setprio 1
	v_mfma_f32_16x16x32_bf16 v[90:93], v[160:163], v[176:179], v[90:93]
	v_mfma_f32_16x16x32_bf16 v[90:93], v[164:167], v[180:183], v[90:93]
	v_mfma_f32_16x16x32_bf16 v[94:97], v[172:175], v[180:183], v[94:97]
	v_mfma_f32_16x16x32_bf16 v[94:97], v[168:171], v[176:179], v[94:97]
	v_mfma_f32_16x16x32_bf16 v[102:105], v[168:171], v[184:187], v[102:105]
	v_mfma_f32_16x16x32_bf16 v[102:105], v[172:175], v[188:191], v[102:105]
	v_mfma_f32_16x16x32_bf16 v[98:101], v[164:167], v[188:191], v[98:101]
	v_mfma_f32_16x16x32_bf16 v[98:101], v[160:163], v[184:187], v[98:101]
	v_mfma_f32_16x16x32_bf16 v[106:109], v[160:163], v[192:195], v[106:109]
	v_mfma_f32_16x16x32_bf16 v[106:109], v[164:167], v[196:199], v[106:109]
	v_mfma_f32_16x16x32_bf16 v[110:113], v[172:175], v[196:199], v[110:113]
	v_mfma_f32_16x16x32_bf16 v[110:113], v[168:171], v[192:195], v[110:113]
	v_mfma_f32_16x16x32_bf16 v[118:121], v[168:171], v[200:203], v[118:121]
	v_mfma_f32_16x16x32_bf16 v[118:121], v[172:175], v[204:207], v[118:121]
	s_setprio 3
	s_barrier
	v_mfma_f32_16x16x32_bf16 v[114:117], v[164:167], v[204:207], v[114:117]
	v_mfma_f32_16x16x32_bf16 v[114:117], v[160:163], v[200:203], v[114:117]
	s_setprio 0
	s_add_i32 s43, s43, 2
	s_add_u32 s36, s36, 0x100
	s_addc_u32 s37, s37, 0
	s_add_u32 s15, s15, 0x100
	s_addc_u32 s42, s42, 0
	s_cmp_gt_u32 s43, 29
	s_cbranch_scc0 .LBB0_383
	s_and_b64 vcc, exec, s[8:9]
	s_cbranch_vccz .LBB0_386
	s_barrier

.LBB0_462:
	v_add_u32_e32 v14, s54, v140
	v_add_u32_e32 v30, s55, v140
	ds_read_b128 v[2:5], v14
	ds_read_b128 v[6:9], v14 offset:1024
	ds_read_b128 v[10:13], v14 offset:2048
	ds_read_b128 v[14:17], v14 offset:3072
	ds_read_b128 v[18:21], v30
	ds_read_b128 v[22:25], v30 offset:1024
	ds_read_b128 v[26:29], v30 offset:2048
	ds_read_b128 v[30:33], v30 offset:3072
	v_add_u32_e32 v141, 0, v1
	ds_read_b128 v[34:37], v141
	ds_read_b128 v[38:41], v141 offset:1024
	ds_read_b128 v[42:45], v141 offset:2048
	ds_read_b128 v[46:49], v141 offset:3072
	ds_read_b128 v[50:53], v141 offset:4096
	ds_read_b128 v[54:57], v141 offset:5120
	ds_read_b128 v[58:61], v141 offset:6144
	ds_read_b128 v[62:65], v141 offset:7168
	s_waitcnt vmcnt(8)
	s_waitcnt lgkmcnt(0)
	s_barrier
	s_setprio 1
	s_waitcnt lgkmcnt(0)
	v_mfma_f32_16x16x32_bf16 v[66:69], v[2:5], v[34:37], 0
	v_mfma_f32_16x16x32_bf16 v[66:69], v[6:9], v[38:41], v[66:69]
	v_mfma_f32_16x16x32_bf16 v[70:73], v[10:13], v[34:37], 0
	v_mfma_f32_16x16x32_bf16 v[70:73], v[14:17], v[38:41], v[70:73]
	v_mfma_f32_16x16x32_bf16 v[78:81], v[10:13], v[42:45], 0
	v_mfma_f32_16x16x32_bf16 v[78:81], v[14:17], v[46:49], v[78:81]
	v_mfma_f32_16x16x32_bf16 v[74:77], v[2:5], v[42:45], 0
	v_mfma_f32_16x16x32_bf16 v[74:77], v[6:9], v[46:49], v[74:77]
	v_mfma_f32_16x16x32_bf16 v[82:85], v[2:5], v[50:53], 0
	v_mfma_f32_16x16x32_bf16 v[82:85], v[6:9], v[54:57], v[82:85]
	v_mfma_f32_16x16x32_bf16 v[86:89], v[10:13], v[50:53], 0
	v_mfma_f32_16x16x32_bf16 v[86:89], v[14:17], v[54:57], v[86:89]
	v_mfma_f32_16x16x32_bf16 v[94:97], v[10:13], v[58:61], 0
	v_mfma_f32_16x16x32_bf16 v[94:97], v[14:17], v[62:65], v[94:97]
	v_mfma_f32_16x16x32_bf16 v[90:93], v[2:5], v[58:61], 0
	v_mfma_f32_16x16x32_bf16 v[90:93], v[6:9], v[62:65], v[90:93]
	s_setprio 0
	s_setprio 1
	v_mfma_f32_16x16x32_bf16 v[98:101], v[18:21], v[34:37], 0
	v_mfma_f32_16x16x32_bf16 v[34:37], v[26:29], v[34:37], 0
	v_mfma_f32_16x16x32_bf16 v[102:105], v[18:21], v[42:45], 0
	v_mfma_f32_16x16x32_bf16 v[42:45], v[26:29], v[42:45], 0
	v_mfma_f32_16x16x32_bf16 v[106:109], v[18:21], v[50:53], 0
	v_mfma_f32_16x16x32_bf16 v[50:53], v[26:29], v[50:53], 0
	v_mfma_f32_16x16x32_bf16 v[110:113], v[18:21], v[58:61], 0
	v_mfma_f32_16x16x32_bf16 v[58:61], v[26:29], v[58:61], 0
	v_mfma_f32_16x16x32_bf16 v[98:101], v[22:25], v[38:41], v[98:101]
	v_mfma_f32_16x16x32_bf16 v[38:41], v[30:33], v[38:41], v[34:37]
	v_mfma_f32_16x16x32_bf16 v[102:105], v[22:25], v[46:49], v[102:105]
	v_mfma_f32_16x16x32_bf16 v[46:49], v[30:33], v[46:49], v[42:45]
	v_mfma_f32_16x16x32_bf16 v[106:109], v[22:25], v[54:57], v[106:109]
	v_mfma_f32_16x16x32_bf16 v[54:57], v[30:33], v[54:57], v[50:53]
	s_setprio 3
	s_barrier
	v_mfma_f32_16x16x32_bf16 v[110:113], v[22:25], v[62:65], v[110:113]
	v_mfma_f32_16x16x32_bf16 v[62:65], v[30:33], v[62:65], v[58:61]
	s_setprio 0
	v_lshl_add_u64 v[136:137], s[36:37], 0, v[130:131]
	s_add_i32 s62, s54, s21
	v_mov_b32_e32 v135, v131
	v_lshl_add_u64 v[142:143], v[136:137], 0, s[12:13]
	s_mov_b32 m0, s62
	v_lshl_add_u64 v[244:245], s[36:37], 0, v[134:135]
	ds_read_b128 v[34:37], v141 offset:16384
	ds_read_b128 v[42:45], v141 offset:17408
	ds_read_b128 v[50:53], v141 offset:18432
	ds_read_b128 v[58:61], v141 offset:19456
	ds_read_b128 v[114:117], v141 offset:20480
	ds_read_b128 v[118:121], v141 offset:21504
	ds_read_b128 v[122:125], v141 offset:22528
	ds_read_b128 v[126:129], v141 offset:23552
	global_load_lds_dwordx4 v[142:143], off
	v_lshl_add_u64 v[142:143], v[244:245], 0, s[12:13]
	s_add_i32 m0, s62, 0x2000
	s_add_i32 s62, s55, s21
	global_load_lds_dwordx4 v[142:143], off
	s_mov_b32 m0, s62
	v_mov_b32_e32 v139, v131
	global_load_lds_dwordx4 v130, s[38:39]
	s_add_i32 m0, s62, 0x2000
	v_lshl_add_u64 v[246:247], s[34:35], 0, v[138:139]
	v_mov_b32_e32 v133, v131
	global_load_lds_dwordx4 v134, s[38:39]
	v_lshl_add_u64 v[142:143], v[246:247], 0, s[12:13]
	s_mov_b32 m0, s33
	v_lshl_add_u64 v[248:249], s[34:35], 0, v[132:133]
	global_load_lds_dwordx4 v[142:143], off
	v_lshl_add_u64 v[142:143], v[248:249], 0, s[12:13]
	s_mov_b32 m0, s44
	s_nop 0
	global_load_lds_dwordx4 v[142:143], off
	s_waitcnt vmcnt(8)
	s_waitcnt lgkmcnt(0)
	s_barrier
	s_setprio 1
	s_waitcnt lgkmcnt(0)
	v_mfma_f32_16x16x32_bf16 v[142:145], v[2:5], v[34:37], 0
	v_mfma_f32_16x16x32_bf16 v[148:151], v[10:13], v[34:37], 0
	v_mfma_f32_16x16x32_bf16 v[152:155], v[2:5], v[50:53], 0
	v_mfma_f32_16x16x32_bf16 v[156:159], v[10:13], v[50:53], 0
	v_mfma_f32_16x16x32_bf16 v[160:163], v[2:5], v[114:117], 0
	v_mfma_f32_16x16x32_bf16 v[164:167], v[10:13], v[114:117], 0
	v_mfma_f32_16x16x32_bf16 v[2:5], v[2:5], v[122:125], 0
	v_mfma_f32_16x16x32_bf16 v[10:13], v[10:13], v[122:125], 0
	v_mfma_f32_16x16x32_bf16 v[142:145], v[6:9], v[42:45], v[142:145]
	v_mfma_f32_16x16x32_bf16 v[148:151], v[14:17], v[42:45], v[148:151]
	v_mfma_f32_16x16x32_bf16 v[152:155], v[6:9], v[58:61], v[152:155]
	v_mfma_f32_16x16x32_bf16 v[156:159], v[14:17], v[58:61], v[156:159]
	v_mfma_f32_16x16x32_bf16 v[160:163], v[6:9], v[118:121], v[160:163]
	v_mfma_f32_16x16x32_bf16 v[164:167], v[14:17], v[118:121], v[164:167]
	v_mfma_f32_16x16x32_bf16 v[168:171], v[6:9], v[126:129], v[2:5]
	v_mfma_f32_16x16x32_bf16 v[172:175], v[14:17], v[126:129], v[10:13]
	s_setprio 0
	s_setprio 1
	v_mfma_f32_16x16x32_bf16 v[2:5], v[18:21], v[34:37], 0
	v_mfma_f32_16x16x32_bf16 v[6:9], v[26:29], v[34:37], 0
	v_mfma_f32_16x16x32_bf16 v[10:13], v[18:21], v[50:53], 0
	v_mfma_f32_16x16x32_bf16 v[14:17], v[26:29], v[50:53], 0
	v_mfma_f32_16x16x32_bf16 v[34:37], v[18:21], v[114:117], 0
	v_mfma_f32_16x16x32_bf16 v[50:53], v[26:29], v[114:117], 0
	v_mfma_f32_16x16x32_bf16 v[18:21], v[18:21], v[122:125], 0
	v_mfma_f32_16x16x32_bf16 v[26:29], v[26:29], v[122:125], 0
	v_mfma_f32_16x16x32_bf16 v[114:117], v[22:25], v[42:45], v[2:5]
	v_mfma_f32_16x16x32_bf16 v[122:125], v[30:33], v[42:45], v[6:9]
	v_mfma_f32_16x16x32_bf16 v[184:187], v[22:25], v[118:121], v[34:37]
	v_mfma_f32_16x16x32_bf16 v[118:121], v[30:33], v[118:121], v[50:53]
	v_mfma_f32_16x16x32_bf16 v[188:191], v[22:25], v[126:129], v[18:21]
	v_mfma_f32_16x16x32_bf16 v[126:129], v[30:33], v[126:129], v[26:29]
	s_setprio 3
	s_barrier
	v_mfma_f32_16x16x32_bf16 v[176:179], v[22:25], v[58:61], v[10:13]
	v_mfma_f32_16x16x32_bf16 v[180:183], v[30:33], v[58:61], v[14:17]
	s_setprio 0
	s_add_i32 s62, 0, 0x18000
	v_add_u32_e32 v2, s62, v140
	s_add_i32 s63, 0, 0x1c000
	ds_read_b128 v[192:195], v2
	ds_read_b128 v[196:199], v2 offset:1024
	ds_read_b128 v[200:203], v2 offset:2048
	ds_read_b128 v[204:207], v2 offset:3072
	v_add_u32_e32 v2, s63, v140
	ds_read_b128 v[208:211], v2
	ds_read_b128 v[212:215], v2 offset:1024
	ds_read_b128 v[216:219], v2 offset:2048
	ds_read_b128 v[220:223], v2 offset:3072
	s_mov_b32 m0, s45
	ds_read_b128 v[42:45], v141 offset:32768
	ds_read_b128 v[50:53], v141 offset:33792
	ds_read_b128 v[58:61], v141 offset:34816
	ds_read_b128 v[224:227], v141 offset:35840
	ds_read_b128 v[228:231], v141 offset:36864
	ds_read_b128 v[232:235], v141 offset:37888
	ds_read_b128 v[236:239], v141 offset:38912
	ds_read_b128 v[240:243], v141 offset:39936
	global_load_lds_dwordx4 v138, s[40:41]
	s_mov_b32 m0, s46
	s_nop 0
	global_load_lds_dwordx4 v132, s[40:41]
	s_waitcnt vmcnt(8)
	s_waitcnt lgkmcnt(0)
	s_barrier
	s_setprio 1
	s_waitcnt lgkmcnt(0)
	v_mfma_f32_16x16x32_bf16 v[2:5], v[192:195], v[42:45], v[66:69]
	v_mfma_f32_16x16x32_bf16 v[6:9], v[200:203], v[42:45], v[70:73]
	v_mfma_f32_16x16x32_bf16 v[10:13], v[192:195], v[58:61], v[74:77]
	v_mfma_f32_16x16x32_bf16 v[14:17], v[200:203], v[58:61], v[78:81]
	v_mfma_f32_16x16x32_bf16 v[18:21], v[192:195], v[228:231], v[82:85]
	v_mfma_f32_16x16x32_bf16 v[22:25], v[200:203], v[228:231], v[86:89]
	v_mfma_f32_16x16x32_bf16 v[26:29], v[192:195], v[236:239], v[90:93]
	v_mfma_f32_16x16x32_bf16 v[30:33], v[200:203], v[236:239], v[94:97]
	v_mfma_f32_16x16x32_bf16 v[2:5], v[196:199], v[50:53], v[2:5]
	v_mfma_f32_16x16x32_bf16 v[6:9], v[204:207], v[50:53], v[6:9]
	v_mfma_f32_16x16x32_bf16 v[10:13], v[196:199], v[224:227], v[10:13]
	v_mfma_f32_16x16x32_bf16 v[14:17], v[204:207], v[224:227], v[14:17]
	v_mfma_f32_16x16x32_bf16 v[18:21], v[196:199], v[232:235], v[18:21]
	v_mfma_f32_16x16x32_bf16 v[22:25], v[204:207], v[232:235], v[22:25]
	v_mfma_f32_16x16x32_bf16 v[26:29], v[196:199], v[240:243], v[26:29]
	v_mfma_f32_16x16x32_bf16 v[30:33], v[204:207], v[240:243], v[30:33]
	s_setprio 0
	s_setprio 1
	v_mfma_f32_16x16x32_bf16 v[34:37], v[208:211], v[42:45], v[98:101]
	v_mfma_f32_16x16x32_bf16 v[38:41], v[216:219], v[42:45], v[38:41]
	v_mfma_f32_16x16x32_bf16 v[34:37], v[212:215], v[50:53], v[34:37]
	v_mfma_f32_16x16x32_bf16 v[38:41], v[220:223], v[50:53], v[38:41]
	v_mfma_f32_16x16x32_bf16 v[42:45], v[208:211], v[58:61], v[102:105]
	v_mfma_f32_16x16x32_bf16 v[46:49], v[216:219], v[58:61], v[46:49]
	v_mfma_f32_16x16x32_bf16 v[50:53], v[208:211], v[228:231], v[106:109]
	v_mfma_f32_16x16x32_bf16 v[54:57], v[216:219], v[228:231], v[54:57]
	v_mfma_f32_16x16x32_bf16 v[58:61], v[208:211], v[236:239], v[110:113]
	v_mfma_f32_16x16x32_bf16 v[62:65], v[216:219], v[236:239], v[62:65]
	v_mfma_f32_16x16x32_bf16 v[42:45], v[212:215], v[224:227], v[42:45]
	v_mfma_f32_16x16x32_bf16 v[46:49], v[220:223], v[224:227], v[46:49]
	v_mfma_f32_16x16x32_bf16 v[50:53], v[212:215], v[232:235], v[50:53]
	v_mfma_f32_16x16x32_bf16 v[54:57], v[220:223], v[232:235], v[54:57]
	s_setprio 3
	s_barrier
	v_mfma_f32_16x16x32_bf16 v[58:61], v[212:215], v[240:243], v[58:61]
	v_mfma_f32_16x16x32_bf16 v[62:65], v[220:223], v[240:243], v[62:65]
	s_setprio 0
	s_add_i32 s62, s62, s21
	v_lshl_add_u64 v[66:67], v[136:137], 0, s[14:15]
	s_mov_b32 m0, s62
	ds_read_b128 v[102:105], v141 offset:49152
	ds_read_b128 v[106:109], v141 offset:50176
	ds_read_b128 v[110:113], v141 offset:51200
	ds_read_b128 v[224:227], v141 offset:52224
	ds_read_b128 v[228:231], v141 offset:53248
	ds_read_b128 v[232:235], v141 offset:54272
	ds_read_b128 v[236:239], v141 offset:55296
	ds_read_b128 v[240:243], v141 offset:56320
	global_load_lds_dwordx4 v[66:67], off
	v_lshl_add_u64 v[66:67], v[244:245], 0, s[14:15]
	s_add_i32 m0, s62, 0x2000
	s_add_i32 s62, s63, s21
	global_load_lds_dwordx4 v[66:67], off
	s_mov_b32 m0, s62
	v_lshl_add_u64 v[66:67], v[246:247], 0, s[14:15]
	global_load_lds_dwordx4 v130, s[42:43]
	s_add_i32 m0, s62, 0x2000
	s_nop 0
	global_load_lds_dwordx4 v134, s[42:43]
	s_mov_b32 m0, s50
	s_nop 0
	global_load_lds_dwordx4 v[66:67], off
	v_lshl_add_u64 v[66:67], v[248:249], 0, s[14:15]
	s_mov_b32 m0, s51
	s_nop 0
	global_load_lds_dwordx4 v[66:67], off
	s_waitcnt vmcnt(8)
	s_waitcnt lgkmcnt(0)
	s_barrier
	s_setprio 1
	s_waitcnt lgkmcnt(0)
	v_mfma_f32_16x16x32_bf16 v[66:69], v[192:195], v[102:105], v[142:145]
	v_mfma_f32_16x16x32_bf16 v[70:73], v[200:203], v[102:105], v[148:151]
	v_mfma_f32_16x16x32_bf16 v[74:77], v[192:195], v[110:113], v[152:155]
	v_mfma_f32_16x16x32_bf16 v[78:81], v[200:203], v[110:113], v[156:159]
	v_mfma_f32_16x16x32_bf16 v[82:85], v[192:195], v[228:231], v[160:163]
	v_mfma_f32_16x16x32_bf16 v[86:89], v[200:203], v[228:231], v[164:167]
	v_mfma_f32_16x16x32_bf16 v[90:93], v[192:195], v[236:239], v[168:171]
	v_mfma_f32_16x16x32_bf16 v[94:97], v[200:203], v[236:239], v[172:175]
	v_mfma_f32_16x16x32_bf16 v[66:69], v[196:199], v[106:109], v[66:69]
	v_mfma_f32_16x16x32_bf16 v[70:73], v[204:207], v[106:109], v[70:73]
	v_mfma_f32_16x16x32_bf16 v[74:77], v[196:199], v[224:227], v[74:77]
	v_mfma_f32_16x16x32_bf16 v[78:81], v[204:207], v[224:227], v[78:81]
	v_mfma_f32_16x16x32_bf16 v[82:85], v[196:199], v[232:235], v[82:85]
	v_mfma_f32_16x16x32_bf16 v[86:89], v[204:207], v[232:235], v[86:89]
	v_mfma_f32_16x16x32_bf16 v[90:93], v[196:199], v[240:243], v[90:93]
	v_mfma_f32_16x16x32_bf16 v[94:97], v[204:207], v[240:243], v[94:97]
	s_setprio 0
	s_setprio 1
	v_mfma_f32_16x16x32_bf16 v[98:101], v[208:211], v[102:105], v[114:117]
	v_mfma_f32_16x16x32_bf16 v[102:105], v[216:219], v[102:105], v[122:125]
	v_mfma_f32_16x16x32_bf16 v[98:101], v[212:215], v[106:109], v[98:101]
	v_mfma_f32_16x16x32_bf16 v[102:105], v[220:223], v[106:109], v[102:105]
	v_mfma_f32_16x16x32_bf16 v[106:109], v[208:211], v[110:113], v[176:179]
	v_mfma_f32_16x16x32_bf16 v[110:113], v[216:219], v[110:113], v[180:183]
	v_mfma_f32_16x16x32_bf16 v[114:117], v[208:211], v[228:231], v[184:187]
	v_mfma_f32_16x16x32_bf16 v[118:121], v[216:219], v[228:231], v[118:121]
	v_mfma_f32_16x16x32_bf16 v[122:125], v[208:211], v[236:239], v[188:191]
	v_mfma_f32_16x16x32_bf16 v[126:129], v[216:219], v[236:239], v[126:129]
	v_mfma_f32_16x16x32_bf16 v[106:109], v[212:215], v[224:227], v[106:109]
	v_mfma_f32_16x16x32_bf16 v[110:113], v[220:223], v[224:227], v[110:113]
	v_mfma_f32_16x16x32_bf16 v[114:117], v[212:215], v[232:235], v[114:117]
	v_mfma_f32_16x16x32_bf16 v[118:121], v[220:223], v[232:235], v[118:121]
	s_setprio 3
	s_barrier
	v_mfma_f32_16x16x32_bf16 v[122:125], v[212:215], v[240:243], v[122:125]
	v_mfma_f32_16x16x32_bf16 v[126:129], v[220:223], v[240:243], v[126:129]
	s_setprio 0
	s_add_i32 s61, s61, 2
	s_cmp_ge_i32 s61, s60
	s_cbranch_scc0 .LBB0_462
	v_mov_b32_e32 v136, v130
	s_branch .LBB0_465

.LBB0_466:
	v_add_u32_e32 v133, s54, v140
	ds_read_b128 v[142:145], v133
	ds_read_b128 v[148:151], v133 offset:1024
	ds_read_b128 v[152:155], v133 offset:2048
	ds_read_b128 v[156:159], v133 offset:3072
	v_add_u32_e32 v133, s55, v140
	ds_read_b128 v[160:163], v133
	ds_read_b128 v[164:167], v133 offset:1024
	ds_read_b128 v[168:171], v133 offset:2048
	ds_read_b128 v[172:175], v133 offset:3072
	s_add_u32 s36, s34, 0xffc00080
	s_addc_u32 s37, s35, -1
	s_cmp_eq_u32 s42, 4
	s_cselect_b32 s39, s29, s37
	s_cselect_b32 s38, s28, s36
	s_cselect_b32 s37, s31, s41
	s_cselect_b32 s36, s30, s40
	s_mov_b32 m0, s52
	v_add_u32_e32 v141, 0, v1
	ds_read_b128 v[176:179], v141
	ds_read_b128 v[180:183], v141 offset:1024
	ds_read_b128 v[184:187], v141 offset:2048
	ds_read_b128 v[188:191], v141 offset:3072
	ds_read_b128 v[192:195], v141 offset:4096
	ds_read_b128 v[196:199], v141 offset:5120
	ds_read_b128 v[200:203], v141 offset:6144
	ds_read_b128 v[204:207], v141 offset:7168
	global_load_lds_dwordx4 v130, s[34:35]
	s_mov_b32 m0, s53
	v_mov_b32_e32 v133, v131
	global_load_lds_dwordx4 v132, s[34:35]
	s_waitcnt vmcnt(8)
	s_waitcnt lgkmcnt(0)
	s_barrier
	s_setprio 1
	s_waitcnt lgkmcnt(0)
	v_mfma_f32_16x16x32_bf16 v[2:5], v[142:145], v[176:179], v[2:5]
	v_mfma_f32_16x16x32_bf16 v[2:5], v[148:151], v[180:183], v[2:5]
	v_mfma_f32_16x16x32_bf16 v[6:9], v[156:159], v[180:183], v[6:9]
	v_mfma_f32_16x16x32_bf16 v[6:9], v[152:155], v[176:179], v[6:9]
	v_mfma_f32_16x16x32_bf16 v[14:17], v[152:155], v[184:187], v[14:17]
	v_mfma_f32_16x16x32_bf16 v[14:17], v[156:159], v[188:191], v[14:17]
	v_mfma_f32_16x16x32_bf16 v[10:13], v[148:151], v[188:191], v[10:13]
	v_mfma_f32_16x16x32_bf16 v[10:13], v[142:145], v[184:187], v[10:13]
	v_mfma_f32_16x16x32_bf16 v[18:21], v[142:145], v[192:195], v[18:21]
	v_mfma_f32_16x16x32_bf16 v[18:21], v[148:151], v[196:199], v[18:21]
	v_mfma_f32_16x16x32_bf16 v[22:25], v[156:159], v[196:199], v[22:25]
	v_mfma_f32_16x16x32_bf16 v[22:25], v[152:155], v[192:195], v[22:25]
	v_mfma_f32_16x16x32_bf16 v[30:33], v[152:155], v[200:203], v[30:33]
	v_mfma_f32_16x16x32_bf16 v[30:33], v[156:159], v[204:207], v[30:33]
	v_mfma_f32_16x16x32_bf16 v[26:29], v[148:151], v[204:207], v[26:29]
	v_mfma_f32_16x16x32_bf16 v[26:29], v[142:145], v[200:203], v[26:29]
	s_setprio 0
	s_setprio 1
	v_mfma_f32_16x16x32_bf16 v[34:37], v[160:163], v[176:179], v[34:37]
	v_mfma_f32_16x16x32_bf16 v[34:37], v[164:167], v[180:183], v[34:37]
	v_mfma_f32_16x16x32_bf16 v[38:41], v[172:175], v[180:183], v[38:41]
	v_mfma_f32_16x16x32_bf16 v[38:41], v[168:171], v[176:179], v[38:41]
	v_mfma_f32_16x16x32_bf16 v[46:49], v[168:171], v[184:187], v[46:49]
	v_mfma_f32_16x16x32_bf16 v[46:49], v[172:175], v[188:191], v[46:49]
	v_mfma_f32_16x16x32_bf16 v[42:45], v[164:167], v[188:191], v[42:45]
	v_mfma_f32_16x16x32_bf16 v[42:45], v[160:163], v[184:187], v[42:45]
	v_mfma_f32_16x16x32_bf16 v[50:53], v[160:163], v[192:195], v[50:53]
	v_mfma_f32_16x16x32_bf16 v[50:53], v[164:167], v[196:199], v[50:53]
	v_mfma_f32_16x16x32_bf16 v[54:57], v[172:175], v[196:199], v[54:57]
	v_mfma_f32_16x16x32_bf16 v[54:57], v[168:171], v[192:195], v[54:57]
	v_mfma_f32_16x16x32_bf16 v[62:65], v[168:171], v[200:203], v[62:65]
	v_mfma_f32_16x16x32_bf16 v[62:65], v[172:175], v[204:207], v[62:65]
	s_setprio 3
	s_barrier
	v_mfma_f32_16x16x32_bf16 v[58:61], v[164:167], v[204:207], v[58:61]
	v_mfma_f32_16x16x32_bf16 v[58:61], v[160:163], v[200:203], v[58:61]
	s_setprio 0
	s_add_i32 s43, s54, s21
	s_mov_b32 m0, s43
	ds_read_b128 v[176:179], v141 offset:16384
	ds_read_b128 v[180:183], v141 offset:17408
	ds_read_b128 v[184:187], v141 offset:18432
	ds_read_b128 v[188:191], v141 offset:19456
	ds_read_b128 v[192:195], v141 offset:20480
	ds_read_b128 v[196:199], v141 offset:21504
	ds_read_b128 v[200:203], v141 offset:22528
	ds_read_b128 v[204:207], v141 offset:23552
	global_load_lds_dwordx4 v136, s[36:37]
	s_add_i32 m0, s43, 0x2000
	s_add_u32 s60, s36, 0x80000
	s_addc_u32 s61, s37, 0
	s_add_i32 s43, s55, s21
	global_load_lds_dwordx4 v134, s[36:37]
	s_mov_b32 m0, s43
	v_mov_b32_e32 v137, v131
	global_load_lds_dwordx4 v136, s[60:61]
	s_add_i32 m0, s43, 0x2000
	v_mov_b32_e32 v135, v131
	global_load_lds_dwordx4 v134, s[60:61]
	s_mov_b32 m0, s33
	v_lshl_add_u64 v[138:139], s[36:37], 0, v[136:137]
	global_load_lds_dwordx4 v130, s[38:39]
	s_mov_b32 m0, s44
	v_lshl_add_u64 v[208:209], s[36:37], 0, v[134:135]
	global_load_lds_dwordx4 v132, s[38:39]
	s_waitcnt vmcnt(8)
	s_waitcnt lgkmcnt(0)
	v_lshl_add_u64 v[210:211], s[38:39], 0, v[130:131]
	v_lshl_add_u64 v[212:213], s[38:39], 0, v[132:133]
	s_barrier
	s_setprio 1
	s_waitcnt lgkmcnt(0)
	v_mfma_f32_16x16x32_bf16 v[66:69], v[142:145], v[176:179], v[66:69]
	v_mfma_f32_16x16x32_bf16 v[66:69], v[148:151], v[180:183], v[66:69]
	v_mfma_f32_16x16x32_bf16 v[70:73], v[156:159], v[180:183], v[70:73]
	v_mfma_f32_16x16x32_bf16 v[70:73], v[152:155], v[176:179], v[70:73]
	v_mfma_f32_16x16x32_bf16 v[78:81], v[152:155], v[184:187], v[78:81]
	v_mfma_f32_16x16x32_bf16 v[78:81], v[156:159], v[188:191], v[78:81]
	v_mfma_f32_16x16x32_bf16 v[74:77], v[148:151], v[188:191], v[74:77]
	v_mfma_f32_16x16x32_bf16 v[74:77], v[142:145], v[184:187], v[74:77]
	v_mfma_f32_16x16x32_bf16 v[82:85], v[142:145], v[192:195], v[82:85]
	v_mfma_f32_16x16x32_bf16 v[82:85], v[148:151], v[196:199], v[82:85]
	v_mfma_f32_16x16x32_bf16 v[86:89], v[156:159], v[196:199], v[86:89]
	v_mfma_f32_16x16x32_bf16 v[86:89], v[152:155], v[192:195], v[86:89]
	v_mfma_f32_16x16x32_bf16 v[94:97], v[152:155], v[200:203], v[94:97]
	v_mfma_f32_16x16x32_bf16 v[94:97], v[156:159], v[204:207], v[94:97]
	v_mfma_f32_16x16x32_bf16 v[90:93], v[148:151], v[204:207], v[90:93]
	v_mfma_f32_16x16x32_bf16 v[90:93], v[142:145], v[200:203], v[90:93]
	s_setprio 0
	s_setprio 1
	v_mfma_f32_16x16x32_bf16 v[98:101], v[160:163], v[176:179], v[98:101]
	v_mfma_f32_16x16x32_bf16 v[98:101], v[164:167], v[180:183], v[98:101]
	v_mfma_f32_16x16x32_bf16 v[102:105], v[172:175], v[180:183], v[102:105]
	v_mfma_f32_16x16x32_bf16 v[102:105], v[168:171], v[176:179], v[102:105]
	v_mfma_f32_16x16x32_bf16 v[110:113], v[168:171], v[184:187], v[110:113]
	v_mfma_f32_16x16x32_bf16 v[110:113], v[172:175], v[188:191], v[110:113]
	v_mfma_f32_16x16x32_bf16 v[106:109], v[164:167], v[188:191], v[106:109]
	v_mfma_f32_16x16x32_bf16 v[106:109], v[160:163], v[184:187], v[106:109]
	v_mfma_f32_16x16x32_bf16 v[114:117], v[160:163], v[192:195], v[114:117]
	v_mfma_f32_16x16x32_bf16 v[114:117], v[164:167], v[196:199], v[114:117]
	v_mfma_f32_16x16x32_bf16 v[118:121], v[172:175], v[196:199], v[118:121]
	v_mfma_f32_16x16x32_bf16 v[118:121], v[168:171], v[192:195], v[118:121]
	v_mfma_f32_16x16x32_bf16 v[126:129], v[168:171], v[200:203], v[126:129]
	v_mfma_f32_16x16x32_bf16 v[126:129], v[172:175], v[204:207], v[126:129]
	s_setprio 3
	s_barrier
	v_mfma_f32_16x16x32_bf16 v[122:125], v[164:167], v[204:207], v[122:125]
	v_mfma_f32_16x16x32_bf16 v[122:125], v[160:163], v[200:203], v[122:125]
	s_setprio 0
	s_add_i32 s43, 0, 0x18000
	v_add_u32_e32 v135, s43, v140
	s_add_i32 s60, 0, 0x1c000
	ds_read_b128 v[142:145], v135
	ds_read_b128 v[148:151], v135 offset:1024
	ds_read_b128 v[152:155], v135 offset:2048
	ds_read_b128 v[156:159], v135 offset:3072
	v_add_u32_e32 v135, s60, v140
	ds_read_b128 v[160:163], v135
	ds_read_b128 v[164:167], v135 offset:1024
	ds_read_b128 v[168:171], v135 offset:2048
	ds_read_b128 v[172:175], v135 offset:3072
	s_add_u32 s38, s38, 0x400000
	s_addc_u32 s39, s39, 0
	s_mov_b32 m0, s45
	ds_read_b128 v[176:179], v141 offset:32768
	ds_read_b128 v[180:183], v141 offset:33792
	ds_read_b128 v[184:187], v141 offset:34816
	ds_read_b128 v[188:191], v141 offset:35840
	ds_read_b128 v[192:195], v141 offset:36864
	ds_read_b128 v[196:199], v141 offset:37888
	ds_read_b128 v[200:203], v141 offset:38912
	ds_read_b128 v[204:207], v141 offset:39936
	global_load_lds_dwordx4 v130, s[38:39]
	s_mov_b32 m0, s46
	s_nop 0
	global_load_lds_dwordx4 v132, s[38:39]
	s_waitcnt vmcnt(8)
	s_waitcnt lgkmcnt(0)
	s_barrier
	s_setprio 1
	s_waitcnt lgkmcnt(0)
	v_mfma_f32_16x16x32_bf16 v[2:5], v[142:145], v[176:179], v[2:5]
	v_mfma_f32_16x16x32_bf16 v[2:5], v[148:151], v[180:183], v[2:5]
	v_mfma_f32_16x16x32_bf16 v[6:9], v[156:159], v[180:183], v[6:9]
	v_mfma_f32_16x16x32_bf16 v[6:9], v[152:155], v[176:179], v[6:9]
	v_mfma_f32_16x16x32_bf16 v[14:17], v[152:155], v[184:187], v[14:17]
	v_mfma_f32_16x16x32_bf16 v[14:17], v[156:159], v[188:191], v[14:17]
	v_mfma_f32_16x16x32_bf16 v[10:13], v[148:151], v[188:191], v[10:13]
	v_mfma_f32_16x16x32_bf16 v[10:13], v[142:145], v[184:187], v[10:13]
	v_mfma_f32_16x16x32_bf16 v[18:21], v[142:145], v[192:195], v[18:21]
	v_mfma_f32_16x16x32_bf16 v[18:21], v[148:151], v[196:199], v[18:21]
	v_mfma_f32_16x16x32_bf16 v[22:25], v[156:159], v[196:199], v[22:25]
	v_mfma_f32_16x16x32_bf16 v[22:25], v[152:155], v[192:195], v[22:25]
	v_mfma_f32_16x16x32_bf16 v[30:33], v[152:155], v[200:203], v[30:33]
	v_mfma_f32_16x16x32_bf16 v[30:33], v[156:159], v[204:207], v[30:33]
	v_mfma_f32_16x16x32_bf16 v[26:29], v[148:151], v[204:207], v[26:29]
	v_mfma_f32_16x16x32_bf16 v[26:29], v[142:145], v[200:203], v[26:29]
	s_setprio 0
	s_setprio 1
	v_mfma_f32_16x16x32_bf16 v[34:37], v[160:163], v[176:179], v[34:37]
	v_mfma_f32_16x16x32_bf16 v[34:37], v[164:167], v[180:183], v[34:37]
	v_mfma_f32_16x16x32_bf16 v[38:41], v[172:175], v[180:183], v[38:41]
	v_mfma_f32_16x16x32_bf16 v[38:41], v[168:171], v[176:179], v[38:41]
	v_mfma_f32_16x16x32_bf16 v[46:49], v[168:171], v[184:187], v[46:49]
	v_mfma_f32_16x16x32_bf16 v[46:49], v[172:175], v[188:191], v[46:49]
	v_mfma_f32_16x16x32_bf16 v[42:45], v[164:167], v[188:191], v[42:45]
	v_mfma_f32_16x16x32_bf16 v[42:45], v[160:163], v[184:187], v[42:45]
	v_mfma_f32_16x16x32_bf16 v[50:53], v[160:163], v[192:195], v[50:53]
	v_mfma_f32_16x16x32_bf16 v[50:53], v[164:167], v[196:199], v[50:53]
	v_mfma_f32_16x16x32_bf16 v[54:57], v[172:175], v[196:199], v[54:57]
	v_mfma_f32_16x16x32_bf16 v[54:57], v[168:171], v[192:195], v[54:57]
	v_mfma_f32_16x16x32_bf16 v[62:65], v[168:171], v[200:203], v[62:65]
	v_mfma_f32_16x16x32_bf16 v[62:65], v[172:175], v[204:207], v[62:65]
	s_setprio 3
	s_barrier
	v_mfma_f32_16x16x32_bf16 v[58:61], v[164:167], v[204:207], v[58:61]
	v_mfma_f32_16x16x32_bf16 v[58:61], v[160:163], v[200:203], v[58:61]
	s_setprio 0
	s_add_i32 s38, s43, s21
	v_lshl_add_u64 v[138:139], v[138:139], 0, s[8:9]
	s_mov_b32 m0, s38
	ds_read_b128 v[176:179], v141 offset:49152
	ds_read_b128 v[180:183], v141 offset:50176
	ds_read_b128 v[184:187], v141 offset:51200
	ds_read_b128 v[188:191], v141 offset:52224
	ds_read_b128 v[192:195], v141 offset:53248
	ds_read_b128 v[196:199], v141 offset:54272
	ds_read_b128 v[200:203], v141 offset:55296
	ds_read_b128 v[204:207], v141 offset:56320
	global_load_lds_dwordx4 v[138:139], off
	s_add_i32 m0, s38, 0x2000
	s_add_u32 s36, s36, 0x80080
	v_lshl_add_u64 v[138:139], v[208:209], 0, s[8:9]
	s_addc_u32 s37, s37, 0
	s_add_i32 s38, s60, s21
	global_load_lds_dwordx4 v[138:139], off
	s_mov_b32 m0, s38
	v_lshl_add_u64 v[138:139], v[210:211], 0, s[8:9]
	global_load_lds_dwordx4 v136, s[36:37]
	s_add_i32 m0, s38, 0x2000
	s_nop 0
	global_load_lds_dwordx4 v134, s[36:37]
	s_mov_b32 m0, s50
	s_nop 0
	global_load_lds_dwordx4 v[138:139], off
	v_lshl_add_u64 v[138:139], v[212:213], 0, s[8:9]
	s_mov_b32 m0, s51
	s_nop 0
	global_load_lds_dwordx4 v[138:139], off
	s_waitcnt vmcnt(8)
	s_waitcnt lgkmcnt(0)
	s_barrier
	s_setprio 1
	s_waitcnt lgkmcnt(0)
	v_mfma_f32_16x16x32_bf16 v[66:69], v[142:145], v[176:179], v[66:69]
	v_mfma_f32_16x16x32_bf16 v[66:69], v[148:151], v[180:183], v[66:69]
	v_mfma_f32_16x16x32_bf16 v[70:73], v[156:159], v[180:183], v[70:73]
	v_mfma_f32_16x16x32_bf16 v[70:73], v[152:155], v[176:179], v[70:73]
	v_mfma_f32_16x16x32_bf16 v[78:81], v[152:155], v[184:187], v[78:81]
	v_mfma_f32_16x16x32_bf16 v[78:81], v[156:159], v[188:191], v[78:81]
	v_mfma_f32_16x16x32_bf16 v[74:77], v[148:151], v[188:191], v[74:77]
	v_mfma_f32_16x16x32_bf16 v[74:77], v[142:145], v[184:187], v[74:77]
	v_mfma_f32_16x16x32_bf16 v[82:85], v[142:145], v[192:195], v[82:85]
	v_mfma_f32_16x16x32_bf16 v[82:85], v[148:151], v[196:199], v[82:85]
	v_mfma_f32_16x16x32_bf16 v[86:89], v[156:159], v[196:199], v[86:89]
	v_mfma_f32_16x16x32_bf16 v[86:89], v[152:155], v[192:195], v[86:89]
	v_mfma_f32_16x16x32_bf16 v[94:97], v[152:155], v[200:203], v[94:97]
	v_mfma_f32_16x16x32_bf16 v[94:97], v[156:159], v[204:207], v[94:97]
	v_mfma_f32_16x16x32_bf16 v[90:93], v[148:151], v[204:207], v[90:93]
	v_mfma_f32_16x16x32_bf16 v[90:93], v[142:145], v[200:203], v[90:93]
	s_setprio 0
	s_setprio 1
	v_mfma_f32_16x16x32_bf16 v[98:101], v[160:163], v[176:179], v[98:101]
	v_mfma_f32_16x16x32_bf16 v[98:101], v[164:167], v[180:183], v[98:101]
	v_mfma_f32_16x16x32_bf16 v[102:105], v[172:175], v[180:183], v[102:105]
	v_mfma_f32_16x16x32_bf16 v[102:105], v[168:171], v[176:179], v[102:105]
	v_mfma_f32_16x16x32_bf16 v[110:113], v[168:171], v[184:187], v[110:113]
	v_mfma_f32_16x16x32_bf16 v[110:113], v[172:175], v[188:191], v[110:113]
	v_mfma_f32_16x16x32_bf16 v[106:109], v[164:167], v[188:191], v[106:109]
	v_mfma_f32_16x16x32_bf16 v[106:109], v[160:163], v[184:187], v[106:109]
	v_mfma_f32_16x16x32_bf16 v[114:117], v[160:163], v[192:195], v[114:117]
	v_mfma_f32_16x16x32_bf16 v[114:117], v[164:167], v[196:199], v[114:117]
	v_mfma_f32_16x16x32_bf16 v[118:121], v[172:175], v[196:199], v[118:121]
	v_mfma_f32_16x16x32_bf16 v[118:121], v[168:171], v[192:195], v[118:121]
	v_mfma_f32_16x16x32_bf16 v[126:129], v[168:171], v[200:203], v[126:129]
	v_mfma_f32_16x16x32_bf16 v[126:129], v[172:175], v[204:207], v[126:129]
	s_setprio 3
	s_barrier
	v_mfma_f32_16x16x32_bf16 v[122:125], v[164:167], v[204:207], v[122:125]
	v_mfma_f32_16x16x32_bf16 v[122:125], v[160:163], v[200:203], v[122:125]
	s_setprio 0
	s_add_i32 s42, s42, 2
	s_add_u32 s34, s34, 0x100
	s_addc_u32 s35, s35, 0
	s_add_u32 s40, s40, 0x100
	s_addc_u32 s41, s41, 0
	s_cmp_gt_u32 s42, 5
	s_cbranch_scc0 .LBB0_466
	s_and_b64 vcc, exec, s[10:11]
	s_cbranch_vccz .LBB0_469
	s_barrier

.LBB0_495:
	v_add_u32_e32 v14, s58, v140
	v_add_u32_e32 v30, s59, v140
	ds_read_b128 v[2:5], v14
	ds_read_b128 v[6:9], v14 offset:1024
	ds_read_b128 v[10:13], v14 offset:2048
	ds_read_b128 v[14:17], v14 offset:3072
	ds_read_b128 v[18:21], v30
	ds_read_b128 v[22:25], v30 offset:1024
	ds_read_b128 v[26:29], v30 offset:2048
	ds_read_b128 v[30:33], v30 offset:3072
	v_add_u32_e32 v141, 0, v1
	ds_read_b128 v[34:37], v141
	ds_read_b128 v[38:41], v141 offset:1024
	ds_read_b128 v[42:45], v141 offset:2048
	ds_read_b128 v[46:49], v141 offset:3072
	ds_read_b128 v[50:53], v141 offset:4096
	ds_read_b128 v[54:57], v141 offset:5120
	ds_read_b128 v[58:61], v141 offset:6144
	ds_read_b128 v[62:65], v141 offset:7168
	s_waitcnt vmcnt(8)
	s_waitcnt lgkmcnt(0)
	s_barrier
	s_setprio 1
	s_waitcnt lgkmcnt(0)
	v_mfma_f32_16x16x32_bf16 v[66:69], v[2:5], v[34:37], 0
	v_mfma_f32_16x16x32_bf16 v[66:69], v[6:9], v[38:41], v[66:69]
	v_mfma_f32_16x16x32_bf16 v[70:73], v[10:13], v[34:37], 0
	v_mfma_f32_16x16x32_bf16 v[70:73], v[14:17], v[38:41], v[70:73]
	v_mfma_f32_16x16x32_bf16 v[78:81], v[10:13], v[42:45], 0
	v_mfma_f32_16x16x32_bf16 v[78:81], v[14:17], v[46:49], v[78:81]
	v_mfma_f32_16x16x32_bf16 v[74:77], v[2:5], v[42:45], 0
	v_mfma_f32_16x16x32_bf16 v[74:77], v[6:9], v[46:49], v[74:77]
	v_mfma_f32_16x16x32_bf16 v[82:85], v[2:5], v[50:53], 0
	v_mfma_f32_16x16x32_bf16 v[82:85], v[6:9], v[54:57], v[82:85]
	v_mfma_f32_16x16x32_bf16 v[86:89], v[10:13], v[50:53], 0
	v_mfma_f32_16x16x32_bf16 v[86:89], v[14:17], v[54:57], v[86:89]
	v_mfma_f32_16x16x32_bf16 v[94:97], v[10:13], v[58:61], 0
	v_mfma_f32_16x16x32_bf16 v[94:97], v[14:17], v[62:65], v[94:97]
	v_mfma_f32_16x16x32_bf16 v[90:93], v[2:5], v[58:61], 0
	v_mfma_f32_16x16x32_bf16 v[90:93], v[6:9], v[62:65], v[90:93]
	s_setprio 0
	s_setprio 1
	v_mfma_f32_16x16x32_bf16 v[98:101], v[18:21], v[34:37], 0
	v_mfma_f32_16x16x32_bf16 v[34:37], v[26:29], v[34:37], 0
	v_mfma_f32_16x16x32_bf16 v[102:105], v[18:21], v[42:45], 0
	v_mfma_f32_16x16x32_bf16 v[42:45], v[26:29], v[42:45], 0
	v_mfma_f32_16x16x32_bf16 v[106:109], v[18:21], v[50:53], 0
	v_mfma_f32_16x16x32_bf16 v[50:53], v[26:29], v[50:53], 0
	v_mfma_f32_16x16x32_bf16 v[110:113], v[18:21], v[58:61], 0
	v_mfma_f32_16x16x32_bf16 v[58:61], v[26:29], v[58:61], 0
	v_mfma_f32_16x16x32_bf16 v[98:101], v[22:25], v[38:41], v[98:101]
	v_mfma_f32_16x16x32_bf16 v[38:41], v[30:33], v[38:41], v[34:37]
	v_mfma_f32_16x16x32_bf16 v[102:105], v[22:25], v[46:49], v[102:105]
	v_mfma_f32_16x16x32_bf16 v[46:49], v[30:33], v[46:49], v[42:45]
	v_mfma_f32_16x16x32_bf16 v[106:109], v[22:25], v[54:57], v[106:109]
	v_mfma_f32_16x16x32_bf16 v[54:57], v[30:33], v[54:57], v[50:53]
	s_setprio 3
	s_barrier
	v_mfma_f32_16x16x32_bf16 v[110:113], v[22:25], v[62:65], v[110:113]
	v_mfma_f32_16x16x32_bf16 v[62:65], v[30:33], v[62:65], v[58:61]
	s_setprio 0
	v_lshl_add_u64 v[136:137], s[38:39], 0, v[130:131]
	s_add_i32 s62, s58, s46
	v_mov_b32_e32 v135, v131
	v_lshl_add_u64 v[142:143], v[136:137], 0, s[10:11]
	s_mov_b32 m0, s62
	v_lshl_add_u64 v[244:245], s[38:39], 0, v[134:135]
	ds_read_b128 v[34:37], v141 offset:16384
	ds_read_b128 v[42:45], v141 offset:17408
	ds_read_b128 v[50:53], v141 offset:18432
	ds_read_b128 v[58:61], v141 offset:19456
	ds_read_b128 v[114:117], v141 offset:20480
	ds_read_b128 v[118:121], v141 offset:21504
	ds_read_b128 v[122:125], v141 offset:22528
	ds_read_b128 v[126:129], v141 offset:23552
	global_load_lds_dwordx4 v[142:143], off
	v_lshl_add_u64 v[142:143], v[244:245], 0, s[10:11]
	s_add_i32 m0, s62, 0x2000
	s_add_i32 s62, s59, s46
	global_load_lds_dwordx4 v[142:143], off
	s_mov_b32 m0, s62
	v_mov_b32_e32 v139, v131
	global_load_lds_dwordx4 v130, s[40:41]
	s_add_i32 m0, s62, 0x2000
	v_lshl_add_u64 v[246:247], s[36:37], 0, v[138:139]
	v_mov_b32_e32 v133, v131
	global_load_lds_dwordx4 v134, s[40:41]
	v_lshl_add_u64 v[142:143], v[246:247], 0, s[10:11]
	s_mov_b32 m0, s47
	v_lshl_add_u64 v[248:249], s[36:37], 0, v[132:133]
	global_load_lds_dwordx4 v[142:143], off
	v_lshl_add_u64 v[142:143], v[248:249], 0, s[10:11]
	s_mov_b32 m0, s48
	s_nop 0
	global_load_lds_dwordx4 v[142:143], off
	s_waitcnt vmcnt(8)
	s_waitcnt lgkmcnt(0)
	s_barrier
	s_setprio 1
	s_waitcnt lgkmcnt(0)
	v_mfma_f32_16x16x32_bf16 v[142:145], v[2:5], v[34:37], 0
	v_mfma_f32_16x16x32_bf16 v[148:151], v[10:13], v[34:37], 0
	v_mfma_f32_16x16x32_bf16 v[152:155], v[2:5], v[50:53], 0
	v_mfma_f32_16x16x32_bf16 v[156:159], v[10:13], v[50:53], 0
	v_mfma_f32_16x16x32_bf16 v[160:163], v[2:5], v[114:117], 0
	v_mfma_f32_16x16x32_bf16 v[164:167], v[10:13], v[114:117], 0
	v_mfma_f32_16x16x32_bf16 v[2:5], v[2:5], v[122:125], 0
	v_mfma_f32_16x16x32_bf16 v[10:13], v[10:13], v[122:125], 0
	v_mfma_f32_16x16x32_bf16 v[142:145], v[6:9], v[42:45], v[142:145]
	v_mfma_f32_16x16x32_bf16 v[148:151], v[14:17], v[42:45], v[148:151]
	v_mfma_f32_16x16x32_bf16 v[152:155], v[6:9], v[58:61], v[152:155]
	v_mfma_f32_16x16x32_bf16 v[156:159], v[14:17], v[58:61], v[156:159]
	v_mfma_f32_16x16x32_bf16 v[160:163], v[6:9], v[118:121], v[160:163]
	v_mfma_f32_16x16x32_bf16 v[164:167], v[14:17], v[118:121], v[164:167]
	v_mfma_f32_16x16x32_bf16 v[168:171], v[6:9], v[126:129], v[2:5]
	v_mfma_f32_16x16x32_bf16 v[172:175], v[14:17], v[126:129], v[10:13]
	s_setprio 0
	s_setprio 1
	v_mfma_f32_16x16x32_bf16 v[2:5], v[18:21], v[34:37], 0
	v_mfma_f32_16x16x32_bf16 v[6:9], v[26:29], v[34:37], 0
	v_mfma_f32_16x16x32_bf16 v[10:13], v[18:21], v[50:53], 0
	v_mfma_f32_16x16x32_bf16 v[14:17], v[26:29], v[50:53], 0
	v_mfma_f32_16x16x32_bf16 v[34:37], v[18:21], v[114:117], 0
	v_mfma_f32_16x16x32_bf16 v[50:53], v[26:29], v[114:117], 0
	v_mfma_f32_16x16x32_bf16 v[18:21], v[18:21], v[122:125], 0
	v_mfma_f32_16x16x32_bf16 v[26:29], v[26:29], v[122:125], 0
	v_mfma_f32_16x16x32_bf16 v[114:117], v[22:25], v[42:45], v[2:5]
	v_mfma_f32_16x16x32_bf16 v[122:125], v[30:33], v[42:45], v[6:9]
	v_mfma_f32_16x16x32_bf16 v[184:187], v[22:25], v[118:121], v[34:37]
	v_mfma_f32_16x16x32_bf16 v[118:121], v[30:33], v[118:121], v[50:53]
	v_mfma_f32_16x16x32_bf16 v[188:191], v[22:25], v[126:129], v[18:21]
	v_mfma_f32_16x16x32_bf16 v[126:129], v[30:33], v[126:129], v[26:29]
	s_setprio 3
	s_barrier
	v_mfma_f32_16x16x32_bf16 v[176:179], v[22:25], v[58:61], v[10:13]
	v_mfma_f32_16x16x32_bf16 v[180:183], v[30:33], v[58:61], v[14:17]
	s_setprio 0
	s_add_i32 s62, 0, 0x18000
	v_add_u32_e32 v2, s62, v140
	s_add_i32 s63, 0, 0x1c000
	ds_read_b128 v[192:195], v2
	ds_read_b128 v[196:199], v2 offset:1024
	ds_read_b128 v[200:203], v2 offset:2048
	ds_read_b128 v[204:207], v2 offset:3072
	v_add_u32_e32 v2, s63, v140
	ds_read_b128 v[208:211], v2
	ds_read_b128 v[212:215], v2 offset:1024
	ds_read_b128 v[216:219], v2 offset:2048
	ds_read_b128 v[220:223], v2 offset:3072
	s_mov_b32 m0, s49
	ds_read_b128 v[42:45], v141 offset:32768
	ds_read_b128 v[50:53], v141 offset:33792
	ds_read_b128 v[58:61], v141 offset:34816
	ds_read_b128 v[224:227], v141 offset:35840
	ds_read_b128 v[228:231], v141 offset:36864
	ds_read_b128 v[232:235], v141 offset:37888
	ds_read_b128 v[236:239], v141 offset:38912
	ds_read_b128 v[240:243], v141 offset:39936
	global_load_lds_dwordx4 v138, s[42:43]
	s_mov_b32 m0, s50
	s_nop 0
	global_load_lds_dwordx4 v132, s[42:43]
	s_waitcnt vmcnt(8)
	s_waitcnt lgkmcnt(0)
	s_barrier
	s_setprio 1
	s_waitcnt lgkmcnt(0)
	v_mfma_f32_16x16x32_bf16 v[2:5], v[192:195], v[42:45], v[66:69]
	v_mfma_f32_16x16x32_bf16 v[6:9], v[200:203], v[42:45], v[70:73]
	v_mfma_f32_16x16x32_bf16 v[10:13], v[192:195], v[58:61], v[74:77]
	v_mfma_f32_16x16x32_bf16 v[14:17], v[200:203], v[58:61], v[78:81]
	v_mfma_f32_16x16x32_bf16 v[18:21], v[192:195], v[228:231], v[82:85]
	v_mfma_f32_16x16x32_bf16 v[22:25], v[200:203], v[228:231], v[86:89]
	v_mfma_f32_16x16x32_bf16 v[26:29], v[192:195], v[236:239], v[90:93]
	v_mfma_f32_16x16x32_bf16 v[30:33], v[200:203], v[236:239], v[94:97]
	v_mfma_f32_16x16x32_bf16 v[2:5], v[196:199], v[50:53], v[2:5]
	v_mfma_f32_16x16x32_bf16 v[6:9], v[204:207], v[50:53], v[6:9]
	v_mfma_f32_16x16x32_bf16 v[10:13], v[196:199], v[224:227], v[10:13]
	v_mfma_f32_16x16x32_bf16 v[14:17], v[204:207], v[224:227], v[14:17]
	v_mfma_f32_16x16x32_bf16 v[18:21], v[196:199], v[232:235], v[18:21]
	v_mfma_f32_16x16x32_bf16 v[22:25], v[204:207], v[232:235], v[22:25]
	v_mfma_f32_16x16x32_bf16 v[26:29], v[196:199], v[240:243], v[26:29]
	v_mfma_f32_16x16x32_bf16 v[30:33], v[204:207], v[240:243], v[30:33]
	s_setprio 0
	s_setprio 1
	v_mfma_f32_16x16x32_bf16 v[34:37], v[208:211], v[42:45], v[98:101]
	v_mfma_f32_16x16x32_bf16 v[38:41], v[216:219], v[42:45], v[38:41]
	v_mfma_f32_16x16x32_bf16 v[34:37], v[212:215], v[50:53], v[34:37]
	v_mfma_f32_16x16x32_bf16 v[38:41], v[220:223], v[50:53], v[38:41]
	v_mfma_f32_16x16x32_bf16 v[42:45], v[208:211], v[58:61], v[102:105]
	v_mfma_f32_16x16x32_bf16 v[46:49], v[216:219], v[58:61], v[46:49]
	v_mfma_f32_16x16x32_bf16 v[50:53], v[208:211], v[228:231], v[106:109]
	v_mfma_f32_16x16x32_bf16 v[54:57], v[216:219], v[228:231], v[54:57]
	v_mfma_f32_16x16x32_bf16 v[58:61], v[208:211], v[236:239], v[110:113]
	v_mfma_f32_16x16x32_bf16 v[62:65], v[216:219], v[236:239], v[62:65]
	v_mfma_f32_16x16x32_bf16 v[42:45], v[212:215], v[224:227], v[42:45]
	v_mfma_f32_16x16x32_bf16 v[46:49], v[220:223], v[224:227], v[46:49]
	v_mfma_f32_16x16x32_bf16 v[50:53], v[212:215], v[232:235], v[50:53]
	v_mfma_f32_16x16x32_bf16 v[54:57], v[220:223], v[232:235], v[54:57]
	s_setprio 3
	s_barrier
	v_mfma_f32_16x16x32_bf16 v[58:61], v[212:215], v[240:243], v[58:61]
	v_mfma_f32_16x16x32_bf16 v[62:65], v[220:223], v[240:243], v[62:65]
	s_setprio 0
	s_add_i32 s62, s62, s46
	v_lshl_add_u64 v[66:67], v[136:137], 0, s[12:13]
	s_mov_b32 m0, s62
	ds_read_b128 v[102:105], v141 offset:49152
	ds_read_b128 v[106:109], v141 offset:50176
	ds_read_b128 v[110:113], v141 offset:51200
	ds_read_b128 v[224:227], v141 offset:52224
	ds_read_b128 v[228:231], v141 offset:53248
	ds_read_b128 v[232:235], v141 offset:54272
	ds_read_b128 v[236:239], v141 offset:55296
	ds_read_b128 v[240:243], v141 offset:56320
	global_load_lds_dwordx4 v[66:67], off
	v_lshl_add_u64 v[66:67], v[244:245], 0, s[12:13]
	s_add_i32 m0, s62, 0x2000
	s_add_i32 s62, s63, s46
	global_load_lds_dwordx4 v[66:67], off
	s_mov_b32 m0, s62
	v_lshl_add_u64 v[66:67], v[246:247], 0, s[12:13]
	global_load_lds_dwordx4 v130, s[44:45]
	s_add_i32 m0, s62, 0x2000
	s_nop 0
	global_load_lds_dwordx4 v134, s[44:45]
	s_mov_b32 m0, s54
	s_nop 0
	global_load_lds_dwordx4 v[66:67], off
	v_lshl_add_u64 v[66:67], v[248:249], 0, s[12:13]
	s_mov_b32 m0, s55
	s_nop 0
	global_load_lds_dwordx4 v[66:67], off
	s_waitcnt vmcnt(8)
	s_waitcnt lgkmcnt(0)
	s_barrier
	s_setprio 1
	s_waitcnt lgkmcnt(0)
	v_mfma_f32_16x16x32_bf16 v[66:69], v[192:195], v[102:105], v[142:145]
	v_mfma_f32_16x16x32_bf16 v[70:73], v[200:203], v[102:105], v[148:151]
	v_mfma_f32_16x16x32_bf16 v[74:77], v[192:195], v[110:113], v[152:155]
	v_mfma_f32_16x16x32_bf16 v[78:81], v[200:203], v[110:113], v[156:159]
	v_mfma_f32_16x16x32_bf16 v[82:85], v[192:195], v[228:231], v[160:163]
	v_mfma_f32_16x16x32_bf16 v[86:89], v[200:203], v[228:231], v[164:167]
	v_mfma_f32_16x16x32_bf16 v[90:93], v[192:195], v[236:239], v[168:171]
	v_mfma_f32_16x16x32_bf16 v[94:97], v[200:203], v[236:239], v[172:175]
	v_mfma_f32_16x16x32_bf16 v[66:69], v[196:199], v[106:109], v[66:69]
	v_mfma_f32_16x16x32_bf16 v[70:73], v[204:207], v[106:109], v[70:73]
	v_mfma_f32_16x16x32_bf16 v[74:77], v[196:199], v[224:227], v[74:77]
	v_mfma_f32_16x16x32_bf16 v[78:81], v[204:207], v[224:227], v[78:81]
	v_mfma_f32_16x16x32_bf16 v[82:85], v[196:199], v[232:235], v[82:85]
	v_mfma_f32_16x16x32_bf16 v[86:89], v[204:207], v[232:235], v[86:89]
	v_mfma_f32_16x16x32_bf16 v[90:93], v[196:199], v[240:243], v[90:93]
	v_mfma_f32_16x16x32_bf16 v[94:97], v[204:207], v[240:243], v[94:97]
	s_setprio 0
	s_setprio 1
	v_mfma_f32_16x16x32_bf16 v[98:101], v[208:211], v[102:105], v[114:117]
	v_mfma_f32_16x16x32_bf16 v[102:105], v[216:219], v[102:105], v[122:125]
	v_mfma_f32_16x16x32_bf16 v[98:101], v[212:215], v[106:109], v[98:101]
	v_mfma_f32_16x16x32_bf16 v[102:105], v[220:223], v[106:109], v[102:105]
	v_mfma_f32_16x16x32_bf16 v[106:109], v[208:211], v[110:113], v[176:179]
	v_mfma_f32_16x16x32_bf16 v[110:113], v[216:219], v[110:113], v[180:183]
	v_mfma_f32_16x16x32_bf16 v[114:117], v[208:211], v[228:231], v[184:187]
	v_mfma_f32_16x16x32_bf16 v[118:121], v[216:219], v[228:231], v[118:121]
	v_mfma_f32_16x16x32_bf16 v[122:125], v[208:211], v[236:239], v[188:191]
	v_mfma_f32_16x16x32_bf16 v[126:129], v[216:219], v[236:239], v[126:129]
	v_mfma_f32_16x16x32_bf16 v[106:109], v[212:215], v[224:227], v[106:109]
	v_mfma_f32_16x16x32_bf16 v[110:113], v[220:223], v[224:227], v[110:113]
	v_mfma_f32_16x16x32_bf16 v[114:117], v[212:215], v[232:235], v[114:117]
	v_mfma_f32_16x16x32_bf16 v[118:121], v[220:223], v[232:235], v[118:121]
	s_setprio 3
	s_barrier
	v_mfma_f32_16x16x32_bf16 v[122:125], v[212:215], v[240:243], v[122:125]
	v_mfma_f32_16x16x32_bf16 v[126:129], v[220:223], v[240:243], v[126:129]
	s_setprio 0
	s_add_i32 s27, s27, 2
	s_cmp_ge_i32 s27, s15
	s_cbranch_scc0 .LBB0_495
	v_mov_b32_e32 v136, v130
	s_branch .LBB0_498

.LBB0_499:
	v_add_u32_e32 v133, s58, v140
	ds_read_b128 v[142:145], v133
	ds_read_b128 v[148:151], v133 offset:1024
	ds_read_b128 v[152:155], v133 offset:2048
	ds_read_b128 v[156:159], v133 offset:3072
	v_add_u32_e32 v133, s59, v140
	ds_read_b128 v[160:163], v133
	ds_read_b128 v[164:167], v133 offset:1024
	ds_read_b128 v[168:171], v133 offset:2048
	ds_read_b128 v[172:175], v133 offset:3072
	s_add_u32 s38, s36, 0xfff80080
	s_addc_u32 s39, s37, -1
	s_cmp_eq_u32 s42, 4
	s_cselect_b32 s41, s31, s39
	s_cselect_b32 s40, s30, s38
	s_cselect_b32 s39, s35, s27
	s_cselect_b32 s38, s34, s15
	s_mov_b32 m0, s56
	v_add_u32_e32 v141, 0, v1
	ds_read_b128 v[176:179], v141
	ds_read_b128 v[180:183], v141 offset:1024
	ds_read_b128 v[184:187], v141 offset:2048
	ds_read_b128 v[188:191], v141 offset:3072
	ds_read_b128 v[192:195], v141 offset:4096
	ds_read_b128 v[196:199], v141 offset:5120
	ds_read_b128 v[200:203], v141 offset:6144
	ds_read_b128 v[204:207], v141 offset:7168
	global_load_lds_dwordx4 v130, s[36:37]
	s_mov_b32 m0, s57
	v_mov_b32_e32 v133, v131
	global_load_lds_dwordx4 v132, s[36:37]
	s_waitcnt vmcnt(8)
	s_waitcnt lgkmcnt(0)
	s_barrier
	s_setprio 1
	s_waitcnt lgkmcnt(0)
	v_mfma_f32_16x16x32_bf16 v[2:5], v[142:145], v[176:179], v[2:5]
	v_mfma_f32_16x16x32_bf16 v[2:5], v[148:151], v[180:183], v[2:5]
	v_mfma_f32_16x16x32_bf16 v[6:9], v[156:159], v[180:183], v[6:9]
	v_mfma_f32_16x16x32_bf16 v[6:9], v[152:155], v[176:179], v[6:9]
	v_mfma_f32_16x16x32_bf16 v[14:17], v[152:155], v[184:187], v[14:17]
	v_mfma_f32_16x16x32_bf16 v[14:17], v[156:159], v[188:191], v[14:17]
	v_mfma_f32_16x16x32_bf16 v[10:13], v[148:151], v[188:191], v[10:13]
	v_mfma_f32_16x16x32_bf16 v[10:13], v[142:145], v[184:187], v[10:13]
	v_mfma_f32_16x16x32_bf16 v[18:21], v[142:145], v[192:195], v[18:21]
	v_mfma_f32_16x16x32_bf16 v[18:21], v[148:151], v[196:199], v[18:21]
	v_mfma_f32_16x16x32_bf16 v[22:25], v[156:159], v[196:199], v[22:25]
	v_mfma_f32_16x16x32_bf16 v[22:25], v[152:155], v[192:195], v[22:25]
	v_mfma_f32_16x16x32_bf16 v[30:33], v[152:155], v[200:203], v[30:33]
	v_mfma_f32_16x16x32_bf16 v[30:33], v[156:159], v[204:207], v[30:33]
	v_mfma_f32_16x16x32_bf16 v[26:29], v[148:151], v[204:207], v[26:29]
	v_mfma_f32_16x16x32_bf16 v[26:29], v[142:145], v[200:203], v[26:29]
	s_setprio 0
	s_setprio 1
	v_mfma_f32_16x16x32_bf16 v[34:37], v[160:163], v[176:179], v[34:37]
	v_mfma_f32_16x16x32_bf16 v[34:37], v[164:167], v[180:183], v[34:37]
	v_mfma_f32_16x16x32_bf16 v[38:41], v[172:175], v[180:183], v[38:41]
	v_mfma_f32_16x16x32_bf16 v[38:41], v[168:171], v[176:179], v[38:41]
	v_mfma_f32_16x16x32_bf16 v[46:49], v[168:171], v[184:187], v[46:49]
	v_mfma_f32_16x16x32_bf16 v[46:49], v[172:175], v[188:191], v[46:49]
	v_mfma_f32_16x16x32_bf16 v[42:45], v[164:167], v[188:191], v[42:45]
	v_mfma_f32_16x16x32_bf16 v[42:45], v[160:163], v[184:187], v[42:45]
	v_mfma_f32_16x16x32_bf16 v[50:53], v[160:163], v[192:195], v[50:53]
	v_mfma_f32_16x16x32_bf16 v[50:53], v[164:167], v[196:199], v[50:53]
	v_mfma_f32_16x16x32_bf16 v[54:57], v[172:175], v[196:199], v[54:57]
	v_mfma_f32_16x16x32_bf16 v[54:57], v[168:171], v[192:195], v[54:57]
	v_mfma_f32_16x16x32_bf16 v[62:65], v[168:171], v[200:203], v[62:65]
	v_mfma_f32_16x16x32_bf16 v[62:65], v[172:175], v[204:207], v[62:65]
	s_setprio 3
	s_barrier
	v_mfma_f32_16x16x32_bf16 v[58:61], v[164:167], v[204:207], v[58:61]
	v_mfma_f32_16x16x32_bf16 v[58:61], v[160:163], v[200:203], v[58:61]
	s_setprio 0
	s_add_i32 s43, s58, s46
	s_mov_b32 m0, s43
	ds_read_b128 v[176:179], v141 offset:16384
	ds_read_b128 v[180:183], v141 offset:17408
	ds_read_b128 v[184:187], v141 offset:18432
	ds_read_b128 v[188:191], v141 offset:19456
	ds_read_b128 v[192:195], v141 offset:20480
	ds_read_b128 v[196:199], v141 offset:21504
	ds_read_b128 v[200:203], v141 offset:22528
	ds_read_b128 v[204:207], v141 offset:23552
	global_load_lds_dwordx4 v136, s[38:39]
	s_add_i32 m0, s43, 0x2000
	s_add_u32 s44, s38, 0x400000
	s_addc_u32 s45, s39, 0
	s_add_i32 s43, s59, s46
	global_load_lds_dwordx4 v134, s[38:39]
	s_mov_b32 m0, s43
	v_mov_b32_e32 v137, v131
	global_load_lds_dwordx4 v136, s[44:45]
	s_add_i32 m0, s43, 0x2000
	v_mov_b32_e32 v135, v131
	global_load_lds_dwordx4 v134, s[44:45]
	s_mov_b32 m0, s47
	v_lshl_add_u64 v[138:139], s[38:39], 0, v[136:137]
	global_load_lds_dwordx4 v130, s[40:41]
	s_mov_b32 m0, s48
	v_lshl_add_u64 v[208:209], s[38:39], 0, v[134:135]
	global_load_lds_dwordx4 v132, s[40:41]
	s_waitcnt vmcnt(8)
	s_waitcnt lgkmcnt(0)
	v_lshl_add_u64 v[210:211], s[40:41], 0, v[130:131]
	v_lshl_add_u64 v[212:213], s[40:41], 0, v[132:133]
	s_barrier
	s_setprio 1
	s_waitcnt lgkmcnt(0)
	v_mfma_f32_16x16x32_bf16 v[66:69], v[142:145], v[176:179], v[66:69]
	v_mfma_f32_16x16x32_bf16 v[66:69], v[148:151], v[180:183], v[66:69]
	v_mfma_f32_16x16x32_bf16 v[70:73], v[156:159], v[180:183], v[70:73]
	v_mfma_f32_16x16x32_bf16 v[70:73], v[152:155], v[176:179], v[70:73]
	v_mfma_f32_16x16x32_bf16 v[78:81], v[152:155], v[184:187], v[78:81]
	v_mfma_f32_16x16x32_bf16 v[78:81], v[156:159], v[188:191], v[78:81]
	v_mfma_f32_16x16x32_bf16 v[74:77], v[148:151], v[188:191], v[74:77]
	v_mfma_f32_16x16x32_bf16 v[74:77], v[142:145], v[184:187], v[74:77]
	v_mfma_f32_16x16x32_bf16 v[82:85], v[142:145], v[192:195], v[82:85]
	v_mfma_f32_16x16x32_bf16 v[82:85], v[148:151], v[196:199], v[82:85]
	v_mfma_f32_16x16x32_bf16 v[86:89], v[156:159], v[196:199], v[86:89]
	v_mfma_f32_16x16x32_bf16 v[86:89], v[152:155], v[192:195], v[86:89]
	v_mfma_f32_16x16x32_bf16 v[94:97], v[152:155], v[200:203], v[94:97]
	v_mfma_f32_16x16x32_bf16 v[94:97], v[156:159], v[204:207], v[94:97]
	v_mfma_f32_16x16x32_bf16 v[90:93], v[148:151], v[204:207], v[90:93]
	v_mfma_f32_16x16x32_bf16 v[90:93], v[142:145], v[200:203], v[90:93]
	s_setprio 0
	s_setprio 1
	v_mfma_f32_16x16x32_bf16 v[98:101], v[160:163], v[176:179], v[98:101]
	v_mfma_f32_16x16x32_bf16 v[98:101], v[164:167], v[180:183], v[98:101]
	v_mfma_f32_16x16x32_bf16 v[102:105], v[172:175], v[180:183], v[102:105]
	v_mfma_f32_16x16x32_bf16 v[102:105], v[168:171], v[176:179], v[102:105]
	v_mfma_f32_16x16x32_bf16 v[110:113], v[168:171], v[184:187], v[110:113]
	v_mfma_f32_16x16x32_bf16 v[110:113], v[172:175], v[188:191], v[110:113]
	v_mfma_f32_16x16x32_bf16 v[106:109], v[164:167], v[188:191], v[106:109]
	v_mfma_f32_16x16x32_bf16 v[106:109], v[160:163], v[184:187], v[106:109]
	v_mfma_f32_16x16x32_bf16 v[114:117], v[160:163], v[192:195], v[114:117]
	v_mfma_f32_16x16x32_bf16 v[114:117], v[164:167], v[196:199], v[114:117]
	v_mfma_f32_16x16x32_bf16 v[118:121], v[172:175], v[196:199], v[118:121]
	v_mfma_f32_16x16x32_bf16 v[118:121], v[168:171], v[192:195], v[118:121]
	v_mfma_f32_16x16x32_bf16 v[126:129], v[168:171], v[200:203], v[126:129]
	v_mfma_f32_16x16x32_bf16 v[126:129], v[172:175], v[204:207], v[126:129]
	s_setprio 3
	s_barrier
	v_mfma_f32_16x16x32_bf16 v[122:125], v[164:167], v[204:207], v[122:125]
	v_mfma_f32_16x16x32_bf16 v[122:125], v[160:163], v[200:203], v[122:125]
	s_setprio 0
	s_add_i32 s43, 0, 0x18000
	v_add_u32_e32 v135, s43, v140
	s_add_i32 s44, 0, 0x1c000
	ds_read_b128 v[142:145], v135
	ds_read_b128 v[148:151], v135 offset:1024
	ds_read_b128 v[152:155], v135 offset:2048
	ds_read_b128 v[156:159], v135 offset:3072
	v_add_u32_e32 v135, s44, v140
	ds_read_b128 v[160:163], v135
	ds_read_b128 v[164:167], v135 offset:1024
	ds_read_b128 v[168:171], v135 offset:2048
	ds_read_b128 v[172:175], v135 offset:3072
	s_add_u32 s40, s40, 0x80000
	s_addc_u32 s41, s41, 0
	s_mov_b32 m0, s49
	ds_read_b128 v[176:179], v141 offset:32768
	ds_read_b128 v[180:183], v141 offset:33792
	ds_read_b128 v[184:187], v141 offset:34816
	ds_read_b128 v[188:191], v141 offset:35840
	ds_read_b128 v[192:195], v141 offset:36864
	ds_read_b128 v[196:199], v141 offset:37888
	ds_read_b128 v[200:203], v141 offset:38912
	ds_read_b128 v[204:207], v141 offset:39936
	global_load_lds_dwordx4 v130, s[40:41]
	s_mov_b32 m0, s50
	s_nop 0
	global_load_lds_dwordx4 v132, s[40:41]
	s_waitcnt vmcnt(8)
	s_waitcnt lgkmcnt(0)
	s_barrier
	s_setprio 1
	s_waitcnt lgkmcnt(0)
	v_mfma_f32_16x16x32_bf16 v[2:5], v[142:145], v[176:179], v[2:5]
	v_mfma_f32_16x16x32_bf16 v[2:5], v[148:151], v[180:183], v[2:5]
	v_mfma_f32_16x16x32_bf16 v[6:9], v[156:159], v[180:183], v[6:9]
	v_mfma_f32_16x16x32_bf16 v[6:9], v[152:155], v[176:179], v[6:9]
	v_mfma_f32_16x16x32_bf16 v[14:17], v[152:155], v[184:187], v[14:17]
	v_mfma_f32_16x16x32_bf16 v[14:17], v[156:159], v[188:191], v[14:17]
	v_mfma_f32_16x16x32_bf16 v[10:13], v[148:151], v[188:191], v[10:13]
	v_mfma_f32_16x16x32_bf16 v[10:13], v[142:145], v[184:187], v[10:13]
	v_mfma_f32_16x16x32_bf16 v[18:21], v[142:145], v[192:195], v[18:21]
	v_mfma_f32_16x16x32_bf16 v[18:21], v[148:151], v[196:199], v[18:21]
	v_mfma_f32_16x16x32_bf16 v[22:25], v[156:159], v[196:199], v[22:25]
	v_mfma_f32_16x16x32_bf16 v[22:25], v[152:155], v[192:195], v[22:25]
	v_mfma_f32_16x16x32_bf16 v[30:33], v[152:155], v[200:203], v[30:33]
	v_mfma_f32_16x16x32_bf16 v[30:33], v[156:159], v[204:207], v[30:33]
	v_mfma_f32_16x16x32_bf16 v[26:29], v[148:151], v[204:207], v[26:29]
	v_mfma_f32_16x16x32_bf16 v[26:29], v[142:145], v[200:203], v[26:29]
	s_setprio 0
	s_setprio 1
	v_mfma_f32_16x16x32_bf16 v[34:37], v[160:163], v[176:179], v[34:37]
	v_mfma_f32_16x16x32_bf16 v[34:37], v[164:167], v[180:183], v[34:37]
	v_mfma_f32_16x16x32_bf16 v[38:41], v[172:175], v[180:183], v[38:41]
	v_mfma_f32_16x16x32_bf16 v[38:41], v[168:171], v[176:179], v[38:41]
	v_mfma_f32_16x16x32_bf16 v[46:49], v[168:171], v[184:187], v[46:49]
	v_mfma_f32_16x16x32_bf16 v[46:49], v[172:175], v[188:191], v[46:49]
	v_mfma_f32_16x16x32_bf16 v[42:45], v[164:167], v[188:191], v[42:45]
	v_mfma_f32_16x16x32_bf16 v[42:45], v[160:163], v[184:187], v[42:45]
	v_mfma_f32_16x16x32_bf16 v[50:53], v[160:163], v[192:195], v[50:53]
	v_mfma_f32_16x16x32_bf16 v[50:53], v[164:167], v[196:199], v[50:53]
	v_mfma_f32_16x16x32_bf16 v[54:57], v[172:175], v[196:199], v[54:57]
	v_mfma_f32_16x16x32_bf16 v[54:57], v[168:171], v[192:195], v[54:57]
	v_mfma_f32_16x16x32_bf16 v[62:65], v[168:171], v[200:203], v[62:65]
	v_mfma_f32_16x16x32_bf16 v[62:65], v[172:175], v[204:207], v[62:65]
	s_setprio 3
	s_barrier
	v_mfma_f32_16x16x32_bf16 v[58:61], v[164:167], v[204:207], v[58:61]
	v_mfma_f32_16x16x32_bf16 v[58:61], v[160:163], v[200:203], v[58:61]
	s_setprio 0
	s_add_i32 s40, s43, s46
	v_lshl_add_u64 v[138:139], v[138:139], 0, s[6:7]
	s_mov_b32 m0, s40
	ds_read_b128 v[176:179], v141 offset:49152
	ds_read_b128 v[180:183], v141 offset:50176
	ds_read_b128 v[184:187], v141 offset:51200
	ds_read_b128 v[188:191], v141 offset:52224
	ds_read_b128 v[192:195], v141 offset:53248
	ds_read_b128 v[196:199], v141 offset:54272
	ds_read_b128 v[200:203], v141 offset:55296
	ds_read_b128 v[204:207], v141 offset:56320
	global_load_lds_dwordx4 v[138:139], off
	s_add_i32 m0, s40, 0x2000
	s_add_u32 s38, s38, 0x400080
	v_lshl_add_u64 v[138:139], v[208:209], 0, s[6:7]
	s_addc_u32 s39, s39, 0
	s_add_i32 s40, s44, s46
	global_load_lds_dwordx4 v[138:139], off
	s_mov_b32 m0, s40
	v_lshl_add_u64 v[138:139], v[210:211], 0, s[6:7]
	global_load_lds_dwordx4 v136, s[38:39]
	s_add_i32 m0, s40, 0x2000
	s_nop 0
	global_load_lds_dwordx4 v134, s[38:39]
	s_mov_b32 m0, s54
	s_nop 0
	global_load_lds_dwordx4 v[138:139], off
	v_lshl_add_u64 v[138:139], v[212:213], 0, s[6:7]
	s_mov_b32 m0, s55
	s_nop 0
	global_load_lds_dwordx4 v[138:139], off
	s_waitcnt vmcnt(8)
	s_waitcnt lgkmcnt(0)
	s_barrier
	s_setprio 1
	s_waitcnt lgkmcnt(0)
	v_mfma_f32_16x16x32_bf16 v[66:69], v[142:145], v[176:179], v[66:69]
	v_mfma_f32_16x16x32_bf16 v[66:69], v[148:151], v[180:183], v[66:69]
	v_mfma_f32_16x16x32_bf16 v[70:73], v[156:159], v[180:183], v[70:73]
	v_mfma_f32_16x16x32_bf16 v[70:73], v[152:155], v[176:179], v[70:73]
	v_mfma_f32_16x16x32_bf16 v[78:81], v[152:155], v[184:187], v[78:81]
	v_mfma_f32_16x16x32_bf16 v[78:81], v[156:159], v[188:191], v[78:81]
	v_mfma_f32_16x16x32_bf16 v[74:77], v[148:151], v[188:191], v[74:77]
	v_mfma_f32_16x16x32_bf16 v[74:77], v[142:145], v[184:187], v[74:77]
	v_mfma_f32_16x16x32_bf16 v[82:85], v[142:145], v[192:195], v[82:85]
	v_mfma_f32_16x16x32_bf16 v[82:85], v[148:151], v[196:199], v[82:85]
	v_mfma_f32_16x16x32_bf16 v[86:89], v[156:159], v[196:199], v[86:89]
	v_mfma_f32_16x16x32_bf16 v[86:89], v[152:155], v[192:195], v[86:89]
	v_mfma_f32_16x16x32_bf16 v[94:97], v[152:155], v[200:203], v[94:97]
	v_mfma_f32_16x16x32_bf16 v[94:97], v[156:159], v[204:207], v[94:97]
	v_mfma_f32_16x16x32_bf16 v[90:93], v[148:151], v[204:207], v[90:93]
	v_mfma_f32_16x16x32_bf16 v[90:93], v[142:145], v[200:203], v[90:93]
	s_setprio 0
	s_setprio 1
	v_mfma_f32_16x16x32_bf16 v[98:101], v[160:163], v[176:179], v[98:101]
	v_mfma_f32_16x16x32_bf16 v[98:101], v[164:167], v[180:183], v[98:101]
	v_mfma_f32_16x16x32_bf16 v[102:105], v[172:175], v[180:183], v[102:105]
	v_mfma_f32_16x16x32_bf16 v[102:105], v[168:171], v[176:179], v[102:105]
	v_mfma_f32_16x16x32_bf16 v[110:113], v[168:171], v[184:187], v[110:113]
	v_mfma_f32_16x16x32_bf16 v[110:113], v[172:175], v[188:191], v[110:113]
	v_mfma_f32_16x16x32_bf16 v[106:109], v[164:167], v[188:191], v[106:109]
	v_mfma_f32_16x16x32_bf16 v[106:109], v[160:163], v[184:187], v[106:109]
	v_mfma_f32_16x16x32_bf16 v[114:117], v[160:163], v[192:195], v[114:117]
	v_mfma_f32_16x16x32_bf16 v[114:117], v[164:167], v[196:199], v[114:117]
	v_mfma_f32_16x16x32_bf16 v[118:121], v[172:175], v[196:199], v[118:121]
	v_mfma_f32_16x16x32_bf16 v[118:121], v[168:171], v[192:195], v[118:121]
	v_mfma_f32_16x16x32_bf16 v[126:129], v[168:171], v[200:203], v[126:129]
	v_mfma_f32_16x16x32_bf16 v[126:129], v[172:175], v[204:207], v[126:129]
	s_setprio 3
	s_barrier
	v_mfma_f32_16x16x32_bf16 v[122:125], v[164:167], v[204:207], v[122:125]
	v_mfma_f32_16x16x32_bf16 v[122:125], v[160:163], v[200:203], v[122:125]
	s_setprio 0
	s_add_i32 s42, s42, 2
	s_add_u32 s36, s36, 0x100
	s_addc_u32 s37, s37, 0
	s_add_u32 s15, s15, 0x100
	s_addc_u32 s27, s27, 0
	s_cmp_gt_u32 s42, 5
	s_cbranch_scc0 .LBB0_499
	s_and_b64 vcc, exec, s[8:9]
	s_cbranch_vccz .LBB0_502
	s_barrier

.LBB0_528:
	s_add_i32 s53, 0, 0x10000
	s_add_i32 s72, 0, 0x14000
	v_add_u32_e32 v16, s53, v147
	v_add_u32_e32 v32, s72, v147
	ds_read_b128 v[4:7], v16
	ds_read_b128 v[8:11], v16 offset:1024
	ds_read_b128 v[12:15], v16 offset:2048
	ds_read_b128 v[16:19], v16 offset:3072
	ds_read_b128 v[20:23], v32
	ds_read_b128 v[24:27], v32 offset:1024
	ds_read_b128 v[28:31], v32 offset:2048
	ds_read_b128 v[32:35], v32 offset:3072
	v_add_u32_e32 v231, 0, v146
	ds_read_b128 v[36:39], v231
	ds_read_b128 v[40:43], v231 offset:1024
	ds_read_b128 v[44:47], v231 offset:2048
	ds_read_b128 v[48:51], v231 offset:3072
	ds_read_b128 v[52:55], v231 offset:4096
	ds_read_b128 v[56:59], v231 offset:5120
	ds_read_b128 v[60:63], v231 offset:6144
	ds_read_b128 v[64:67], v231 offset:7168
	s_waitcnt vmcnt(8)
	s_waitcnt lgkmcnt(0)
	s_barrier
	s_setprio 1
	s_waitcnt lgkmcnt(0)
	v_mfma_f32_16x16x32_f16 v[68:71], v[4:7], v[36:39], 0
	v_mfma_f32_16x16x32_f16 v[68:71], v[8:11], v[40:43], v[68:71]
	v_mfma_f32_16x16x32_f16 v[72:75], v[12:15], v[36:39], 0
	v_mfma_f32_16x16x32_f16 v[72:75], v[16:19], v[40:43], v[72:75]
	v_mfma_f32_16x16x32_f16 v[80:83], v[12:15], v[44:47], 0
	v_mfma_f32_16x16x32_f16 v[80:83], v[16:19], v[48:51], v[80:83]
	v_mfma_f32_16x16x32_f16 v[76:79], v[4:7], v[44:47], 0
	v_mfma_f32_16x16x32_f16 v[76:79], v[8:11], v[48:51], v[76:79]
	v_mfma_f32_16x16x32_f16 v[84:87], v[4:7], v[52:55], 0
	v_mfma_f32_16x16x32_f16 v[84:87], v[8:11], v[56:59], v[84:87]
	v_mfma_f32_16x16x32_f16 v[88:91], v[12:15], v[52:55], 0
	v_mfma_f32_16x16x32_f16 v[88:91], v[16:19], v[56:59], v[88:91]
	v_mfma_f32_16x16x32_f16 v[96:99], v[12:15], v[60:63], 0
	v_mfma_f32_16x16x32_f16 v[96:99], v[16:19], v[64:67], v[96:99]
	v_mfma_f32_16x16x32_f16 v[92:95], v[4:7], v[60:63], 0
	v_mfma_f32_16x16x32_f16 v[92:95], v[8:11], v[64:67], v[92:95]
	s_setprio 0
	s_setprio 1
	v_mfma_f32_16x16x32_f16 v[100:103], v[20:23], v[36:39], 0
	v_mfma_f32_16x16x32_f16 v[36:39], v[28:31], v[36:39], 0
	v_mfma_f32_16x16x32_f16 v[104:107], v[20:23], v[44:47], 0
	v_mfma_f32_16x16x32_f16 v[44:47], v[28:31], v[44:47], 0
	v_mfma_f32_16x16x32_f16 v[108:111], v[20:23], v[52:55], 0
	v_mfma_f32_16x16x32_f16 v[52:55], v[28:31], v[52:55], 0
	v_mfma_f32_16x16x32_f16 v[112:115], v[20:23], v[60:63], 0
	v_mfma_f32_16x16x32_f16 v[60:63], v[28:31], v[60:63], 0
	v_mfma_f32_16x16x32_f16 v[100:103], v[24:27], v[40:43], v[100:103]
	v_mfma_f32_16x16x32_f16 v[40:43], v[32:35], v[40:43], v[36:39]
	v_mfma_f32_16x16x32_f16 v[104:107], v[24:27], v[48:51], v[104:107]
	v_mfma_f32_16x16x32_f16 v[48:51], v[32:35], v[48:51], v[44:47]
	v_mfma_f32_16x16x32_f16 v[108:111], v[24:27], v[56:59], v[108:111]
	v_mfma_f32_16x16x32_f16 v[56:59], v[32:35], v[56:59], v[52:55]
	s_setprio 3
	s_barrier
	v_mfma_f32_16x16x32_f16 v[112:115], v[24:27], v[64:67], v[112:115]
	v_mfma_f32_16x16x32_f16 v[64:67], v[32:35], v[64:67], v[60:63]
	s_setprio 0
	v_lshl_add_u64 v[136:137], s[6:7], 0, v[2:3]
	s_add_i32 s53, s53, s38
	v_mov_b32_e32 v135, v3
	v_lshl_add_u64 v[140:141], v[136:137], 0, s[74:75]
	s_mov_b32 m0, s53
	v_lshl_add_u64 v[144:145], s[6:7], 0, v[134:135]
	ds_read_b128 v[36:39], v231 offset:16384
	ds_read_b128 v[44:47], v231 offset:17408
	ds_read_b128 v[52:55], v231 offset:18432
	ds_read_b128 v[60:63], v231 offset:19456
	ds_read_b128 v[116:119], v231 offset:20480
	ds_read_b128 v[120:123], v231 offset:21504
	ds_read_b128 v[124:127], v231 offset:22528
	ds_read_b128 v[128:131], v231 offset:23552
	global_load_lds_dwordx4 v[140:141], off
	v_lshl_add_u64 v[140:141], v[144:145], 0, s[74:75]
	s_add_i32 m0, s53, 0x2000
	s_add_i32 s53, s72, s38
	global_load_lds_dwordx4 v[140:141], off
	s_mov_b32 m0, s53
	v_mov_b32_e32 v139, v3
	global_load_lds_dwordx4 v2, s[16:17]
	s_add_i32 m0, s53, 0x2000
	v_lshl_add_u64 v[248:249], s[8:9], 0, v[138:139]
	v_mov_b32_e32 v133, v3
	global_load_lds_dwordx4 v134, s[16:17]
	v_lshl_add_u64 v[140:141], v[248:249], 0, s[74:75]
	s_mov_b32 m0, s58
	v_lshl_add_u64 v[250:251], s[8:9], 0, v[132:133]
	global_load_lds_dwordx4 v[140:141], off
	v_lshl_add_u64 v[140:141], v[250:251], 0, s[74:75]
	s_mov_b32 m0, s59
	s_nop 0
	global_load_lds_dwordx4 v[140:141], off
	s_waitcnt vmcnt(8)
	s_waitcnt lgkmcnt(0)
	s_barrier
	s_setprio 1
	s_waitcnt lgkmcnt(0)
	v_mfma_f32_16x16x32_f16 v[140:143], v[4:7], v[36:39], 0
	v_mfma_f32_16x16x32_f16 v[148:151], v[12:15], v[36:39], 0
	v_mfma_f32_16x16x32_f16 v[152:155], v[4:7], v[52:55], 0
	v_mfma_f32_16x16x32_f16 v[156:159], v[12:15], v[52:55], 0
	v_mfma_f32_16x16x32_f16 v[160:163], v[4:7], v[116:119], 0
	v_mfma_f32_16x16x32_f16 v[164:167], v[12:15], v[116:119], 0
	v_mfma_f32_16x16x32_f16 v[4:7], v[4:7], v[124:127], 0
	v_mfma_f32_16x16x32_f16 v[12:15], v[12:15], v[124:127], 0
	v_mfma_f32_16x16x32_f16 v[140:143], v[8:11], v[44:47], v[140:143]
	v_mfma_f32_16x16x32_f16 v[148:151], v[16:19], v[44:47], v[148:151]
	v_mfma_f32_16x16x32_f16 v[152:155], v[8:11], v[60:63], v[152:155]
	v_mfma_f32_16x16x32_f16 v[156:159], v[16:19], v[60:63], v[156:159]
	v_mfma_f32_16x16x32_f16 v[160:163], v[8:11], v[120:123], v[160:163]
	v_mfma_f32_16x16x32_f16 v[164:167], v[16:19], v[120:123], v[164:167]
	v_mfma_f32_16x16x32_f16 v[168:171], v[8:11], v[128:131], v[4:7]
	v_mfma_f32_16x16x32_f16 v[172:175], v[16:19], v[128:131], v[12:15]
	s_setprio 0
	s_setprio 1
	v_mfma_f32_16x16x32_f16 v[4:7], v[20:23], v[36:39], 0
	v_mfma_f32_16x16x32_f16 v[8:11], v[28:31], v[36:39], 0
	v_mfma_f32_16x16x32_f16 v[12:15], v[20:23], v[52:55], 0
	v_mfma_f32_16x16x32_f16 v[16:19], v[28:31], v[52:55], 0
	v_mfma_f32_16x16x32_f16 v[36:39], v[20:23], v[116:119], 0
	v_mfma_f32_16x16x32_f16 v[52:55], v[28:31], v[116:119], 0
	v_mfma_f32_16x16x32_f16 v[20:23], v[20:23], v[124:127], 0
	v_mfma_f32_16x16x32_f16 v[28:31], v[28:31], v[124:127], 0
	v_mfma_f32_16x16x32_f16 v[116:119], v[24:27], v[44:47], v[4:7]
	v_mfma_f32_16x16x32_f16 v[124:127], v[32:35], v[44:47], v[8:11]
	v_mfma_f32_16x16x32_f16 v[184:187], v[24:27], v[120:123], v[36:39]
	v_mfma_f32_16x16x32_f16 v[120:123], v[32:35], v[120:123], v[52:55]
	v_mfma_f32_16x16x32_f16 v[188:191], v[24:27], v[128:131], v[20:23]
	v_mfma_f32_16x16x32_f16 v[128:131], v[32:35], v[128:131], v[28:31]
	s_setprio 3
	s_barrier
	v_mfma_f32_16x16x32_f16 v[176:179], v[24:27], v[60:63], v[12:15]
	v_mfma_f32_16x16x32_f16 v[180:183], v[32:35], v[60:63], v[16:19]
	s_setprio 0
	s_add_i32 s53, 0, 0x18000
	v_add_u32_e32 v4, s53, v147
	s_add_i32 s72, 0, 0x1c000
	ds_read_b128 v[192:195], v4
	ds_read_b128 v[196:199], v4 offset:1024
	ds_read_b128 v[200:203], v4 offset:2048
	ds_read_b128 v[204:207], v4 offset:3072
	v_add_u32_e32 v4, s72, v147
	ds_read_b128 v[208:211], v4
	ds_read_b128 v[212:215], v4 offset:1024
	ds_read_b128 v[216:219], v4 offset:2048
	ds_read_b128 v[220:223], v4 offset:3072
	s_mov_b32 m0, s60
	ds_read_b128 v[44:47], v231 offset:32768
	ds_read_b128 v[52:55], v231 offset:33792
	ds_read_b128 v[60:63], v231 offset:34816
	ds_read_b128 v[224:227], v231 offset:35840
	ds_read_b128 v[232:235], v231 offset:36864
	ds_read_b128 v[236:239], v231 offset:37888
	ds_read_b128 v[240:243], v231 offset:38912
	ds_read_b128 v[244:247], v231 offset:39936
	global_load_lds_dwordx4 v138, s[26:27]
	s_mov_b32 m0, s61
	s_nop 0
	global_load_lds_dwordx4 v132, s[26:27]
	s_waitcnt vmcnt(8)
	s_waitcnt lgkmcnt(0)
	s_barrier
	s_setprio 1
	s_waitcnt lgkmcnt(0)
	v_mfma_f32_16x16x32_f16 v[4:7], v[192:195], v[44:47], v[68:71]
	v_mfma_f32_16x16x32_f16 v[8:11], v[200:203], v[44:47], v[72:75]
	v_mfma_f32_16x16x32_f16 v[12:15], v[192:195], v[60:63], v[76:79]
	v_mfma_f32_16x16x32_f16 v[16:19], v[200:203], v[60:63], v[80:83]
	v_mfma_f32_16x16x32_f16 v[20:23], v[192:195], v[232:235], v[84:87]
	v_mfma_f32_16x16x32_f16 v[24:27], v[200:203], v[232:235], v[88:91]
	v_mfma_f32_16x16x32_f16 v[28:31], v[192:195], v[240:243], v[92:95]
	v_mfma_f32_16x16x32_f16 v[32:35], v[200:203], v[240:243], v[96:99]
	v_mfma_f32_16x16x32_f16 v[4:7], v[196:199], v[52:55], v[4:7]
	v_mfma_f32_16x16x32_f16 v[8:11], v[204:207], v[52:55], v[8:11]
	v_mfma_f32_16x16x32_f16 v[12:15], v[196:199], v[224:227], v[12:15]
	v_mfma_f32_16x16x32_f16 v[16:19], v[204:207], v[224:227], v[16:19]
	v_mfma_f32_16x16x32_f16 v[20:23], v[196:199], v[236:239], v[20:23]
	v_mfma_f32_16x16x32_f16 v[24:27], v[204:207], v[236:239], v[24:27]
	v_mfma_f32_16x16x32_f16 v[28:31], v[196:199], v[244:247], v[28:31]
	v_mfma_f32_16x16x32_f16 v[32:35], v[204:207], v[244:247], v[32:35]
	s_setprio 0
	s_setprio 1
	v_mfma_f32_16x16x32_f16 v[36:39], v[208:211], v[44:47], v[100:103]
	v_mfma_f32_16x16x32_f16 v[40:43], v[216:219], v[44:47], v[40:43]
	v_mfma_f32_16x16x32_f16 v[36:39], v[212:215], v[52:55], v[36:39]
	v_mfma_f32_16x16x32_f16 v[40:43], v[220:223], v[52:55], v[40:43]
	v_mfma_f32_16x16x32_f16 v[44:47], v[208:211], v[60:63], v[104:107]
	v_mfma_f32_16x16x32_f16 v[48:51], v[216:219], v[60:63], v[48:51]
	v_mfma_f32_16x16x32_f16 v[52:55], v[208:211], v[232:235], v[108:111]
	v_mfma_f32_16x16x32_f16 v[56:59], v[216:219], v[232:235], v[56:59]
	v_mfma_f32_16x16x32_f16 v[60:63], v[208:211], v[240:243], v[112:115]
	v_mfma_f32_16x16x32_f16 v[64:67], v[216:219], v[240:243], v[64:67]
	v_mfma_f32_16x16x32_f16 v[44:47], v[212:215], v[224:227], v[44:47]
	v_mfma_f32_16x16x32_f16 v[48:51], v[220:223], v[224:227], v[48:51]
	v_mfma_f32_16x16x32_f16 v[52:55], v[212:215], v[236:239], v[52:55]
	v_mfma_f32_16x16x32_f16 v[56:59], v[220:223], v[236:239], v[56:59]
	s_setprio 3
	s_barrier
	v_mfma_f32_16x16x32_f16 v[60:63], v[212:215], v[244:247], v[60:63]
	v_mfma_f32_16x16x32_f16 v[64:67], v[220:223], v[244:247], v[64:67]
	s_setprio 0
	s_add_i32 s53, s53, s38
	v_lshl_add_u64 v[68:69], v[136:137], 0, s[24:25]
	s_mov_b32 m0, s53
	ds_read_b128 v[104:107], v231 offset:49152
	ds_read_b128 v[108:111], v231 offset:50176
	ds_read_b128 v[112:115], v231 offset:51200
	ds_read_b128 v[224:227], v231 offset:52224
	ds_read_b128 v[232:235], v231 offset:53248
	ds_read_b128 v[236:239], v231 offset:54272
	ds_read_b128 v[240:243], v231 offset:55296
	ds_read_b128 v[244:247], v231 offset:56320
	global_load_lds_dwordx4 v[68:69], off
	v_lshl_add_u64 v[68:69], v[144:145], 0, s[24:25]
	s_add_i32 m0, s53, 0x2000
	s_add_i32 s53, s72, s38
	global_load_lds_dwordx4 v[68:69], off
	s_mov_b32 m0, s53
	v_lshl_add_u64 v[68:69], v[248:249], 0, s[24:25]
	global_load_lds_dwordx4 v2, s[28:29]
	s_add_i32 m0, s53, 0x2000
	s_nop 0
	global_load_lds_dwordx4 v134, s[28:29]
	s_mov_b32 m0, s64
	s_nop 0
	global_load_lds_dwordx4 v[68:69], off
	v_lshl_add_u64 v[68:69], v[250:251], 0, s[24:25]
	s_mov_b32 m0, s65
	s_nop 0
	global_load_lds_dwordx4 v[68:69], off
	s_waitcnt vmcnt(8)
	s_waitcnt lgkmcnt(0)
	s_barrier
	s_setprio 1
	s_waitcnt lgkmcnt(0)
	v_mfma_f32_16x16x32_f16 v[68:71], v[192:195], v[104:107], v[140:143]
	v_mfma_f32_16x16x32_f16 v[72:75], v[200:203], v[104:107], v[148:151]
	v_mfma_f32_16x16x32_f16 v[76:79], v[192:195], v[112:115], v[152:155]
	v_mfma_f32_16x16x32_f16 v[80:83], v[200:203], v[112:115], v[156:159]
	v_mfma_f32_16x16x32_f16 v[84:87], v[192:195], v[232:235], v[160:163]
	v_mfma_f32_16x16x32_f16 v[88:91], v[200:203], v[232:235], v[164:167]
	v_mfma_f32_16x16x32_f16 v[92:95], v[192:195], v[240:243], v[168:171]
	v_mfma_f32_16x16x32_f16 v[96:99], v[200:203], v[240:243], v[172:175]
	v_mfma_f32_16x16x32_f16 v[68:71], v[196:199], v[108:111], v[68:71]
	v_mfma_f32_16x16x32_f16 v[72:75], v[204:207], v[108:111], v[72:75]
	v_mfma_f32_16x16x32_f16 v[76:79], v[196:199], v[224:227], v[76:79]
	v_mfma_f32_16x16x32_f16 v[80:83], v[204:207], v[224:227], v[80:83]
	v_mfma_f32_16x16x32_f16 v[84:87], v[196:199], v[236:239], v[84:87]
	v_mfma_f32_16x16x32_f16 v[88:91], v[204:207], v[236:239], v[88:91]
	v_mfma_f32_16x16x32_f16 v[92:95], v[196:199], v[244:247], v[92:95]
	v_mfma_f32_16x16x32_f16 v[96:99], v[204:207], v[244:247], v[96:99]
	s_setprio 0
	s_setprio 1
	v_mfma_f32_16x16x32_f16 v[100:103], v[208:211], v[104:107], v[116:119]
	v_mfma_f32_16x16x32_f16 v[104:107], v[216:219], v[104:107], v[124:127]
	v_mfma_f32_16x16x32_f16 v[100:103], v[212:215], v[108:111], v[100:103]
	v_mfma_f32_16x16x32_f16 v[104:107], v[220:223], v[108:111], v[104:107]
	v_mfma_f32_16x16x32_f16 v[108:111], v[208:211], v[112:115], v[176:179]
	v_mfma_f32_16x16x32_f16 v[112:115], v[216:219], v[112:115], v[180:183]
	v_mfma_f32_16x16x32_f16 v[116:119], v[208:211], v[232:235], v[184:187]
	v_mfma_f32_16x16x32_f16 v[120:123], v[216:219], v[232:235], v[120:123]
	v_mfma_f32_16x16x32_f16 v[124:127], v[208:211], v[240:243], v[188:191]
	v_mfma_f32_16x16x32_f16 v[128:131], v[216:219], v[240:243], v[128:131]
	v_mfma_f32_16x16x32_f16 v[108:111], v[212:215], v[224:227], v[108:111]
	v_mfma_f32_16x16x32_f16 v[112:115], v[220:223], v[224:227], v[112:115]
	v_mfma_f32_16x16x32_f16 v[116:119], v[212:215], v[236:239], v[116:119]
	v_mfma_f32_16x16x32_f16 v[120:123], v[220:223], v[236:239], v[120:123]
	s_setprio 3
	s_barrier
	v_mfma_f32_16x16x32_f16 v[124:127], v[212:215], v[244:247], v[124:127]
	v_mfma_f32_16x16x32_f16 v[128:131], v[220:223], v[244:247], v[128:131]
	s_setprio 0
	s_add_i32 s41, s41, 2
	s_cmp_ge_i32 s41, s40
	s_cbranch_scc0 .LBB0_528
	v_mov_b32_e32 v136, v2
	s_branch .LBB0_531

.LBB0_532:
	s_add_u32 s6, s8, 0xfff80080
	s_addc_u32 s7, s9, -1
	s_add_i32 s29, 0, 0x10000
	s_cmp_eq_u32 s28, 28
	s_cselect_b32 s17, s13, s7
	s_cselect_b32 s16, s12, s6
	s_cselect_b32 s7, s15, s27
	s_cselect_b32 s6, s14, s26
	s_add_i32 s53, 0, 0x14000
	ds_read_b128 v[138:141], v240
	ds_read_b128 v[142:145], v240 offset:1024
	ds_read_b128 v[148:151], v240 offset:2048
	ds_read_b128 v[152:155], v240 offset:3072
	ds_read_b128 v[156:159], v240 offset:16384
	ds_read_b128 v[160:163], v240 offset:17408
	ds_read_b128 v[164:167], v240 offset:18432
	ds_read_b128 v[168:171], v240 offset:19456
	s_mov_b32 m0, s66
	ds_read_b128 v[172:175], v146
	ds_read_b128 v[176:179], v146 offset:1024
	ds_read_b128 v[180:183], v146 offset:2048
	ds_read_b128 v[184:187], v146 offset:3072
	ds_read_b128 v[188:191], v146 offset:4096
	ds_read_b128 v[192:195], v146 offset:5120
	ds_read_b128 v[196:199], v146 offset:6144
	ds_read_b128 v[200:203], v146 offset:7168
	global_load_lds_dwordx4 v2, s[8:9]
	s_mov_b32 m0, s67
	v_mov_b32_e32 v133, v3
	global_load_lds_dwordx4 v132, s[8:9]
	s_waitcnt vmcnt(8)
	s_waitcnt lgkmcnt(0)
	s_barrier
	s_setprio 1
	s_waitcnt lgkmcnt(0)
	v_mfma_f32_16x16x32_f16 v[4:7], v[138:141], v[172:175], v[4:7]
	v_mfma_f32_16x16x32_f16 v[4:7], v[142:145], v[176:179], v[4:7]
	v_mfma_f32_16x16x32_f16 v[8:11], v[152:155], v[176:179], v[8:11]
	v_mfma_f32_16x16x32_f16 v[8:11], v[148:151], v[172:175], v[8:11]
	v_mfma_f32_16x16x32_f16 v[16:19], v[148:151], v[180:183], v[16:19]
	v_mfma_f32_16x16x32_f16 v[16:19], v[152:155], v[184:187], v[16:19]
	v_mfma_f32_16x16x32_f16 v[12:15], v[142:145], v[184:187], v[12:15]
	v_mfma_f32_16x16x32_f16 v[12:15], v[138:141], v[180:183], v[12:15]
	v_mfma_f32_16x16x32_f16 v[20:23], v[138:141], v[188:191], v[20:23]
	v_mfma_f32_16x16x32_f16 v[20:23], v[142:145], v[192:195], v[20:23]
	v_mfma_f32_16x16x32_f16 v[24:27], v[152:155], v[192:195], v[24:27]
	v_mfma_f32_16x16x32_f16 v[24:27], v[148:151], v[188:191], v[24:27]
	v_mfma_f32_16x16x32_f16 v[32:35], v[148:151], v[196:199], v[32:35]
	v_mfma_f32_16x16x32_f16 v[32:35], v[152:155], v[200:203], v[32:35]
	v_mfma_f32_16x16x32_f16 v[28:31], v[142:145], v[200:203], v[28:31]
	v_mfma_f32_16x16x32_f16 v[28:31], v[138:141], v[196:199], v[28:31]
	s_setprio 0
	s_setprio 1
	v_mfma_f32_16x16x32_f16 v[36:39], v[156:159], v[172:175], v[36:39]
	v_mfma_f32_16x16x32_f16 v[36:39], v[160:163], v[176:179], v[36:39]
	v_mfma_f32_16x16x32_f16 v[40:43], v[168:171], v[176:179], v[40:43]
	v_mfma_f32_16x16x32_f16 v[40:43], v[164:167], v[172:175], v[40:43]
	v_mfma_f32_16x16x32_f16 v[48:51], v[164:167], v[180:183], v[48:51]
	v_mfma_f32_16x16x32_f16 v[48:51], v[168:171], v[184:187], v[48:51]
	v_mfma_f32_16x16x32_f16 v[44:47], v[160:163], v[184:187], v[44:47]
	v_mfma_f32_16x16x32_f16 v[44:47], v[156:159], v[180:183], v[44:47]
	v_mfma_f32_16x16x32_f16 v[52:55], v[156:159], v[188:191], v[52:55]
	v_mfma_f32_16x16x32_f16 v[52:55], v[160:163], v[192:195], v[52:55]
	v_mfma_f32_16x16x32_f16 v[56:59], v[168:171], v[192:195], v[56:59]
	v_mfma_f32_16x16x32_f16 v[56:59], v[164:167], v[188:191], v[56:59]
	v_mfma_f32_16x16x32_f16 v[64:67], v[164:167], v[196:199], v[64:67]
	v_mfma_f32_16x16x32_f16 v[64:67], v[168:171], v[200:203], v[64:67]
	s_setprio 3
	s_barrier
	v_mfma_f32_16x16x32_f16 v[60:63], v[160:163], v[200:203], v[60:63]
	v_mfma_f32_16x16x32_f16 v[60:63], v[156:159], v[196:199], v[60:63]
	s_setprio 0
	s_add_i32 s29, s29, s38
	s_mov_b32 m0, s29
	ds_read_b128 v[172:175], v146 offset:16384
	ds_read_b128 v[176:179], v146 offset:17408
	ds_read_b128 v[180:183], v146 offset:18432
	ds_read_b128 v[184:187], v146 offset:19456
	ds_read_b128 v[188:191], v146 offset:20480
	ds_read_b128 v[192:195], v146 offset:21504
	ds_read_b128 v[196:199], v146 offset:22528
	ds_read_b128 v[200:203], v146 offset:23552
	global_load_lds_dwordx4 v136, s[6:7]
	s_add_i32 m0, s29, 0x2000
	s_add_u32 s40, s6, 0x80000
	s_addc_u32 s41, s7, 0
	s_add_i32 s29, s53, s38
	global_load_lds_dwordx4 v134, s[6:7]
	s_mov_b32 m0, s29
	v_mov_b32_e32 v137, v3
	global_load_lds_dwordx4 v136, s[40:41]
	s_add_i32 m0, s29, 0x2000
	v_mov_b32_e32 v135, v3
	global_load_lds_dwordx4 v134, s[40:41]
	s_mov_b32 m0, s58
	s_nop 0
	global_load_lds_dwordx4 v2, s[16:17]
	s_mov_b32 m0, s59
	s_nop 0
	global_load_lds_dwordx4 v132, s[16:17]
	s_waitcnt vmcnt(8)
	s_waitcnt lgkmcnt(0)
	s_add_u32 s88, s6, s86
	s_addc_u32 s89, s7, s87
	s_add_u32 s90, s16, s86
	s_addc_u32 s91, s17, s87
	s_barrier
	s_setprio 1
	s_waitcnt lgkmcnt(0)
	v_mfma_f32_16x16x32_f16 v[68:71], v[138:141], v[172:175], v[68:71]
	v_mfma_f32_16x16x32_f16 v[68:71], v[142:145], v[176:179], v[68:71]
	v_mfma_f32_16x16x32_f16 v[72:75], v[152:155], v[176:179], v[72:75]
	v_mfma_f32_16x16x32_f16 v[72:75], v[148:151], v[172:175], v[72:75]
	v_mfma_f32_16x16x32_f16 v[80:83], v[148:151], v[180:183], v[80:83]
	v_mfma_f32_16x16x32_f16 v[80:83], v[152:155], v[184:187], v[80:83]
	v_mfma_f32_16x16x32_f16 v[76:79], v[142:145], v[184:187], v[76:79]
	v_mfma_f32_16x16x32_f16 v[76:79], v[138:141], v[180:183], v[76:79]
	v_mfma_f32_16x16x32_f16 v[84:87], v[138:141], v[188:191], v[84:87]
	v_mfma_f32_16x16x32_f16 v[84:87], v[142:145], v[192:195], v[84:87]
	v_mfma_f32_16x16x32_f16 v[88:91], v[152:155], v[192:195], v[88:91]
	v_mfma_f32_16x16x32_f16 v[88:91], v[148:151], v[188:191], v[88:91]
	v_mfma_f32_16x16x32_f16 v[96:99], v[148:151], v[196:199], v[96:99]
	v_mfma_f32_16x16x32_f16 v[96:99], v[152:155], v[200:203], v[96:99]
	v_mfma_f32_16x16x32_f16 v[92:95], v[142:145], v[200:203], v[92:95]
	v_mfma_f32_16x16x32_f16 v[92:95], v[138:141], v[196:199], v[92:95]
	s_setprio 0
	s_setprio 1
	v_mfma_f32_16x16x32_f16 v[100:103], v[156:159], v[172:175], v[100:103]
	v_mfma_f32_16x16x32_f16 v[100:103], v[160:163], v[176:179], v[100:103]
	v_mfma_f32_16x16x32_f16 v[104:107], v[168:171], v[176:179], v[104:107]
	v_mfma_f32_16x16x32_f16 v[104:107], v[164:167], v[172:175], v[104:107]
	v_mfma_f32_16x16x32_f16 v[112:115], v[164:167], v[180:183], v[112:115]
	v_mfma_f32_16x16x32_f16 v[112:115], v[168:171], v[184:187], v[112:115]
	v_mfma_f32_16x16x32_f16 v[108:111], v[160:163], v[184:187], v[108:111]
	v_mfma_f32_16x16x32_f16 v[108:111], v[156:159], v[180:183], v[108:111]
	v_mfma_f32_16x16x32_f16 v[116:119], v[156:159], v[188:191], v[116:119]
	v_mfma_f32_16x16x32_f16 v[116:119], v[160:163], v[192:195], v[116:119]
	v_mfma_f32_16x16x32_f16 v[120:123], v[168:171], v[192:195], v[120:123]
	v_mfma_f32_16x16x32_f16 v[120:123], v[164:167], v[188:191], v[120:123]
	v_mfma_f32_16x16x32_f16 v[128:131], v[164:167], v[196:199], v[128:131]
	v_mfma_f32_16x16x32_f16 v[128:131], v[168:171], v[200:203], v[128:131]
	s_setprio 3
	s_barrier
	v_mfma_f32_16x16x32_f16 v[124:127], v[160:163], v[200:203], v[124:127]
	v_mfma_f32_16x16x32_f16 v[124:127], v[156:159], v[196:199], v[124:127]
	s_setprio 0
	s_add_i32 s29, 0, 0x18000
	s_add_i32 s40, 0, 0x1c000
	ds_read_b128 v[138:141], v240 offset:32768
	ds_read_b128 v[142:145], v240 offset:33792
	ds_read_b128 v[148:151], v240 offset:34816
	ds_read_b128 v[152:155], v240 offset:35840
	ds_read_b128 v[156:159], v240 offset:49152
	ds_read_b128 v[160:163], v240 offset:50176
	ds_read_b128 v[164:167], v240 offset:51200
	ds_read_b128 v[168:171], v240 offset:52224
	s_add_u32 s16, s16, 0x80000
	s_addc_u32 s17, s17, 0
	s_mov_b32 m0, s60
	ds_read_b128 v[172:175], v146 offset:32768
	ds_read_b128 v[176:179], v146 offset:33792
	ds_read_b128 v[180:183], v146 offset:34816
	ds_read_b128 v[184:187], v146 offset:35840
	ds_read_b128 v[188:191], v146 offset:36864
	ds_read_b128 v[192:195], v146 offset:37888
	ds_read_b128 v[196:199], v146 offset:38912
	ds_read_b128 v[200:203], v146 offset:39936
	global_load_lds_dwordx4 v2, s[16:17]
	s_mov_b32 m0, s61
	s_nop 0
	global_load_lds_dwordx4 v132, s[16:17]
	s_waitcnt vmcnt(8)
	s_waitcnt lgkmcnt(0)
	s_barrier
	s_setprio 1
	s_waitcnt lgkmcnt(0)
	v_mfma_f32_16x16x32_f16 v[4:7], v[138:141], v[172:175], v[4:7]
	v_mfma_f32_16x16x32_f16 v[4:7], v[142:145], v[176:179], v[4:7]
	v_mfma_f32_16x16x32_f16 v[8:11], v[152:155], v[176:179], v[8:11]
	v_mfma_f32_16x16x32_f16 v[8:11], v[148:151], v[172:175], v[8:11]
	v_mfma_f32_16x16x32_f16 v[16:19], v[148:151], v[180:183], v[16:19]
	v_mfma_f32_16x16x32_f16 v[16:19], v[152:155], v[184:187], v[16:19]
	v_mfma_f32_16x16x32_f16 v[12:15], v[142:145], v[184:187], v[12:15]
	v_mfma_f32_16x16x32_f16 v[12:15], v[138:141], v[180:183], v[12:15]
	v_mfma_f32_16x16x32_f16 v[20:23], v[138:141], v[188:191], v[20:23]
	v_mfma_f32_16x16x32_f16 v[20:23], v[142:145], v[192:195], v[20:23]
	v_mfma_f32_16x16x32_f16 v[24:27], v[152:155], v[192:195], v[24:27]
	v_mfma_f32_16x16x32_f16 v[24:27], v[148:151], v[188:191], v[24:27]
	v_mfma_f32_16x16x32_f16 v[32:35], v[148:151], v[196:199], v[32:35]
	v_mfma_f32_16x16x32_f16 v[32:35], v[152:155], v[200:203], v[32:35]
	v_mfma_f32_16x16x32_f16 v[28:31], v[142:145], v[200:203], v[28:31]
	v_mfma_f32_16x16x32_f16 v[28:31], v[138:141], v[196:199], v[28:31]
	s_setprio 0
	s_setprio 1
	v_mfma_f32_16x16x32_f16 v[36:39], v[156:159], v[172:175], v[36:39]
	v_mfma_f32_16x16x32_f16 v[36:39], v[160:163], v[176:179], v[36:39]
	v_mfma_f32_16x16x32_f16 v[40:43], v[168:171], v[176:179], v[40:43]
	v_mfma_f32_16x16x32_f16 v[40:43], v[164:167], v[172:175], v[40:43]
	v_mfma_f32_16x16x32_f16 v[48:51], v[164:167], v[180:183], v[48:51]
	v_mfma_f32_16x16x32_f16 v[48:51], v[168:171], v[184:187], v[48:51]
	v_mfma_f32_16x16x32_f16 v[44:47], v[160:163], v[184:187], v[44:47]
	v_mfma_f32_16x16x32_f16 v[44:47], v[156:159], v[180:183], v[44:47]
	v_mfma_f32_16x16x32_f16 v[52:55], v[156:159], v[188:191], v[52:55]
	v_mfma_f32_16x16x32_f16 v[52:55], v[160:163], v[192:195], v[52:55]
	v_mfma_f32_16x16x32_f16 v[56:59], v[168:171], v[192:195], v[56:59]
	v_mfma_f32_16x16x32_f16 v[56:59], v[164:167], v[188:191], v[56:59]
	v_mfma_f32_16x16x32_f16 v[64:67], v[164:167], v[196:199], v[64:67]
	v_mfma_f32_16x16x32_f16 v[64:67], v[168:171], v[200:203], v[64:67]
	s_setprio 3
	s_barrier
	v_mfma_f32_16x16x32_f16 v[60:63], v[160:163], v[200:203], v[60:63]
	v_mfma_f32_16x16x32_f16 v[60:63], v[156:159], v[196:199], v[60:63]
	s_setprio 0
	s_add_i32 s16, s29, s38
	s_mov_b32 m0, s16
	ds_read_b128 v[172:175], v146 offset:49152
	ds_read_b128 v[176:179], v146 offset:50176
	ds_read_b128 v[180:183], v146 offset:51200
	ds_read_b128 v[184:187], v146 offset:52224
	ds_read_b128 v[188:191], v146 offset:53248
	ds_read_b128 v[192:195], v146 offset:54272
	ds_read_b128 v[196:199], v146 offset:55296
	ds_read_b128 v[200:203], v146 offset:56320
	global_load_lds_dwordx4 v136, s[88:89]
	s_add_i32 m0, s16, 0x2000
	s_add_u32 s6, s6, 0x80080
	s_addc_u32 s7, s7, 0
	s_add_i32 s16, s40, s38
	global_load_lds_dwordx4 v134, s[88:89]
	s_mov_b32 m0, s16
	s_nop 0
	global_load_lds_dwordx4 v136, s[6:7]
	s_add_i32 m0, s16, 0x2000
	s_nop 0
	global_load_lds_dwordx4 v134, s[6:7]
	s_mov_b32 m0, s64
	s_nop 0
	global_load_lds_dwordx4 v2, s[90:91]
	s_mov_b32 m0, s65
	s_nop 0
	global_load_lds_dwordx4 v132, s[90:91]
	s_waitcnt vmcnt(8)
	s_waitcnt lgkmcnt(0)
	s_barrier
	s_setprio 1
	s_waitcnt lgkmcnt(0)
	v_mfma_f32_16x16x32_f16 v[68:71], v[138:141], v[172:175], v[68:71]
	v_mfma_f32_16x16x32_f16 v[68:71], v[142:145], v[176:179], v[68:71]
	v_mfma_f32_16x16x32_f16 v[72:75], v[152:155], v[176:179], v[72:75]
	v_mfma_f32_16x16x32_f16 v[72:75], v[148:151], v[172:175], v[72:75]
	v_mfma_f32_16x16x32_f16 v[80:83], v[148:151], v[180:183], v[80:83]
	v_mfma_f32_16x16x32_f16 v[80:83], v[152:155], v[184:187], v[80:83]
	v_mfma_f32_16x16x32_f16 v[76:79], v[142:145], v[184:187], v[76:79]
	v_mfma_f32_16x16x32_f16 v[76:79], v[138:141], v[180:183], v[76:79]
	v_mfma_f32_16x16x32_f16 v[84:87], v[138:141], v[188:191], v[84:87]
	v_mfma_f32_16x16x32_f16 v[84:87], v[142:145], v[192:195], v[84:87]
	v_mfma_f32_16x16x32_f16 v[88:91], v[152:155], v[192:195], v[88:91]
	v_mfma_f32_16x16x32_f16 v[88:91], v[148:151], v[188:191], v[88:91]
	v_mfma_f32_16x16x32_f16 v[96:99], v[148:151], v[196:199], v[96:99]
	v_mfma_f32_16x16x32_f16 v[96:99], v[152:155], v[200:203], v[96:99]
	v_mfma_f32_16x16x32_f16 v[92:95], v[142:145], v[200:203], v[92:95]
	v_mfma_f32_16x16x32_f16 v[92:95], v[138:141], v[196:199], v[92:95]
	s_setprio 0
	s_setprio 1
	v_mfma_f32_16x16x32_f16 v[100:103], v[156:159], v[172:175], v[100:103]
	v_mfma_f32_16x16x32_f16 v[100:103], v[160:163], v[176:179], v[100:103]
	v_mfma_f32_16x16x32_f16 v[104:107], v[168:171], v[176:179], v[104:107]
	v_mfma_f32_16x16x32_f16 v[104:107], v[164:167], v[172:175], v[104:107]
	v_mfma_f32_16x16x32_f16 v[112:115], v[164:167], v[180:183], v[112:115]
	v_mfma_f32_16x16x32_f16 v[112:115], v[168:171], v[184:187], v[112:115]
	v_mfma_f32_16x16x32_f16 v[108:111], v[160:163], v[184:187], v[108:111]
	v_mfma_f32_16x16x32_f16 v[108:111], v[156:159], v[180:183], v[108:111]
	v_mfma_f32_16x16x32_f16 v[116:119], v[156:159], v[188:191], v[116:119]
	v_mfma_f32_16x16x32_f16 v[116:119], v[160:163], v[192:195], v[116:119]
	v_mfma_f32_16x16x32_f16 v[120:123], v[168:171], v[192:195], v[120:123]
	v_mfma_f32_16x16x32_f16 v[120:123], v[164:167], v[188:191], v[120:123]
	v_mfma_f32_16x16x32_f16 v[128:131], v[164:167], v[196:199], v[128:131]
	v_mfma_f32_16x16x32_f16 v[128:131], v[168:171], v[200:203], v[128:131]
	s_setprio 3
	s_barrier
	v_mfma_f32_16x16x32_f16 v[124:127], v[160:163], v[200:203], v[124:127]
	v_mfma_f32_16x16x32_f16 v[124:127], v[156:159], v[196:199], v[124:127]
	s_setprio 0
	s_add_i32 s28, s28, 2
	s_add_u32 s8, s8, 0x100
	s_addc_u32 s9, s9, 0
	s_add_u32 s26, s26, 0x100
	s_addc_u32 s27, s27, 0
	s_cmp_gt_u32 s28, 29
	s_cbranch_scc0 .LBB0_532
	s_and_b64 vcc, exec, s[50:51]
	s_cbranch_vccz .LBB0_535
	s_barrier

.LBB0_641:
	s_add_i32 s43, 0, 0x10000
	s_add_i32 s71, 0, 0x14000
	v_add_u32_e32 v16, s43, v232
	v_add_u32_e32 v32, s71, v232
	ds_read_b128 v[4:7], v16
	ds_read_b128 v[8:11], v16 offset:1024
	ds_read_b128 v[12:15], v16 offset:2048
	ds_read_b128 v[16:19], v16 offset:3072
	ds_read_b128 v[20:23], v32
	ds_read_b128 v[24:27], v32 offset:1024
	ds_read_b128 v[28:31], v32 offset:2048
	ds_read_b128 v[32:35], v32 offset:3072
	v_add_u32_e32 v233, 0, v231
	ds_read_b128 v[36:39], v233
	ds_read_b128 v[40:43], v233 offset:1024
	ds_read_b128 v[44:47], v233 offset:2048
	ds_read_b128 v[48:51], v233 offset:3072
	ds_read_b128 v[52:55], v233 offset:4096
	ds_read_b128 v[56:59], v233 offset:5120
	ds_read_b128 v[60:63], v233 offset:6144
	ds_read_b128 v[64:67], v233 offset:7168
	s_waitcnt vmcnt(8)
	s_waitcnt lgkmcnt(0)
	s_barrier
	s_setprio 1
	s_waitcnt lgkmcnt(0)
	v_mfma_f32_16x16x32_bf16 v[68:71], v[4:7], v[36:39], 0
	v_mfma_f32_16x16x32_bf16 v[68:71], v[8:11], v[40:43], v[68:71]
	v_mfma_f32_16x16x32_bf16 v[72:75], v[12:15], v[36:39], 0
	v_mfma_f32_16x16x32_bf16 v[72:75], v[16:19], v[40:43], v[72:75]
	v_mfma_f32_16x16x32_bf16 v[80:83], v[12:15], v[44:47], 0
	v_mfma_f32_16x16x32_bf16 v[80:83], v[16:19], v[48:51], v[80:83]
	v_mfma_f32_16x16x32_bf16 v[76:79], v[4:7], v[44:47], 0
	v_mfma_f32_16x16x32_bf16 v[76:79], v[8:11], v[48:51], v[76:79]
	v_mfma_f32_16x16x32_bf16 v[84:87], v[4:7], v[52:55], 0
	v_mfma_f32_16x16x32_bf16 v[84:87], v[8:11], v[56:59], v[84:87]
	v_mfma_f32_16x16x32_bf16 v[88:91], v[12:15], v[52:55], 0
	v_mfma_f32_16x16x32_bf16 v[88:91], v[16:19], v[56:59], v[88:91]
	v_mfma_f32_16x16x32_bf16 v[96:99], v[12:15], v[60:63], 0
	v_mfma_f32_16x16x32_bf16 v[96:99], v[16:19], v[64:67], v[96:99]
	v_mfma_f32_16x16x32_bf16 v[92:95], v[4:7], v[60:63], 0
	v_mfma_f32_16x16x32_bf16 v[92:95], v[8:11], v[64:67], v[92:95]
	s_setprio 0
	s_setprio 1
	v_mfma_f32_16x16x32_bf16 v[100:103], v[20:23], v[36:39], 0
	v_mfma_f32_16x16x32_bf16 v[36:39], v[28:31], v[36:39], 0
	v_mfma_f32_16x16x32_bf16 v[104:107], v[20:23], v[44:47], 0
	v_mfma_f32_16x16x32_bf16 v[44:47], v[28:31], v[44:47], 0
	v_mfma_f32_16x16x32_bf16 v[108:111], v[20:23], v[52:55], 0
	v_mfma_f32_16x16x32_bf16 v[52:55], v[28:31], v[52:55], 0
	v_mfma_f32_16x16x32_bf16 v[112:115], v[20:23], v[60:63], 0
	v_mfma_f32_16x16x32_bf16 v[60:63], v[28:31], v[60:63], 0
	v_mfma_f32_16x16x32_bf16 v[100:103], v[24:27], v[40:43], v[100:103]
	v_mfma_f32_16x16x32_bf16 v[40:43], v[32:35], v[40:43], v[36:39]
	v_mfma_f32_16x16x32_bf16 v[104:107], v[24:27], v[48:51], v[104:107]
	v_mfma_f32_16x16x32_bf16 v[48:51], v[32:35], v[48:51], v[44:47]
	v_mfma_f32_16x16x32_bf16 v[108:111], v[24:27], v[56:59], v[108:111]
	v_mfma_f32_16x16x32_bf16 v[56:59], v[32:35], v[56:59], v[52:55]
	s_setprio 3
	s_barrier
	v_mfma_f32_16x16x32_bf16 v[112:115], v[24:27], v[64:67], v[112:115]
	v_mfma_f32_16x16x32_bf16 v[64:67], v[32:35], v[64:67], v[60:63]
	s_setprio 0
	v_lshl_add_u64 v[186:187], s[8:9], 0, v[2:3]
	s_add_i32 s43, s43, s54
	v_mov_b32_e32 v191, v3
	v_lshl_add_u64 v[134:135], v[186:187], 0, s[80:81]
	s_mov_b32 m0, s43
	v_lshl_add_u64 v[246:247], s[8:9], 0, v[190:191]
	ds_read_b128 v[36:39], v233 offset:16384
	ds_read_b128 v[44:47], v233 offset:17408
	ds_read_b128 v[52:55], v233 offset:18432
	ds_read_b128 v[60:63], v233 offset:19456
	ds_read_b128 v[116:119], v233 offset:20480
	ds_read_b128 v[120:123], v233 offset:21504
	ds_read_b128 v[124:127], v233 offset:22528
	ds_read_b128 v[128:131], v233 offset:23552
	global_load_lds_dwordx4 v[134:135], off
	v_lshl_add_u64 v[134:135], v[246:247], 0, s[80:81]
	s_add_i32 m0, s43, 0x2000
	s_add_i32 s43, s71, s54
	global_load_lds_dwordx4 v[134:135], off
	s_mov_b32 m0, s43
	v_mov_b32_e32 v133, v3
	global_load_lds_dwordx4 v2, s[16:17]
	s_add_i32 m0, s43, 0x2000
	v_lshl_add_u64 v[248:249], s[6:7], 0, v[132:133]
	v_mov_b32_e32 v189, v3
	global_load_lds_dwordx4 v190, s[16:17]
	v_lshl_add_u64 v[134:135], v[248:249], 0, s[80:81]
	s_mov_b32 m0, s55
	v_lshl_add_u64 v[250:251], s[6:7], 0, v[188:189]
	global_load_lds_dwordx4 v[134:135], off
	v_lshl_add_u64 v[134:135], v[250:251], 0, s[80:81]
	s_mov_b32 m0, s56
	s_nop 0
	global_load_lds_dwordx4 v[134:135], off
	s_waitcnt vmcnt(8)
	s_waitcnt lgkmcnt(0)
	s_barrier
	s_setprio 1
	s_waitcnt lgkmcnt(0)
	v_mfma_f32_16x16x32_bf16 v[134:137], v[4:7], v[36:39], 0
	v_mfma_f32_16x16x32_bf16 v[138:141], v[12:15], v[36:39], 0
	v_mfma_f32_16x16x32_bf16 v[142:145], v[4:7], v[52:55], 0
	v_mfma_f32_16x16x32_bf16 v[146:149], v[12:15], v[52:55], 0
	v_mfma_f32_16x16x32_bf16 v[150:153], v[4:7], v[116:119], 0
	v_mfma_f32_16x16x32_bf16 v[154:157], v[12:15], v[116:119], 0
	v_mfma_f32_16x16x32_bf16 v[4:7], v[4:7], v[124:127], 0
	v_mfma_f32_16x16x32_bf16 v[12:15], v[12:15], v[124:127], 0
	v_mfma_f32_16x16x32_bf16 v[134:137], v[8:11], v[44:47], v[134:137]
	v_mfma_f32_16x16x32_bf16 v[138:141], v[16:19], v[44:47], v[138:141]
	v_mfma_f32_16x16x32_bf16 v[142:145], v[8:11], v[60:63], v[142:145]
	v_mfma_f32_16x16x32_bf16 v[146:149], v[16:19], v[60:63], v[146:149]
	v_mfma_f32_16x16x32_bf16 v[150:153], v[8:11], v[120:123], v[150:153]
	v_mfma_f32_16x16x32_bf16 v[154:157], v[16:19], v[120:123], v[154:157]
	v_mfma_f32_16x16x32_bf16 v[158:161], v[8:11], v[128:131], v[4:7]
	v_mfma_f32_16x16x32_bf16 v[162:165], v[16:19], v[128:131], v[12:15]
	s_setprio 0
	s_setprio 1
	v_mfma_f32_16x16x32_bf16 v[4:7], v[20:23], v[36:39], 0
	v_mfma_f32_16x16x32_bf16 v[8:11], v[28:31], v[36:39], 0
	v_mfma_f32_16x16x32_bf16 v[12:15], v[20:23], v[52:55], 0
	v_mfma_f32_16x16x32_bf16 v[16:19], v[28:31], v[52:55], 0
	v_mfma_f32_16x16x32_bf16 v[36:39], v[20:23], v[116:119], 0
	v_mfma_f32_16x16x32_bf16 v[52:55], v[28:31], v[116:119], 0
	v_mfma_f32_16x16x32_bf16 v[20:23], v[20:23], v[124:127], 0
	v_mfma_f32_16x16x32_bf16 v[28:31], v[28:31], v[124:127], 0
	v_mfma_f32_16x16x32_bf16 v[116:119], v[24:27], v[44:47], v[4:7]
	v_mfma_f32_16x16x32_bf16 v[124:127], v[32:35], v[44:47], v[8:11]
	v_mfma_f32_16x16x32_bf16 v[174:177], v[24:27], v[120:123], v[36:39]
	v_mfma_f32_16x16x32_bf16 v[120:123], v[32:35], v[120:123], v[52:55]
	v_mfma_f32_16x16x32_bf16 v[178:181], v[24:27], v[128:131], v[20:23]
	v_mfma_f32_16x16x32_bf16 v[128:131], v[32:35], v[128:131], v[28:31]
	s_setprio 3
	s_barrier
	v_mfma_f32_16x16x32_bf16 v[166:169], v[24:27], v[60:63], v[12:15]
	v_mfma_f32_16x16x32_bf16 v[170:173], v[32:35], v[60:63], v[16:19]
	s_setprio 0
	s_add_i32 s43, 0, 0x18000
	v_add_u32_e32 v4, s43, v232
	s_add_i32 s71, 0, 0x1c000
	ds_read_b128 v[182:185], v4
	ds_read_b128 v[192:195], v4 offset:1024
	ds_read_b128 v[196:199], v4 offset:2048
	ds_read_b128 v[200:203], v4 offset:3072
	v_add_u32_e32 v4, s71, v232
	ds_read_b128 v[204:207], v4
	ds_read_b128 v[208:211], v4 offset:1024
	ds_read_b128 v[212:215], v4 offset:2048
	ds_read_b128 v[216:219], v4 offset:3072
	s_mov_b32 m0, s57
	ds_read_b128 v[44:47], v233 offset:32768
	ds_read_b128 v[52:55], v233 offset:33792
	ds_read_b128 v[60:63], v233 offset:34816
	ds_read_b128 v[220:223], v233 offset:35840
	ds_read_b128 v[224:227], v233 offset:36864
	ds_read_b128 v[234:237], v233 offset:37888
	ds_read_b128 v[238:241], v233 offset:38912
	ds_read_b128 v[242:245], v233 offset:39936
	global_load_lds_dwordx4 v132, s[26:27]
	s_mov_b32 m0, s58
	s_nop 0
	global_load_lds_dwordx4 v188, s[26:27]
	s_waitcnt vmcnt(8)
	s_waitcnt lgkmcnt(0)
	s_barrier
	s_setprio 1
	s_waitcnt lgkmcnt(0)
	v_mfma_f32_16x16x32_bf16 v[4:7], v[182:185], v[44:47], v[68:71]
	v_mfma_f32_16x16x32_bf16 v[8:11], v[196:199], v[44:47], v[72:75]
	v_mfma_f32_16x16x32_bf16 v[12:15], v[182:185], v[60:63], v[76:79]
	v_mfma_f32_16x16x32_bf16 v[16:19], v[196:199], v[60:63], v[80:83]
	v_mfma_f32_16x16x32_bf16 v[20:23], v[182:185], v[224:227], v[84:87]
	v_mfma_f32_16x16x32_bf16 v[24:27], v[196:199], v[224:227], v[88:91]
	v_mfma_f32_16x16x32_bf16 v[28:31], v[182:185], v[238:241], v[92:95]
	v_mfma_f32_16x16x32_bf16 v[32:35], v[196:199], v[238:241], v[96:99]
	v_mfma_f32_16x16x32_bf16 v[4:7], v[192:195], v[52:55], v[4:7]
	v_mfma_f32_16x16x32_bf16 v[8:11], v[200:203], v[52:55], v[8:11]
	v_mfma_f32_16x16x32_bf16 v[12:15], v[192:195], v[220:223], v[12:15]
	v_mfma_f32_16x16x32_bf16 v[16:19], v[200:203], v[220:223], v[16:19]
	v_mfma_f32_16x16x32_bf16 v[20:23], v[192:195], v[234:237], v[20:23]
	v_mfma_f32_16x16x32_bf16 v[24:27], v[200:203], v[234:237], v[24:27]
	v_mfma_f32_16x16x32_bf16 v[28:31], v[192:195], v[242:245], v[28:31]
	v_mfma_f32_16x16x32_bf16 v[32:35], v[200:203], v[242:245], v[32:35]
	s_setprio 0
	s_setprio 1
	v_mfma_f32_16x16x32_bf16 v[36:39], v[204:207], v[44:47], v[100:103]
	v_mfma_f32_16x16x32_bf16 v[40:43], v[212:215], v[44:47], v[40:43]
	v_mfma_f32_16x16x32_bf16 v[36:39], v[208:211], v[52:55], v[36:39]
	v_mfma_f32_16x16x32_bf16 v[40:43], v[216:219], v[52:55], v[40:43]
	v_mfma_f32_16x16x32_bf16 v[44:47], v[204:207], v[60:63], v[104:107]
	v_mfma_f32_16x16x32_bf16 v[48:51], v[212:215], v[60:63], v[48:51]
	v_mfma_f32_16x16x32_bf16 v[52:55], v[204:207], v[224:227], v[108:111]
	v_mfma_f32_16x16x32_bf16 v[56:59], v[212:215], v[224:227], v[56:59]
	v_mfma_f32_16x16x32_bf16 v[60:63], v[204:207], v[238:241], v[112:115]
	v_mfma_f32_16x16x32_bf16 v[64:67], v[212:215], v[238:241], v[64:67]
	v_mfma_f32_16x16x32_bf16 v[44:47], v[208:211], v[220:223], v[44:47]
	v_mfma_f32_16x16x32_bf16 v[48:51], v[216:219], v[220:223], v[48:51]
	v_mfma_f32_16x16x32_bf16 v[52:55], v[208:211], v[234:237], v[52:55]
	v_mfma_f32_16x16x32_bf16 v[56:59], v[216:219], v[234:237], v[56:59]
	s_setprio 3
	s_barrier
	v_mfma_f32_16x16x32_bf16 v[60:63], v[208:211], v[242:245], v[60:63]
	v_mfma_f32_16x16x32_bf16 v[64:67], v[216:219], v[242:245], v[64:67]
	s_setprio 0
	s_add_i32 s43, s43, s54
	v_lshl_add_u64 v[68:69], v[186:187], 0, s[0:1]
	s_mov_b32 m0, s43
	ds_read_b128 v[104:107], v233 offset:49152
	ds_read_b128 v[108:111], v233 offset:50176
	ds_read_b128 v[112:115], v233 offset:51200
	ds_read_b128 v[220:223], v233 offset:52224
	ds_read_b128 v[224:227], v233 offset:53248
	ds_read_b128 v[234:237], v233 offset:54272
	ds_read_b128 v[238:241], v233 offset:55296
	ds_read_b128 v[242:245], v233 offset:56320
	global_load_lds_dwordx4 v[68:69], off
	v_lshl_add_u64 v[68:69], v[246:247], 0, s[0:1]
	s_add_i32 m0, s43, 0x2000
	s_add_i32 s43, s71, s54
	global_load_lds_dwordx4 v[68:69], off
	s_mov_b32 m0, s43
	v_lshl_add_u64 v[68:69], v[248:249], 0, s[0:1]
	global_load_lds_dwordx4 v2, s[28:29]
	s_add_i32 m0, s43, 0x2000
	s_nop 0
	global_load_lds_dwordx4 v190, s[28:29]
	s_mov_b32 m0, s62
	s_nop 0
	global_load_lds_dwordx4 v[68:69], off
	v_lshl_add_u64 v[68:69], v[250:251], 0, s[0:1]
	s_mov_b32 m0, s63
	s_nop 0
	global_load_lds_dwordx4 v[68:69], off
	s_waitcnt vmcnt(8)
	s_waitcnt lgkmcnt(0)
	s_barrier
	s_setprio 1
	s_waitcnt lgkmcnt(0)
	v_mfma_f32_16x16x32_bf16 v[68:71], v[182:185], v[104:107], v[134:137]
	v_mfma_f32_16x16x32_bf16 v[72:75], v[196:199], v[104:107], v[138:141]
	v_mfma_f32_16x16x32_bf16 v[76:79], v[182:185], v[112:115], v[142:145]
	v_mfma_f32_16x16x32_bf16 v[80:83], v[196:199], v[112:115], v[146:149]
	v_mfma_f32_16x16x32_bf16 v[84:87], v[182:185], v[224:227], v[150:153]
	v_mfma_f32_16x16x32_bf16 v[88:91], v[196:199], v[224:227], v[154:157]
	v_mfma_f32_16x16x32_bf16 v[92:95], v[182:185], v[238:241], v[158:161]
	v_mfma_f32_16x16x32_bf16 v[96:99], v[196:199], v[238:241], v[162:165]
	v_mfma_f32_16x16x32_bf16 v[68:71], v[192:195], v[108:111], v[68:71]
	v_mfma_f32_16x16x32_bf16 v[72:75], v[200:203], v[108:111], v[72:75]
	v_mfma_f32_16x16x32_bf16 v[76:79], v[192:195], v[220:223], v[76:79]
	v_mfma_f32_16x16x32_bf16 v[80:83], v[200:203], v[220:223], v[80:83]
	v_mfma_f32_16x16x32_bf16 v[84:87], v[192:195], v[234:237], v[84:87]
	v_mfma_f32_16x16x32_bf16 v[88:91], v[200:203], v[234:237], v[88:91]
	v_mfma_f32_16x16x32_bf16 v[92:95], v[192:195], v[242:245], v[92:95]
	v_mfma_f32_16x16x32_bf16 v[96:99], v[200:203], v[242:245], v[96:99]
	s_setprio 0
	s_setprio 1
	v_mfma_f32_16x16x32_bf16 v[100:103], v[204:207], v[104:107], v[116:119]
	v_mfma_f32_16x16x32_bf16 v[104:107], v[212:215], v[104:107], v[124:127]
	v_mfma_f32_16x16x32_bf16 v[100:103], v[208:211], v[108:111], v[100:103]
	v_mfma_f32_16x16x32_bf16 v[104:107], v[216:219], v[108:111], v[104:107]
	v_mfma_f32_16x16x32_bf16 v[108:111], v[204:207], v[112:115], v[166:169]
	v_mfma_f32_16x16x32_bf16 v[112:115], v[212:215], v[112:115], v[170:173]
	v_mfma_f32_16x16x32_bf16 v[116:119], v[204:207], v[224:227], v[174:177]
	v_mfma_f32_16x16x32_bf16 v[120:123], v[212:215], v[224:227], v[120:123]
	v_mfma_f32_16x16x32_bf16 v[124:127], v[204:207], v[238:241], v[178:181]
	v_mfma_f32_16x16x32_bf16 v[128:131], v[212:215], v[238:241], v[128:131]
	v_mfma_f32_16x16x32_bf16 v[108:111], v[208:211], v[220:223], v[108:111]
	v_mfma_f32_16x16x32_bf16 v[112:115], v[216:219], v[220:223], v[112:115]
	v_mfma_f32_16x16x32_bf16 v[116:119], v[208:211], v[234:237], v[116:119]
	v_mfma_f32_16x16x32_bf16 v[120:123], v[216:219], v[234:237], v[120:123]
	s_setprio 3
	s_barrier
	v_mfma_f32_16x16x32_bf16 v[124:127], v[208:211], v[242:245], v[124:127]
	v_mfma_f32_16x16x32_bf16 v[128:131], v[216:219], v[242:245], v[128:131]
	s_setprio 0
	s_add_i32 s42, s42, 2
	s_cmp_ge_i32 s42, s38
	s_cbranch_scc0 .LBB0_641
	v_mov_b32_e32 v192, v2
	s_branch .LBB0_644

.LBB0_649:
	s_or_b32 s38, s28, 1
	s_lshl_b64 s[42:43], s[38:39], 7
	s_sub_u32 s38, 0, s42
	s_subb_u32 s42, 0, s43
	s_add_u32 s38, s6, s38
	s_addc_u32 s43, s7, s42
	s_add_i32 s71, 0, 0x10000
	s_add_i32 s72, 0, 0x14000
	s_waitcnt lgkmcnt(0)
	ds_read_b128 v[132:135], v240
	ds_read_b128 v[136:139], v240 offset:1024
	ds_read_b128 v[140:143], v240 offset:2048
	ds_read_b128 v[144:147], v240 offset:3072
	ds_read_b128 v[148:151], v240 offset:16384
	ds_read_b128 v[152:155], v240 offset:17408
	ds_read_b128 v[156:159], v240 offset:18432
	ds_read_b128 v[160:163], v240 offset:19456
	s_add_u32 s42, s38, 0x160000
	s_mov_b32 m0, s64
	s_addc_u32 s43, s43, 0
	ds_read_b128 v[164:167], v231
	ds_read_b128 v[168:171], v231 offset:1024
	ds_read_b128 v[172:175], v231 offset:2048
	ds_read_b128 v[176:179], v231 offset:3072
	ds_read_b128 v[180:183], v231 offset:4096
	ds_read_b128 v[184:187], v231 offset:5120
	ds_read_b128 v[194:197], v231 offset:6144
	ds_read_b128 v[198:201], v231 offset:7168
	global_load_lds_dwordx4 v2, s[42:43]
	s_mov_b32 m0, s65
	v_mov_b32_e32 v189, v3
	global_load_lds_dwordx4 v188, s[42:43]
	s_waitcnt vmcnt(8)
	s_waitcnt lgkmcnt(0)
	s_barrier
	s_setprio 1
	s_waitcnt lgkmcnt(0)
	v_mfma_f32_16x16x32_bf16 v[4:7], v[132:135], v[164:167], v[4:7]
	v_mfma_f32_16x16x32_bf16 v[4:7], v[136:139], v[168:171], v[4:7]
	v_mfma_f32_16x16x32_bf16 v[8:11], v[144:147], v[168:171], v[8:11]
	v_mfma_f32_16x16x32_bf16 v[8:11], v[140:143], v[164:167], v[8:11]
	v_mfma_f32_16x16x32_bf16 v[16:19], v[140:143], v[172:175], v[16:19]
	v_mfma_f32_16x16x32_bf16 v[16:19], v[144:147], v[176:179], v[16:19]
	v_mfma_f32_16x16x32_bf16 v[12:15], v[136:139], v[176:179], v[12:15]
	v_mfma_f32_16x16x32_bf16 v[12:15], v[132:135], v[172:175], v[12:15]
	v_mfma_f32_16x16x32_bf16 v[20:23], v[132:135], v[180:183], v[20:23]
	v_mfma_f32_16x16x32_bf16 v[20:23], v[136:139], v[184:187], v[20:23]
	v_mfma_f32_16x16x32_bf16 v[24:27], v[144:147], v[184:187], v[24:27]
	v_mfma_f32_16x16x32_bf16 v[24:27], v[140:143], v[180:183], v[24:27]
	v_mfma_f32_16x16x32_bf16 v[32:35], v[140:143], v[194:197], v[32:35]
	v_mfma_f32_16x16x32_bf16 v[32:35], v[144:147], v[198:201], v[32:35]
	v_mfma_f32_16x16x32_bf16 v[28:31], v[136:139], v[198:201], v[28:31]
	v_mfma_f32_16x16x32_bf16 v[28:31], v[132:135], v[194:197], v[28:31]
	s_setprio 0
	s_setprio 1
	v_mfma_f32_16x16x32_bf16 v[36:39], v[148:151], v[164:167], v[36:39]
	v_mfma_f32_16x16x32_bf16 v[36:39], v[152:155], v[168:171], v[36:39]
	v_mfma_f32_16x16x32_bf16 v[40:43], v[160:163], v[168:171], v[40:43]
	v_mfma_f32_16x16x32_bf16 v[40:43], v[156:159], v[164:167], v[40:43]
	v_mfma_f32_16x16x32_bf16 v[48:51], v[156:159], v[172:175], v[48:51]
	v_mfma_f32_16x16x32_bf16 v[48:51], v[160:163], v[176:179], v[48:51]
	v_mfma_f32_16x16x32_bf16 v[44:47], v[152:155], v[176:179], v[44:47]
	v_mfma_f32_16x16x32_bf16 v[44:47], v[148:151], v[172:175], v[44:47]
	v_mfma_f32_16x16x32_bf16 v[52:55], v[148:151], v[180:183], v[52:55]
	v_mfma_f32_16x16x32_bf16 v[52:55], v[152:155], v[184:187], v[52:55]
	v_mfma_f32_16x16x32_bf16 v[56:59], v[160:163], v[184:187], v[56:59]
	v_mfma_f32_16x16x32_bf16 v[56:59], v[156:159], v[180:183], v[56:59]
	v_mfma_f32_16x16x32_bf16 v[64:67], v[156:159], v[194:197], v[64:67]
	v_mfma_f32_16x16x32_bf16 v[64:67], v[160:163], v[198:201], v[64:67]
	s_setprio 3
	s_barrier
	v_mfma_f32_16x16x32_bf16 v[60:63], v[152:155], v[198:201], v[60:63]
	v_mfma_f32_16x16x32_bf16 v[60:63], v[148:151], v[194:197], v[60:63]
	s_setprio 0
	s_add_i32 s38, s71, s54
	s_mov_b32 m0, s38
	ds_read_b128 v[164:167], v231 offset:16384
	ds_read_b128 v[168:171], v231 offset:17408
	ds_read_b128 v[172:175], v231 offset:18432
	ds_read_b128 v[176:179], v231 offset:19456
	ds_read_b128 v[180:183], v231 offset:20480
	ds_read_b128 v[184:187], v231 offset:21504
	ds_read_b128 v[194:197], v231 offset:22528
	ds_read_b128 v[198:201], v231 offset:23552
	global_load_lds_dwordx4 v192, s[16:17]
	s_add_i32 m0, s38, 0x2000
	s_add_u32 s42, s16, 0x160000
	s_addc_u32 s43, s17, 0
	s_add_i32 s38, s72, s54
	global_load_lds_dwordx4 v190, s[16:17]
	s_mov_b32 m0, s38
	v_mov_b32_e32 v193, v3
	global_load_lds_dwordx4 v192, s[42:43]
	s_add_i32 m0, s38, 0x2000
	v_mov_b32_e32 v191, v3
	global_load_lds_dwordx4 v190, s[42:43]
	s_mov_b32 m0, s55
	v_lshl_add_u64 v[202:203], s[16:17], 0, v[192:193]
	global_load_lds_dwordx4 v2, s[26:27]
	s_mov_b32 m0, s56
	v_lshl_add_u64 v[204:205], s[16:17], 0, v[190:191]
	global_load_lds_dwordx4 v188, s[26:27]
	s_waitcnt vmcnt(8)
	s_waitcnt lgkmcnt(0)
	v_lshl_add_u64 v[206:207], s[26:27], 0, v[2:3]
	v_lshl_add_u64 v[208:209], s[26:27], 0, v[188:189]
	s_barrier
	s_setprio 1
	s_waitcnt lgkmcnt(0)
	v_mfma_f32_16x16x32_bf16 v[68:71], v[132:135], v[164:167], v[68:71]
	v_mfma_f32_16x16x32_bf16 v[68:71], v[136:139], v[168:171], v[68:71]
	v_mfma_f32_16x16x32_bf16 v[72:75], v[144:147], v[168:171], v[72:75]
	v_mfma_f32_16x16x32_bf16 v[72:75], v[140:143], v[164:167], v[72:75]
	v_mfma_f32_16x16x32_bf16 v[80:83], v[140:143], v[172:175], v[80:83]
	v_mfma_f32_16x16x32_bf16 v[80:83], v[144:147], v[176:179], v[80:83]
	v_mfma_f32_16x16x32_bf16 v[76:79], v[136:139], v[176:179], v[76:79]
	v_mfma_f32_16x16x32_bf16 v[76:79], v[132:135], v[172:175], v[76:79]
	v_mfma_f32_16x16x32_bf16 v[84:87], v[132:135], v[180:183], v[84:87]
	v_mfma_f32_16x16x32_bf16 v[84:87], v[136:139], v[184:187], v[84:87]
	v_mfma_f32_16x16x32_bf16 v[88:91], v[144:147], v[184:187], v[88:91]
	v_mfma_f32_16x16x32_bf16 v[88:91], v[140:143], v[180:183], v[88:91]
	v_mfma_f32_16x16x32_bf16 v[96:99], v[140:143], v[194:197], v[96:99]
	v_mfma_f32_16x16x32_bf16 v[96:99], v[144:147], v[198:201], v[96:99]
	v_mfma_f32_16x16x32_bf16 v[92:95], v[136:139], v[198:201], v[92:95]
	v_mfma_f32_16x16x32_bf16 v[92:95], v[132:135], v[194:197], v[92:95]
	s_setprio 0
	s_setprio 1
	v_mfma_f32_16x16x32_bf16 v[100:103], v[148:151], v[164:167], v[100:103]
	v_mfma_f32_16x16x32_bf16 v[100:103], v[152:155], v[168:171], v[100:103]
	v_mfma_f32_16x16x32_bf16 v[104:107], v[160:163], v[168:171], v[104:107]
	v_mfma_f32_16x16x32_bf16 v[104:107], v[156:159], v[164:167], v[104:107]
	v_mfma_f32_16x16x32_bf16 v[112:115], v[156:159], v[172:175], v[112:115]
	v_mfma_f32_16x16x32_bf16 v[112:115], v[160:163], v[176:179], v[112:115]
	v_mfma_f32_16x16x32_bf16 v[108:111], v[152:155], v[176:179], v[108:111]
	v_mfma_f32_16x16x32_bf16 v[108:111], v[148:151], v[172:175], v[108:111]
	v_mfma_f32_16x16x32_bf16 v[116:119], v[148:151], v[180:183], v[116:119]
	v_mfma_f32_16x16x32_bf16 v[116:119], v[152:155], v[184:187], v[116:119]
	v_mfma_f32_16x16x32_bf16 v[120:123], v[160:163], v[184:187], v[120:123]
	v_mfma_f32_16x16x32_bf16 v[120:123], v[156:159], v[180:183], v[120:123]
	v_mfma_f32_16x16x32_bf16 v[128:131], v[156:159], v[194:197], v[128:131]
	v_mfma_f32_16x16x32_bf16 v[128:131], v[160:163], v[198:201], v[128:131]
	s_setprio 3
	s_barrier
	v_mfma_f32_16x16x32_bf16 v[124:127], v[152:155], v[198:201], v[124:127]
	v_mfma_f32_16x16x32_bf16 v[124:127], v[148:151], v[194:197], v[124:127]
	s_setprio 0
	s_add_i32 s38, 0, 0x18000
	s_add_i32 s42, 0, 0x1c000
	ds_read_b128 v[132:135], v240 offset:32768
	ds_read_b128 v[136:139], v240 offset:33792
	ds_read_b128 v[140:143], v240 offset:34816
	ds_read_b128 v[144:147], v240 offset:35840
	ds_read_b128 v[148:151], v240 offset:49152
	ds_read_b128 v[152:155], v240 offset:50176
	ds_read_b128 v[156:159], v240 offset:51200
	ds_read_b128 v[160:163], v240 offset:52224
	s_add_u32 s26, s26, 0x160000
	s_addc_u32 s27, s27, 0
	s_mov_b32 m0, s57
	ds_read_b128 v[164:167], v231 offset:32768
	ds_read_b128 v[168:171], v231 offset:33792
	ds_read_b128 v[172:175], v231 offset:34816
	ds_read_b128 v[176:179], v231 offset:35840
	ds_read_b128 v[180:183], v231 offset:36864
	ds_read_b128 v[184:187], v231 offset:37888
	ds_read_b128 v[194:197], v231 offset:38912
	ds_read_b128 v[198:201], v231 offset:39936
	global_load_lds_dwordx4 v2, s[26:27]
	s_mov_b32 m0, s58
	s_nop 0
	global_load_lds_dwordx4 v188, s[26:27]
	s_waitcnt vmcnt(8)
	s_waitcnt lgkmcnt(0)
	s_barrier
	s_setprio 1
	s_waitcnt lgkmcnt(0)
	v_mfma_f32_16x16x32_bf16 v[4:7], v[132:135], v[164:167], v[4:7]
	v_mfma_f32_16x16x32_bf16 v[4:7], v[136:139], v[168:171], v[4:7]
	v_mfma_f32_16x16x32_bf16 v[8:11], v[144:147], v[168:171], v[8:11]
	v_mfma_f32_16x16x32_bf16 v[8:11], v[140:143], v[164:167], v[8:11]
	v_mfma_f32_16x16x32_bf16 v[16:19], v[140:143], v[172:175], v[16:19]
	v_mfma_f32_16x16x32_bf16 v[16:19], v[144:147], v[176:179], v[16:19]
	v_mfma_f32_16x16x32_bf16 v[12:15], v[136:139], v[176:179], v[12:15]
	v_mfma_f32_16x16x32_bf16 v[12:15], v[132:135], v[172:175], v[12:15]
	v_mfma_f32_16x16x32_bf16 v[20:23], v[132:135], v[180:183], v[20:23]
	v_mfma_f32_16x16x32_bf16 v[20:23], v[136:139], v[184:187], v[20:23]
	v_mfma_f32_16x16x32_bf16 v[24:27], v[144:147], v[184:187], v[24:27]
	v_mfma_f32_16x16x32_bf16 v[24:27], v[140:143], v[180:183], v[24:27]
	v_mfma_f32_16x16x32_bf16 v[32:35], v[140:143], v[194:197], v[32:35]
	v_mfma_f32_16x16x32_bf16 v[32:35], v[144:147], v[198:201], v[32:35]
	v_mfma_f32_16x16x32_bf16 v[28:31], v[136:139], v[198:201], v[28:31]
	v_mfma_f32_16x16x32_bf16 v[28:31], v[132:135], v[194:197], v[28:31]
	s_setprio 0
	s_setprio 1
	v_mfma_f32_16x16x32_bf16 v[36:39], v[148:151], v[164:167], v[36:39]
	v_mfma_f32_16x16x32_bf16 v[36:39], v[152:155], v[168:171], v[36:39]
	v_mfma_f32_16x16x32_bf16 v[40:43], v[160:163], v[168:171], v[40:43]
	v_mfma_f32_16x16x32_bf16 v[40:43], v[156:159], v[164:167], v[40:43]
	v_mfma_f32_16x16x32_bf16 v[48:51], v[156:159], v[172:175], v[48:51]
	v_mfma_f32_16x16x32_bf16 v[48:51], v[160:163], v[176:179], v[48:51]
	v_mfma_f32_16x16x32_bf16 v[44:47], v[152:155], v[176:179], v[44:47]
	v_mfma_f32_16x16x32_bf16 v[44:47], v[148:151], v[172:175], v[44:47]
	v_mfma_f32_16x16x32_bf16 v[52:55], v[148:151], v[180:183], v[52:55]
	v_mfma_f32_16x16x32_bf16 v[52:55], v[152:155], v[184:187], v[52:55]
	v_mfma_f32_16x16x32_bf16 v[56:59], v[160:163], v[184:187], v[56:59]
	v_mfma_f32_16x16x32_bf16 v[56:59], v[156:159], v[180:183], v[56:59]
	v_mfma_f32_16x16x32_bf16 v[64:67], v[156:159], v[194:197], v[64:67]
	v_mfma_f32_16x16x32_bf16 v[64:67], v[160:163], v[198:201], v[64:67]
	s_setprio 3
	s_barrier
	v_mfma_f32_16x16x32_bf16 v[60:63], v[152:155], v[198:201], v[60:63]
	v_mfma_f32_16x16x32_bf16 v[60:63], v[148:151], v[194:197], v[60:63]
	s_setprio 0
	s_add_i32 s26, s38, s54
	v_lshl_add_u64 v[202:203], v[202:203], 0, s[4:5]
	s_mov_b32 m0, s26
	ds_read_b128 v[164:167], v231 offset:49152
	ds_read_b128 v[168:171], v231 offset:50176
	ds_read_b128 v[172:175], v231 offset:51200
	ds_read_b128 v[176:179], v231 offset:52224
	ds_read_b128 v[180:183], v231 offset:53248
	ds_read_b128 v[184:187], v231 offset:54272
	ds_read_b128 v[194:197], v231 offset:55296
	ds_read_b128 v[198:201], v231 offset:56320
	global_load_lds_dwordx4 v[202:203], off
	s_add_i32 m0, s26, 0x2000
	s_add_u32 s16, s16, 0x15ff80
	v_lshl_add_u64 v[202:203], v[204:205], 0, s[4:5]
	s_addc_u32 s17, s17, 0
	s_add_i32 s26, s42, s54
	global_load_lds_dwordx4 v[202:203], off
	s_mov_b32 m0, s26
	v_lshl_add_u64 v[202:203], v[206:207], 0, s[4:5]
	global_load_lds_dwordx4 v192, s[16:17]
	s_add_i32 m0, s26, 0x2000
	s_nop 0
	global_load_lds_dwordx4 v190, s[16:17]
	s_mov_b32 m0, s62
	s_nop 0
	global_load_lds_dwordx4 v[202:203], off
	v_lshl_add_u64 v[202:203], v[208:209], 0, s[4:5]
	s_mov_b32 m0, s63
	s_nop 0
	global_load_lds_dwordx4 v[202:203], off
	s_waitcnt vmcnt(8)
	s_waitcnt lgkmcnt(0)
	s_barrier
	s_setprio 1
	s_waitcnt lgkmcnt(0)
	v_mfma_f32_16x16x32_bf16 v[68:71], v[132:135], v[164:167], v[68:71]
	v_mfma_f32_16x16x32_bf16 v[68:71], v[136:139], v[168:171], v[68:71]
	v_mfma_f32_16x16x32_bf16 v[72:75], v[144:147], v[168:171], v[72:75]
	v_mfma_f32_16x16x32_bf16 v[72:75], v[140:143], v[164:167], v[72:75]
	v_mfma_f32_16x16x32_bf16 v[80:83], v[140:143], v[172:175], v[80:83]
	v_mfma_f32_16x16x32_bf16 v[80:83], v[144:147], v[176:179], v[80:83]
	v_mfma_f32_16x16x32_bf16 v[76:79], v[136:139], v[176:179], v[76:79]
	v_mfma_f32_16x16x32_bf16 v[76:79], v[132:135], v[172:175], v[76:79]
	v_mfma_f32_16x16x32_bf16 v[84:87], v[132:135], v[180:183], v[84:87]
	v_mfma_f32_16x16x32_bf16 v[84:87], v[136:139], v[184:187], v[84:87]
	v_mfma_f32_16x16x32_bf16 v[88:91], v[144:147], v[184:187], v[88:91]
	v_mfma_f32_16x16x32_bf16 v[88:91], v[140:143], v[180:183], v[88:91]
	v_mfma_f32_16x16x32_bf16 v[96:99], v[140:143], v[194:197], v[96:99]
	v_mfma_f32_16x16x32_bf16 v[96:99], v[144:147], v[198:201], v[96:99]
	v_mfma_f32_16x16x32_bf16 v[92:95], v[136:139], v[198:201], v[92:95]
	v_mfma_f32_16x16x32_bf16 v[92:95], v[132:135], v[194:197], v[92:95]
	s_setprio 0
	s_setprio 1
	v_mfma_f32_16x16x32_bf16 v[100:103], v[148:151], v[164:167], v[100:103]
	v_mfma_f32_16x16x32_bf16 v[100:103], v[152:155], v[168:171], v[100:103]
	v_mfma_f32_16x16x32_bf16 v[104:107], v[160:163], v[168:171], v[104:107]
	v_mfma_f32_16x16x32_bf16 v[104:107], v[156:159], v[164:167], v[104:107]
	v_mfma_f32_16x16x32_bf16 v[112:115], v[156:159], v[172:175], v[112:115]
	v_mfma_f32_16x16x32_bf16 v[112:115], v[160:163], v[176:179], v[112:115]
	v_mfma_f32_16x16x32_bf16 v[108:111], v[152:155], v[176:179], v[108:111]
	v_mfma_f32_16x16x32_bf16 v[108:111], v[148:151], v[172:175], v[108:111]
	v_mfma_f32_16x16x32_bf16 v[116:119], v[148:151], v[180:183], v[116:119]
	v_mfma_f32_16x16x32_bf16 v[116:119], v[152:155], v[184:187], v[116:119]
	v_mfma_f32_16x16x32_bf16 v[120:123], v[160:163], v[184:187], v[120:123]
	v_mfma_f32_16x16x32_bf16 v[120:123], v[156:159], v[180:183], v[120:123]
	v_mfma_f32_16x16x32_bf16 v[128:131], v[156:159], v[194:197], v[128:131]
	v_mfma_f32_16x16x32_bf16 v[128:131], v[160:163], v[198:201], v[128:131]
	s_setprio 3
	s_barrier
	v_mfma_f32_16x16x32_bf16 v[124:127], v[152:155], v[198:201], v[124:127]
	v_mfma_f32_16x16x32_bf16 v[124:127], v[148:151], v[194:197], v[124:127]
	s_setprio 0
	s_cmpk_gt_u32 s28, 0x55
	s_cbranch_scc1 .LBB0_651
	s_mov_b32 s28, s29
	s_branch .LBB0_645

.LBB0_749:
	s_add_i32 s47, 0, 0x10000
	s_add_i32 s49, 0, 0x14000
	v_add_u32_e32 v16, s47, v147
	v_add_u32_e32 v32, s49, v147
	ds_read_b128 v[4:7], v16
	ds_read_b128 v[8:11], v16 offset:1024
	ds_read_b128 v[12:15], v16 offset:2048
	ds_read_b128 v[16:19], v16 offset:3072
	ds_read_b128 v[20:23], v32
	ds_read_b128 v[24:27], v32 offset:1024
	ds_read_b128 v[28:31], v32 offset:2048
	ds_read_b128 v[32:35], v32 offset:3072
	v_add_u32_e32 v231, 0, v146
	ds_read_b128 v[36:39], v231
	ds_read_b128 v[40:43], v231 offset:1024
	ds_read_b128 v[44:47], v231 offset:2048
	ds_read_b128 v[48:51], v231 offset:3072
	ds_read_b128 v[52:55], v231 offset:4096
	ds_read_b128 v[56:59], v231 offset:5120
	ds_read_b128 v[60:63], v231 offset:6144
	ds_read_b128 v[64:67], v231 offset:7168
	s_waitcnt vmcnt(8)
	s_waitcnt lgkmcnt(0)
	s_barrier
	s_setprio 1
	s_waitcnt lgkmcnt(0)
	v_mfma_f32_16x16x32_f16 v[68:71], v[4:7], v[36:39], 0
	v_mfma_f32_16x16x32_f16 v[68:71], v[8:11], v[40:43], v[68:71]
	v_mfma_f32_16x16x32_f16 v[72:75], v[12:15], v[36:39], 0
	v_mfma_f32_16x16x32_f16 v[72:75], v[16:19], v[40:43], v[72:75]
	v_mfma_f32_16x16x32_f16 v[80:83], v[12:15], v[44:47], 0
	v_mfma_f32_16x16x32_f16 v[80:83], v[16:19], v[48:51], v[80:83]
	v_mfma_f32_16x16x32_f16 v[76:79], v[4:7], v[44:47], 0
	v_mfma_f32_16x16x32_f16 v[76:79], v[8:11], v[48:51], v[76:79]
	v_mfma_f32_16x16x32_f16 v[84:87], v[4:7], v[52:55], 0
	v_mfma_f32_16x16x32_f16 v[84:87], v[8:11], v[56:59], v[84:87]
	v_mfma_f32_16x16x32_f16 v[88:91], v[12:15], v[52:55], 0
	v_mfma_f32_16x16x32_f16 v[88:91], v[16:19], v[56:59], v[88:91]
	v_mfma_f32_16x16x32_f16 v[96:99], v[12:15], v[60:63], 0
	v_mfma_f32_16x16x32_f16 v[96:99], v[16:19], v[64:67], v[96:99]
	v_mfma_f32_16x16x32_f16 v[92:95], v[4:7], v[60:63], 0
	v_mfma_f32_16x16x32_f16 v[92:95], v[8:11], v[64:67], v[92:95]
	s_setprio 0
	s_setprio 1
	v_mfma_f32_16x16x32_f16 v[100:103], v[20:23], v[36:39], 0
	v_mfma_f32_16x16x32_f16 v[36:39], v[28:31], v[36:39], 0
	v_mfma_f32_16x16x32_f16 v[104:107], v[20:23], v[44:47], 0
	v_mfma_f32_16x16x32_f16 v[44:47], v[28:31], v[44:47], 0
	v_mfma_f32_16x16x32_f16 v[108:111], v[20:23], v[52:55], 0
	v_mfma_f32_16x16x32_f16 v[52:55], v[28:31], v[52:55], 0
	v_mfma_f32_16x16x32_f16 v[112:115], v[20:23], v[60:63], 0
	v_mfma_f32_16x16x32_f16 v[60:63], v[28:31], v[60:63], 0
	v_mfma_f32_16x16x32_f16 v[100:103], v[24:27], v[40:43], v[100:103]
	v_mfma_f32_16x16x32_f16 v[40:43], v[32:35], v[40:43], v[36:39]
	v_mfma_f32_16x16x32_f16 v[104:107], v[24:27], v[48:51], v[104:107]
	v_mfma_f32_16x16x32_f16 v[48:51], v[32:35], v[48:51], v[44:47]
	v_mfma_f32_16x16x32_f16 v[108:111], v[24:27], v[56:59], v[108:111]
	v_mfma_f32_16x16x32_f16 v[56:59], v[32:35], v[56:59], v[52:55]
	s_setprio 3
	s_barrier
	v_mfma_f32_16x16x32_f16 v[112:115], v[24:27], v[64:67], v[112:115]
	v_mfma_f32_16x16x32_f16 v[64:67], v[32:35], v[64:67], v[60:63]
	s_setprio 0
	v_lshl_add_u64 v[136:137], s[6:7], 0, v[2:3]
	s_add_i32 s47, s47, s62
	v_mov_b32_e32 v135, v3
	v_lshl_add_u64 v[140:141], v[136:137], 0, s[74:75]
	s_mov_b32 m0, s47
	v_lshl_add_u64 v[144:145], s[6:7], 0, v[134:135]
	ds_read_b128 v[36:39], v231 offset:16384
	ds_read_b128 v[44:47], v231 offset:17408
	ds_read_b128 v[52:55], v231 offset:18432
	ds_read_b128 v[60:63], v231 offset:19456
	ds_read_b128 v[116:119], v231 offset:20480
	ds_read_b128 v[120:123], v231 offset:21504
	ds_read_b128 v[124:127], v231 offset:22528
	ds_read_b128 v[128:131], v231 offset:23552
	global_load_lds_dwordx4 v[140:141], off
	v_lshl_add_u64 v[140:141], v[144:145], 0, s[74:75]
	s_add_i32 m0, s47, 0x2000
	s_add_i32 s47, s49, s62
	global_load_lds_dwordx4 v[140:141], off
	s_mov_b32 m0, s47
	v_mov_b32_e32 v139, v3
	global_load_lds_dwordx4 v2, s[16:17]
	s_add_i32 m0, s47, 0x2000
	v_lshl_add_u64 v[248:249], s[8:9], 0, v[138:139]
	v_mov_b32_e32 v133, v3
	global_load_lds_dwordx4 v134, s[16:17]
	v_lshl_add_u64 v[140:141], v[248:249], 0, s[74:75]
	s_mov_b32 m0, s63
	v_lshl_add_u64 v[250:251], s[8:9], 0, v[132:133]
	global_load_lds_dwordx4 v[140:141], off
	v_lshl_add_u64 v[140:141], v[250:251], 0, s[74:75]
	s_mov_b32 m0, s64
	s_nop 0
	global_load_lds_dwordx4 v[140:141], off
	s_waitcnt vmcnt(8)
	s_waitcnt lgkmcnt(0)
	s_barrier
	s_setprio 1
	s_waitcnt lgkmcnt(0)
	v_mfma_f32_16x16x32_f16 v[140:143], v[4:7], v[36:39], 0
	v_mfma_f32_16x16x32_f16 v[148:151], v[12:15], v[36:39], 0
	v_mfma_f32_16x16x32_f16 v[152:155], v[4:7], v[52:55], 0
	v_mfma_f32_16x16x32_f16 v[156:159], v[12:15], v[52:55], 0
	v_mfma_f32_16x16x32_f16 v[160:163], v[4:7], v[116:119], 0
	v_mfma_f32_16x16x32_f16 v[164:167], v[12:15], v[116:119], 0
	v_mfma_f32_16x16x32_f16 v[4:7], v[4:7], v[124:127], 0
	v_mfma_f32_16x16x32_f16 v[12:15], v[12:15], v[124:127], 0
	v_mfma_f32_16x16x32_f16 v[140:143], v[8:11], v[44:47], v[140:143]
	v_mfma_f32_16x16x32_f16 v[148:151], v[16:19], v[44:47], v[148:151]
	v_mfma_f32_16x16x32_f16 v[152:155], v[8:11], v[60:63], v[152:155]
	v_mfma_f32_16x16x32_f16 v[156:159], v[16:19], v[60:63], v[156:159]
	v_mfma_f32_16x16x32_f16 v[160:163], v[8:11], v[120:123], v[160:163]
	v_mfma_f32_16x16x32_f16 v[164:167], v[16:19], v[120:123], v[164:167]
	v_mfma_f32_16x16x32_f16 v[168:171], v[8:11], v[128:131], v[4:7]
	v_mfma_f32_16x16x32_f16 v[172:175], v[16:19], v[128:131], v[12:15]
	s_setprio 0
	s_setprio 1
	v_mfma_f32_16x16x32_f16 v[4:7], v[20:23], v[36:39], 0
	v_mfma_f32_16x16x32_f16 v[8:11], v[28:31], v[36:39], 0
	v_mfma_f32_16x16x32_f16 v[12:15], v[20:23], v[52:55], 0
	v_mfma_f32_16x16x32_f16 v[16:19], v[28:31], v[52:55], 0
	v_mfma_f32_16x16x32_f16 v[36:39], v[20:23], v[116:119], 0
	v_mfma_f32_16x16x32_f16 v[52:55], v[28:31], v[116:119], 0
	v_mfma_f32_16x16x32_f16 v[20:23], v[20:23], v[124:127], 0
	v_mfma_f32_16x16x32_f16 v[28:31], v[28:31], v[124:127], 0
	v_mfma_f32_16x16x32_f16 v[116:119], v[24:27], v[44:47], v[4:7]
	v_mfma_f32_16x16x32_f16 v[124:127], v[32:35], v[44:47], v[8:11]
	v_mfma_f32_16x16x32_f16 v[184:187], v[24:27], v[120:123], v[36:39]
	v_mfma_f32_16x16x32_f16 v[120:123], v[32:35], v[120:123], v[52:55]
	v_mfma_f32_16x16x32_f16 v[188:191], v[24:27], v[128:131], v[20:23]
	v_mfma_f32_16x16x32_f16 v[128:131], v[32:35], v[128:131], v[28:31]
	s_setprio 3
	s_barrier
	v_mfma_f32_16x16x32_f16 v[176:179], v[24:27], v[60:63], v[12:15]
	v_mfma_f32_16x16x32_f16 v[180:183], v[32:35], v[60:63], v[16:19]
	s_setprio 0
	s_add_i32 s47, 0, 0x18000
	v_add_u32_e32 v4, s47, v147
	s_add_i32 s49, 0, 0x1c000
	ds_read_b128 v[192:195], v4
	ds_read_b128 v[196:199], v4 offset:1024
	ds_read_b128 v[200:203], v4 offset:2048
	ds_read_b128 v[204:207], v4 offset:3072
	v_add_u32_e32 v4, s49, v147
	ds_read_b128 v[208:211], v4
	ds_read_b128 v[212:215], v4 offset:1024
	ds_read_b128 v[216:219], v4 offset:2048
	ds_read_b128 v[220:223], v4 offset:3072
	s_mov_b32 m0, s65
	ds_read_b128 v[44:47], v231 offset:32768
	ds_read_b128 v[52:55], v231 offset:33792
	ds_read_b128 v[60:63], v231 offset:34816
	ds_read_b128 v[224:227], v231 offset:35840
	ds_read_b128 v[232:235], v231 offset:36864
	ds_read_b128 v[236:239], v231 offset:37888
	ds_read_b128 v[240:243], v231 offset:38912
	ds_read_b128 v[244:247], v231 offset:39936
	global_load_lds_dwordx4 v138, s[26:27]
	s_mov_b32 m0, s66
	s_nop 0
	global_load_lds_dwordx4 v132, s[26:27]
	s_waitcnt vmcnt(8)
	s_waitcnt lgkmcnt(0)
	s_barrier
	s_setprio 1
	s_waitcnt lgkmcnt(0)
	v_mfma_f32_16x16x32_f16 v[4:7], v[192:195], v[44:47], v[68:71]
	v_mfma_f32_16x16x32_f16 v[8:11], v[200:203], v[44:47], v[72:75]
	v_mfma_f32_16x16x32_f16 v[12:15], v[192:195], v[60:63], v[76:79]
	v_mfma_f32_16x16x32_f16 v[16:19], v[200:203], v[60:63], v[80:83]
	v_mfma_f32_16x16x32_f16 v[20:23], v[192:195], v[232:235], v[84:87]
	v_mfma_f32_16x16x32_f16 v[24:27], v[200:203], v[232:235], v[88:91]
	v_mfma_f32_16x16x32_f16 v[28:31], v[192:195], v[240:243], v[92:95]
	v_mfma_f32_16x16x32_f16 v[32:35], v[200:203], v[240:243], v[96:99]
	v_mfma_f32_16x16x32_f16 v[4:7], v[196:199], v[52:55], v[4:7]
	v_mfma_f32_16x16x32_f16 v[8:11], v[204:207], v[52:55], v[8:11]
	v_mfma_f32_16x16x32_f16 v[12:15], v[196:199], v[224:227], v[12:15]
	v_mfma_f32_16x16x32_f16 v[16:19], v[204:207], v[224:227], v[16:19]
	v_mfma_f32_16x16x32_f16 v[20:23], v[196:199], v[236:239], v[20:23]
	v_mfma_f32_16x16x32_f16 v[24:27], v[204:207], v[236:239], v[24:27]
	v_mfma_f32_16x16x32_f16 v[28:31], v[196:199], v[244:247], v[28:31]
	v_mfma_f32_16x16x32_f16 v[32:35], v[204:207], v[244:247], v[32:35]
	s_setprio 0
	s_setprio 1
	v_mfma_f32_16x16x32_f16 v[36:39], v[208:211], v[44:47], v[100:103]
	v_mfma_f32_16x16x32_f16 v[40:43], v[216:219], v[44:47], v[40:43]
	v_mfma_f32_16x16x32_f16 v[36:39], v[212:215], v[52:55], v[36:39]
	v_mfma_f32_16x16x32_f16 v[40:43], v[220:223], v[52:55], v[40:43]
	v_mfma_f32_16x16x32_f16 v[44:47], v[208:211], v[60:63], v[104:107]
	v_mfma_f32_16x16x32_f16 v[48:51], v[216:219], v[60:63], v[48:51]
	v_mfma_f32_16x16x32_f16 v[52:55], v[208:211], v[232:235], v[108:111]
	v_mfma_f32_16x16x32_f16 v[56:59], v[216:219], v[232:235], v[56:59]
	v_mfma_f32_16x16x32_f16 v[60:63], v[208:211], v[240:243], v[112:115]
	v_mfma_f32_16x16x32_f16 v[64:67], v[216:219], v[240:243], v[64:67]
	v_mfma_f32_16x16x32_f16 v[44:47], v[212:215], v[224:227], v[44:47]
	v_mfma_f32_16x16x32_f16 v[48:51], v[220:223], v[224:227], v[48:51]
	v_mfma_f32_16x16x32_f16 v[52:55], v[212:215], v[236:239], v[52:55]
	v_mfma_f32_16x16x32_f16 v[56:59], v[220:223], v[236:239], v[56:59]
	s_setprio 3
	s_barrier
	v_mfma_f32_16x16x32_f16 v[60:63], v[212:215], v[244:247], v[60:63]
	v_mfma_f32_16x16x32_f16 v[64:67], v[220:223], v[244:247], v[64:67]
	s_setprio 0
	s_add_i32 s47, s47, s62
	v_lshl_add_u64 v[68:69], v[136:137], 0, s[24:25]
	s_mov_b32 m0, s47
	ds_read_b128 v[104:107], v231 offset:49152
	ds_read_b128 v[108:111], v231 offset:50176
	ds_read_b128 v[112:115], v231 offset:51200
	ds_read_b128 v[224:227], v231 offset:52224
	ds_read_b128 v[232:235], v231 offset:53248
	ds_read_b128 v[236:239], v231 offset:54272
	ds_read_b128 v[240:243], v231 offset:55296
	ds_read_b128 v[244:247], v231 offset:56320
	global_load_lds_dwordx4 v[68:69], off
	v_lshl_add_u64 v[68:69], v[144:145], 0, s[24:25]
	s_add_i32 m0, s47, 0x2000
	s_add_i32 s47, s49, s62
	global_load_lds_dwordx4 v[68:69], off
	s_mov_b32 m0, s47
	v_lshl_add_u64 v[68:69], v[248:249], 0, s[24:25]
	global_load_lds_dwordx4 v2, s[28:29]
	s_add_i32 m0, s47, 0x2000
	s_nop 0
	global_load_lds_dwordx4 v134, s[28:29]
	s_mov_b32 m0, s69
	s_nop 0
	global_load_lds_dwordx4 v[68:69], off
	v_lshl_add_u64 v[68:69], v[250:251], 0, s[24:25]
	s_mov_b32 m0, s70
	s_nop 0
	global_load_lds_dwordx4 v[68:69], off
	s_waitcnt vmcnt(8)
	s_waitcnt lgkmcnt(0)
	s_barrier
	s_setprio 1
	s_waitcnt lgkmcnt(0)
	v_mfma_f32_16x16x32_f16 v[68:71], v[192:195], v[104:107], v[140:143]
	v_mfma_f32_16x16x32_f16 v[72:75], v[200:203], v[104:107], v[148:151]
	v_mfma_f32_16x16x32_f16 v[76:79], v[192:195], v[112:115], v[152:155]
	v_mfma_f32_16x16x32_f16 v[80:83], v[200:203], v[112:115], v[156:159]
	v_mfma_f32_16x16x32_f16 v[84:87], v[192:195], v[232:235], v[160:163]
	v_mfma_f32_16x16x32_f16 v[88:91], v[200:203], v[232:235], v[164:167]
	v_mfma_f32_16x16x32_f16 v[92:95], v[192:195], v[240:243], v[168:171]
	v_mfma_f32_16x16x32_f16 v[96:99], v[200:203], v[240:243], v[172:175]
	v_mfma_f32_16x16x32_f16 v[68:71], v[196:199], v[108:111], v[68:71]
	v_mfma_f32_16x16x32_f16 v[72:75], v[204:207], v[108:111], v[72:75]
	v_mfma_f32_16x16x32_f16 v[76:79], v[196:199], v[224:227], v[76:79]
	v_mfma_f32_16x16x32_f16 v[80:83], v[204:207], v[224:227], v[80:83]
	v_mfma_f32_16x16x32_f16 v[84:87], v[196:199], v[236:239], v[84:87]
	v_mfma_f32_16x16x32_f16 v[88:91], v[204:207], v[236:239], v[88:91]
	v_mfma_f32_16x16x32_f16 v[92:95], v[196:199], v[244:247], v[92:95]
	v_mfma_f32_16x16x32_f16 v[96:99], v[204:207], v[244:247], v[96:99]
	s_setprio 0
	s_setprio 1
	v_mfma_f32_16x16x32_f16 v[100:103], v[208:211], v[104:107], v[116:119]
	v_mfma_f32_16x16x32_f16 v[104:107], v[216:219], v[104:107], v[124:127]
	v_mfma_f32_16x16x32_f16 v[100:103], v[212:215], v[108:111], v[100:103]
	v_mfma_f32_16x16x32_f16 v[104:107], v[220:223], v[108:111], v[104:107]
	v_mfma_f32_16x16x32_f16 v[108:111], v[208:211], v[112:115], v[176:179]
	v_mfma_f32_16x16x32_f16 v[112:115], v[216:219], v[112:115], v[180:183]
	v_mfma_f32_16x16x32_f16 v[116:119], v[208:211], v[232:235], v[184:187]
	v_mfma_f32_16x16x32_f16 v[120:123], v[216:219], v[232:235], v[120:123]
	v_mfma_f32_16x16x32_f16 v[124:127], v[208:211], v[240:243], v[188:191]
	v_mfma_f32_16x16x32_f16 v[128:131], v[216:219], v[240:243], v[128:131]
	v_mfma_f32_16x16x32_f16 v[108:111], v[212:215], v[224:227], v[108:111]
	v_mfma_f32_16x16x32_f16 v[112:115], v[220:223], v[224:227], v[112:115]
	v_mfma_f32_16x16x32_f16 v[116:119], v[212:215], v[236:239], v[116:119]
	v_mfma_f32_16x16x32_f16 v[120:123], v[220:223], v[236:239], v[120:123]
	s_setprio 3
	s_barrier
	v_mfma_f32_16x16x32_f16 v[124:127], v[212:215], v[244:247], v[124:127]
	v_mfma_f32_16x16x32_f16 v[128:131], v[220:223], v[244:247], v[128:131]
	s_setprio 0
	s_add_i32 s45, s45, 2
	s_cmp_ge_i32 s45, s44
	s_cbranch_scc0 .LBB0_749
	v_mov_b32_e32 v136, v2
	s_branch .LBB0_752

.LBB0_753:
	s_add_u32 s6, s8, 0xfff80080
	s_addc_u32 s7, s9, -1
	s_add_i32 s29, 0, 0x10000
	s_cmp_eq_u32 s28, 28
	s_cselect_b32 s17, s13, s7
	s_cselect_b32 s16, s12, s6
	v_add_u32_e32 v133, s29, v147
	s_cselect_b32 s7, s15, s27
	s_cselect_b32 s6, s14, s26
	s_add_i32 s47, 0, 0x14000
	ds_read_b128 v[138:141], v133
	ds_read_b128 v[142:145], v133 offset:1024
	ds_read_b128 v[148:151], v133 offset:2048
	ds_read_b128 v[152:155], v133 offset:3072
	v_add_u32_e32 v133, s47, v147
	ds_read_b128 v[156:159], v133
	ds_read_b128 v[160:163], v133 offset:1024
	ds_read_b128 v[164:167], v133 offset:2048
	ds_read_b128 v[168:171], v133 offset:3072
	s_mov_b32 m0, s71
	v_add_u32_e32 v212, 0, v146
	ds_read_b128 v[172:175], v212
	ds_read_b128 v[176:179], v212 offset:1024
	ds_read_b128 v[180:183], v212 offset:2048
	ds_read_b128 v[184:187], v212 offset:3072
	ds_read_b128 v[188:191], v212 offset:4096
	ds_read_b128 v[192:195], v212 offset:5120
	ds_read_b128 v[196:199], v212 offset:6144
	ds_read_b128 v[200:203], v212 offset:7168
	global_load_lds_dwordx4 v2, s[8:9]
	s_mov_b32 m0, s72
	v_mov_b32_e32 v133, v3
	global_load_lds_dwordx4 v132, s[8:9]
	s_waitcnt vmcnt(8)
	s_waitcnt lgkmcnt(0)
	s_barrier
	s_setprio 1
	s_waitcnt lgkmcnt(0)
	v_mfma_f32_16x16x32_f16 v[4:7], v[138:141], v[172:175], v[4:7]
	v_mfma_f32_16x16x32_f16 v[4:7], v[142:145], v[176:179], v[4:7]
	v_mfma_f32_16x16x32_f16 v[8:11], v[152:155], v[176:179], v[8:11]
	v_mfma_f32_16x16x32_f16 v[8:11], v[148:151], v[172:175], v[8:11]
	v_mfma_f32_16x16x32_f16 v[16:19], v[148:151], v[180:183], v[16:19]
	v_mfma_f32_16x16x32_f16 v[16:19], v[152:155], v[184:187], v[16:19]
	v_mfma_f32_16x16x32_f16 v[12:15], v[142:145], v[184:187], v[12:15]
	v_mfma_f32_16x16x32_f16 v[12:15], v[138:141], v[180:183], v[12:15]
	v_mfma_f32_16x16x32_f16 v[20:23], v[138:141], v[188:191], v[20:23]
	v_mfma_f32_16x16x32_f16 v[20:23], v[142:145], v[192:195], v[20:23]
	v_mfma_f32_16x16x32_f16 v[24:27], v[152:155], v[192:195], v[24:27]
	v_mfma_f32_16x16x32_f16 v[24:27], v[148:151], v[188:191], v[24:27]
	v_mfma_f32_16x16x32_f16 v[32:35], v[148:151], v[196:199], v[32:35]
	v_mfma_f32_16x16x32_f16 v[32:35], v[152:155], v[200:203], v[32:35]
	v_mfma_f32_16x16x32_f16 v[28:31], v[142:145], v[200:203], v[28:31]
	v_mfma_f32_16x16x32_f16 v[28:31], v[138:141], v[196:199], v[28:31]
	s_setprio 0
	s_setprio 1
	v_mfma_f32_16x16x32_f16 v[36:39], v[156:159], v[172:175], v[36:39]
	v_mfma_f32_16x16x32_f16 v[36:39], v[160:163], v[176:179], v[36:39]
	v_mfma_f32_16x16x32_f16 v[40:43], v[168:171], v[176:179], v[40:43]
	v_mfma_f32_16x16x32_f16 v[40:43], v[164:167], v[172:175], v[40:43]
	v_mfma_f32_16x16x32_f16 v[48:51], v[164:167], v[180:183], v[48:51]
	v_mfma_f32_16x16x32_f16 v[48:51], v[168:171], v[184:187], v[48:51]
	v_mfma_f32_16x16x32_f16 v[44:47], v[160:163], v[184:187], v[44:47]
	v_mfma_f32_16x16x32_f16 v[44:47], v[156:159], v[180:183], v[44:47]
	v_mfma_f32_16x16x32_f16 v[52:55], v[156:159], v[188:191], v[52:55]
	v_mfma_f32_16x16x32_f16 v[52:55], v[160:163], v[192:195], v[52:55]
	v_mfma_f32_16x16x32_f16 v[56:59], v[168:171], v[192:195], v[56:59]
	v_mfma_f32_16x16x32_f16 v[56:59], v[164:167], v[188:191], v[56:59]
	v_mfma_f32_16x16x32_f16 v[64:67], v[164:167], v[196:199], v[64:67]
	v_mfma_f32_16x16x32_f16 v[64:67], v[168:171], v[200:203], v[64:67]
	s_setprio 3
	s_barrier
	v_mfma_f32_16x16x32_f16 v[60:63], v[160:163], v[200:203], v[60:63]
	v_mfma_f32_16x16x32_f16 v[60:63], v[156:159], v[196:199], v[60:63]
	s_setprio 0
	s_add_i32 s29, s29, s62
	s_mov_b32 m0, s29
	ds_read_b128 v[172:175], v212 offset:16384
	ds_read_b128 v[176:179], v212 offset:17408
	ds_read_b128 v[180:183], v212 offset:18432
	ds_read_b128 v[184:187], v212 offset:19456
	ds_read_b128 v[188:191], v212 offset:20480
	ds_read_b128 v[192:195], v212 offset:21504
	ds_read_b128 v[196:199], v212 offset:22528
	ds_read_b128 v[200:203], v212 offset:23552
	global_load_lds_dwordx4 v136, s[6:7]
	s_add_i32 m0, s29, 0x2000
	s_add_u32 s44, s6, 0x80000
	s_addc_u32 s45, s7, 0
	s_add_i32 s29, s47, s62
	global_load_lds_dwordx4 v134, s[6:7]
	s_mov_b32 m0, s29
	v_mov_b32_e32 v137, v3
	global_load_lds_dwordx4 v136, s[44:45]
	s_add_i32 m0, s29, 0x2000
	v_mov_b32_e32 v135, v3
	global_load_lds_dwordx4 v134, s[44:45]
	s_mov_b32 m0, s63
	v_lshl_add_u64 v[204:205], s[6:7], 0, v[136:137]
	global_load_lds_dwordx4 v2, s[16:17]
	s_mov_b32 m0, s64
	v_lshl_add_u64 v[206:207], s[6:7], 0, v[134:135]
	global_load_lds_dwordx4 v132, s[16:17]
	s_waitcnt vmcnt(8)
	s_waitcnt lgkmcnt(0)
	v_lshl_add_u64 v[208:209], s[16:17], 0, v[2:3]
	v_lshl_add_u64 v[210:211], s[16:17], 0, v[132:133]
	s_barrier
	s_setprio 1
	s_waitcnt lgkmcnt(0)
	v_mfma_f32_16x16x32_f16 v[68:71], v[138:141], v[172:175], v[68:71]
	v_mfma_f32_16x16x32_f16 v[68:71], v[142:145], v[176:179], v[68:71]
	v_mfma_f32_16x16x32_f16 v[72:75], v[152:155], v[176:179], v[72:75]
	v_mfma_f32_16x16x32_f16 v[72:75], v[148:151], v[172:175], v[72:75]
	v_mfma_f32_16x16x32_f16 v[80:83], v[148:151], v[180:183], v[80:83]
	v_mfma_f32_16x16x32_f16 v[80:83], v[152:155], v[184:187], v[80:83]
	v_mfma_f32_16x16x32_f16 v[76:79], v[142:145], v[184:187], v[76:79]
	v_mfma_f32_16x16x32_f16 v[76:79], v[138:141], v[180:183], v[76:79]
	v_mfma_f32_16x16x32_f16 v[84:87], v[138:141], v[188:191], v[84:87]
	v_mfma_f32_16x16x32_f16 v[84:87], v[142:145], v[192:195], v[84:87]
	v_mfma_f32_16x16x32_f16 v[88:91], v[152:155], v[192:195], v[88:91]
	v_mfma_f32_16x16x32_f16 v[88:91], v[148:151], v[188:191], v[88:91]
	v_mfma_f32_16x16x32_f16 v[96:99], v[148:151], v[196:199], v[96:99]
	v_mfma_f32_16x16x32_f16 v[96:99], v[152:155], v[200:203], v[96:99]
	v_mfma_f32_16x16x32_f16 v[92:95], v[142:145], v[200:203], v[92:95]
	v_mfma_f32_16x16x32_f16 v[92:95], v[138:141], v[196:199], v[92:95]
	s_setprio 0
	s_setprio 1
	v_mfma_f32_16x16x32_f16 v[100:103], v[156:159], v[172:175], v[100:103]
	v_mfma_f32_16x16x32_f16 v[100:103], v[160:163], v[176:179], v[100:103]
	v_mfma_f32_16x16x32_f16 v[104:107], v[168:171], v[176:179], v[104:107]
	v_mfma_f32_16x16x32_f16 v[104:107], v[164:167], v[172:175], v[104:107]
	v_mfma_f32_16x16x32_f16 v[112:115], v[164:167], v[180:183], v[112:115]
	v_mfma_f32_16x16x32_f16 v[112:115], v[168:171], v[184:187], v[112:115]
	v_mfma_f32_16x16x32_f16 v[108:111], v[160:163], v[184:187], v[108:111]
	v_mfma_f32_16x16x32_f16 v[108:111], v[156:159], v[180:183], v[108:111]
	v_mfma_f32_16x16x32_f16 v[116:119], v[156:159], v[188:191], v[116:119]
	v_mfma_f32_16x16x32_f16 v[116:119], v[160:163], v[192:195], v[116:119]
	v_mfma_f32_16x16x32_f16 v[120:123], v[168:171], v[192:195], v[120:123]
	v_mfma_f32_16x16x32_f16 v[120:123], v[164:167], v[188:191], v[120:123]
	v_mfma_f32_16x16x32_f16 v[128:131], v[164:167], v[196:199], v[128:131]
	v_mfma_f32_16x16x32_f16 v[128:131], v[168:171], v[200:203], v[128:131]
	s_setprio 3
	s_barrier
	v_mfma_f32_16x16x32_f16 v[124:127], v[160:163], v[200:203], v[124:127]
	v_mfma_f32_16x16x32_f16 v[124:127], v[156:159], v[196:199], v[124:127]
	s_setprio 0
	s_add_i32 s29, 0, 0x18000
	v_add_u32_e32 v135, s29, v147
	s_add_i32 s44, 0, 0x1c000
	ds_read_b128 v[138:141], v135
	ds_read_b128 v[142:145], v135 offset:1024
	ds_read_b128 v[148:151], v135 offset:2048
	ds_read_b128 v[152:155], v135 offset:3072
	v_add_u32_e32 v135, s44, v147
	ds_read_b128 v[156:159], v135
	ds_read_b128 v[160:163], v135 offset:1024
	ds_read_b128 v[164:167], v135 offset:2048
	ds_read_b128 v[168:171], v135 offset:3072
	s_add_u32 s16, s16, 0x80000
	s_addc_u32 s17, s17, 0
	s_mov_b32 m0, s65
	ds_read_b128 v[172:175], v212 offset:32768
	ds_read_b128 v[176:179], v212 offset:33792
	ds_read_b128 v[180:183], v212 offset:34816
	ds_read_b128 v[184:187], v212 offset:35840
	ds_read_b128 v[188:191], v212 offset:36864
	ds_read_b128 v[192:195], v212 offset:37888
	ds_read_b128 v[196:199], v212 offset:38912
	ds_read_b128 v[200:203], v212 offset:39936
	global_load_lds_dwordx4 v2, s[16:17]
	s_mov_b32 m0, s66
	s_nop 0
	global_load_lds_dwordx4 v132, s[16:17]
	s_waitcnt vmcnt(8)
	s_waitcnt lgkmcnt(0)
	s_barrier
	s_setprio 1
	s_waitcnt lgkmcnt(0)
	v_mfma_f32_16x16x32_f16 v[4:7], v[138:141], v[172:175], v[4:7]
	v_mfma_f32_16x16x32_f16 v[4:7], v[142:145], v[176:179], v[4:7]
	v_mfma_f32_16x16x32_f16 v[8:11], v[152:155], v[176:179], v[8:11]
	v_mfma_f32_16x16x32_f16 v[8:11], v[148:151], v[172:175], v[8:11]
	v_mfma_f32_16x16x32_f16 v[16:19], v[148:151], v[180:183], v[16:19]
	v_mfma_f32_16x16x32_f16 v[16:19], v[152:155], v[184:187], v[16:19]
	v_mfma_f32_16x16x32_f16 v[12:15], v[142:145], v[184:187], v[12:15]
	v_mfma_f32_16x16x32_f16 v[12:15], v[138:141], v[180:183], v[12:15]
	v_mfma_f32_16x16x32_f16 v[20:23], v[138:141], v[188:191], v[20:23]
	v_mfma_f32_16x16x32_f16 v[20:23], v[142:145], v[192:195], v[20:23]
	v_mfma_f32_16x16x32_f16 v[24:27], v[152:155], v[192:195], v[24:27]
	v_mfma_f32_16x16x32_f16 v[24:27], v[148:151], v[188:191], v[24:27]
	v_mfma_f32_16x16x32_f16 v[32:35], v[148:151], v[196:199], v[32:35]
	v_mfma_f32_16x16x32_f16 v[32:35], v[152:155], v[200:203], v[32:35]
	v_mfma_f32_16x16x32_f16 v[28:31], v[142:145], v[200:203], v[28:31]
	v_mfma_f32_16x16x32_f16 v[28:31], v[138:141], v[196:199], v[28:31]
	s_setprio 0
	s_setprio 1
	v_mfma_f32_16x16x32_f16 v[36:39], v[156:159], v[172:175], v[36:39]
	v_mfma_f32_16x16x32_f16 v[36:39], v[160:163], v[176:179], v[36:39]
	v_mfma_f32_16x16x32_f16 v[40:43], v[168:171], v[176:179], v[40:43]
	v_mfma_f32_16x16x32_f16 v[40:43], v[164:167], v[172:175], v[40:43]
	v_mfma_f32_16x16x32_f16 v[48:51], v[164:167], v[180:183], v[48:51]
	v_mfma_f32_16x16x32_f16 v[48:51], v[168:171], v[184:187], v[48:51]
	v_mfma_f32_16x16x32_f16 v[44:47], v[160:163], v[184:187], v[44:47]
	v_mfma_f32_16x16x32_f16 v[44:47], v[156:159], v[180:183], v[44:47]
	v_mfma_f32_16x16x32_f16 v[52:55], v[156:159], v[188:191], v[52:55]
	v_mfma_f32_16x16x32_f16 v[52:55], v[160:163], v[192:195], v[52:55]
	v_mfma_f32_16x16x32_f16 v[56:59], v[168:171], v[192:195], v[56:59]
	v_mfma_f32_16x16x32_f16 v[56:59], v[164:167], v[188:191], v[56:59]
	v_mfma_f32_16x16x32_f16 v[64:67], v[164:167], v[196:199], v[64:67]
	v_mfma_f32_16x16x32_f16 v[64:67], v[168:171], v[200:203], v[64:67]
	s_setprio 3
	s_barrier
	v_mfma_f32_16x16x32_f16 v[60:63], v[160:163], v[200:203], v[60:63]
	v_mfma_f32_16x16x32_f16 v[60:63], v[156:159], v[196:199], v[60:63]
	s_setprio 0
	s_add_i32 s16, s29, s62
	v_lshl_add_u64 v[204:205], v[204:205], 0, s[86:87]
	s_mov_b32 m0, s16
	ds_read_b128 v[172:175], v212 offset:49152
	ds_read_b128 v[176:179], v212 offset:50176
	ds_read_b128 v[180:183], v212 offset:51200
	ds_read_b128 v[184:187], v212 offset:52224
	ds_read_b128 v[188:191], v212 offset:53248
	ds_read_b128 v[192:195], v212 offset:54272
	ds_read_b128 v[196:199], v212 offset:55296
	ds_read_b128 v[200:203], v212 offset:56320
	global_load_lds_dwordx4 v[204:205], off
	s_add_i32 m0, s16, 0x2000
	s_add_u32 s6, s6, 0x80080
	v_lshl_add_u64 v[204:205], v[206:207], 0, s[86:87]
	s_addc_u32 s7, s7, 0
	s_add_i32 s16, s44, s62
	global_load_lds_dwordx4 v[204:205], off
	s_mov_b32 m0, s16
	v_lshl_add_u64 v[204:205], v[208:209], 0, s[86:87]
	global_load_lds_dwordx4 v136, s[6:7]
	s_add_i32 m0, s16, 0x2000
	s_nop 0
	global_load_lds_dwordx4 v134, s[6:7]
	s_mov_b32 m0, s69
	s_nop 0
	global_load_lds_dwordx4 v[204:205], off
	v_lshl_add_u64 v[204:205], v[210:211], 0, s[86:87]
	s_mov_b32 m0, s70
	s_nop 0
	global_load_lds_dwordx4 v[204:205], off
	s_waitcnt vmcnt(8)
	s_waitcnt lgkmcnt(0)
	s_barrier
	s_setprio 1
	s_waitcnt lgkmcnt(0)
	v_mfma_f32_16x16x32_f16 v[68:71], v[138:141], v[172:175], v[68:71]
	v_mfma_f32_16x16x32_f16 v[68:71], v[142:145], v[176:179], v[68:71]
	v_mfma_f32_16x16x32_f16 v[72:75], v[152:155], v[176:179], v[72:75]
	v_mfma_f32_16x16x32_f16 v[72:75], v[148:151], v[172:175], v[72:75]
	v_mfma_f32_16x16x32_f16 v[80:83], v[148:151], v[180:183], v[80:83]
	v_mfma_f32_16x16x32_f16 v[80:83], v[152:155], v[184:187], v[80:83]
	v_mfma_f32_16x16x32_f16 v[76:79], v[142:145], v[184:187], v[76:79]
	v_mfma_f32_16x16x32_f16 v[76:79], v[138:141], v[180:183], v[76:79]
	v_mfma_f32_16x16x32_f16 v[84:87], v[138:141], v[188:191], v[84:87]
	v_mfma_f32_16x16x32_f16 v[84:87], v[142:145], v[192:195], v[84:87]
	v_mfma_f32_16x16x32_f16 v[88:91], v[152:155], v[192:195], v[88:91]
	v_mfma_f32_16x16x32_f16 v[88:91], v[148:151], v[188:191], v[88:91]
	v_mfma_f32_16x16x32_f16 v[96:99], v[148:151], v[196:199], v[96:99]
	v_mfma_f32_16x16x32_f16 v[96:99], v[152:155], v[200:203], v[96:99]
	v_mfma_f32_16x16x32_f16 v[92:95], v[142:145], v[200:203], v[92:95]
	v_mfma_f32_16x16x32_f16 v[92:95], v[138:141], v[196:199], v[92:95]
	s_setprio 0
	s_setprio 1
	v_mfma_f32_16x16x32_f16 v[100:103], v[156:159], v[172:175], v[100:103]
	v_mfma_f32_16x16x32_f16 v[100:103], v[160:163], v[176:179], v[100:103]
	v_mfma_f32_16x16x32_f16 v[104:107], v[168:171], v[176:179], v[104:107]
	v_mfma_f32_16x16x32_f16 v[104:107], v[164:167], v[172:175], v[104:107]
	v_mfma_f32_16x16x32_f16 v[112:115], v[164:167], v[180:183], v[112:115]
	v_mfma_f32_16x16x32_f16 v[112:115], v[168:171], v[184:187], v[112:115]
	v_mfma_f32_16x16x32_f16 v[108:111], v[160:163], v[184:187], v[108:111]
	v_mfma_f32_16x16x32_f16 v[108:111], v[156:159], v[180:183], v[108:111]
	v_mfma_f32_16x16x32_f16 v[116:119], v[156:159], v[188:191], v[116:119]
	v_mfma_f32_16x16x32_f16 v[116:119], v[160:163], v[192:195], v[116:119]
	v_mfma_f32_16x16x32_f16 v[120:123], v[168:171], v[192:195], v[120:123]
	v_mfma_f32_16x16x32_f16 v[120:123], v[164:167], v[188:191], v[120:123]
	v_mfma_f32_16x16x32_f16 v[128:131], v[164:167], v[196:199], v[128:131]
	v_mfma_f32_16x16x32_f16 v[128:131], v[168:171], v[200:203], v[128:131]
	s_setprio 3
	s_barrier
	v_mfma_f32_16x16x32_f16 v[124:127], v[160:163], v[200:203], v[124:127]
	v_mfma_f32_16x16x32_f16 v[124:127], v[156:159], v[196:199], v[124:127]
	s_setprio 0
	s_add_i32 s28, s28, 2
	s_add_u32 s8, s8, 0x100
	s_addc_u32 s9, s9, 0
	s_add_u32 s26, s26, 0x100
	s_addc_u32 s27, s27, 0
	s_cmp_gt_u32 s28, 29
	s_cbranch_scc0 .LBB0_753
	s_and_b64 vcc, exec, s[52:53]
	s_cbranch_vccz .LBB0_756
	s_barrier

.LBB0_1175:
	s_add_i32 s61, 0, 0x10000
	s_add_i32 s79, 0, 0x14000
	v_add_u32_e32 v16, s61, v209
	v_add_u32_e32 v32, s79, v209
	ds_read_b128 v[4:7], v16
	ds_read_b128 v[8:11], v16 offset:1024
	ds_read_b128 v[12:15], v16 offset:2048
	ds_read_b128 v[16:19], v16 offset:3072
	ds_read_b128 v[20:23], v32
	ds_read_b128 v[24:27], v32 offset:1024
	ds_read_b128 v[28:31], v32 offset:2048
	ds_read_b128 v[32:35], v32 offset:3072
	v_add_u32_e32 v231, 0, v208
	ds_read_b128 v[36:39], v231
	ds_read_b128 v[40:43], v231 offset:1024
	ds_read_b128 v[44:47], v231 offset:2048
	ds_read_b128 v[48:51], v231 offset:3072
	ds_read_b128 v[52:55], v231 offset:4096
	ds_read_b128 v[56:59], v231 offset:5120
	ds_read_b128 v[60:63], v231 offset:6144
	ds_read_b128 v[64:67], v231 offset:7168
	s_waitcnt vmcnt(8)
	s_waitcnt lgkmcnt(0)
	s_barrier
	s_setprio 1
	s_waitcnt lgkmcnt(0)
	v_mfma_f32_16x16x32_bf16 v[68:71], v[4:7], v[36:39], 0
	v_mfma_f32_16x16x32_bf16 v[68:71], v[8:11], v[40:43], v[68:71]
	v_mfma_f32_16x16x32_bf16 v[72:75], v[12:15], v[36:39], 0
	v_mfma_f32_16x16x32_bf16 v[72:75], v[16:19], v[40:43], v[72:75]
	v_mfma_f32_16x16x32_bf16 v[80:83], v[12:15], v[44:47], 0
	v_mfma_f32_16x16x32_bf16 v[80:83], v[16:19], v[48:51], v[80:83]
	v_mfma_f32_16x16x32_bf16 v[76:79], v[4:7], v[44:47], 0
	v_mfma_f32_16x16x32_bf16 v[76:79], v[8:11], v[48:51], v[76:79]
	v_mfma_f32_16x16x32_bf16 v[84:87], v[4:7], v[52:55], 0
	v_mfma_f32_16x16x32_bf16 v[84:87], v[8:11], v[56:59], v[84:87]
	v_mfma_f32_16x16x32_bf16 v[88:91], v[12:15], v[52:55], 0
	v_mfma_f32_16x16x32_bf16 v[88:91], v[16:19], v[56:59], v[88:91]
	v_mfma_f32_16x16x32_bf16 v[96:99], v[12:15], v[60:63], 0
	v_mfma_f32_16x16x32_bf16 v[96:99], v[16:19], v[64:67], v[96:99]
	v_mfma_f32_16x16x32_bf16 v[92:95], v[4:7], v[60:63], 0
	v_mfma_f32_16x16x32_bf16 v[92:95], v[8:11], v[64:67], v[92:95]
	s_setprio 0
	s_setprio 1
	v_mfma_f32_16x16x32_bf16 v[100:103], v[20:23], v[36:39], 0
	v_mfma_f32_16x16x32_bf16 v[36:39], v[28:31], v[36:39], 0
	v_mfma_f32_16x16x32_bf16 v[104:107], v[20:23], v[44:47], 0
	v_mfma_f32_16x16x32_bf16 v[44:47], v[28:31], v[44:47], 0
	v_mfma_f32_16x16x32_bf16 v[108:111], v[20:23], v[52:55], 0
	v_mfma_f32_16x16x32_bf16 v[52:55], v[28:31], v[52:55], 0
	v_mfma_f32_16x16x32_bf16 v[112:115], v[20:23], v[60:63], 0
	v_mfma_f32_16x16x32_bf16 v[60:63], v[28:31], v[60:63], 0
	v_mfma_f32_16x16x32_bf16 v[100:103], v[24:27], v[40:43], v[100:103]
	v_mfma_f32_16x16x32_bf16 v[40:43], v[32:35], v[40:43], v[36:39]
	v_mfma_f32_16x16x32_bf16 v[104:107], v[24:27], v[48:51], v[104:107]
	v_mfma_f32_16x16x32_bf16 v[48:51], v[32:35], v[48:51], v[44:47]
	v_mfma_f32_16x16x32_bf16 v[108:111], v[24:27], v[56:59], v[108:111]
	v_mfma_f32_16x16x32_bf16 v[56:59], v[32:35], v[56:59], v[52:55]
	s_setprio 3
	s_barrier
	v_mfma_f32_16x16x32_bf16 v[112:115], v[24:27], v[64:67], v[112:115]
	v_mfma_f32_16x16x32_bf16 v[64:67], v[32:35], v[64:67], v[60:63]
	s_setprio 0
	v_lshl_add_u64 v[186:187], s[12:13], 0, v[2:3]
	s_add_i32 s61, s61, s36
	v_mov_b32_e32 v191, v3
	v_lshl_add_u64 v[134:135], v[186:187], 0, s[74:75]
	s_mov_b32 m0, s61
	v_lshl_add_u64 v[226:227], s[12:13], 0, v[190:191]
	ds_read_b128 v[36:39], v231 offset:16384
	ds_read_b128 v[44:47], v231 offset:17408
	ds_read_b128 v[52:55], v231 offset:18432
	ds_read_b128 v[60:63], v231 offset:19456
	ds_read_b128 v[116:119], v231 offset:20480
	ds_read_b128 v[120:123], v231 offset:21504
	ds_read_b128 v[124:127], v231 offset:22528
	ds_read_b128 v[128:131], v231 offset:23552
	global_load_lds_dwordx4 v[134:135], off
	v_lshl_add_u64 v[134:135], v[226:227], 0, s[74:75]
	s_add_i32 m0, s61, 0x2000
	s_add_i32 s61, s79, s36
	global_load_lds_dwordx4 v[134:135], off
	s_mov_b32 m0, s61
	v_mov_b32_e32 v133, v3
	global_load_lds_dwordx4 v2, s[16:17]
	s_add_i32 m0, s61, 0x2000
	v_lshl_add_u64 v[248:249], s[6:7], 0, v[132:133]
	v_mov_b32_e32 v189, v3
	global_load_lds_dwordx4 v190, s[16:17]
	v_lshl_add_u64 v[134:135], v[248:249], 0, s[74:75]
	s_mov_b32 m0, s37
	v_lshl_add_u64 v[250:251], s[6:7], 0, v[188:189]
	global_load_lds_dwordx4 v[134:135], off
	v_lshl_add_u64 v[134:135], v[250:251], 0, s[74:75]
	s_mov_b32 m0, s66
	s_nop 0
	global_load_lds_dwordx4 v[134:135], off
	s_waitcnt vmcnt(8)
	s_waitcnt lgkmcnt(0)
	s_barrier
	s_setprio 1
	s_waitcnt lgkmcnt(0)
	v_mfma_f32_16x16x32_bf16 v[134:137], v[4:7], v[36:39], 0
	v_mfma_f32_16x16x32_bf16 v[138:141], v[12:15], v[36:39], 0
	v_mfma_f32_16x16x32_bf16 v[142:145], v[4:7], v[52:55], 0
	v_mfma_f32_16x16x32_bf16 v[146:149], v[12:15], v[52:55], 0
	v_mfma_f32_16x16x32_bf16 v[150:153], v[4:7], v[116:119], 0
	v_mfma_f32_16x16x32_bf16 v[154:157], v[12:15], v[116:119], 0
	v_mfma_f32_16x16x32_bf16 v[4:7], v[4:7], v[124:127], 0
	v_mfma_f32_16x16x32_bf16 v[12:15], v[12:15], v[124:127], 0
	v_mfma_f32_16x16x32_bf16 v[134:137], v[8:11], v[44:47], v[134:137]
	v_mfma_f32_16x16x32_bf16 v[138:141], v[16:19], v[44:47], v[138:141]
	v_mfma_f32_16x16x32_bf16 v[142:145], v[8:11], v[60:63], v[142:145]
	v_mfma_f32_16x16x32_bf16 v[146:149], v[16:19], v[60:63], v[146:149]
	v_mfma_f32_16x16x32_bf16 v[150:153], v[8:11], v[120:123], v[150:153]
	v_mfma_f32_16x16x32_bf16 v[154:157], v[16:19], v[120:123], v[154:157]
	v_mfma_f32_16x16x32_bf16 v[158:161], v[8:11], v[128:131], v[4:7]
	v_mfma_f32_16x16x32_bf16 v[162:165], v[16:19], v[128:131], v[12:15]
	s_setprio 0
	s_setprio 1
	v_mfma_f32_16x16x32_bf16 v[4:7], v[20:23], v[36:39], 0
	v_mfma_f32_16x16x32_bf16 v[8:11], v[28:31], v[36:39], 0
	v_mfma_f32_16x16x32_bf16 v[12:15], v[20:23], v[52:55], 0
	v_mfma_f32_16x16x32_bf16 v[16:19], v[28:31], v[52:55], 0
	v_mfma_f32_16x16x32_bf16 v[36:39], v[20:23], v[116:119], 0
	v_mfma_f32_16x16x32_bf16 v[52:55], v[28:31], v[116:119], 0
	v_mfma_f32_16x16x32_bf16 v[20:23], v[20:23], v[124:127], 0
	v_mfma_f32_16x16x32_bf16 v[28:31], v[28:31], v[124:127], 0
	v_mfma_f32_16x16x32_bf16 v[116:119], v[24:27], v[44:47], v[4:7]
	v_mfma_f32_16x16x32_bf16 v[124:127], v[32:35], v[44:47], v[8:11]
	v_mfma_f32_16x16x32_bf16 v[174:177], v[24:27], v[120:123], v[36:39]
	v_mfma_f32_16x16x32_bf16 v[120:123], v[32:35], v[120:123], v[52:55]
	v_mfma_f32_16x16x32_bf16 v[178:181], v[24:27], v[128:131], v[20:23]
	v_mfma_f32_16x16x32_bf16 v[128:131], v[32:35], v[128:131], v[28:31]
	s_setprio 3
	s_barrier
	v_mfma_f32_16x16x32_bf16 v[166:169], v[24:27], v[60:63], v[12:15]
	v_mfma_f32_16x16x32_bf16 v[170:173], v[32:35], v[60:63], v[16:19]
	s_setprio 0
	s_add_i32 s61, 0, 0x18000
	v_add_u32_e32 v4, s61, v209
	s_add_i32 s79, 0, 0x1c000
	ds_read_b128 v[182:185], v4
	ds_read_b128 v[192:195], v4 offset:1024
	ds_read_b128 v[196:199], v4 offset:2048
	ds_read_b128 v[200:203], v4 offset:3072
	v_add_u32_e32 v4, s79, v209
	ds_read_b128 v[204:207], v4
	ds_read_b128 v[210:213], v4 offset:1024
	ds_read_b128 v[214:217], v4 offset:2048
	ds_read_b128 v[218:221], v4 offset:3072
	s_mov_b32 m0, s67
	ds_read_b128 v[44:47], v231 offset:32768
	ds_read_b128 v[52:55], v231 offset:33792
	ds_read_b128 v[60:63], v231 offset:34816
	ds_read_b128 v[222:225], v231 offset:35840
	ds_read_b128 v[232:235], v231 offset:36864
	ds_read_b128 v[236:239], v231 offset:37888
	ds_read_b128 v[240:243], v231 offset:38912
	ds_read_b128 v[244:247], v231 offset:39936
	global_load_lds_dwordx4 v132, s[26:27]
	s_mov_b32 m0, s68
	s_nop 0
	global_load_lds_dwordx4 v188, s[26:27]
	s_waitcnt vmcnt(8)
	s_waitcnt lgkmcnt(0)
	s_barrier
	s_setprio 1
	s_waitcnt lgkmcnt(0)
	v_mfma_f32_16x16x32_bf16 v[4:7], v[182:185], v[44:47], v[68:71]
	v_mfma_f32_16x16x32_bf16 v[8:11], v[196:199], v[44:47], v[72:75]
	v_mfma_f32_16x16x32_bf16 v[12:15], v[182:185], v[60:63], v[76:79]
	v_mfma_f32_16x16x32_bf16 v[16:19], v[196:199], v[60:63], v[80:83]
	v_mfma_f32_16x16x32_bf16 v[20:23], v[182:185], v[232:235], v[84:87]
	v_mfma_f32_16x16x32_bf16 v[24:27], v[196:199], v[232:235], v[88:91]
	v_mfma_f32_16x16x32_bf16 v[28:31], v[182:185], v[240:243], v[92:95]
	v_mfma_f32_16x16x32_bf16 v[32:35], v[196:199], v[240:243], v[96:99]
	v_mfma_f32_16x16x32_bf16 v[4:7], v[192:195], v[52:55], v[4:7]
	v_mfma_f32_16x16x32_bf16 v[8:11], v[200:203], v[52:55], v[8:11]
	v_mfma_f32_16x16x32_bf16 v[12:15], v[192:195], v[222:225], v[12:15]
	v_mfma_f32_16x16x32_bf16 v[16:19], v[200:203], v[222:225], v[16:19]
	v_mfma_f32_16x16x32_bf16 v[20:23], v[192:195], v[236:239], v[20:23]
	v_mfma_f32_16x16x32_bf16 v[24:27], v[200:203], v[236:239], v[24:27]
	v_mfma_f32_16x16x32_bf16 v[28:31], v[192:195], v[244:247], v[28:31]
	v_mfma_f32_16x16x32_bf16 v[32:35], v[200:203], v[244:247], v[32:35]
	s_setprio 0
	s_setprio 1
	v_mfma_f32_16x16x32_bf16 v[36:39], v[204:207], v[44:47], v[100:103]
	v_mfma_f32_16x16x32_bf16 v[40:43], v[214:217], v[44:47], v[40:43]
	v_mfma_f32_16x16x32_bf16 v[36:39], v[210:213], v[52:55], v[36:39]
	v_mfma_f32_16x16x32_bf16 v[40:43], v[218:221], v[52:55], v[40:43]
	v_mfma_f32_16x16x32_bf16 v[44:47], v[204:207], v[60:63], v[104:107]
	v_mfma_f32_16x16x32_bf16 v[48:51], v[214:217], v[60:63], v[48:51]
	v_mfma_f32_16x16x32_bf16 v[52:55], v[204:207], v[232:235], v[108:111]
	v_mfma_f32_16x16x32_bf16 v[56:59], v[214:217], v[232:235], v[56:59]
	v_mfma_f32_16x16x32_bf16 v[60:63], v[204:207], v[240:243], v[112:115]
	v_mfma_f32_16x16x32_bf16 v[64:67], v[214:217], v[240:243], v[64:67]
	v_mfma_f32_16x16x32_bf16 v[44:47], v[210:213], v[222:225], v[44:47]
	v_mfma_f32_16x16x32_bf16 v[48:51], v[218:221], v[222:225], v[48:51]
	v_mfma_f32_16x16x32_bf16 v[52:55], v[210:213], v[236:239], v[52:55]
	v_mfma_f32_16x16x32_bf16 v[56:59], v[218:221], v[236:239], v[56:59]
	s_setprio 3
	s_barrier
	v_mfma_f32_16x16x32_bf16 v[60:63], v[210:213], v[244:247], v[60:63]
	v_mfma_f32_16x16x32_bf16 v[64:67], v[218:221], v[244:247], v[64:67]
	s_setprio 0
	s_add_i32 s61, s61, s36
	v_lshl_add_u64 v[68:69], v[186:187], 0, s[24:25]
	s_mov_b32 m0, s61
	ds_read_b128 v[104:107], v231 offset:49152
	ds_read_b128 v[108:111], v231 offset:50176
	ds_read_b128 v[112:115], v231 offset:51200
	ds_read_b128 v[222:225], v231 offset:52224
	ds_read_b128 v[232:235], v231 offset:53248
	ds_read_b128 v[236:239], v231 offset:54272
	ds_read_b128 v[240:243], v231 offset:55296
	ds_read_b128 v[244:247], v231 offset:56320
	global_load_lds_dwordx4 v[68:69], off
	v_lshl_add_u64 v[68:69], v[226:227], 0, s[24:25]
	s_add_i32 m0, s61, 0x2000
	s_add_i32 s61, s79, s36
	global_load_lds_dwordx4 v[68:69], off
	s_mov_b32 m0, s61
	v_lshl_add_u64 v[68:69], v[248:249], 0, s[24:25]
	global_load_lds_dwordx4 v2, s[28:29]
	s_add_i32 m0, s61, 0x2000
	s_nop 0
	global_load_lds_dwordx4 v190, s[28:29]
	s_mov_b32 m0, s71
	s_nop 0
	global_load_lds_dwordx4 v[68:69], off
	v_lshl_add_u64 v[68:69], v[250:251], 0, s[24:25]
	s_mov_b32 m0, s72
	s_nop 0
	global_load_lds_dwordx4 v[68:69], off
	s_waitcnt vmcnt(8)
	s_waitcnt lgkmcnt(0)
	s_barrier
	s_setprio 1
	s_waitcnt lgkmcnt(0)
	v_mfma_f32_16x16x32_bf16 v[68:71], v[182:185], v[104:107], v[134:137]
	v_mfma_f32_16x16x32_bf16 v[72:75], v[196:199], v[104:107], v[138:141]
	v_mfma_f32_16x16x32_bf16 v[76:79], v[182:185], v[112:115], v[142:145]
	v_mfma_f32_16x16x32_bf16 v[80:83], v[196:199], v[112:115], v[146:149]
	v_mfma_f32_16x16x32_bf16 v[84:87], v[182:185], v[232:235], v[150:153]
	v_mfma_f32_16x16x32_bf16 v[88:91], v[196:199], v[232:235], v[154:157]
	v_mfma_f32_16x16x32_bf16 v[92:95], v[182:185], v[240:243], v[158:161]
	v_mfma_f32_16x16x32_bf16 v[96:99], v[196:199], v[240:243], v[162:165]
	v_mfma_f32_16x16x32_bf16 v[68:71], v[192:195], v[108:111], v[68:71]
	v_mfma_f32_16x16x32_bf16 v[72:75], v[200:203], v[108:111], v[72:75]
	v_mfma_f32_16x16x32_bf16 v[76:79], v[192:195], v[222:225], v[76:79]
	v_mfma_f32_16x16x32_bf16 v[80:83], v[200:203], v[222:225], v[80:83]
	v_mfma_f32_16x16x32_bf16 v[84:87], v[192:195], v[236:239], v[84:87]
	v_mfma_f32_16x16x32_bf16 v[88:91], v[200:203], v[236:239], v[88:91]
	v_mfma_f32_16x16x32_bf16 v[92:95], v[192:195], v[244:247], v[92:95]
	v_mfma_f32_16x16x32_bf16 v[96:99], v[200:203], v[244:247], v[96:99]
	s_setprio 0
	s_setprio 1
	v_mfma_f32_16x16x32_bf16 v[100:103], v[204:207], v[104:107], v[116:119]
	v_mfma_f32_16x16x32_bf16 v[104:107], v[214:217], v[104:107], v[124:127]
	v_mfma_f32_16x16x32_bf16 v[100:103], v[210:213], v[108:111], v[100:103]
	v_mfma_f32_16x16x32_bf16 v[104:107], v[218:221], v[108:111], v[104:107]
	v_mfma_f32_16x16x32_bf16 v[108:111], v[204:207], v[112:115], v[166:169]
	v_mfma_f32_16x16x32_bf16 v[112:115], v[214:217], v[112:115], v[170:173]
	v_mfma_f32_16x16x32_bf16 v[116:119], v[204:207], v[232:235], v[174:177]
	v_mfma_f32_16x16x32_bf16 v[120:123], v[214:217], v[232:235], v[120:123]
	v_mfma_f32_16x16x32_bf16 v[124:127], v[204:207], v[240:243], v[178:181]
	v_mfma_f32_16x16x32_bf16 v[128:131], v[214:217], v[240:243], v[128:131]
	v_mfma_f32_16x16x32_bf16 v[108:111], v[210:213], v[222:225], v[108:111]
	v_mfma_f32_16x16x32_bf16 v[112:115], v[218:221], v[222:225], v[112:115]
	v_mfma_f32_16x16x32_bf16 v[116:119], v[210:213], v[236:239], v[116:119]
	v_mfma_f32_16x16x32_bf16 v[120:123], v[218:221], v[236:239], v[120:123]
	s_setprio 3
	s_barrier
	v_mfma_f32_16x16x32_bf16 v[124:127], v[210:213], v[244:247], v[124:127]
	v_mfma_f32_16x16x32_bf16 v[128:131], v[218:221], v[244:247], v[128:131]
	s_setprio 0
	s_add_i32 s43, s43, 2
	s_cmp_ge_i32 s43, s42
	s_cbranch_scc0 .LBB0_1175
.LBB0_1176:
	s_add_i32 s12, 0, 0x10000
	s_add_i32 s13, 0, 0x14000
	v_mov_b32_e32 v192, v2
	v_mov_b32_e32 v2, v132
	v_add_u32_e32 v144, s12, v209
	v_add_u32_e32 v160, s13, v209
	ds_read_b128 v[132:135], v144
	ds_read_b128 v[136:139], v144 offset:1024
	ds_read_b128 v[140:143], v144 offset:2048
	ds_read_b128 v[144:147], v144 offset:3072
	ds_read_b128 v[148:151], v160
	ds_read_b128 v[152:155], v160 offset:1024
	ds_read_b128 v[156:159], v160 offset:2048
	ds_read_b128 v[160:163], v160 offset:3072
	s_add_u32 s6, s6, 0x80180
	s_mov_b32 m0, s73
	v_add_u32_e32 v212, 0, v208
	s_addc_u32 s7, s7, 0
	ds_read_b128 v[164:167], v212
	ds_read_b128 v[168:171], v212 offset:1024
	ds_read_b128 v[172:175], v212 offset:2048
	ds_read_b128 v[176:179], v212 offset:3072
	ds_read_b128 v[180:183], v212 offset:4096
	ds_read_b128 v[184:187], v212 offset:5120
	ds_read_b128 v[194:197], v212 offset:6144
	ds_read_b128 v[198:201], v212 offset:7168
	global_load_lds_dwordx4 v2, s[6:7]
	s_mov_b32 m0, s76
	v_mov_b32_e32 v189, v3
	global_load_lds_dwordx4 v188, s[6:7]
	s_waitcnt vmcnt(8)
	s_waitcnt lgkmcnt(0)
	s_barrier
	s_setprio 1
	s_waitcnt lgkmcnt(0)
	v_mfma_f32_16x16x32_bf16 v[4:7], v[132:135], v[164:167], v[4:7]
	v_mfma_f32_16x16x32_bf16 v[4:7], v[136:139], v[168:171], v[4:7]
	v_mfma_f32_16x16x32_bf16 v[8:11], v[144:147], v[168:171], v[8:11]
	v_mfma_f32_16x16x32_bf16 v[8:11], v[140:143], v[164:167], v[8:11]
	v_mfma_f32_16x16x32_bf16 v[16:19], v[140:143], v[172:175], v[16:19]
	v_mfma_f32_16x16x32_bf16 v[16:19], v[144:147], v[176:179], v[16:19]
	v_mfma_f32_16x16x32_bf16 v[12:15], v[136:139], v[176:179], v[12:15]
	v_mfma_f32_16x16x32_bf16 v[12:15], v[132:135], v[172:175], v[12:15]
	v_mfma_f32_16x16x32_bf16 v[20:23], v[132:135], v[180:183], v[20:23]
	v_mfma_f32_16x16x32_bf16 v[20:23], v[136:139], v[184:187], v[20:23]
	v_mfma_f32_16x16x32_bf16 v[24:27], v[144:147], v[184:187], v[24:27]
	v_mfma_f32_16x16x32_bf16 v[24:27], v[140:143], v[180:183], v[24:27]
	v_mfma_f32_16x16x32_bf16 v[32:35], v[140:143], v[194:197], v[32:35]
	v_mfma_f32_16x16x32_bf16 v[32:35], v[144:147], v[198:201], v[32:35]
	v_mfma_f32_16x16x32_bf16 v[28:31], v[136:139], v[198:201], v[28:31]
	v_mfma_f32_16x16x32_bf16 v[28:31], v[132:135], v[194:197], v[28:31]
	s_setprio 0
	s_setprio 1
	v_mfma_f32_16x16x32_bf16 v[36:39], v[148:151], v[164:167], v[36:39]
	v_mfma_f32_16x16x32_bf16 v[36:39], v[152:155], v[168:171], v[36:39]
	v_mfma_f32_16x16x32_bf16 v[40:43], v[160:163], v[168:171], v[40:43]
	v_mfma_f32_16x16x32_bf16 v[40:43], v[156:159], v[164:167], v[40:43]
	v_mfma_f32_16x16x32_bf16 v[48:51], v[156:159], v[172:175], v[48:51]
	v_mfma_f32_16x16x32_bf16 v[48:51], v[160:163], v[176:179], v[48:51]
	v_mfma_f32_16x16x32_bf16 v[44:47], v[152:155], v[176:179], v[44:47]
	v_mfma_f32_16x16x32_bf16 v[44:47], v[148:151], v[172:175], v[44:47]
	v_mfma_f32_16x16x32_bf16 v[52:55], v[148:151], v[180:183], v[52:55]
	v_mfma_f32_16x16x32_bf16 v[52:55], v[152:155], v[184:187], v[52:55]
	v_mfma_f32_16x16x32_bf16 v[56:59], v[160:163], v[184:187], v[56:59]
	v_mfma_f32_16x16x32_bf16 v[56:59], v[156:159], v[180:183], v[56:59]
	v_mfma_f32_16x16x32_bf16 v[64:67], v[156:159], v[194:197], v[64:67]
	v_mfma_f32_16x16x32_bf16 v[64:67], v[160:163], v[198:201], v[64:67]
	s_setprio 3
	s_barrier
	v_mfma_f32_16x16x32_bf16 v[60:63], v[152:155], v[198:201], v[60:63]
	v_mfma_f32_16x16x32_bf16 v[60:63], v[148:151], v[194:197], v[60:63]
	s_setprio 0
	s_add_i32 s6, s12, s36
	s_mov_b32 m0, s6
	ds_read_b128 v[164:167], v212 offset:16384
	ds_read_b128 v[168:171], v212 offset:17408
	ds_read_b128 v[172:175], v212 offset:18432
	ds_read_b128 v[176:179], v212 offset:19456
	ds_read_b128 v[180:183], v212 offset:20480
	ds_read_b128 v[184:187], v212 offset:21504
	ds_read_b128 v[194:197], v212 offset:22528
	ds_read_b128 v[198:201], v212 offset:23552
	global_load_lds_dwordx4 v192, s[14:15]
	s_add_i32 m0, s6, 0x2000
	s_add_u32 s6, s14, 0x10000
	s_addc_u32 s7, s15, 0
	s_add_i32 s12, s13, s36
	global_load_lds_dwordx4 v190, s[14:15]
	s_mov_b32 m0, s12
	v_mov_b32_e32 v193, v3
	global_load_lds_dwordx4 v192, s[6:7]
	s_add_i32 m0, s12, 0x2000
	v_mov_b32_e32 v191, v3
	global_load_lds_dwordx4 v190, s[6:7]
	s_mov_b32 m0, s37
	v_lshl_add_u64 v[202:203], s[14:15], 0, v[192:193]
	global_load_lds_dwordx4 v2, s[10:11]
	s_mov_b32 m0, s66
	v_lshl_add_u64 v[204:205], s[14:15], 0, v[190:191]
	global_load_lds_dwordx4 v188, s[10:11]
	s_waitcnt vmcnt(8)
	s_waitcnt lgkmcnt(0)
	v_lshl_add_u64 v[206:207], s[10:11], 0, v[2:3]
	v_lshl_add_u64 v[210:211], s[10:11], 0, v[188:189]
	s_barrier
	s_setprio 1
	s_waitcnt lgkmcnt(0)
	v_mfma_f32_16x16x32_bf16 v[68:71], v[132:135], v[164:167], v[68:71]
	v_mfma_f32_16x16x32_bf16 v[68:71], v[136:139], v[168:171], v[68:71]
	v_mfma_f32_16x16x32_bf16 v[72:75], v[144:147], v[168:171], v[72:75]
	v_mfma_f32_16x16x32_bf16 v[72:75], v[140:143], v[164:167], v[72:75]
	v_mfma_f32_16x16x32_bf16 v[80:83], v[140:143], v[172:175], v[80:83]
	v_mfma_f32_16x16x32_bf16 v[80:83], v[144:147], v[176:179], v[80:83]
	v_mfma_f32_16x16x32_bf16 v[76:79], v[136:139], v[176:179], v[76:79]
	v_mfma_f32_16x16x32_bf16 v[76:79], v[132:135], v[172:175], v[76:79]
	v_mfma_f32_16x16x32_bf16 v[84:87], v[132:135], v[180:183], v[84:87]
	v_mfma_f32_16x16x32_bf16 v[84:87], v[136:139], v[184:187], v[84:87]
	v_mfma_f32_16x16x32_bf16 v[88:91], v[144:147], v[184:187], v[88:91]
	v_mfma_f32_16x16x32_bf16 v[88:91], v[140:143], v[180:183], v[88:91]
	v_mfma_f32_16x16x32_bf16 v[96:99], v[140:143], v[194:197], v[96:99]
	v_mfma_f32_16x16x32_bf16 v[96:99], v[144:147], v[198:201], v[96:99]
	v_mfma_f32_16x16x32_bf16 v[92:95], v[136:139], v[198:201], v[92:95]
	v_mfma_f32_16x16x32_bf16 v[92:95], v[132:135], v[194:197], v[92:95]
	s_setprio 0
	s_setprio 1
	v_mfma_f32_16x16x32_bf16 v[100:103], v[148:151], v[164:167], v[100:103]
	v_mfma_f32_16x16x32_bf16 v[100:103], v[152:155], v[168:171], v[100:103]
	v_mfma_f32_16x16x32_bf16 v[104:107], v[160:163], v[168:171], v[104:107]
	v_mfma_f32_16x16x32_bf16 v[104:107], v[156:159], v[164:167], v[104:107]
	v_mfma_f32_16x16x32_bf16 v[112:115], v[156:159], v[172:175], v[112:115]
	v_mfma_f32_16x16x32_bf16 v[112:115], v[160:163], v[176:179], v[112:115]
	v_mfma_f32_16x16x32_bf16 v[108:111], v[152:155], v[176:179], v[108:111]
	v_mfma_f32_16x16x32_bf16 v[108:111], v[148:151], v[172:175], v[108:111]
	v_mfma_f32_16x16x32_bf16 v[116:119], v[148:151], v[180:183], v[116:119]
	v_mfma_f32_16x16x32_bf16 v[116:119], v[152:155], v[184:187], v[116:119]
	v_mfma_f32_16x16x32_bf16 v[120:123], v[160:163], v[184:187], v[120:123]
	v_mfma_f32_16x16x32_bf16 v[120:123], v[156:159], v[180:183], v[120:123]
	v_mfma_f32_16x16x32_bf16 v[128:131], v[156:159], v[194:197], v[128:131]
	v_mfma_f32_16x16x32_bf16 v[128:131], v[160:163], v[198:201], v[128:131]
	s_setprio 3
	s_barrier
	v_mfma_f32_16x16x32_bf16 v[124:127], v[152:155], v[198:201], v[124:127]
	v_mfma_f32_16x16x32_bf16 v[124:127], v[148:151], v[194:197], v[124:127]
	s_setprio 0
	s_add_i32 s12, 0, 0x18000
	s_add_i32 s13, 0, 0x1c000
	v_add_u32_e32 v144, s12, v209
	v_add_u32_e32 v160, s13, v209
	ds_read_b128 v[132:135], v144
	ds_read_b128 v[136:139], v144 offset:1024
	ds_read_b128 v[140:143], v144 offset:2048
	ds_read_b128 v[144:147], v144 offset:3072
	ds_read_b128 v[148:151], v160
	ds_read_b128 v[152:155], v160 offset:1024
	ds_read_b128 v[156:159], v160 offset:2048
	ds_read_b128 v[160:163], v160 offset:3072
	s_add_u32 s6, s10, 0x80000
	s_addc_u32 s7, s11, 0
	s_mov_b32 m0, s67
	ds_read_b128 v[164:167], v212 offset:32768
	ds_read_b128 v[168:171], v212 offset:33792
	ds_read_b128 v[172:175], v212 offset:34816
	ds_read_b128 v[176:179], v212 offset:35840
	ds_read_b128 v[180:183], v212 offset:36864
	ds_read_b128 v[184:187], v212 offset:37888
	ds_read_b128 v[194:197], v212 offset:38912
	ds_read_b128 v[198:201], v212 offset:39936
	global_load_lds_dwordx4 v2, s[6:7]
	s_mov_b32 m0, s68
	s_nop 0
	global_load_lds_dwordx4 v188, s[6:7]
	s_waitcnt vmcnt(8)
	s_waitcnt lgkmcnt(0)
	s_barrier
	s_setprio 1
	s_waitcnt lgkmcnt(0)
	v_mfma_f32_16x16x32_bf16 v[4:7], v[132:135], v[164:167], v[4:7]
	v_mfma_f32_16x16x32_bf16 v[4:7], v[136:139], v[168:171], v[4:7]
	v_mfma_f32_16x16x32_bf16 v[8:11], v[144:147], v[168:171], v[8:11]
	v_mfma_f32_16x16x32_bf16 v[8:11], v[140:143], v[164:167], v[8:11]
	v_mfma_f32_16x16x32_bf16 v[16:19], v[140:143], v[172:175], v[16:19]
	v_mfma_f32_16x16x32_bf16 v[16:19], v[144:147], v[176:179], v[16:19]
	v_mfma_f32_16x16x32_bf16 v[12:15], v[136:139], v[176:179], v[12:15]
	v_mfma_f32_16x16x32_bf16 v[12:15], v[132:135], v[172:175], v[12:15]
	v_mfma_f32_16x16x32_bf16 v[20:23], v[132:135], v[180:183], v[20:23]
	v_mfma_f32_16x16x32_bf16 v[20:23], v[136:139], v[184:187], v[20:23]
	v_mfma_f32_16x16x32_bf16 v[24:27], v[144:147], v[184:187], v[24:27]
	v_mfma_f32_16x16x32_bf16 v[24:27], v[140:143], v[180:183], v[24:27]
	v_mfma_f32_16x16x32_bf16 v[32:35], v[140:143], v[194:197], v[32:35]
	v_mfma_f32_16x16x32_bf16 v[32:35], v[144:147], v[198:201], v[32:35]
	v_mfma_f32_16x16x32_bf16 v[28:31], v[136:139], v[198:201], v[28:31]
	v_mfma_f32_16x16x32_bf16 v[28:31], v[132:135], v[194:197], v[28:31]
	s_setprio 0
	s_setprio 1
	v_mfma_f32_16x16x32_bf16 v[36:39], v[148:151], v[164:167], v[36:39]
	v_mfma_f32_16x16x32_bf16 v[36:39], v[152:155], v[168:171], v[36:39]
	v_mfma_f32_16x16x32_bf16 v[40:43], v[160:163], v[168:171], v[40:43]
	v_mfma_f32_16x16x32_bf16 v[40:43], v[156:159], v[164:167], v[40:43]
	v_mfma_f32_16x16x32_bf16 v[48:51], v[156:159], v[172:175], v[48:51]
	v_mfma_f32_16x16x32_bf16 v[48:51], v[160:163], v[176:179], v[48:51]
	v_mfma_f32_16x16x32_bf16 v[44:47], v[152:155], v[176:179], v[44:47]
	v_mfma_f32_16x16x32_bf16 v[44:47], v[148:151], v[172:175], v[44:47]
	v_mfma_f32_16x16x32_bf16 v[52:55], v[148:151], v[180:183], v[52:55]
	v_mfma_f32_16x16x32_bf16 v[52:55], v[152:155], v[184:187], v[52:55]
	v_mfma_f32_16x16x32_bf16 v[56:59], v[160:163], v[184:187], v[56:59]
	v_mfma_f32_16x16x32_bf16 v[56:59], v[156:159], v[180:183], v[56:59]
	v_mfma_f32_16x16x32_bf16 v[64:67], v[156:159], v[194:197], v[64:67]
	v_mfma_f32_16x16x32_bf16 v[64:67], v[160:163], v[198:201], v[64:67]
	s_setprio 3
	s_barrier
	v_mfma_f32_16x16x32_bf16 v[60:63], v[152:155], v[198:201], v[60:63]
	v_mfma_f32_16x16x32_bf16 v[60:63], v[148:151], v[194:197], v[60:63]
	s_setprio 0
	s_add_i32 s6, s12, s36
	v_lshl_add_u64 v[202:203], v[202:203], 0, s[86:87]
	s_mov_b32 m0, s6
	ds_read_b128 v[164:167], v212 offset:49152
	ds_read_b128 v[168:171], v212 offset:50176
	ds_read_b128 v[172:175], v212 offset:51200
	ds_read_b128 v[176:179], v212 offset:52224
	ds_read_b128 v[180:183], v212 offset:53248
	ds_read_b128 v[184:187], v212 offset:54272
	ds_read_b128 v[194:197], v212 offset:55296
	ds_read_b128 v[198:201], v212 offset:56320
	global_load_lds_dwordx4 v[202:203], off
	s_add_i32 m0, s6, 0x2000
	s_add_u32 s6, s14, 0x10080
	v_lshl_add_u64 v[202:203], v[204:205], 0, s[86:87]
	s_addc_u32 s7, s15, 0
	s_add_i32 s12, s13, s36
	global_load_lds_dwordx4 v[202:203], off
	s_mov_b32 m0, s12
	v_lshl_add_u64 v[202:203], v[206:207], 0, s[86:87]
	global_load_lds_dwordx4 v192, s[6:7]
	s_add_i32 m0, s12, 0x2000
	s_nop 0
	global_load_lds_dwordx4 v190, s[6:7]
	s_mov_b32 m0, s71
	s_nop 0
	global_load_lds_dwordx4 v[202:203], off
	v_lshl_add_u64 v[202:203], v[210:211], 0, s[86:87]
	s_mov_b32 m0, s72
	s_nop 0
	global_load_lds_dwordx4 v[202:203], off
	s_waitcnt vmcnt(8)
	s_waitcnt lgkmcnt(0)
	s_barrier
	s_setprio 1
	s_waitcnt lgkmcnt(0)
	v_mfma_f32_16x16x32_bf16 v[68:71], v[132:135], v[164:167], v[68:71]
	v_mfma_f32_16x16x32_bf16 v[68:71], v[136:139], v[168:171], v[68:71]
	v_mfma_f32_16x16x32_bf16 v[72:75], v[144:147], v[168:171], v[72:75]
	v_mfma_f32_16x16x32_bf16 v[72:75], v[140:143], v[164:167], v[72:75]
	v_mfma_f32_16x16x32_bf16 v[80:83], v[140:143], v[172:175], v[80:83]
	v_mfma_f32_16x16x32_bf16 v[80:83], v[144:147], v[176:179], v[80:83]
	v_mfma_f32_16x16x32_bf16 v[76:79], v[136:139], v[176:179], v[76:79]
	v_mfma_f32_16x16x32_bf16 v[76:79], v[132:135], v[172:175], v[76:79]
	v_mfma_f32_16x16x32_bf16 v[84:87], v[132:135], v[180:183], v[84:87]
	v_mfma_f32_16x16x32_bf16 v[84:87], v[136:139], v[184:187], v[84:87]
	v_mfma_f32_16x16x32_bf16 v[88:91], v[144:147], v[184:187], v[88:91]
	v_mfma_f32_16x16x32_bf16 v[88:91], v[140:143], v[180:183], v[88:91]
	v_mfma_f32_16x16x32_bf16 v[96:99], v[140:143], v[194:197], v[96:99]
	v_mfma_f32_16x16x32_bf16 v[96:99], v[144:147], v[198:201], v[96:99]
	v_mfma_f32_16x16x32_bf16 v[92:95], v[136:139], v[198:201], v[92:95]
	v_mfma_f32_16x16x32_bf16 v[92:95], v[132:135], v[194:197], v[92:95]
	s_setprio 0
	s_setprio 1
	v_mfma_f32_16x16x32_bf16 v[100:103], v[148:151], v[164:167], v[100:103]
	v_mfma_f32_16x16x32_bf16 v[100:103], v[152:155], v[168:171], v[100:103]
	v_mfma_f32_16x16x32_bf16 v[104:107], v[160:163], v[168:171], v[104:107]
	v_mfma_f32_16x16x32_bf16 v[104:107], v[156:159], v[164:167], v[104:107]
	v_mfma_f32_16x16x32_bf16 v[112:115], v[156:159], v[172:175], v[112:115]
	v_mfma_f32_16x16x32_bf16 v[112:115], v[160:163], v[176:179], v[112:115]
	v_mfma_f32_16x16x32_bf16 v[108:111], v[152:155], v[176:179], v[108:111]
	v_mfma_f32_16x16x32_bf16 v[108:111], v[148:151], v[172:175], v[108:111]
	v_mfma_f32_16x16x32_bf16 v[116:119], v[148:151], v[180:183], v[116:119]
	v_mfma_f32_16x16x32_bf16 v[116:119], v[152:155], v[184:187], v[116:119]
	v_mfma_f32_16x16x32_bf16 v[120:123], v[160:163], v[184:187], v[120:123]
	v_mfma_f32_16x16x32_bf16 v[120:123], v[156:159], v[180:183], v[120:123]
	v_mfma_f32_16x16x32_bf16 v[128:131], v[156:159], v[194:197], v[128:131]
	v_mfma_f32_16x16x32_bf16 v[128:131], v[160:163], v[198:201], v[128:131]
	s_setprio 3
	s_barrier
	v_mfma_f32_16x16x32_bf16 v[124:127], v[152:155], v[198:201], v[124:127]
	v_mfma_f32_16x16x32_bf16 v[124:127], v[148:151], v[194:197], v[124:127]
	s_setprio 0
	s_and_b64 vcc, exec, s[58:59]
	s_cbranch_vccz .LBB0_1178
	s_barrier

.LBB0_1625:
	s_add_i32 s51, 0, 0x10000
	s_add_i32 s72, 0, 0x14000
	v_add_u32_e32 v16, s51, v232
	v_add_u32_e32 v32, s72, v232
	ds_read_b128 v[4:7], v16
	ds_read_b128 v[8:11], v16 offset:1024
	ds_read_b128 v[12:15], v16 offset:2048
	ds_read_b128 v[16:19], v16 offset:3072
	ds_read_b128 v[20:23], v32
	ds_read_b128 v[24:27], v32 offset:1024
	ds_read_b128 v[28:31], v32 offset:2048
	ds_read_b128 v[32:35], v32 offset:3072
	v_add_u32_e32 v233, 0, v231
	ds_read_b128 v[36:39], v233
	ds_read_b128 v[40:43], v233 offset:1024
	ds_read_b128 v[44:47], v233 offset:2048
	ds_read_b128 v[48:51], v233 offset:3072
	ds_read_b128 v[52:55], v233 offset:4096
	ds_read_b128 v[56:59], v233 offset:5120
	ds_read_b128 v[60:63], v233 offset:6144
	ds_read_b128 v[64:67], v233 offset:7168
	s_waitcnt vmcnt(8)
	s_waitcnt lgkmcnt(0)
	s_barrier
	s_setprio 1
	s_waitcnt lgkmcnt(0)
	v_mfma_f32_16x16x32_bf16 v[68:71], v[4:7], v[36:39], 0
	v_mfma_f32_16x16x32_bf16 v[68:71], v[8:11], v[40:43], v[68:71]
	v_mfma_f32_16x16x32_bf16 v[72:75], v[12:15], v[36:39], 0
	v_mfma_f32_16x16x32_bf16 v[72:75], v[16:19], v[40:43], v[72:75]
	v_mfma_f32_16x16x32_bf16 v[80:83], v[12:15], v[44:47], 0
	v_mfma_f32_16x16x32_bf16 v[80:83], v[16:19], v[48:51], v[80:83]
	v_mfma_f32_16x16x32_bf16 v[76:79], v[4:7], v[44:47], 0
	v_mfma_f32_16x16x32_bf16 v[76:79], v[8:11], v[48:51], v[76:79]
	v_mfma_f32_16x16x32_bf16 v[84:87], v[4:7], v[52:55], 0
	v_mfma_f32_16x16x32_bf16 v[84:87], v[8:11], v[56:59], v[84:87]
	v_mfma_f32_16x16x32_bf16 v[88:91], v[12:15], v[52:55], 0
	v_mfma_f32_16x16x32_bf16 v[88:91], v[16:19], v[56:59], v[88:91]
	v_mfma_f32_16x16x32_bf16 v[96:99], v[12:15], v[60:63], 0
	v_mfma_f32_16x16x32_bf16 v[96:99], v[16:19], v[64:67], v[96:99]
	v_mfma_f32_16x16x32_bf16 v[92:95], v[4:7], v[60:63], 0
	v_mfma_f32_16x16x32_bf16 v[92:95], v[8:11], v[64:67], v[92:95]
	s_setprio 0
	s_setprio 1
	v_mfma_f32_16x16x32_bf16 v[100:103], v[20:23], v[36:39], 0
	v_mfma_f32_16x16x32_bf16 v[36:39], v[28:31], v[36:39], 0
	v_mfma_f32_16x16x32_bf16 v[104:107], v[20:23], v[44:47], 0
	v_mfma_f32_16x16x32_bf16 v[44:47], v[28:31], v[44:47], 0
	v_mfma_f32_16x16x32_bf16 v[108:111], v[20:23], v[52:55], 0
	v_mfma_f32_16x16x32_bf16 v[52:55], v[28:31], v[52:55], 0
	v_mfma_f32_16x16x32_bf16 v[112:115], v[20:23], v[60:63], 0
	v_mfma_f32_16x16x32_bf16 v[60:63], v[28:31], v[60:63], 0
	v_mfma_f32_16x16x32_bf16 v[100:103], v[24:27], v[40:43], v[100:103]
	v_mfma_f32_16x16x32_bf16 v[40:43], v[32:35], v[40:43], v[36:39]
	v_mfma_f32_16x16x32_bf16 v[104:107], v[24:27], v[48:51], v[104:107]
	v_mfma_f32_16x16x32_bf16 v[48:51], v[32:35], v[48:51], v[44:47]
	v_mfma_f32_16x16x32_bf16 v[108:111], v[24:27], v[56:59], v[108:111]
	v_mfma_f32_16x16x32_bf16 v[56:59], v[32:35], v[56:59], v[52:55]
	s_setprio 3
	s_barrier
	v_mfma_f32_16x16x32_bf16 v[112:115], v[24:27], v[64:67], v[112:115]
	v_mfma_f32_16x16x32_bf16 v[64:67], v[32:35], v[64:67], v[60:63]
	s_setprio 0
	v_lshl_add_u64 v[186:187], s[12:13], 0, v[2:3]
	s_add_i32 s51, s51, s56
	v_mov_b32_e32 v191, v3
	v_lshl_add_u64 v[134:135], v[186:187], 0, s[74:75]
	s_mov_b32 m0, s51
	v_lshl_add_u64 v[246:247], s[12:13], 0, v[190:191]
	ds_read_b128 v[36:39], v233 offset:16384
	ds_read_b128 v[44:47], v233 offset:17408
	ds_read_b128 v[52:55], v233 offset:18432
	ds_read_b128 v[60:63], v233 offset:19456
	ds_read_b128 v[116:119], v233 offset:20480
	ds_read_b128 v[120:123], v233 offset:21504
	ds_read_b128 v[124:127], v233 offset:22528
	ds_read_b128 v[128:131], v233 offset:23552
	global_load_lds_dwordx4 v[134:135], off
	v_lshl_add_u64 v[134:135], v[246:247], 0, s[74:75]
	s_add_i32 m0, s51, 0x2000
	s_add_i32 s51, s72, s56
	global_load_lds_dwordx4 v[134:135], off
	s_mov_b32 m0, s51
	v_mov_b32_e32 v133, v3
	global_load_lds_dwordx4 v2, s[16:17]
	s_add_i32 m0, s51, 0x2000
	v_lshl_add_u64 v[248:249], s[14:15], 0, v[132:133]
	v_mov_b32_e32 v189, v3
	global_load_lds_dwordx4 v190, s[16:17]
	v_lshl_add_u64 v[134:135], v[248:249], 0, s[74:75]
	s_mov_b32 m0, s57
	v_lshl_add_u64 v[250:251], s[14:15], 0, v[188:189]
	global_load_lds_dwordx4 v[134:135], off
	v_lshl_add_u64 v[134:135], v[250:251], 0, s[74:75]
	s_mov_b32 m0, s58
	s_nop 0
	global_load_lds_dwordx4 v[134:135], off
	s_waitcnt vmcnt(8)
	s_waitcnt lgkmcnt(0)
	s_barrier
	s_setprio 1
	s_waitcnt lgkmcnt(0)
	v_mfma_f32_16x16x32_bf16 v[134:137], v[4:7], v[36:39], 0
	v_mfma_f32_16x16x32_bf16 v[138:141], v[12:15], v[36:39], 0
	v_mfma_f32_16x16x32_bf16 v[142:145], v[4:7], v[52:55], 0
	v_mfma_f32_16x16x32_bf16 v[146:149], v[12:15], v[52:55], 0
	v_mfma_f32_16x16x32_bf16 v[150:153], v[4:7], v[116:119], 0
	v_mfma_f32_16x16x32_bf16 v[154:157], v[12:15], v[116:119], 0
	v_mfma_f32_16x16x32_bf16 v[4:7], v[4:7], v[124:127], 0
	v_mfma_f32_16x16x32_bf16 v[12:15], v[12:15], v[124:127], 0
	v_mfma_f32_16x16x32_bf16 v[134:137], v[8:11], v[44:47], v[134:137]
	v_mfma_f32_16x16x32_bf16 v[138:141], v[16:19], v[44:47], v[138:141]
	v_mfma_f32_16x16x32_bf16 v[142:145], v[8:11], v[60:63], v[142:145]
	v_mfma_f32_16x16x32_bf16 v[146:149], v[16:19], v[60:63], v[146:149]
	v_mfma_f32_16x16x32_bf16 v[150:153], v[8:11], v[120:123], v[150:153]
	v_mfma_f32_16x16x32_bf16 v[154:157], v[16:19], v[120:123], v[154:157]
	v_mfma_f32_16x16x32_bf16 v[158:161], v[8:11], v[128:131], v[4:7]
	v_mfma_f32_16x16x32_bf16 v[162:165], v[16:19], v[128:131], v[12:15]
	s_setprio 0
	s_setprio 1
	v_mfma_f32_16x16x32_bf16 v[4:7], v[20:23], v[36:39], 0
	v_mfma_f32_16x16x32_bf16 v[8:11], v[28:31], v[36:39], 0
	v_mfma_f32_16x16x32_bf16 v[12:15], v[20:23], v[52:55], 0
	v_mfma_f32_16x16x32_bf16 v[16:19], v[28:31], v[52:55], 0
	v_mfma_f32_16x16x32_bf16 v[36:39], v[20:23], v[116:119], 0
	v_mfma_f32_16x16x32_bf16 v[52:55], v[28:31], v[116:119], 0
	v_mfma_f32_16x16x32_bf16 v[20:23], v[20:23], v[124:127], 0
	v_mfma_f32_16x16x32_bf16 v[28:31], v[28:31], v[124:127], 0
	v_mfma_f32_16x16x32_bf16 v[116:119], v[24:27], v[44:47], v[4:7]
	v_mfma_f32_16x16x32_bf16 v[124:127], v[32:35], v[44:47], v[8:11]
	v_mfma_f32_16x16x32_bf16 v[174:177], v[24:27], v[120:123], v[36:39]
	v_mfma_f32_16x16x32_bf16 v[120:123], v[32:35], v[120:123], v[52:55]
	v_mfma_f32_16x16x32_bf16 v[178:181], v[24:27], v[128:131], v[20:23]
	v_mfma_f32_16x16x32_bf16 v[128:131], v[32:35], v[128:131], v[28:31]
	s_setprio 3
	s_barrier
	v_mfma_f32_16x16x32_bf16 v[166:169], v[24:27], v[60:63], v[12:15]
	v_mfma_f32_16x16x32_bf16 v[170:173], v[32:35], v[60:63], v[16:19]
	s_setprio 0
	s_add_i32 s51, 0, 0x18000
	v_add_u32_e32 v4, s51, v232
	s_add_i32 s72, 0, 0x1c000
	ds_read_b128 v[182:185], v4
	ds_read_b128 v[192:195], v4 offset:1024
	ds_read_b128 v[196:199], v4 offset:2048
	ds_read_b128 v[200:203], v4 offset:3072
	v_add_u32_e32 v4, s72, v232
	ds_read_b128 v[204:207], v4
	ds_read_b128 v[208:211], v4 offset:1024
	ds_read_b128 v[212:215], v4 offset:2048
	ds_read_b128 v[216:219], v4 offset:3072
	s_mov_b32 m0, s59
	ds_read_b128 v[44:47], v233 offset:32768
	ds_read_b128 v[52:55], v233 offset:33792
	ds_read_b128 v[60:63], v233 offset:34816
	ds_read_b128 v[220:223], v233 offset:35840
	ds_read_b128 v[224:227], v233 offset:36864
	ds_read_b128 v[234:237], v233 offset:37888
	ds_read_b128 v[238:241], v233 offset:38912
	ds_read_b128 v[242:245], v233 offset:39936
	global_load_lds_dwordx4 v132, s[26:27]
	s_mov_b32 m0, s60
	s_nop 0
	global_load_lds_dwordx4 v188, s[26:27]
	s_waitcnt vmcnt(8)
	s_waitcnt lgkmcnt(0)
	s_barrier
	s_setprio 1
	s_waitcnt lgkmcnt(0)
	v_mfma_f32_16x16x32_bf16 v[4:7], v[182:185], v[44:47], v[68:71]
	v_mfma_f32_16x16x32_bf16 v[8:11], v[196:199], v[44:47], v[72:75]
	v_mfma_f32_16x16x32_bf16 v[12:15], v[182:185], v[60:63], v[76:79]
	v_mfma_f32_16x16x32_bf16 v[16:19], v[196:199], v[60:63], v[80:83]
	v_mfma_f32_16x16x32_bf16 v[20:23], v[182:185], v[224:227], v[84:87]
	v_mfma_f32_16x16x32_bf16 v[24:27], v[196:199], v[224:227], v[88:91]
	v_mfma_f32_16x16x32_bf16 v[28:31], v[182:185], v[238:241], v[92:95]
	v_mfma_f32_16x16x32_bf16 v[32:35], v[196:199], v[238:241], v[96:99]
	v_mfma_f32_16x16x32_bf16 v[4:7], v[192:195], v[52:55], v[4:7]
	v_mfma_f32_16x16x32_bf16 v[8:11], v[200:203], v[52:55], v[8:11]
	v_mfma_f32_16x16x32_bf16 v[12:15], v[192:195], v[220:223], v[12:15]
	v_mfma_f32_16x16x32_bf16 v[16:19], v[200:203], v[220:223], v[16:19]
	v_mfma_f32_16x16x32_bf16 v[20:23], v[192:195], v[234:237], v[20:23]
	v_mfma_f32_16x16x32_bf16 v[24:27], v[200:203], v[234:237], v[24:27]
	v_mfma_f32_16x16x32_bf16 v[28:31], v[192:195], v[242:245], v[28:31]
	v_mfma_f32_16x16x32_bf16 v[32:35], v[200:203], v[242:245], v[32:35]
	s_setprio 0
	s_setprio 1
	v_mfma_f32_16x16x32_bf16 v[36:39], v[204:207], v[44:47], v[100:103]
	v_mfma_f32_16x16x32_bf16 v[40:43], v[212:215], v[44:47], v[40:43]
	v_mfma_f32_16x16x32_bf16 v[36:39], v[208:211], v[52:55], v[36:39]
	v_mfma_f32_16x16x32_bf16 v[40:43], v[216:219], v[52:55], v[40:43]
	v_mfma_f32_16x16x32_bf16 v[44:47], v[204:207], v[60:63], v[104:107]
	v_mfma_f32_16x16x32_bf16 v[48:51], v[212:215], v[60:63], v[48:51]
	v_mfma_f32_16x16x32_bf16 v[52:55], v[204:207], v[224:227], v[108:111]
	v_mfma_f32_16x16x32_bf16 v[56:59], v[212:215], v[224:227], v[56:59]
	v_mfma_f32_16x16x32_bf16 v[60:63], v[204:207], v[238:241], v[112:115]
	v_mfma_f32_16x16x32_bf16 v[64:67], v[212:215], v[238:241], v[64:67]
	v_mfma_f32_16x16x32_bf16 v[44:47], v[208:211], v[220:223], v[44:47]
	v_mfma_f32_16x16x32_bf16 v[48:51], v[216:219], v[220:223], v[48:51]
	v_mfma_f32_16x16x32_bf16 v[52:55], v[208:211], v[234:237], v[52:55]
	v_mfma_f32_16x16x32_bf16 v[56:59], v[216:219], v[234:237], v[56:59]
	s_setprio 3
	s_barrier
	v_mfma_f32_16x16x32_bf16 v[60:63], v[208:211], v[242:245], v[60:63]
	v_mfma_f32_16x16x32_bf16 v[64:67], v[216:219], v[242:245], v[64:67]
	s_setprio 0
	s_add_i32 s51, s51, s56
	v_lshl_add_u64 v[68:69], v[186:187], 0, s[24:25]
	s_mov_b32 m0, s51
	ds_read_b128 v[104:107], v233 offset:49152
	ds_read_b128 v[108:111], v233 offset:50176
	ds_read_b128 v[112:115], v233 offset:51200
	ds_read_b128 v[220:223], v233 offset:52224
	ds_read_b128 v[224:227], v233 offset:53248
	ds_read_b128 v[234:237], v233 offset:54272
	ds_read_b128 v[238:241], v233 offset:55296
	ds_read_b128 v[242:245], v233 offset:56320
	global_load_lds_dwordx4 v[68:69], off
	v_lshl_add_u64 v[68:69], v[246:247], 0, s[24:25]
	s_add_i32 m0, s51, 0x2000
	s_add_i32 s51, s72, s56
	global_load_lds_dwordx4 v[68:69], off
	s_mov_b32 m0, s51
	v_lshl_add_u64 v[68:69], v[248:249], 0, s[24:25]
	global_load_lds_dwordx4 v2, s[28:29]
	s_add_i32 m0, s51, 0x2000
	s_nop 0
	global_load_lds_dwordx4 v190, s[28:29]
	s_mov_b32 m0, s64
	s_nop 0
	global_load_lds_dwordx4 v[68:69], off
	v_lshl_add_u64 v[68:69], v[250:251], 0, s[24:25]
	s_mov_b32 m0, s65
	s_nop 0
	global_load_lds_dwordx4 v[68:69], off
	s_waitcnt vmcnt(8)
	s_waitcnt lgkmcnt(0)
	s_barrier
	s_setprio 1
	s_waitcnt lgkmcnt(0)
	v_mfma_f32_16x16x32_bf16 v[68:71], v[182:185], v[104:107], v[134:137]
	v_mfma_f32_16x16x32_bf16 v[72:75], v[196:199], v[104:107], v[138:141]
	v_mfma_f32_16x16x32_bf16 v[76:79], v[182:185], v[112:115], v[142:145]
	v_mfma_f32_16x16x32_bf16 v[80:83], v[196:199], v[112:115], v[146:149]
	v_mfma_f32_16x16x32_bf16 v[84:87], v[182:185], v[224:227], v[150:153]
	v_mfma_f32_16x16x32_bf16 v[88:91], v[196:199], v[224:227], v[154:157]
	v_mfma_f32_16x16x32_bf16 v[92:95], v[182:185], v[238:241], v[158:161]
	v_mfma_f32_16x16x32_bf16 v[96:99], v[196:199], v[238:241], v[162:165]
	v_mfma_f32_16x16x32_bf16 v[68:71], v[192:195], v[108:111], v[68:71]
	v_mfma_f32_16x16x32_bf16 v[72:75], v[200:203], v[108:111], v[72:75]
	v_mfma_f32_16x16x32_bf16 v[76:79], v[192:195], v[220:223], v[76:79]
	v_mfma_f32_16x16x32_bf16 v[80:83], v[200:203], v[220:223], v[80:83]
	v_mfma_f32_16x16x32_bf16 v[84:87], v[192:195], v[234:237], v[84:87]
	v_mfma_f32_16x16x32_bf16 v[88:91], v[200:203], v[234:237], v[88:91]
	v_mfma_f32_16x16x32_bf16 v[92:95], v[192:195], v[242:245], v[92:95]
	v_mfma_f32_16x16x32_bf16 v[96:99], v[200:203], v[242:245], v[96:99]
	s_setprio 0
	s_setprio 1
	v_mfma_f32_16x16x32_bf16 v[100:103], v[204:207], v[104:107], v[116:119]
	v_mfma_f32_16x16x32_bf16 v[104:107], v[212:215], v[104:107], v[124:127]
	v_mfma_f32_16x16x32_bf16 v[100:103], v[208:211], v[108:111], v[100:103]
	v_mfma_f32_16x16x32_bf16 v[104:107], v[216:219], v[108:111], v[104:107]
	v_mfma_f32_16x16x32_bf16 v[108:111], v[204:207], v[112:115], v[166:169]
	v_mfma_f32_16x16x32_bf16 v[112:115], v[212:215], v[112:115], v[170:173]
	v_mfma_f32_16x16x32_bf16 v[116:119], v[204:207], v[224:227], v[174:177]
	v_mfma_f32_16x16x32_bf16 v[120:123], v[212:215], v[224:227], v[120:123]
	v_mfma_f32_16x16x32_bf16 v[124:127], v[204:207], v[238:241], v[178:181]
	v_mfma_f32_16x16x32_bf16 v[128:131], v[212:215], v[238:241], v[128:131]
	v_mfma_f32_16x16x32_bf16 v[108:111], v[208:211], v[220:223], v[108:111]
	v_mfma_f32_16x16x32_bf16 v[112:115], v[216:219], v[220:223], v[112:115]
	v_mfma_f32_16x16x32_bf16 v[116:119], v[208:211], v[234:237], v[116:119]
	v_mfma_f32_16x16x32_bf16 v[120:123], v[216:219], v[234:237], v[120:123]
	s_setprio 3
	s_barrier
	v_mfma_f32_16x16x32_bf16 v[124:127], v[208:211], v[242:245], v[124:127]
	v_mfma_f32_16x16x32_bf16 v[128:131], v[216:219], v[242:245], v[128:131]
	s_setprio 0
	s_add_i32 s43, s43, 2
	s_cmp_ge_i32 s43, s42
	s_cbranch_scc0 .LBB0_1625
	v_mov_b32_e32 v192, v2
	s_branch .LBB0_1628

.LBB0_1629:
	s_add_u32 s12, s14, 0xfff80080
	s_addc_u32 s13, s15, -1
	s_add_i32 s29, 0, 0x10000
	s_cmp_eq_u32 s28, 28
	s_cselect_b32 s17, s9, s13
	s_cselect_b32 s16, s8, s12
	s_cselect_b32 s13, s11, s27
	s_cselect_b32 s12, s10, s26
	s_add_i32 s51, 0, 0x14000
	v_add_u32_e32 v144, s29, v232
	v_add_u32_e32 v160, s51, v232
	s_waitcnt lgkmcnt(0)
	ds_read_b128 v[132:135], v144
	ds_read_b128 v[136:139], v144 offset:1024
	ds_read_b128 v[140:143], v144 offset:2048
	ds_read_b128 v[144:147], v144 offset:3072
	ds_read_b128 v[148:151], v160
	ds_read_b128 v[152:155], v160 offset:1024
	ds_read_b128 v[156:159], v160 offset:2048
	ds_read_b128 v[160:163], v160 offset:3072
	s_mov_b32 m0, s66
	v_add_u32_e32 v210, 0, v231
	ds_read_b128 v[164:167], v210
	ds_read_b128 v[168:171], v210 offset:1024
	ds_read_b128 v[172:175], v210 offset:2048
	ds_read_b128 v[176:179], v210 offset:3072
	ds_read_b128 v[180:183], v210 offset:4096
	ds_read_b128 v[184:187], v210 offset:5120
	ds_read_b128 v[194:197], v210 offset:6144
	ds_read_b128 v[198:201], v210 offset:7168
	global_load_lds_dwordx4 v2, s[14:15]
	s_mov_b32 m0, s67
	v_mov_b32_e32 v189, v3
	global_load_lds_dwordx4 v188, s[14:15]
	s_waitcnt vmcnt(8)
	s_waitcnt lgkmcnt(0)
	s_barrier
	s_setprio 1
	s_waitcnt lgkmcnt(0)
	v_mfma_f32_16x16x32_bf16 v[4:7], v[132:135], v[164:167], v[4:7]
	v_mfma_f32_16x16x32_bf16 v[4:7], v[136:139], v[168:171], v[4:7]
	v_mfma_f32_16x16x32_bf16 v[8:11], v[144:147], v[168:171], v[8:11]
	v_mfma_f32_16x16x32_bf16 v[8:11], v[140:143], v[164:167], v[8:11]
	v_mfma_f32_16x16x32_bf16 v[16:19], v[140:143], v[172:175], v[16:19]
	v_mfma_f32_16x16x32_bf16 v[16:19], v[144:147], v[176:179], v[16:19]
	v_mfma_f32_16x16x32_bf16 v[12:15], v[136:139], v[176:179], v[12:15]
	v_mfma_f32_16x16x32_bf16 v[12:15], v[132:135], v[172:175], v[12:15]
	v_mfma_f32_16x16x32_bf16 v[20:23], v[132:135], v[180:183], v[20:23]
	v_mfma_f32_16x16x32_bf16 v[20:23], v[136:139], v[184:187], v[20:23]
	v_mfma_f32_16x16x32_bf16 v[24:27], v[144:147], v[184:187], v[24:27]
	v_mfma_f32_16x16x32_bf16 v[24:27], v[140:143], v[180:183], v[24:27]
	v_mfma_f32_16x16x32_bf16 v[32:35], v[140:143], v[194:197], v[32:35]
	v_mfma_f32_16x16x32_bf16 v[32:35], v[144:147], v[198:201], v[32:35]
	v_mfma_f32_16x16x32_bf16 v[28:31], v[136:139], v[198:201], v[28:31]
	v_mfma_f32_16x16x32_bf16 v[28:31], v[132:135], v[194:197], v[28:31]
	s_setprio 0
	s_setprio 1
	v_mfma_f32_16x16x32_bf16 v[36:39], v[148:151], v[164:167], v[36:39]
	v_mfma_f32_16x16x32_bf16 v[36:39], v[152:155], v[168:171], v[36:39]
	v_mfma_f32_16x16x32_bf16 v[40:43], v[160:163], v[168:171], v[40:43]
	v_mfma_f32_16x16x32_bf16 v[40:43], v[156:159], v[164:167], v[40:43]
	v_mfma_f32_16x16x32_bf16 v[48:51], v[156:159], v[172:175], v[48:51]
	v_mfma_f32_16x16x32_bf16 v[48:51], v[160:163], v[176:179], v[48:51]
	v_mfma_f32_16x16x32_bf16 v[44:47], v[152:155], v[176:179], v[44:47]
	v_mfma_f32_16x16x32_bf16 v[44:47], v[148:151], v[172:175], v[44:47]
	v_mfma_f32_16x16x32_bf16 v[52:55], v[148:151], v[180:183], v[52:55]
	v_mfma_f32_16x16x32_bf16 v[52:55], v[152:155], v[184:187], v[52:55]
	v_mfma_f32_16x16x32_bf16 v[56:59], v[160:163], v[184:187], v[56:59]
	v_mfma_f32_16x16x32_bf16 v[56:59], v[156:159], v[180:183], v[56:59]
	v_mfma_f32_16x16x32_bf16 v[64:67], v[156:159], v[194:197], v[64:67]
	v_mfma_f32_16x16x32_bf16 v[64:67], v[160:163], v[198:201], v[64:67]
	s_setprio 3
	s_barrier
	v_mfma_f32_16x16x32_bf16 v[60:63], v[152:155], v[198:201], v[60:63]
	v_mfma_f32_16x16x32_bf16 v[60:63], v[148:151], v[194:197], v[60:63]
	s_setprio 0
	s_add_i32 s29, s29, s56
	s_mov_b32 m0, s29
	ds_read_b128 v[164:167], v210 offset:16384
	ds_read_b128 v[168:171], v210 offset:17408
	ds_read_b128 v[172:175], v210 offset:18432
	ds_read_b128 v[176:179], v210 offset:19456
	ds_read_b128 v[180:183], v210 offset:20480
	ds_read_b128 v[184:187], v210 offset:21504
	ds_read_b128 v[194:197], v210 offset:22528
	ds_read_b128 v[198:201], v210 offset:23552
	global_load_lds_dwordx4 v192, s[12:13]
	s_add_i32 m0, s29, 0x2000
	s_add_u32 s42, s12, 0x80000
	s_addc_u32 s43, s13, 0
	s_add_i32 s29, s51, s56
	global_load_lds_dwordx4 v190, s[12:13]
	s_mov_b32 m0, s29
	v_mov_b32_e32 v193, v3
	global_load_lds_dwordx4 v192, s[42:43]
	s_add_i32 m0, s29, 0x2000
	v_mov_b32_e32 v191, v3
	global_load_lds_dwordx4 v190, s[42:43]
	s_mov_b32 m0, s57
	v_lshl_add_u64 v[202:203], s[12:13], 0, v[192:193]
	global_load_lds_dwordx4 v2, s[16:17]
	s_mov_b32 m0, s58
	v_lshl_add_u64 v[204:205], s[12:13], 0, v[190:191]
	global_load_lds_dwordx4 v188, s[16:17]
	s_waitcnt vmcnt(8)
	s_waitcnt lgkmcnt(0)
	v_lshl_add_u64 v[206:207], s[16:17], 0, v[2:3]
	v_lshl_add_u64 v[208:209], s[16:17], 0, v[188:189]
	s_barrier
	s_setprio 1
	s_waitcnt lgkmcnt(0)
	v_mfma_f32_16x16x32_bf16 v[68:71], v[132:135], v[164:167], v[68:71]
	v_mfma_f32_16x16x32_bf16 v[68:71], v[136:139], v[168:171], v[68:71]
	v_mfma_f32_16x16x32_bf16 v[72:75], v[144:147], v[168:171], v[72:75]
	v_mfma_f32_16x16x32_bf16 v[72:75], v[140:143], v[164:167], v[72:75]
	v_mfma_f32_16x16x32_bf16 v[80:83], v[140:143], v[172:175], v[80:83]
	v_mfma_f32_16x16x32_bf16 v[80:83], v[144:147], v[176:179], v[80:83]
	v_mfma_f32_16x16x32_bf16 v[76:79], v[136:139], v[176:179], v[76:79]
	v_mfma_f32_16x16x32_bf16 v[76:79], v[132:135], v[172:175], v[76:79]
	v_mfma_f32_16x16x32_bf16 v[84:87], v[132:135], v[180:183], v[84:87]
	v_mfma_f32_16x16x32_bf16 v[84:87], v[136:139], v[184:187], v[84:87]
	v_mfma_f32_16x16x32_bf16 v[88:91], v[144:147], v[184:187], v[88:91]
	v_mfma_f32_16x16x32_bf16 v[88:91], v[140:143], v[180:183], v[88:91]
	v_mfma_f32_16x16x32_bf16 v[96:99], v[140:143], v[194:197], v[96:99]
	v_mfma_f32_16x16x32_bf16 v[96:99], v[144:147], v[198:201], v[96:99]
	v_mfma_f32_16x16x32_bf16 v[92:95], v[136:139], v[198:201], v[92:95]
	v_mfma_f32_16x16x32_bf16 v[92:95], v[132:135], v[194:197], v[92:95]
	s_setprio 0
	s_setprio 1
	v_mfma_f32_16x16x32_bf16 v[100:103], v[148:151], v[164:167], v[100:103]
	v_mfma_f32_16x16x32_bf16 v[100:103], v[152:155], v[168:171], v[100:103]
	v_mfma_f32_16x16x32_bf16 v[104:107], v[160:163], v[168:171], v[104:107]
	v_mfma_f32_16x16x32_bf16 v[104:107], v[156:159], v[164:167], v[104:107]
	v_mfma_f32_16x16x32_bf16 v[112:115], v[156:159], v[172:175], v[112:115]
	v_mfma_f32_16x16x32_bf16 v[112:115], v[160:163], v[176:179], v[112:115]
	v_mfma_f32_16x16x32_bf16 v[108:111], v[152:155], v[176:179], v[108:111]
	v_mfma_f32_16x16x32_bf16 v[108:111], v[148:151], v[172:175], v[108:111]
	v_mfma_f32_16x16x32_bf16 v[116:119], v[148:151], v[180:183], v[116:119]
	v_mfma_f32_16x16x32_bf16 v[116:119], v[152:155], v[184:187], v[116:119]
	v_mfma_f32_16x16x32_bf16 v[120:123], v[160:163], v[184:187], v[120:123]
	v_mfma_f32_16x16x32_bf16 v[120:123], v[156:159], v[180:183], v[120:123]
	v_mfma_f32_16x16x32_bf16 v[128:131], v[156:159], v[194:197], v[128:131]
	v_mfma_f32_16x16x32_bf16 v[128:131], v[160:163], v[198:201], v[128:131]
	s_setprio 3
	s_barrier
	v_mfma_f32_16x16x32_bf16 v[124:127], v[152:155], v[198:201], v[124:127]
	v_mfma_f32_16x16x32_bf16 v[124:127], v[148:151], v[194:197], v[124:127]
	s_setprio 0
	s_add_i32 s29, 0, 0x18000
	s_add_i32 s42, 0, 0x1c000
	v_add_u32_e32 v144, s29, v232
	v_add_u32_e32 v160, s42, v232
	ds_read_b128 v[132:135], v144
	ds_read_b128 v[136:139], v144 offset:1024
	ds_read_b128 v[140:143], v144 offset:2048
	ds_read_b128 v[144:147], v144 offset:3072
	ds_read_b128 v[148:151], v160
	ds_read_b128 v[152:155], v160 offset:1024
	ds_read_b128 v[156:159], v160 offset:2048
	ds_read_b128 v[160:163], v160 offset:3072
	s_add_u32 s16, s16, 0x80000
	s_addc_u32 s17, s17, 0
	s_mov_b32 m0, s59
	ds_read_b128 v[164:167], v210 offset:32768
	ds_read_b128 v[168:171], v210 offset:33792
	ds_read_b128 v[172:175], v210 offset:34816
	ds_read_b128 v[176:179], v210 offset:35840
	ds_read_b128 v[180:183], v210 offset:36864
	ds_read_b128 v[184:187], v210 offset:37888
	ds_read_b128 v[194:197], v210 offset:38912
	ds_read_b128 v[198:201], v210 offset:39936
	global_load_lds_dwordx4 v2, s[16:17]
	s_mov_b32 m0, s60
	s_nop 0
	global_load_lds_dwordx4 v188, s[16:17]
	s_waitcnt vmcnt(8)
	s_waitcnt lgkmcnt(0)
	s_barrier
	s_setprio 1
	s_waitcnt lgkmcnt(0)
	v_mfma_f32_16x16x32_bf16 v[4:7], v[132:135], v[164:167], v[4:7]
	v_mfma_f32_16x16x32_bf16 v[4:7], v[136:139], v[168:171], v[4:7]
	v_mfma_f32_16x16x32_bf16 v[8:11], v[144:147], v[168:171], v[8:11]
	v_mfma_f32_16x16x32_bf16 v[8:11], v[140:143], v[164:167], v[8:11]
	v_mfma_f32_16x16x32_bf16 v[16:19], v[140:143], v[172:175], v[16:19]
	v_mfma_f32_16x16x32_bf16 v[16:19], v[144:147], v[176:179], v[16:19]
	v_mfma_f32_16x16x32_bf16 v[12:15], v[136:139], v[176:179], v[12:15]
	v_mfma_f32_16x16x32_bf16 v[12:15], v[132:135], v[172:175], v[12:15]
	v_mfma_f32_16x16x32_bf16 v[20:23], v[132:135], v[180:183], v[20:23]
	v_mfma_f32_16x16x32_bf16 v[20:23], v[136:139], v[184:187], v[20:23]
	v_mfma_f32_16x16x32_bf16 v[24:27], v[144:147], v[184:187], v[24:27]
	v_mfma_f32_16x16x32_bf16 v[24:27], v[140:143], v[180:183], v[24:27]
	v_mfma_f32_16x16x32_bf16 v[32:35], v[140:143], v[194:197], v[32:35]
	v_mfma_f32_16x16x32_bf16 v[32:35], v[144:147], v[198:201], v[32:35]
	v_mfma_f32_16x16x32_bf16 v[28:31], v[136:139], v[198:201], v[28:31]
	v_mfma_f32_16x16x32_bf16 v[28:31], v[132:135], v[194:197], v[28:31]
	s_setprio 0
	s_setprio 1
	v_mfma_f32_16x16x32_bf16 v[36:39], v[148:151], v[164:167], v[36:39]
	v_mfma_f32_16x16x32_bf16 v[36:39], v[152:155], v[168:171], v[36:39]
	v_mfma_f32_16x16x32_bf16 v[40:43], v[160:163], v[168:171], v[40:43]
	v_mfma_f32_16x16x32_bf16 v[40:43], v[156:159], v[164:167], v[40:43]
	v_mfma_f32_16x16x32_bf16 v[48:51], v[156:159], v[172:175], v[48:51]
	v_mfma_f32_16x16x32_bf16 v[48:51], v[160:163], v[176:179], v[48:51]
	v_mfma_f32_16x16x32_bf16 v[44:47], v[152:155], v[176:179], v[44:47]
	v_mfma_f32_16x16x32_bf16 v[44:47], v[148:151], v[172:175], v[44:47]
	v_mfma_f32_16x16x32_bf16 v[52:55], v[148:151], v[180:183], v[52:55]
	v_mfma_f32_16x16x32_bf16 v[52:55], v[152:155], v[184:187], v[52:55]
	v_mfma_f32_16x16x32_bf16 v[56:59], v[160:163], v[184:187], v[56:59]
	v_mfma_f32_16x16x32_bf16 v[56:59], v[156:159], v[180:183], v[56:59]
	v_mfma_f32_16x16x32_bf16 v[64:67], v[156:159], v[194:197], v[64:67]
	v_mfma_f32_16x16x32_bf16 v[64:67], v[160:163], v[198:201], v[64:67]
	s_setprio 3
	s_barrier
	v_mfma_f32_16x16x32_bf16 v[60:63], v[152:155], v[198:201], v[60:63]
	v_mfma_f32_16x16x32_bf16 v[60:63], v[148:151], v[194:197], v[60:63]
	s_setprio 0
	s_add_i32 s16, s29, s56
	v_lshl_add_u64 v[202:203], v[202:203], 0, s[86:87]
	s_mov_b32 m0, s16
	ds_read_b128 v[164:167], v210 offset:49152
	ds_read_b128 v[168:171], v210 offset:50176
	ds_read_b128 v[172:175], v210 offset:51200
	ds_read_b128 v[176:179], v210 offset:52224
	ds_read_b128 v[180:183], v210 offset:53248
	ds_read_b128 v[184:187], v210 offset:54272
	ds_read_b128 v[194:197], v210 offset:55296
	ds_read_b128 v[198:201], v210 offset:56320
	global_load_lds_dwordx4 v[202:203], off
	s_add_i32 m0, s16, 0x2000
	s_add_u32 s12, s12, 0x80080
	v_lshl_add_u64 v[202:203], v[204:205], 0, s[86:87]
	s_addc_u32 s13, s13, 0
	s_add_i32 s16, s42, s56
	global_load_lds_dwordx4 v[202:203], off
	s_mov_b32 m0, s16
	v_lshl_add_u64 v[202:203], v[206:207], 0, s[86:87]
	global_load_lds_dwordx4 v192, s[12:13]
	s_add_i32 m0, s16, 0x2000
	s_nop 0
	global_load_lds_dwordx4 v190, s[12:13]
	s_mov_b32 m0, s64
	s_nop 0
	global_load_lds_dwordx4 v[202:203], off
	v_lshl_add_u64 v[202:203], v[208:209], 0, s[86:87]
	s_mov_b32 m0, s65
	s_nop 0
	global_load_lds_dwordx4 v[202:203], off
	s_waitcnt vmcnt(8)
	s_waitcnt lgkmcnt(0)
	s_barrier
	s_setprio 1
	s_waitcnt lgkmcnt(0)
	v_mfma_f32_16x16x32_bf16 v[68:71], v[132:135], v[164:167], v[68:71]
	v_mfma_f32_16x16x32_bf16 v[68:71], v[136:139], v[168:171], v[68:71]
	v_mfma_f32_16x16x32_bf16 v[72:75], v[144:147], v[168:171], v[72:75]
	v_mfma_f32_16x16x32_bf16 v[72:75], v[140:143], v[164:167], v[72:75]
	v_mfma_f32_16x16x32_bf16 v[80:83], v[140:143], v[172:175], v[80:83]
	v_mfma_f32_16x16x32_bf16 v[80:83], v[144:147], v[176:179], v[80:83]
	v_mfma_f32_16x16x32_bf16 v[76:79], v[136:139], v[176:179], v[76:79]
	v_mfma_f32_16x16x32_bf16 v[76:79], v[132:135], v[172:175], v[76:79]
	v_mfma_f32_16x16x32_bf16 v[84:87], v[132:135], v[180:183], v[84:87]
	v_mfma_f32_16x16x32_bf16 v[84:87], v[136:139], v[184:187], v[84:87]
	v_mfma_f32_16x16x32_bf16 v[88:91], v[144:147], v[184:187], v[88:91]
	v_mfma_f32_16x16x32_bf16 v[88:91], v[140:143], v[180:183], v[88:91]
	v_mfma_f32_16x16x32_bf16 v[96:99], v[140:143], v[194:197], v[96:99]
	v_mfma_f32_16x16x32_bf16 v[96:99], v[144:147], v[198:201], v[96:99]
	v_mfma_f32_16x16x32_bf16 v[92:95], v[136:139], v[198:201], v[92:95]
	v_mfma_f32_16x16x32_bf16 v[92:95], v[132:135], v[194:197], v[92:95]
	s_setprio 0
	s_setprio 1
	v_mfma_f32_16x16x32_bf16 v[100:103], v[148:151], v[164:167], v[100:103]
	v_mfma_f32_16x16x32_bf16 v[100:103], v[152:155], v[168:171], v[100:103]
	v_mfma_f32_16x16x32_bf16 v[104:107], v[160:163], v[168:171], v[104:107]
	v_mfma_f32_16x16x32_bf16 v[104:107], v[156:159], v[164:167], v[104:107]
	v_mfma_f32_16x16x32_bf16 v[112:115], v[156:159], v[172:175], v[112:115]
	v_mfma_f32_16x16x32_bf16 v[112:115], v[160:163], v[176:179], v[112:115]
	v_mfma_f32_16x16x32_bf16 v[108:111], v[152:155], v[176:179], v[108:111]
	v_mfma_f32_16x16x32_bf16 v[108:111], v[148:151], v[172:175], v[108:111]
	v_mfma_f32_16x16x32_bf16 v[116:119], v[148:151], v[180:183], v[116:119]
	v_mfma_f32_16x16x32_bf16 v[116:119], v[152:155], v[184:187], v[116:119]
	v_mfma_f32_16x16x32_bf16 v[120:123], v[160:163], v[184:187], v[120:123]
	v_mfma_f32_16x16x32_bf16 v[120:123], v[156:159], v[180:183], v[120:123]
	v_mfma_f32_16x16x32_bf16 v[128:131], v[156:159], v[194:197], v[128:131]
	v_mfma_f32_16x16x32_bf16 v[128:131], v[160:163], v[198:201], v[128:131]
	s_setprio 3
	s_barrier
	v_mfma_f32_16x16x32_bf16 v[124:127], v[152:155], v[198:201], v[124:127]
	v_mfma_f32_16x16x32_bf16 v[124:127], v[148:151], v[194:197], v[124:127]
	s_setprio 0
	s_add_i32 s28, s28, 2
	s_add_u32 s14, s14, 0x100
	s_addc_u32 s15, s15, 0
	s_add_u32 s26, s26, 0x100
	s_addc_u32 s27, s27, 0
	s_cmp_gt_u32 s28, 29
	s_cbranch_scc0 .LBB0_1629
	s_and_b64 vcc, exec, s[48:49]
	s_cbranch_vccz .LBB0_1632
	s_barrier

.LBB0_2065:
	s_add_i32 s51, 0, 0x10000
	s_add_i32 s71, 0, 0x14000
	v_add_u32_e32 v16, s51, v232
	v_add_u32_e32 v32, s71, v232
	ds_read_b128 v[4:7], v16
	ds_read_b128 v[8:11], v16 offset:1024
	ds_read_b128 v[12:15], v16 offset:2048
	ds_read_b128 v[16:19], v16 offset:3072
	ds_read_b128 v[20:23], v32
	ds_read_b128 v[24:27], v32 offset:1024
	ds_read_b128 v[28:31], v32 offset:2048
	ds_read_b128 v[32:35], v32 offset:3072
	v_add_u32_e32 v233, 0, v231
	ds_read_b128 v[36:39], v233
	ds_read_b128 v[40:43], v233 offset:1024
	ds_read_b128 v[44:47], v233 offset:2048
	ds_read_b128 v[48:51], v233 offset:3072
	ds_read_b128 v[52:55], v233 offset:4096
	ds_read_b128 v[56:59], v233 offset:5120
	ds_read_b128 v[60:63], v233 offset:6144
	ds_read_b128 v[64:67], v233 offset:7168
	s_waitcnt vmcnt(8)
	s_waitcnt lgkmcnt(0)
	s_barrier
	s_setprio 1
	s_waitcnt lgkmcnt(0)
	v_mfma_f32_16x16x32_bf16 v[68:71], v[4:7], v[36:39], 0
	v_mfma_f32_16x16x32_bf16 v[68:71], v[8:11], v[40:43], v[68:71]
	v_mfma_f32_16x16x32_bf16 v[72:75], v[12:15], v[36:39], 0
	v_mfma_f32_16x16x32_bf16 v[72:75], v[16:19], v[40:43], v[72:75]
	v_mfma_f32_16x16x32_bf16 v[80:83], v[12:15], v[44:47], 0
	v_mfma_f32_16x16x32_bf16 v[80:83], v[16:19], v[48:51], v[80:83]
	v_mfma_f32_16x16x32_bf16 v[76:79], v[4:7], v[44:47], 0
	v_mfma_f32_16x16x32_bf16 v[76:79], v[8:11], v[48:51], v[76:79]
	v_mfma_f32_16x16x32_bf16 v[84:87], v[4:7], v[52:55], 0
	v_mfma_f32_16x16x32_bf16 v[84:87], v[8:11], v[56:59], v[84:87]
	v_mfma_f32_16x16x32_bf16 v[88:91], v[12:15], v[52:55], 0
	v_mfma_f32_16x16x32_bf16 v[88:91], v[16:19], v[56:59], v[88:91]
	v_mfma_f32_16x16x32_bf16 v[96:99], v[12:15], v[60:63], 0
	v_mfma_f32_16x16x32_bf16 v[96:99], v[16:19], v[64:67], v[96:99]
	v_mfma_f32_16x16x32_bf16 v[92:95], v[4:7], v[60:63], 0
	v_mfma_f32_16x16x32_bf16 v[92:95], v[8:11], v[64:67], v[92:95]
	s_setprio 0
	s_setprio 1
	v_mfma_f32_16x16x32_bf16 v[100:103], v[20:23], v[36:39], 0
	v_mfma_f32_16x16x32_bf16 v[36:39], v[28:31], v[36:39], 0
	v_mfma_f32_16x16x32_bf16 v[104:107], v[20:23], v[44:47], 0
	v_mfma_f32_16x16x32_bf16 v[44:47], v[28:31], v[44:47], 0
	v_mfma_f32_16x16x32_bf16 v[108:111], v[20:23], v[52:55], 0
	v_mfma_f32_16x16x32_bf16 v[52:55], v[28:31], v[52:55], 0
	v_mfma_f32_16x16x32_bf16 v[112:115], v[20:23], v[60:63], 0
	v_mfma_f32_16x16x32_bf16 v[60:63], v[28:31], v[60:63], 0
	v_mfma_f32_16x16x32_bf16 v[100:103], v[24:27], v[40:43], v[100:103]
	v_mfma_f32_16x16x32_bf16 v[40:43], v[32:35], v[40:43], v[36:39]
	v_mfma_f32_16x16x32_bf16 v[104:107], v[24:27], v[48:51], v[104:107]
	v_mfma_f32_16x16x32_bf16 v[48:51], v[32:35], v[48:51], v[44:47]
	v_mfma_f32_16x16x32_bf16 v[108:111], v[24:27], v[56:59], v[108:111]
	v_mfma_f32_16x16x32_bf16 v[56:59], v[32:35], v[56:59], v[52:55]
	s_setprio 3
	s_barrier
	v_mfma_f32_16x16x32_bf16 v[112:115], v[24:27], v[64:67], v[112:115]
	v_mfma_f32_16x16x32_bf16 v[64:67], v[32:35], v[64:67], v[60:63]
	s_setprio 0
	v_lshl_add_u64 v[186:187], s[12:13], 0, v[2:3]
	s_add_i32 s51, s51, s38
	v_mov_b32_e32 v191, v3
	v_lshl_add_u64 v[134:135], v[186:187], 0, s[74:75]
	s_mov_b32 m0, s51
	v_lshl_add_u64 v[246:247], s[12:13], 0, v[190:191]
	ds_read_b128 v[36:39], v233 offset:16384
	ds_read_b128 v[44:47], v233 offset:17408
	ds_read_b128 v[52:55], v233 offset:18432
	ds_read_b128 v[60:63], v233 offset:19456
	ds_read_b128 v[116:119], v233 offset:20480
	ds_read_b128 v[120:123], v233 offset:21504
	ds_read_b128 v[124:127], v233 offset:22528
	ds_read_b128 v[128:131], v233 offset:23552
	global_load_lds_dwordx4 v[134:135], off
	v_lshl_add_u64 v[134:135], v[246:247], 0, s[74:75]
	s_add_i32 m0, s51, 0x2000
	s_add_i32 s51, s71, s38
	global_load_lds_dwordx4 v[134:135], off
	s_mov_b32 m0, s51
	v_mov_b32_e32 v133, v3
	global_load_lds_dwordx4 v2, s[16:17]
	s_add_i32 m0, s51, 0x2000
	v_lshl_add_u64 v[248:249], s[14:15], 0, v[132:133]
	v_mov_b32_e32 v189, v3
	global_load_lds_dwordx4 v190, s[16:17]
	v_lshl_add_u64 v[134:135], v[248:249], 0, s[74:75]
	s_mov_b32 m0, s56
	v_lshl_add_u64 v[250:251], s[14:15], 0, v[188:189]
	global_load_lds_dwordx4 v[134:135], off
	v_lshl_add_u64 v[134:135], v[250:251], 0, s[74:75]
	s_mov_b32 m0, s57
	s_nop 0
	global_load_lds_dwordx4 v[134:135], off
	s_waitcnt vmcnt(8)
	s_waitcnt lgkmcnt(0)
	s_barrier
	s_setprio 1
	s_waitcnt lgkmcnt(0)
	v_mfma_f32_16x16x32_bf16 v[134:137], v[4:7], v[36:39], 0
	v_mfma_f32_16x16x32_bf16 v[138:141], v[12:15], v[36:39], 0
	v_mfma_f32_16x16x32_bf16 v[142:145], v[4:7], v[52:55], 0
	v_mfma_f32_16x16x32_bf16 v[146:149], v[12:15], v[52:55], 0
	v_mfma_f32_16x16x32_bf16 v[150:153], v[4:7], v[116:119], 0
	v_mfma_f32_16x16x32_bf16 v[154:157], v[12:15], v[116:119], 0
	v_mfma_f32_16x16x32_bf16 v[4:7], v[4:7], v[124:127], 0
	v_mfma_f32_16x16x32_bf16 v[12:15], v[12:15], v[124:127], 0
	v_mfma_f32_16x16x32_bf16 v[134:137], v[8:11], v[44:47], v[134:137]
	v_mfma_f32_16x16x32_bf16 v[138:141], v[16:19], v[44:47], v[138:141]
	v_mfma_f32_16x16x32_bf16 v[142:145], v[8:11], v[60:63], v[142:145]
	v_mfma_f32_16x16x32_bf16 v[146:149], v[16:19], v[60:63], v[146:149]
	v_mfma_f32_16x16x32_bf16 v[150:153], v[8:11], v[120:123], v[150:153]
	v_mfma_f32_16x16x32_bf16 v[154:157], v[16:19], v[120:123], v[154:157]
	v_mfma_f32_16x16x32_bf16 v[158:161], v[8:11], v[128:131], v[4:7]
	v_mfma_f32_16x16x32_bf16 v[162:165], v[16:19], v[128:131], v[12:15]
	s_setprio 0
	s_setprio 1
	v_mfma_f32_16x16x32_bf16 v[4:7], v[20:23], v[36:39], 0
	v_mfma_f32_16x16x32_bf16 v[8:11], v[28:31], v[36:39], 0
	v_mfma_f32_16x16x32_bf16 v[12:15], v[20:23], v[52:55], 0
	v_mfma_f32_16x16x32_bf16 v[16:19], v[28:31], v[52:55], 0
	v_mfma_f32_16x16x32_bf16 v[36:39], v[20:23], v[116:119], 0
	v_mfma_f32_16x16x32_bf16 v[52:55], v[28:31], v[116:119], 0
	v_mfma_f32_16x16x32_bf16 v[20:23], v[20:23], v[124:127], 0
	v_mfma_f32_16x16x32_bf16 v[28:31], v[28:31], v[124:127], 0
	v_mfma_f32_16x16x32_bf16 v[116:119], v[24:27], v[44:47], v[4:7]
	v_mfma_f32_16x16x32_bf16 v[124:127], v[32:35], v[44:47], v[8:11]
	v_mfma_f32_16x16x32_bf16 v[174:177], v[24:27], v[120:123], v[36:39]
	v_mfma_f32_16x16x32_bf16 v[120:123], v[32:35], v[120:123], v[52:55]
	v_mfma_f32_16x16x32_bf16 v[178:181], v[24:27], v[128:131], v[20:23]
	v_mfma_f32_16x16x32_bf16 v[128:131], v[32:35], v[128:131], v[28:31]
	s_setprio 3
	s_barrier
	v_mfma_f32_16x16x32_bf16 v[166:169], v[24:27], v[60:63], v[12:15]
	v_mfma_f32_16x16x32_bf16 v[170:173], v[32:35], v[60:63], v[16:19]
	s_setprio 0
	s_add_i32 s51, 0, 0x18000
	v_add_u32_e32 v4, s51, v232
	s_add_i32 s71, 0, 0x1c000
	ds_read_b128 v[182:185], v4
	ds_read_b128 v[192:195], v4 offset:1024
	ds_read_b128 v[196:199], v4 offset:2048
	ds_read_b128 v[200:203], v4 offset:3072
	v_add_u32_e32 v4, s71, v232
	ds_read_b128 v[204:207], v4
	ds_read_b128 v[208:211], v4 offset:1024
	ds_read_b128 v[212:215], v4 offset:2048
	ds_read_b128 v[216:219], v4 offset:3072
	s_mov_b32 m0, s58
	ds_read_b128 v[44:47], v233 offset:32768
	ds_read_b128 v[52:55], v233 offset:33792
	ds_read_b128 v[60:63], v233 offset:34816
	ds_read_b128 v[220:223], v233 offset:35840
	ds_read_b128 v[224:227], v233 offset:36864
	ds_read_b128 v[234:237], v233 offset:37888
	ds_read_b128 v[238:241], v233 offset:38912
	ds_read_b128 v[242:245], v233 offset:39936
	global_load_lds_dwordx4 v132, s[26:27]
	s_mov_b32 m0, s59
	s_nop 0
	global_load_lds_dwordx4 v188, s[26:27]
	s_waitcnt vmcnt(8)
	s_waitcnt lgkmcnt(0)
	s_barrier
	s_setprio 1
	s_waitcnt lgkmcnt(0)
	v_mfma_f32_16x16x32_bf16 v[4:7], v[182:185], v[44:47], v[68:71]
	v_mfma_f32_16x16x32_bf16 v[8:11], v[196:199], v[44:47], v[72:75]
	v_mfma_f32_16x16x32_bf16 v[12:15], v[182:185], v[60:63], v[76:79]
	v_mfma_f32_16x16x32_bf16 v[16:19], v[196:199], v[60:63], v[80:83]
	v_mfma_f32_16x16x32_bf16 v[20:23], v[182:185], v[224:227], v[84:87]
	v_mfma_f32_16x16x32_bf16 v[24:27], v[196:199], v[224:227], v[88:91]
	v_mfma_f32_16x16x32_bf16 v[28:31], v[182:185], v[238:241], v[92:95]
	v_mfma_f32_16x16x32_bf16 v[32:35], v[196:199], v[238:241], v[96:99]
	v_mfma_f32_16x16x32_bf16 v[4:7], v[192:195], v[52:55], v[4:7]
	v_mfma_f32_16x16x32_bf16 v[8:11], v[200:203], v[52:55], v[8:11]
	v_mfma_f32_16x16x32_bf16 v[12:15], v[192:195], v[220:223], v[12:15]
	v_mfma_f32_16x16x32_bf16 v[16:19], v[200:203], v[220:223], v[16:19]
	v_mfma_f32_16x16x32_bf16 v[20:23], v[192:195], v[234:237], v[20:23]
	v_mfma_f32_16x16x32_bf16 v[24:27], v[200:203], v[234:237], v[24:27]
	v_mfma_f32_16x16x32_bf16 v[28:31], v[192:195], v[242:245], v[28:31]
	v_mfma_f32_16x16x32_bf16 v[32:35], v[200:203], v[242:245], v[32:35]
	s_setprio 0
	s_setprio 1
	v_mfma_f32_16x16x32_bf16 v[36:39], v[204:207], v[44:47], v[100:103]
	v_mfma_f32_16x16x32_bf16 v[40:43], v[212:215], v[44:47], v[40:43]
	v_mfma_f32_16x16x32_bf16 v[36:39], v[208:211], v[52:55], v[36:39]
	v_mfma_f32_16x16x32_bf16 v[40:43], v[216:219], v[52:55], v[40:43]
	v_mfma_f32_16x16x32_bf16 v[44:47], v[204:207], v[60:63], v[104:107]
	v_mfma_f32_16x16x32_bf16 v[48:51], v[212:215], v[60:63], v[48:51]
	v_mfma_f32_16x16x32_bf16 v[52:55], v[204:207], v[224:227], v[108:111]
	v_mfma_f32_16x16x32_bf16 v[56:59], v[212:215], v[224:227], v[56:59]
	v_mfma_f32_16x16x32_bf16 v[60:63], v[204:207], v[238:241], v[112:115]
	v_mfma_f32_16x16x32_bf16 v[64:67], v[212:215], v[238:241], v[64:67]
	v_mfma_f32_16x16x32_bf16 v[44:47], v[208:211], v[220:223], v[44:47]
	v_mfma_f32_16x16x32_bf16 v[48:51], v[216:219], v[220:223], v[48:51]
	v_mfma_f32_16x16x32_bf16 v[52:55], v[208:211], v[234:237], v[52:55]
	v_mfma_f32_16x16x32_bf16 v[56:59], v[216:219], v[234:237], v[56:59]
	s_setprio 3
	s_barrier
	v_mfma_f32_16x16x32_bf16 v[60:63], v[208:211], v[242:245], v[60:63]
	v_mfma_f32_16x16x32_bf16 v[64:67], v[216:219], v[242:245], v[64:67]
	s_setprio 0
	s_add_i32 s51, s51, s38
	v_lshl_add_u64 v[68:69], v[186:187], 0, s[24:25]
	s_mov_b32 m0, s51
	ds_read_b128 v[104:107], v233 offset:49152
	ds_read_b128 v[108:111], v233 offset:50176
	ds_read_b128 v[112:115], v233 offset:51200
	ds_read_b128 v[220:223], v233 offset:52224
	ds_read_b128 v[224:227], v233 offset:53248
	ds_read_b128 v[234:237], v233 offset:54272
	ds_read_b128 v[238:241], v233 offset:55296
	ds_read_b128 v[242:245], v233 offset:56320
	global_load_lds_dwordx4 v[68:69], off
	v_lshl_add_u64 v[68:69], v[246:247], 0, s[24:25]
	s_add_i32 m0, s51, 0x2000
	s_add_i32 s51, s71, s38
	global_load_lds_dwordx4 v[68:69], off
	s_mov_b32 m0, s51
	v_lshl_add_u64 v[68:69], v[248:249], 0, s[24:25]
	global_load_lds_dwordx4 v2, s[28:29]
	s_add_i32 m0, s51, 0x2000
	s_nop 0
	global_load_lds_dwordx4 v190, s[28:29]
	s_mov_b32 m0, s63
	s_nop 0
	global_load_lds_dwordx4 v[68:69], off
	v_lshl_add_u64 v[68:69], v[250:251], 0, s[24:25]
	s_mov_b32 m0, s64
	s_nop 0
	global_load_lds_dwordx4 v[68:69], off
	s_waitcnt vmcnt(8)
	s_waitcnt lgkmcnt(0)
	s_barrier
	s_setprio 1
	s_waitcnt lgkmcnt(0)
	v_mfma_f32_16x16x32_bf16 v[68:71], v[182:185], v[104:107], v[134:137]
	v_mfma_f32_16x16x32_bf16 v[72:75], v[196:199], v[104:107], v[138:141]
	v_mfma_f32_16x16x32_bf16 v[76:79], v[182:185], v[112:115], v[142:145]
	v_mfma_f32_16x16x32_bf16 v[80:83], v[196:199], v[112:115], v[146:149]
	v_mfma_f32_16x16x32_bf16 v[84:87], v[182:185], v[224:227], v[150:153]
	v_mfma_f32_16x16x32_bf16 v[88:91], v[196:199], v[224:227], v[154:157]
	v_mfma_f32_16x16x32_bf16 v[92:95], v[182:185], v[238:241], v[158:161]
	v_mfma_f32_16x16x32_bf16 v[96:99], v[196:199], v[238:241], v[162:165]
	v_mfma_f32_16x16x32_bf16 v[68:71], v[192:195], v[108:111], v[68:71]
	v_mfma_f32_16x16x32_bf16 v[72:75], v[200:203], v[108:111], v[72:75]
	v_mfma_f32_16x16x32_bf16 v[76:79], v[192:195], v[220:223], v[76:79]
	v_mfma_f32_16x16x32_bf16 v[80:83], v[200:203], v[220:223], v[80:83]
	v_mfma_f32_16x16x32_bf16 v[84:87], v[192:195], v[234:237], v[84:87]
	v_mfma_f32_16x16x32_bf16 v[88:91], v[200:203], v[234:237], v[88:91]
	v_mfma_f32_16x16x32_bf16 v[92:95], v[192:195], v[242:245], v[92:95]
	v_mfma_f32_16x16x32_bf16 v[96:99], v[200:203], v[242:245], v[96:99]
	s_setprio 0
	s_setprio 1
	v_mfma_f32_16x16x32_bf16 v[100:103], v[204:207], v[104:107], v[116:119]
	v_mfma_f32_16x16x32_bf16 v[104:107], v[212:215], v[104:107], v[124:127]
	v_mfma_f32_16x16x32_bf16 v[100:103], v[208:211], v[108:111], v[100:103]
	v_mfma_f32_16x16x32_bf16 v[104:107], v[216:219], v[108:111], v[104:107]
	v_mfma_f32_16x16x32_bf16 v[108:111], v[204:207], v[112:115], v[166:169]
	v_mfma_f32_16x16x32_bf16 v[112:115], v[212:215], v[112:115], v[170:173]
	v_mfma_f32_16x16x32_bf16 v[116:119], v[204:207], v[224:227], v[174:177]
	v_mfma_f32_16x16x32_bf16 v[120:123], v[212:215], v[224:227], v[120:123]
	v_mfma_f32_16x16x32_bf16 v[124:127], v[204:207], v[238:241], v[178:181]
	v_mfma_f32_16x16x32_bf16 v[128:131], v[212:215], v[238:241], v[128:131]
	v_mfma_f32_16x16x32_bf16 v[108:111], v[208:211], v[220:223], v[108:111]
	v_mfma_f32_16x16x32_bf16 v[112:115], v[216:219], v[220:223], v[112:115]
	v_mfma_f32_16x16x32_bf16 v[116:119], v[208:211], v[234:237], v[116:119]
	v_mfma_f32_16x16x32_bf16 v[120:123], v[216:219], v[234:237], v[120:123]
	s_setprio 3
	s_barrier
	v_mfma_f32_16x16x32_bf16 v[124:127], v[208:211], v[242:245], v[124:127]
	v_mfma_f32_16x16x32_bf16 v[128:131], v[216:219], v[242:245], v[128:131]
	s_setprio 0
	s_add_i32 s45, s45, 2
	s_cmp_ge_i32 s45, s44
	s_cbranch_scc0 .LBB0_2065
	v_mov_b32_e32 v192, v2
	s_branch .LBB0_2068

.LBB0_2069:
	s_add_u32 s12, s14, 0xfff80080
	s_addc_u32 s13, s15, -1
	s_add_i32 s29, 0, 0x10000
	s_cmp_eq_u32 s28, 4
	s_cselect_b32 s17, s9, s13
	s_cselect_b32 s16, s8, s12
	s_cselect_b32 s13, s11, s27
	s_cselect_b32 s12, s10, s26
	s_add_i32 s51, 0, 0x14000
	v_add_u32_e32 v144, s29, v232
	v_add_u32_e32 v160, s51, v232
	s_waitcnt lgkmcnt(0)
	ds_read_b128 v[132:135], v144
	ds_read_b128 v[136:139], v144 offset:1024
	ds_read_b128 v[140:143], v144 offset:2048
	ds_read_b128 v[144:147], v144 offset:3072
	ds_read_b128 v[148:151], v160
	ds_read_b128 v[152:155], v160 offset:1024
	ds_read_b128 v[156:159], v160 offset:2048
	ds_read_b128 v[160:163], v160 offset:3072
	s_mov_b32 m0, s65
	v_add_u32_e32 v210, 0, v231
	ds_read_b128 v[164:167], v210
	ds_read_b128 v[168:171], v210 offset:1024
	ds_read_b128 v[172:175], v210 offset:2048
	ds_read_b128 v[176:179], v210 offset:3072
	ds_read_b128 v[180:183], v210 offset:4096
	ds_read_b128 v[184:187], v210 offset:5120
	ds_read_b128 v[194:197], v210 offset:6144
	ds_read_b128 v[198:201], v210 offset:7168
	global_load_lds_dwordx4 v2, s[14:15]
	s_mov_b32 m0, s66
	v_mov_b32_e32 v189, v3
	global_load_lds_dwordx4 v188, s[14:15]
	s_waitcnt vmcnt(8)
	s_waitcnt lgkmcnt(0)
	s_barrier
	s_setprio 1
	s_waitcnt lgkmcnt(0)
	v_mfma_f32_16x16x32_bf16 v[4:7], v[132:135], v[164:167], v[4:7]
	v_mfma_f32_16x16x32_bf16 v[4:7], v[136:139], v[168:171], v[4:7]
	v_mfma_f32_16x16x32_bf16 v[8:11], v[144:147], v[168:171], v[8:11]
	v_mfma_f32_16x16x32_bf16 v[8:11], v[140:143], v[164:167], v[8:11]
	v_mfma_f32_16x16x32_bf16 v[16:19], v[140:143], v[172:175], v[16:19]
	v_mfma_f32_16x16x32_bf16 v[16:19], v[144:147], v[176:179], v[16:19]
	v_mfma_f32_16x16x32_bf16 v[12:15], v[136:139], v[176:179], v[12:15]
	v_mfma_f32_16x16x32_bf16 v[12:15], v[132:135], v[172:175], v[12:15]
	v_mfma_f32_16x16x32_bf16 v[20:23], v[132:135], v[180:183], v[20:23]
	v_mfma_f32_16x16x32_bf16 v[20:23], v[136:139], v[184:187], v[20:23]
	v_mfma_f32_16x16x32_bf16 v[24:27], v[144:147], v[184:187], v[24:27]
	v_mfma_f32_16x16x32_bf16 v[24:27], v[140:143], v[180:183], v[24:27]
	v_mfma_f32_16x16x32_bf16 v[32:35], v[140:143], v[194:197], v[32:35]
	v_mfma_f32_16x16x32_bf16 v[32:35], v[144:147], v[198:201], v[32:35]
	v_mfma_f32_16x16x32_bf16 v[28:31], v[136:139], v[198:201], v[28:31]
	v_mfma_f32_16x16x32_bf16 v[28:31], v[132:135], v[194:197], v[28:31]
	s_setprio 0
	s_setprio 1
	v_mfma_f32_16x16x32_bf16 v[36:39], v[148:151], v[164:167], v[36:39]
	v_mfma_f32_16x16x32_bf16 v[36:39], v[152:155], v[168:171], v[36:39]
	v_mfma_f32_16x16x32_bf16 v[40:43], v[160:163], v[168:171], v[40:43]
	v_mfma_f32_16x16x32_bf16 v[40:43], v[156:159], v[164:167], v[40:43]
	v_mfma_f32_16x16x32_bf16 v[48:51], v[156:159], v[172:175], v[48:51]
	v_mfma_f32_16x16x32_bf16 v[48:51], v[160:163], v[176:179], v[48:51]
	v_mfma_f32_16x16x32_bf16 v[44:47], v[152:155], v[176:179], v[44:47]
	v_mfma_f32_16x16x32_bf16 v[44:47], v[148:151], v[172:175], v[44:47]
	v_mfma_f32_16x16x32_bf16 v[52:55], v[148:151], v[180:183], v[52:55]
	v_mfma_f32_16x16x32_bf16 v[52:55], v[152:155], v[184:187], v[52:55]
	v_mfma_f32_16x16x32_bf16 v[56:59], v[160:163], v[184:187], v[56:59]
	v_mfma_f32_16x16x32_bf16 v[56:59], v[156:159], v[180:183], v[56:59]
	v_mfma_f32_16x16x32_bf16 v[64:67], v[156:159], v[194:197], v[64:67]
	v_mfma_f32_16x16x32_bf16 v[64:67], v[160:163], v[198:201], v[64:67]
	s_setprio 3
	s_barrier
	v_mfma_f32_16x16x32_bf16 v[60:63], v[152:155], v[198:201], v[60:63]
	v_mfma_f32_16x16x32_bf16 v[60:63], v[148:151], v[194:197], v[60:63]
	s_setprio 0
	s_add_i32 s29, s29, s38
	s_mov_b32 m0, s29
	ds_read_b128 v[164:167], v210 offset:16384
	ds_read_b128 v[168:171], v210 offset:17408
	ds_read_b128 v[172:175], v210 offset:18432
	ds_read_b128 v[176:179], v210 offset:19456
	ds_read_b128 v[180:183], v210 offset:20480
	ds_read_b128 v[184:187], v210 offset:21504
	ds_read_b128 v[194:197], v210 offset:22528
	ds_read_b128 v[198:201], v210 offset:23552
	global_load_lds_dwordx4 v192, s[12:13]
	s_add_i32 m0, s29, 0x2000
	s_add_u32 s44, s12, 0x20000
	s_addc_u32 s45, s13, 0
	s_add_i32 s29, s51, s38
	global_load_lds_dwordx4 v190, s[12:13]
	s_mov_b32 m0, s29
	v_mov_b32_e32 v193, v3
	global_load_lds_dwordx4 v192, s[44:45]
	s_add_i32 m0, s29, 0x2000
	v_mov_b32_e32 v191, v3
	global_load_lds_dwordx4 v190, s[44:45]
	s_mov_b32 m0, s56
	v_lshl_add_u64 v[202:203], s[12:13], 0, v[192:193]
	global_load_lds_dwordx4 v2, s[16:17]
	s_mov_b32 m0, s57
	v_lshl_add_u64 v[204:205], s[12:13], 0, v[190:191]
	global_load_lds_dwordx4 v188, s[16:17]
	s_waitcnt vmcnt(8)
	s_waitcnt lgkmcnt(0)
	v_lshl_add_u64 v[206:207], s[16:17], 0, v[2:3]
	v_lshl_add_u64 v[208:209], s[16:17], 0, v[188:189]
	s_barrier
	s_setprio 1
	s_waitcnt lgkmcnt(0)
	v_mfma_f32_16x16x32_bf16 v[68:71], v[132:135], v[164:167], v[68:71]
	v_mfma_f32_16x16x32_bf16 v[68:71], v[136:139], v[168:171], v[68:71]
	v_mfma_f32_16x16x32_bf16 v[72:75], v[144:147], v[168:171], v[72:75]
	v_mfma_f32_16x16x32_bf16 v[72:75], v[140:143], v[164:167], v[72:75]
	v_mfma_f32_16x16x32_bf16 v[80:83], v[140:143], v[172:175], v[80:83]
	v_mfma_f32_16x16x32_bf16 v[80:83], v[144:147], v[176:179], v[80:83]
	v_mfma_f32_16x16x32_bf16 v[76:79], v[136:139], v[176:179], v[76:79]
	v_mfma_f32_16x16x32_bf16 v[76:79], v[132:135], v[172:175], v[76:79]
	v_mfma_f32_16x16x32_bf16 v[84:87], v[132:135], v[180:183], v[84:87]
	v_mfma_f32_16x16x32_bf16 v[84:87], v[136:139], v[184:187], v[84:87]
	v_mfma_f32_16x16x32_bf16 v[88:91], v[144:147], v[184:187], v[88:91]
	v_mfma_f32_16x16x32_bf16 v[88:91], v[140:143], v[180:183], v[88:91]
	v_mfma_f32_16x16x32_bf16 v[96:99], v[140:143], v[194:197], v[96:99]
	v_mfma_f32_16x16x32_bf16 v[96:99], v[144:147], v[198:201], v[96:99]
	v_mfma_f32_16x16x32_bf16 v[92:95], v[136:139], v[198:201], v[92:95]
	v_mfma_f32_16x16x32_bf16 v[92:95], v[132:135], v[194:197], v[92:95]
	s_setprio 0
	s_setprio 1
	v_mfma_f32_16x16x32_bf16 v[100:103], v[148:151], v[164:167], v[100:103]
	v_mfma_f32_16x16x32_bf16 v[100:103], v[152:155], v[168:171], v[100:103]
	v_mfma_f32_16x16x32_bf16 v[104:107], v[160:163], v[168:171], v[104:107]
	v_mfma_f32_16x16x32_bf16 v[104:107], v[156:159], v[164:167], v[104:107]
	v_mfma_f32_16x16x32_bf16 v[112:115], v[156:159], v[172:175], v[112:115]
	v_mfma_f32_16x16x32_bf16 v[112:115], v[160:163], v[176:179], v[112:115]
	v_mfma_f32_16x16x32_bf16 v[108:111], v[152:155], v[176:179], v[108:111]
	v_mfma_f32_16x16x32_bf16 v[108:111], v[148:151], v[172:175], v[108:111]
	v_mfma_f32_16x16x32_bf16 v[116:119], v[148:151], v[180:183], v[116:119]
	v_mfma_f32_16x16x32_bf16 v[116:119], v[152:155], v[184:187], v[116:119]
	v_mfma_f32_16x16x32_bf16 v[120:123], v[160:163], v[184:187], v[120:123]
	v_mfma_f32_16x16x32_bf16 v[120:123], v[156:159], v[180:183], v[120:123]
	v_mfma_f32_16x16x32_bf16 v[128:131], v[156:159], v[194:197], v[128:131]
	v_mfma_f32_16x16x32_bf16 v[128:131], v[160:163], v[198:201], v[128:131]
	s_setprio 3
	s_barrier
	v_mfma_f32_16x16x32_bf16 v[124:127], v[152:155], v[198:201], v[124:127]
	v_mfma_f32_16x16x32_bf16 v[124:127], v[148:151], v[194:197], v[124:127]
	s_setprio 0
	s_add_i32 s29, 0, 0x18000
	s_add_i32 s44, 0, 0x1c000
	v_add_u32_e32 v144, s29, v232
	v_add_u32_e32 v160, s44, v232
	ds_read_b128 v[132:135], v144
	ds_read_b128 v[136:139], v144 offset:1024
	ds_read_b128 v[140:143], v144 offset:2048
	ds_read_b128 v[144:147], v144 offset:3072
	ds_read_b128 v[148:151], v160
	ds_read_b128 v[152:155], v160 offset:1024
	ds_read_b128 v[156:159], v160 offset:2048
	ds_read_b128 v[160:163], v160 offset:3072
	s_add_u32 s16, s16, 0x80000
	s_addc_u32 s17, s17, 0
	s_mov_b32 m0, s58
	ds_read_b128 v[164:167], v210 offset:32768
	ds_read_b128 v[168:171], v210 offset:33792
	ds_read_b128 v[172:175], v210 offset:34816
	ds_read_b128 v[176:179], v210 offset:35840
	ds_read_b128 v[180:183], v210 offset:36864
	ds_read_b128 v[184:187], v210 offset:37888
	ds_read_b128 v[194:197], v210 offset:38912
	ds_read_b128 v[198:201], v210 offset:39936
	global_load_lds_dwordx4 v2, s[16:17]
	s_mov_b32 m0, s59
	s_nop 0
	global_load_lds_dwordx4 v188, s[16:17]
	s_waitcnt vmcnt(8)
	s_waitcnt lgkmcnt(0)
	s_barrier
	s_setprio 1
	s_waitcnt lgkmcnt(0)
	v_mfma_f32_16x16x32_bf16 v[4:7], v[132:135], v[164:167], v[4:7]
	v_mfma_f32_16x16x32_bf16 v[4:7], v[136:139], v[168:171], v[4:7]
	v_mfma_f32_16x16x32_bf16 v[8:11], v[144:147], v[168:171], v[8:11]
	v_mfma_f32_16x16x32_bf16 v[8:11], v[140:143], v[164:167], v[8:11]
	v_mfma_f32_16x16x32_bf16 v[16:19], v[140:143], v[172:175], v[16:19]
	v_mfma_f32_16x16x32_bf16 v[16:19], v[144:147], v[176:179], v[16:19]
	v_mfma_f32_16x16x32_bf16 v[12:15], v[136:139], v[176:179], v[12:15]
	v_mfma_f32_16x16x32_bf16 v[12:15], v[132:135], v[172:175], v[12:15]
	v_mfma_f32_16x16x32_bf16 v[20:23], v[132:135], v[180:183], v[20:23]
	v_mfma_f32_16x16x32_bf16 v[20:23], v[136:139], v[184:187], v[20:23]
	v_mfma_f32_16x16x32_bf16 v[24:27], v[144:147], v[184:187], v[24:27]
	v_mfma_f32_16x16x32_bf16 v[24:27], v[140:143], v[180:183], v[24:27]
	v_mfma_f32_16x16x32_bf16 v[32:35], v[140:143], v[194:197], v[32:35]
	v_mfma_f32_16x16x32_bf16 v[32:35], v[144:147], v[198:201], v[32:35]
	v_mfma_f32_16x16x32_bf16 v[28:31], v[136:139], v[198:201], v[28:31]
	v_mfma_f32_16x16x32_bf16 v[28:31], v[132:135], v[194:197], v[28:31]
	s_setprio 0
	s_setprio 1
	v_mfma_f32_16x16x32_bf16 v[36:39], v[148:151], v[164:167], v[36:39]
	v_mfma_f32_16x16x32_bf16 v[36:39], v[152:155], v[168:171], v[36:39]
	v_mfma_f32_16x16x32_bf16 v[40:43], v[160:163], v[168:171], v[40:43]
	v_mfma_f32_16x16x32_bf16 v[40:43], v[156:159], v[164:167], v[40:43]
	v_mfma_f32_16x16x32_bf16 v[48:51], v[156:159], v[172:175], v[48:51]
	v_mfma_f32_16x16x32_bf16 v[48:51], v[160:163], v[176:179], v[48:51]
	v_mfma_f32_16x16x32_bf16 v[44:47], v[152:155], v[176:179], v[44:47]
	v_mfma_f32_16x16x32_bf16 v[44:47], v[148:151], v[172:175], v[44:47]
	v_mfma_f32_16x16x32_bf16 v[52:55], v[148:151], v[180:183], v[52:55]
	v_mfma_f32_16x16x32_bf16 v[52:55], v[152:155], v[184:187], v[52:55]
	v_mfma_f32_16x16x32_bf16 v[56:59], v[160:163], v[184:187], v[56:59]
	v_mfma_f32_16x16x32_bf16 v[56:59], v[156:159], v[180:183], v[56:59]
	v_mfma_f32_16x16x32_bf16 v[64:67], v[156:159], v[194:197], v[64:67]
	v_mfma_f32_16x16x32_bf16 v[64:67], v[160:163], v[198:201], v[64:67]
	s_setprio 3
	s_barrier
	v_mfma_f32_16x16x32_bf16 v[60:63], v[152:155], v[198:201], v[60:63]
	v_mfma_f32_16x16x32_bf16 v[60:63], v[148:151], v[194:197], v[60:63]
	s_setprio 0
	s_add_i32 s16, s29, s38
	v_lshl_add_u64 v[202:203], v[202:203], 0, s[86:87]
	s_mov_b32 m0, s16
	ds_read_b128 v[164:167], v210 offset:49152
	ds_read_b128 v[168:171], v210 offset:50176
	ds_read_b128 v[172:175], v210 offset:51200
	ds_read_b128 v[176:179], v210 offset:52224
	ds_read_b128 v[180:183], v210 offset:53248
	ds_read_b128 v[184:187], v210 offset:54272
	ds_read_b128 v[194:197], v210 offset:55296
	ds_read_b128 v[198:201], v210 offset:56320
	global_load_lds_dwordx4 v[202:203], off
	s_add_i32 m0, s16, 0x2000
	s_add_u32 s12, s12, 0x20080
	v_lshl_add_u64 v[202:203], v[204:205], 0, s[86:87]
	s_addc_u32 s13, s13, 0
	s_add_i32 s16, s44, s38
	global_load_lds_dwordx4 v[202:203], off
	s_mov_b32 m0, s16
	v_lshl_add_u64 v[202:203], v[206:207], 0, s[86:87]
	global_load_lds_dwordx4 v192, s[12:13]
	s_add_i32 m0, s16, 0x2000
	s_nop 0
	global_load_lds_dwordx4 v190, s[12:13]
	s_mov_b32 m0, s63
	s_nop 0
	global_load_lds_dwordx4 v[202:203], off
	v_lshl_add_u64 v[202:203], v[208:209], 0, s[86:87]
	s_mov_b32 m0, s64
	s_nop 0
	global_load_lds_dwordx4 v[202:203], off
	s_waitcnt vmcnt(8)
	s_waitcnt lgkmcnt(0)
	s_barrier
	s_setprio 1
	s_waitcnt lgkmcnt(0)
	v_mfma_f32_16x16x32_bf16 v[68:71], v[132:135], v[164:167], v[68:71]
	v_mfma_f32_16x16x32_bf16 v[68:71], v[136:139], v[168:171], v[68:71]
	v_mfma_f32_16x16x32_bf16 v[72:75], v[144:147], v[168:171], v[72:75]
	v_mfma_f32_16x16x32_bf16 v[72:75], v[140:143], v[164:167], v[72:75]
	v_mfma_f32_16x16x32_bf16 v[80:83], v[140:143], v[172:175], v[80:83]
	v_mfma_f32_16x16x32_bf16 v[80:83], v[144:147], v[176:179], v[80:83]
	v_mfma_f32_16x16x32_bf16 v[76:79], v[136:139], v[176:179], v[76:79]
	v_mfma_f32_16x16x32_bf16 v[76:79], v[132:135], v[172:175], v[76:79]
	v_mfma_f32_16x16x32_bf16 v[84:87], v[132:135], v[180:183], v[84:87]
	v_mfma_f32_16x16x32_bf16 v[84:87], v[136:139], v[184:187], v[84:87]
	v_mfma_f32_16x16x32_bf16 v[88:91], v[144:147], v[184:187], v[88:91]
	v_mfma_f32_16x16x32_bf16 v[88:91], v[140:143], v[180:183], v[88:91]
	v_mfma_f32_16x16x32_bf16 v[96:99], v[140:143], v[194:197], v[96:99]
	v_mfma_f32_16x16x32_bf16 v[96:99], v[144:147], v[198:201], v[96:99]
	v_mfma_f32_16x16x32_bf16 v[92:95], v[136:139], v[198:201], v[92:95]
	v_mfma_f32_16x16x32_bf16 v[92:95], v[132:135], v[194:197], v[92:95]
	s_setprio 0
	s_setprio 1
	v_mfma_f32_16x16x32_bf16 v[100:103], v[148:151], v[164:167], v[100:103]
	v_mfma_f32_16x16x32_bf16 v[100:103], v[152:155], v[168:171], v[100:103]
	v_mfma_f32_16x16x32_bf16 v[104:107], v[160:163], v[168:171], v[104:107]
	v_mfma_f32_16x16x32_bf16 v[104:107], v[156:159], v[164:167], v[104:107]
	v_mfma_f32_16x16x32_bf16 v[112:115], v[156:159], v[172:175], v[112:115]
	v_mfma_f32_16x16x32_bf16 v[112:115], v[160:163], v[176:179], v[112:115]
	v_mfma_f32_16x16x32_bf16 v[108:111], v[152:155], v[176:179], v[108:111]
	v_mfma_f32_16x16x32_bf16 v[108:111], v[148:151], v[172:175], v[108:111]
	v_mfma_f32_16x16x32_bf16 v[116:119], v[148:151], v[180:183], v[116:119]
	v_mfma_f32_16x16x32_bf16 v[116:119], v[152:155], v[184:187], v[116:119]
	v_mfma_f32_16x16x32_bf16 v[120:123], v[160:163], v[184:187], v[120:123]
	v_mfma_f32_16x16x32_bf16 v[120:123], v[156:159], v[180:183], v[120:123]
	v_mfma_f32_16x16x32_bf16 v[128:131], v[156:159], v[194:197], v[128:131]
	v_mfma_f32_16x16x32_bf16 v[128:131], v[160:163], v[198:201], v[128:131]
	s_setprio 3
	s_barrier
	v_mfma_f32_16x16x32_bf16 v[124:127], v[152:155], v[198:201], v[124:127]
	v_mfma_f32_16x16x32_bf16 v[124:127], v[148:151], v[194:197], v[124:127]
	s_setprio 0
	s_add_i32 s28, s28, 2
	s_add_u32 s14, s14, 0x100
	s_addc_u32 s15, s15, 0
	s_add_u32 s26, s26, 0x100
	s_addc_u32 s27, s27, 0
	s_cmp_gt_u32 s28, 5
	s_cbranch_scc0 .LBB0_2069
	s_and_b64 vcc, exec, s[48:49]
	s_cbranch_vccz .LBB0_2072
	s_barrier

.LBB0_2159:
	s_add_i32 s68, 0, 0x10000
	s_add_i32 s69, 0, 0x14000
	v_add_u32_e32 v16, s68, v143
	v_add_u32_e32 v32, s69, v143
	ds_read_b128 v[4:7], v16
	ds_read_b128 v[8:11], v16 offset:1024
	ds_read_b128 v[12:15], v16 offset:2048
	ds_read_b128 v[16:19], v16 offset:3072
	ds_read_b128 v[20:23], v32
	ds_read_b128 v[24:27], v32 offset:1024
	ds_read_b128 v[28:31], v32 offset:2048
	ds_read_b128 v[32:35], v32 offset:3072
	v_add_u32_e32 v231, 0, v142
	ds_read_b128 v[36:39], v231
	ds_read_b128 v[40:43], v231 offset:1024
	ds_read_b128 v[44:47], v231 offset:2048
	ds_read_b128 v[48:51], v231 offset:3072
	ds_read_b128 v[52:55], v231 offset:4096
	ds_read_b128 v[56:59], v231 offset:5120
	ds_read_b128 v[60:63], v231 offset:6144
	ds_read_b128 v[64:67], v231 offset:7168
	s_waitcnt vmcnt(8)
	s_waitcnt lgkmcnt(0)
	s_barrier
	s_setprio 1
	s_waitcnt lgkmcnt(0)
	v_mfma_f32_16x16x32_f16 v[68:71], v[4:7], v[36:39], 0
	v_mfma_f32_16x16x32_f16 v[72:75], v[12:15], v[36:39], 0
	v_mfma_f32_16x16x32_f16 v[76:79], v[4:7], v[44:47], 0
	v_mfma_f32_16x16x32_f16 v[80:83], v[12:15], v[44:47], 0
	v_mfma_f32_16x16x32_f16 v[84:87], v[4:7], v[52:55], 0
	v_mfma_f32_16x16x32_f16 v[88:91], v[12:15], v[52:55], 0
	v_mfma_f32_16x16x32_f16 v[92:95], v[4:7], v[60:63], 0
	v_mfma_f32_16x16x32_f16 v[96:99], v[12:15], v[60:63], 0
	v_mfma_f32_16x16x32_f16 v[68:71], v[8:11], v[40:43], v[68:71]
	v_mfma_f32_16x16x32_f16 v[72:75], v[16:19], v[40:43], v[72:75]
	v_mfma_f32_16x16x32_f16 v[76:79], v[8:11], v[48:51], v[76:79]
	v_mfma_f32_16x16x32_f16 v[80:83], v[16:19], v[48:51], v[80:83]
	v_mfma_f32_16x16x32_f16 v[84:87], v[8:11], v[56:59], v[84:87]
	v_mfma_f32_16x16x32_f16 v[88:91], v[16:19], v[56:59], v[88:91]
	v_mfma_f32_16x16x32_f16 v[92:95], v[8:11], v[64:67], v[92:95]
	v_mfma_f32_16x16x32_f16 v[100:103], v[16:19], v[64:67], v[96:99]
	s_setprio 0
	s_setprio 1
	v_mfma_f32_16x16x32_f16 v[96:99], v[20:23], v[36:39], 0
	v_mfma_f32_16x16x32_f16 v[36:39], v[28:31], v[36:39], 0
	v_mfma_f32_16x16x32_f16 v[104:107], v[20:23], v[44:47], 0
	v_mfma_f32_16x16x32_f16 v[44:47], v[28:31], v[44:47], 0
	v_mfma_f32_16x16x32_f16 v[108:111], v[20:23], v[52:55], 0
	v_mfma_f32_16x16x32_f16 v[52:55], v[28:31], v[52:55], 0
	v_mfma_f32_16x16x32_f16 v[112:115], v[20:23], v[60:63], 0
	v_mfma_f32_16x16x32_f16 v[60:63], v[28:31], v[60:63], 0
	v_mfma_f32_16x16x32_f16 v[116:119], v[24:27], v[40:43], v[96:99]
	v_mfma_f32_16x16x32_f16 v[36:39], v[32:35], v[40:43], v[36:39]
	v_mfma_f32_16x16x32_f16 v[40:43], v[24:27], v[48:51], v[104:107]
	v_mfma_f32_16x16x32_f16 v[44:47], v[32:35], v[48:51], v[44:47]
	v_mfma_f32_16x16x32_f16 v[48:51], v[24:27], v[56:59], v[108:111]
	v_mfma_f32_16x16x32_f16 v[52:55], v[32:35], v[56:59], v[52:55]
	s_setprio 3
	s_barrier
	v_mfma_f32_16x16x32_f16 v[56:59], v[24:27], v[64:67], v[112:115]
	v_mfma_f32_16x16x32_f16 v[60:63], v[32:35], v[64:67], v[60:63]
	s_setprio 0
	v_lshl_add_u64 v[138:139], s[8:9], 0, v[2:3]
	s_add_i32 s68, s68, s53
	v_mov_b32_e32 v135, v3
	v_lshl_add_u64 v[144:145], v[138:139], 0, s[74:75]
	s_mov_b32 m0, s68
	v_lshl_add_u64 v[192:193], s[8:9], 0, v[134:135]
	ds_read_b128 v[64:67], v231 offset:16384
	ds_read_b128 v[96:99], v231 offset:17408
	ds_read_b128 v[104:107], v231 offset:18432
	ds_read_b128 v[108:111], v231 offset:19456
	ds_read_b128 v[112:115], v231 offset:20480
	ds_read_b128 v[120:123], v231 offset:21504
	ds_read_b128 v[124:127], v231 offset:22528
	ds_read_b128 v[128:131], v231 offset:23552
	global_load_lds_dwordx4 v[144:145], off
	v_lshl_add_u64 v[144:145], v[192:193], 0, s[74:75]
	s_add_i32 m0, s68, 0x2000
	s_add_i32 s68, s69, s53
	global_load_lds_dwordx4 v[144:145], off
	s_mov_b32 m0, s68
	v_mov_b32_e32 v137, v3
	global_load_lds_dwordx4 v2, s[40:41]
	s_add_i32 m0, s68, 0x2000
	v_lshl_add_u64 v[248:249], s[6:7], 0, v[136:137]
	v_mov_b32_e32 v133, v3
	global_load_lds_dwordx4 v134, s[40:41]
	v_lshl_add_u64 v[144:145], v[248:249], 0, s[74:75]
	s_mov_b32 m0, s54
	v_lshl_add_u64 v[250:251], s[6:7], 0, v[132:133]
	global_load_lds_dwordx4 v[144:145], off
	v_lshl_add_u64 v[144:145], v[250:251], 0, s[74:75]
	s_mov_b32 m0, s55
	s_nop 0
	global_load_lds_dwordx4 v[144:145], off
	s_waitcnt vmcnt(8)
	s_waitcnt lgkmcnt(0)
	s_barrier
	s_setprio 1
	s_waitcnt lgkmcnt(0)
	v_mfma_f32_16x16x32_f16 v[144:147], v[4:7], v[64:67], 0
	v_mfma_f32_16x16x32_f16 v[148:151], v[12:15], v[64:67], 0
	v_mfma_f32_16x16x32_f16 v[152:155], v[4:7], v[104:107], 0
	v_mfma_f32_16x16x32_f16 v[156:159], v[12:15], v[104:107], 0
	v_mfma_f32_16x16x32_f16 v[160:163], v[4:7], v[112:115], 0
	v_mfma_f32_16x16x32_f16 v[164:167], v[12:15], v[112:115], 0
	v_mfma_f32_16x16x32_f16 v[4:7], v[4:7], v[124:127], 0
	v_mfma_f32_16x16x32_f16 v[12:15], v[12:15], v[124:127], 0
	v_mfma_f32_16x16x32_f16 v[144:147], v[8:11], v[96:99], v[144:147]
	v_mfma_f32_16x16x32_f16 v[152:155], v[8:11], v[108:111], v[152:155]
	v_mfma_f32_16x16x32_f16 v[160:163], v[8:11], v[120:123], v[160:163]
	v_mfma_f32_16x16x32_f16 v[4:7], v[8:11], v[128:131], v[4:7]
	v_mfma_f32_16x16x32_f16 v[8:11], v[16:19], v[128:131], v[12:15]
	v_mfma_f32_16x16x32_f16 v[148:151], v[16:19], v[96:99], v[148:151]
	v_mfma_f32_16x16x32_f16 v[156:159], v[16:19], v[108:111], v[156:159]
	v_mfma_f32_16x16x32_f16 v[164:167], v[16:19], v[120:123], v[164:167]
	s_setprio 0
	s_setprio 1
	v_mfma_f32_16x16x32_f16 v[12:15], v[20:23], v[64:67], 0
	v_mfma_f32_16x16x32_f16 v[16:19], v[28:31], v[64:67], 0
	v_mfma_f32_16x16x32_f16 v[64:67], v[20:23], v[104:107], 0
	v_mfma_f32_16x16x32_f16 v[104:107], v[28:31], v[104:107], 0
	v_mfma_f32_16x16x32_f16 v[168:171], v[20:23], v[112:115], 0
	v_mfma_f32_16x16x32_f16 v[112:115], v[28:31], v[112:115], 0
	v_mfma_f32_16x16x32_f16 v[20:23], v[20:23], v[124:127], 0
	v_mfma_f32_16x16x32_f16 v[28:31], v[28:31], v[124:127], 0
	v_mfma_f32_16x16x32_f16 v[12:15], v[24:27], v[96:99], v[12:15]
	v_mfma_f32_16x16x32_f16 v[172:175], v[32:35], v[96:99], v[16:19]
	v_mfma_f32_16x16x32_f16 v[176:179], v[24:27], v[108:111], v[64:67]
	v_mfma_f32_16x16x32_f16 v[180:183], v[32:35], v[108:111], v[104:107]
	v_mfma_f32_16x16x32_f16 v[168:171], v[24:27], v[120:123], v[168:171]
	v_mfma_f32_16x16x32_f16 v[184:187], v[32:35], v[120:123], v[112:115]
	s_setprio 3
	s_barrier
	v_mfma_f32_16x16x32_f16 v[188:191], v[24:27], v[128:131], v[20:23]
	v_mfma_f32_16x16x32_f16 v[196:199], v[32:35], v[128:131], v[28:31]
	s_setprio 0
	s_add_i32 s68, 0, 0x18000
	v_add_u32_e32 v24, s68, v143
	s_add_i32 s69, 0, 0x1c000
	ds_read_b128 v[16:19], v24
	ds_read_b128 v[20:23], v24 offset:1024
	ds_read_b128 v[28:31], v24 offset:2048
	ds_read_b128 v[200:203], v24 offset:3072
	v_add_u32_e32 v24, s69, v143
	ds_read_b128 v[204:207], v24
	ds_read_b128 v[208:211], v24 offset:1024
	ds_read_b128 v[212:215], v24 offset:2048
	ds_read_b128 v[216:219], v24 offset:3072
	s_mov_b32 m0, s56
	ds_read_b128 v[24:27], v231 offset:32768
	ds_read_b128 v[32:35], v231 offset:33792
	ds_read_b128 v[64:67], v231 offset:34816
	ds_read_b128 v[220:223], v231 offset:35840
	ds_read_b128 v[224:227], v231 offset:36864
	ds_read_b128 v[232:235], v231 offset:37888
	ds_read_b128 v[236:239], v231 offset:38912
	ds_read_b128 v[240:243], v231 offset:39936
	global_load_lds_dwordx4 v136, s[42:43]
	s_mov_b32 m0, s57
	s_nop 0
	global_load_lds_dwordx4 v132, s[42:43]
	s_waitcnt vmcnt(8)
	s_waitcnt lgkmcnt(0)
	s_barrier
	s_setprio 1
	s_waitcnt lgkmcnt(0)
	v_mfma_f32_16x16x32_f16 v[68:71], v[16:19], v[24:27], v[68:71]
	v_mfma_f32_16x16x32_f16 v[128:131], v[20:23], v[32:35], v[68:71]
	v_mfma_f32_16x16x32_f16 v[68:71], v[28:31], v[24:27], v[72:75]
	v_mfma_f32_16x16x32_f16 v[120:123], v[200:203], v[32:35], v[68:71]
	v_mfma_f32_16x16x32_f16 v[68:71], v[16:19], v[64:67], v[76:79]
	v_mfma_f32_16x16x32_f16 v[112:115], v[20:23], v[220:223], v[68:71]
	v_mfma_f32_16x16x32_f16 v[68:71], v[28:31], v[64:67], v[80:83]
	v_mfma_f32_16x16x32_f16 v[104:107], v[200:203], v[220:223], v[68:71]
	v_mfma_f32_16x16x32_f16 v[68:71], v[16:19], v[224:227], v[84:87]
	v_mfma_f32_16x16x32_f16 v[96:99], v[20:23], v[232:235], v[68:71]
	v_mfma_f32_16x16x32_f16 v[68:71], v[28:31], v[224:227], v[88:91]
	v_mfma_f32_16x16x32_f16 v[88:91], v[200:203], v[232:235], v[68:71]
	v_mfma_f32_16x16x32_f16 v[68:71], v[16:19], v[236:239], v[92:95]
	v_mfma_f32_16x16x32_f16 v[80:83], v[20:23], v[240:243], v[68:71]
	v_mfma_f32_16x16x32_f16 v[68:71], v[28:31], v[236:239], v[100:103]
	v_mfma_f32_16x16x32_f16 v[72:75], v[200:203], v[240:243], v[68:71]
	s_setprio 0
	s_setprio 1
	v_mfma_f32_16x16x32_f16 v[68:71], v[204:207], v[24:27], v[116:119]
	v_mfma_f32_16x16x32_f16 v[24:27], v[212:215], v[24:27], v[36:39]
	v_mfma_f32_16x16x32_f16 v[116:119], v[216:219], v[32:35], v[24:27]
	v_mfma_f32_16x16x32_f16 v[24:27], v[204:207], v[64:67], v[40:43]
	v_mfma_f32_16x16x32_f16 v[108:111], v[208:211], v[220:223], v[24:27]
	v_mfma_f32_16x16x32_f16 v[24:27], v[212:215], v[64:67], v[44:47]
	v_mfma_f32_16x16x32_f16 v[100:103], v[216:219], v[220:223], v[24:27]
	v_mfma_f32_16x16x32_f16 v[24:27], v[204:207], v[224:227], v[48:51]
	v_mfma_f32_16x16x32_f16 v[92:95], v[208:211], v[232:235], v[24:27]
	v_mfma_f32_16x16x32_f16 v[24:27], v[212:215], v[224:227], v[52:55]
	v_mfma_f32_16x16x32_f16 v[84:87], v[216:219], v[232:235], v[24:27]
	v_mfma_f32_16x16x32_f16 v[24:27], v[204:207], v[236:239], v[56:59]
	v_mfma_f32_16x16x32_f16 v[76:79], v[208:211], v[240:243], v[24:27]
	v_mfma_f32_16x16x32_f16 v[24:27], v[212:215], v[236:239], v[60:63]
	s_setprio 3
	s_barrier
	v_mfma_f32_16x16x32_f16 v[124:127], v[208:211], v[32:35], v[68:71]
	v_mfma_f32_16x16x32_f16 v[68:71], v[216:219], v[240:243], v[24:27]
	s_setprio 0
	s_add_i32 s68, s68, s53
	s_nop 2
	v_lshl_add_u64 v[24:25], v[138:139], 0, s[24:25]
	s_mov_b32 m0, s68
	ds_read_b128 v[36:39], v231 offset:49152
	ds_read_b128 v[44:47], v231 offset:50176
	ds_read_b128 v[220:223], v231 offset:51200
	ds_read_b128 v[224:227], v231 offset:52224
	ds_read_b128 v[232:235], v231 offset:53248
	ds_read_b128 v[236:239], v231 offset:54272
	ds_read_b128 v[240:243], v231 offset:55296
	ds_read_b128 v[244:247], v231 offset:56320
	global_load_lds_dwordx4 v[24:25], off
	v_lshl_add_u64 v[24:25], v[192:193], 0, s[24:25]
	s_add_i32 m0, s68, 0x2000
	s_add_i32 s68, s69, s53
	global_load_lds_dwordx4 v[24:25], off
	s_mov_b32 m0, s68
	v_lshl_add_u64 v[24:25], v[248:249], 0, s[24:25]
	global_load_lds_dwordx4 v2, s[44:45]
	s_add_i32 m0, s68, 0x2000
	s_nop 0
	global_load_lds_dwordx4 v134, s[44:45]
	s_mov_b32 m0, s59
	s_nop 0
	global_load_lds_dwordx4 v[24:25], off
	v_lshl_add_u64 v[24:25], v[250:251], 0, s[24:25]
	s_mov_b32 m0, s60
	s_nop 0
	global_load_lds_dwordx4 v[24:25], off
	s_waitcnt vmcnt(8)
	s_waitcnt lgkmcnt(0)
	s_barrier
	s_setprio 1
	s_waitcnt lgkmcnt(0)
	v_mfma_f32_16x16x32_f16 v[24:27], v[16:19], v[36:39], v[144:147]
	v_mfma_f32_16x16x32_f16 v[64:67], v[20:23], v[44:47], v[24:27]
	v_mfma_f32_16x16x32_f16 v[24:27], v[28:31], v[36:39], v[148:151]
	v_mfma_f32_16x16x32_f16 v[56:59], v[200:203], v[44:47], v[24:27]
	v_mfma_f32_16x16x32_f16 v[24:27], v[16:19], v[220:223], v[152:155]
	v_mfma_f32_16x16x32_f16 v[48:51], v[20:23], v[224:227], v[24:27]
	v_mfma_f32_16x16x32_f16 v[24:27], v[28:31], v[220:223], v[156:159]
	v_mfma_f32_16x16x32_f16 v[40:43], v[200:203], v[224:227], v[24:27]
	v_mfma_f32_16x16x32_f16 v[24:27], v[16:19], v[232:235], v[160:163]
	v_mfma_f32_16x16x32_f16 v[4:7], v[16:19], v[240:243], v[4:7]
	v_mfma_f32_16x16x32_f16 v[32:35], v[20:23], v[236:239], v[24:27]
	v_mfma_f32_16x16x32_f16 v[24:27], v[28:31], v[232:235], v[164:167]
	v_mfma_f32_16x16x32_f16 v[16:19], v[20:23], v[244:247], v[4:7]
	v_mfma_f32_16x16x32_f16 v[4:7], v[28:31], v[240:243], v[8:11]
	v_mfma_f32_16x16x32_f16 v[24:27], v[200:203], v[236:239], v[24:27]
	v_mfma_f32_16x16x32_f16 v[8:11], v[200:203], v[244:247], v[4:7]
	s_setprio 0
	s_setprio 1
	v_mfma_f32_16x16x32_f16 v[4:7], v[204:207], v[36:39], v[12:15]
	v_mfma_f32_16x16x32_f16 v[60:63], v[208:211], v[44:47], v[4:7]
	v_mfma_f32_16x16x32_f16 v[4:7], v[212:215], v[36:39], v[172:175]
	v_mfma_f32_16x16x32_f16 v[52:55], v[216:219], v[44:47], v[4:7]
	v_mfma_f32_16x16x32_f16 v[4:7], v[204:207], v[220:223], v[176:179]
	v_mfma_f32_16x16x32_f16 v[44:47], v[208:211], v[224:227], v[4:7]
	v_mfma_f32_16x16x32_f16 v[4:7], v[212:215], v[220:223], v[180:183]
	v_mfma_f32_16x16x32_f16 v[36:39], v[216:219], v[224:227], v[4:7]
	v_mfma_f32_16x16x32_f16 v[4:7], v[204:207], v[232:235], v[168:171]
	v_mfma_f32_16x16x32_f16 v[28:31], v[208:211], v[236:239], v[4:7]
	v_mfma_f32_16x16x32_f16 v[4:7], v[212:215], v[232:235], v[184:187]
	v_mfma_f32_16x16x32_f16 v[20:23], v[216:219], v[236:239], v[4:7]
	v_mfma_f32_16x16x32_f16 v[4:7], v[204:207], v[240:243], v[188:191]
	v_mfma_f32_16x16x32_f16 v[12:15], v[208:211], v[244:247], v[4:7]
	s_setprio 3
	s_barrier
	v_mfma_f32_16x16x32_f16 v[4:7], v[212:215], v[240:243], v[196:199]
	v_mfma_f32_16x16x32_f16 v[4:7], v[216:219], v[244:247], v[4:7]
	s_setprio 0
	s_add_i32 s67, s67, 2
	s_cmp_ge_i32 s67, s11
	s_cbranch_scc0 .LBB0_2159

.LBB0_2161:
	s_add_u32 s68, s6, s40
	s_addc_u32 s69, s7, s41
	s_add_u32 s42, s68, 0x200
	s_addc_u32 s43, s69, 0
	s_add_u32 s44, s8, s40
	s_addc_u32 s45, s9, s41
	s_add_u32 s67, s44, 0x200
	s_addc_u32 s70, s45, 0
	s_add_i32 s71, 0, 0x10000
	s_cmp_eq_u32 s11, 28
	s_cselect_b32 s45, s29, s43
	s_cselect_b32 s44, s28, s42
	v_add_u32_e32 v133, s71, v143
	s_cselect_b32 s43, s37, s70
	s_cselect_b32 s42, s36, s67
	s_add_i32 s67, 0, 0x14000
	ds_read_b128 v[144:147], v133
	ds_read_b128 v[148:151], v133 offset:1024
	ds_read_b128 v[152:155], v133 offset:2048
	ds_read_b128 v[156:159], v133 offset:3072
	v_add_u32_e32 v133, s67, v143
	ds_read_b128 v[160:163], v133
	ds_read_b128 v[164:167], v133 offset:1024
	ds_read_b128 v[168:171], v133 offset:2048
	ds_read_b128 v[172:175], v133 offset:3072
	v_lshl_add_u64 v[136:137], s[68:69], 0, v[2:3]
	s_mov_b32 m0, s61
	v_add_u32_e32 v216, 0, v142
	v_lshl_add_u64 v[136:137], v[136:137], 0, s[34:35]
	v_mov_b32_e32 v133, v3
	ds_read_b128 v[176:179], v216
	ds_read_b128 v[180:183], v216 offset:1024
	ds_read_b128 v[184:187], v216 offset:2048
	ds_read_b128 v[188:191], v216 offset:3072
	ds_read_b128 v[196:199], v216 offset:4096
	ds_read_b128 v[200:203], v216 offset:5120
	ds_read_b128 v[204:207], v216 offset:6144
	ds_read_b128 v[208:211], v216 offset:7168
	global_load_lds_dwordx4 v[136:137], off
	v_lshl_add_u64 v[136:137], s[68:69], 0, v[132:133]
	v_lshl_add_u64 v[136:137], v[136:137], 0, s[34:35]
	s_mov_b32 m0, s62
	s_nop 0
	global_load_lds_dwordx4 v[136:137], off
	s_waitcnt vmcnt(8)
	s_waitcnt lgkmcnt(0)
	s_barrier
	s_setprio 1
	s_waitcnt lgkmcnt(0)
	v_mfma_f32_16x16x32_f16 v[128:131], v[144:147], v[176:179], v[128:131]
	v_mfma_f32_16x16x32_f16 v[128:131], v[148:151], v[180:183], v[128:131]
	v_mfma_f32_16x16x32_f16 v[120:123], v[156:159], v[180:183], v[120:123]
	v_mfma_f32_16x16x32_f16 v[120:123], v[152:155], v[176:179], v[120:123]
	v_mfma_f32_16x16x32_f16 v[104:107], v[152:155], v[184:187], v[104:107]
	v_mfma_f32_16x16x32_f16 v[104:107], v[156:159], v[188:191], v[104:107]
	v_mfma_f32_16x16x32_f16 v[112:115], v[148:151], v[188:191], v[112:115]
	v_mfma_f32_16x16x32_f16 v[112:115], v[144:147], v[184:187], v[112:115]
	v_mfma_f32_16x16x32_f16 v[96:99], v[144:147], v[196:199], v[96:99]
	v_mfma_f32_16x16x32_f16 v[96:99], v[148:151], v[200:203], v[96:99]
	v_mfma_f32_16x16x32_f16 v[88:91], v[156:159], v[200:203], v[88:91]
	v_mfma_f32_16x16x32_f16 v[88:91], v[152:155], v[196:199], v[88:91]
	v_mfma_f32_16x16x32_f16 v[72:75], v[152:155], v[204:207], v[72:75]
	v_mfma_f32_16x16x32_f16 v[72:75], v[156:159], v[208:211], v[72:75]
	v_mfma_f32_16x16x32_f16 v[80:83], v[148:151], v[208:211], v[80:83]
	v_mfma_f32_16x16x32_f16 v[80:83], v[144:147], v[204:207], v[80:83]
	s_setprio 0
	s_setprio 1
	v_mfma_f32_16x16x32_f16 v[124:127], v[160:163], v[176:179], v[124:127]
	v_mfma_f32_16x16x32_f16 v[124:127], v[164:167], v[180:183], v[124:127]
	v_mfma_f32_16x16x32_f16 v[116:119], v[172:175], v[180:183], v[116:119]
	v_mfma_f32_16x16x32_f16 v[116:119], v[168:171], v[176:179], v[116:119]
	v_mfma_f32_16x16x32_f16 v[100:103], v[168:171], v[184:187], v[100:103]
	v_mfma_f32_16x16x32_f16 v[100:103], v[172:175], v[188:191], v[100:103]
	v_mfma_f32_16x16x32_f16 v[108:111], v[164:167], v[188:191], v[108:111]
	v_mfma_f32_16x16x32_f16 v[108:111], v[160:163], v[184:187], v[108:111]
	v_mfma_f32_16x16x32_f16 v[92:95], v[160:163], v[196:199], v[92:95]
	v_mfma_f32_16x16x32_f16 v[92:95], v[164:167], v[200:203], v[92:95]
	v_mfma_f32_16x16x32_f16 v[84:87], v[172:175], v[200:203], v[84:87]
	v_mfma_f32_16x16x32_f16 v[84:87], v[168:171], v[196:199], v[84:87]
	v_mfma_f32_16x16x32_f16 v[68:71], v[168:171], v[204:207], v[68:71]
	v_mfma_f32_16x16x32_f16 v[68:71], v[172:175], v[208:211], v[68:71]
	s_setprio 3
	s_barrier
	v_mfma_f32_16x16x32_f16 v[76:79], v[164:167], v[208:211], v[76:79]
	v_mfma_f32_16x16x32_f16 v[76:79], v[160:163], v[204:207], v[76:79]
	s_setprio 0
	s_add_i32 s68, s71, s53
	s_mov_b32 m0, s68
	ds_read_b128 v[176:179], v216 offset:16384
	ds_read_b128 v[180:183], v216 offset:17408
	ds_read_b128 v[184:187], v216 offset:18432
	ds_read_b128 v[188:191], v216 offset:19456
	ds_read_b128 v[196:199], v216 offset:20480
	ds_read_b128 v[200:203], v216 offset:21504
	ds_read_b128 v[204:207], v216 offset:22528
	ds_read_b128 v[208:211], v216 offset:23552
	global_load_lds_dwordx4 v138, s[42:43]
	s_add_i32 m0, s68, 0x2000
	s_add_u32 s68, s42, 0x80000
	s_addc_u32 s69, s43, 0
	s_add_i32 s67, s67, s53
	global_load_lds_dwordx4 v134, s[42:43]
	s_mov_b32 m0, s67
	v_mov_b32_e32 v139, v3
	global_load_lds_dwordx4 v138, s[68:69]
	s_add_i32 m0, s67, 0x2000
	v_mov_b32_e32 v135, v3
	global_load_lds_dwordx4 v134, s[68:69]
	s_mov_b32 m0, s54
	v_lshl_add_u64 v[136:137], s[42:43], 0, v[138:139]
	global_load_lds_dwordx4 v2, s[44:45]
	s_mov_b32 m0, s55
	v_lshl_add_u64 v[192:193], s[42:43], 0, v[134:135]
	global_load_lds_dwordx4 v132, s[44:45]
	s_waitcnt vmcnt(8)
	s_waitcnt lgkmcnt(0)
	v_lshl_add_u64 v[212:213], s[44:45], 0, v[2:3]
	v_lshl_add_u64 v[214:215], s[44:45], 0, v[132:133]
	s_barrier
	s_setprio 1
	s_waitcnt lgkmcnt(0)
	v_mfma_f32_16x16x32_f16 v[64:67], v[144:147], v[176:179], v[64:67]
	v_mfma_f32_16x16x32_f16 v[64:67], v[148:151], v[180:183], v[64:67]
	v_mfma_f32_16x16x32_f16 v[56:59], v[156:159], v[180:183], v[56:59]
	v_mfma_f32_16x16x32_f16 v[56:59], v[152:155], v[176:179], v[56:59]
	v_mfma_f32_16x16x32_f16 v[40:43], v[152:155], v[184:187], v[40:43]
	v_mfma_f32_16x16x32_f16 v[40:43], v[156:159], v[188:191], v[40:43]
	v_mfma_f32_16x16x32_f16 v[48:51], v[148:151], v[188:191], v[48:51]
	v_mfma_f32_16x16x32_f16 v[48:51], v[144:147], v[184:187], v[48:51]
	v_mfma_f32_16x16x32_f16 v[32:35], v[144:147], v[196:199], v[32:35]
	v_mfma_f32_16x16x32_f16 v[32:35], v[148:151], v[200:203], v[32:35]
	v_mfma_f32_16x16x32_f16 v[24:27], v[156:159], v[200:203], v[24:27]
	v_mfma_f32_16x16x32_f16 v[24:27], v[152:155], v[196:199], v[24:27]
	v_mfma_f32_16x16x32_f16 v[8:11], v[152:155], v[204:207], v[8:11]
	v_mfma_f32_16x16x32_f16 v[8:11], v[156:159], v[208:211], v[8:11]
	v_mfma_f32_16x16x32_f16 v[16:19], v[148:151], v[208:211], v[16:19]
	v_mfma_f32_16x16x32_f16 v[16:19], v[144:147], v[204:207], v[16:19]
	s_setprio 0
	s_setprio 1
	v_mfma_f32_16x16x32_f16 v[60:63], v[160:163], v[176:179], v[60:63]
	v_mfma_f32_16x16x32_f16 v[60:63], v[164:167], v[180:183], v[60:63]
	v_mfma_f32_16x16x32_f16 v[52:55], v[172:175], v[180:183], v[52:55]
	v_mfma_f32_16x16x32_f16 v[52:55], v[168:171], v[176:179], v[52:55]
	v_mfma_f32_16x16x32_f16 v[36:39], v[168:171], v[184:187], v[36:39]
	v_mfma_f32_16x16x32_f16 v[36:39], v[172:175], v[188:191], v[36:39]
	v_mfma_f32_16x16x32_f16 v[44:47], v[164:167], v[188:191], v[44:47]
	v_mfma_f32_16x16x32_f16 v[44:47], v[160:163], v[184:187], v[44:47]
	v_mfma_f32_16x16x32_f16 v[28:31], v[160:163], v[196:199], v[28:31]
	v_mfma_f32_16x16x32_f16 v[28:31], v[164:167], v[200:203], v[28:31]
	v_mfma_f32_16x16x32_f16 v[20:23], v[172:175], v[200:203], v[20:23]
	v_mfma_f32_16x16x32_f16 v[20:23], v[168:171], v[196:199], v[20:23]
	v_mfma_f32_16x16x32_f16 v[4:7], v[168:171], v[204:207], v[4:7]
	v_mfma_f32_16x16x32_f16 v[4:7], v[172:175], v[208:211], v[4:7]
	s_setprio 3
	s_barrier
	v_mfma_f32_16x16x32_f16 v[12:15], v[164:167], v[208:211], v[12:15]
	v_mfma_f32_16x16x32_f16 v[12:15], v[160:163], v[204:207], v[12:15]
	s_setprio 0
	s_add_i32 s67, 0, 0x18000
	v_add_u32_e32 v135, s67, v143
	s_add_i32 s68, 0, 0x1c000
	ds_read_b128 v[144:147], v135
	ds_read_b128 v[148:151], v135 offset:1024
	ds_read_b128 v[152:155], v135 offset:2048
	ds_read_b128 v[156:159], v135 offset:3072
	v_add_u32_e32 v135, s68, v143
	ds_read_b128 v[160:163], v135
	ds_read_b128 v[164:167], v135 offset:1024
	ds_read_b128 v[168:171], v135 offset:2048
	ds_read_b128 v[172:175], v135 offset:3072
	s_add_u32 s44, s44, 0x80000
	s_addc_u32 s45, s45, 0
	s_mov_b32 m0, s56
	ds_read_b128 v[176:179], v216 offset:32768
	ds_read_b128 v[180:183], v216 offset:33792
	ds_read_b128 v[184:187], v216 offset:34816
	ds_read_b128 v[188:191], v216 offset:35840
	ds_read_b128 v[196:199], v216 offset:36864
	ds_read_b128 v[200:203], v216 offset:37888
	ds_read_b128 v[204:207], v216 offset:38912
	ds_read_b128 v[208:211], v216 offset:39936
	global_load_lds_dwordx4 v2, s[44:45]
	s_mov_b32 m0, s57
	s_nop 0
	global_load_lds_dwordx4 v132, s[44:45]
	s_waitcnt vmcnt(8)
	s_waitcnt lgkmcnt(0)
	s_barrier
	s_setprio 1
	s_waitcnt lgkmcnt(0)
	v_mfma_f32_16x16x32_f16 v[128:131], v[144:147], v[176:179], v[128:131]
	v_mfma_f32_16x16x32_f16 v[128:131], v[148:151], v[180:183], v[128:131]
	v_mfma_f32_16x16x32_f16 v[120:123], v[156:159], v[180:183], v[120:123]
	v_mfma_f32_16x16x32_f16 v[120:123], v[152:155], v[176:179], v[120:123]
	v_mfma_f32_16x16x32_f16 v[104:107], v[152:155], v[184:187], v[104:107]
	v_mfma_f32_16x16x32_f16 v[104:107], v[156:159], v[188:191], v[104:107]
	v_mfma_f32_16x16x32_f16 v[112:115], v[148:151], v[188:191], v[112:115]
	v_mfma_f32_16x16x32_f16 v[112:115], v[144:147], v[184:187], v[112:115]
	v_mfma_f32_16x16x32_f16 v[96:99], v[144:147], v[196:199], v[96:99]
	v_mfma_f32_16x16x32_f16 v[96:99], v[148:151], v[200:203], v[96:99]
	v_mfma_f32_16x16x32_f16 v[88:91], v[156:159], v[200:203], v[88:91]
	v_mfma_f32_16x16x32_f16 v[88:91], v[152:155], v[196:199], v[88:91]
	v_mfma_f32_16x16x32_f16 v[72:75], v[152:155], v[204:207], v[72:75]
	v_mfma_f32_16x16x32_f16 v[72:75], v[156:159], v[208:211], v[72:75]
	v_mfma_f32_16x16x32_f16 v[80:83], v[148:151], v[208:211], v[80:83]
	v_mfma_f32_16x16x32_f16 v[80:83], v[144:147], v[204:207], v[80:83]
	s_setprio 0
	s_setprio 1
	v_mfma_f32_16x16x32_f16 v[124:127], v[160:163], v[176:179], v[124:127]
	v_mfma_f32_16x16x32_f16 v[124:127], v[164:167], v[180:183], v[124:127]
	v_mfma_f32_16x16x32_f16 v[116:119], v[172:175], v[180:183], v[116:119]
	v_mfma_f32_16x16x32_f16 v[116:119], v[168:171], v[176:179], v[116:119]
	v_mfma_f32_16x16x32_f16 v[100:103], v[168:171], v[184:187], v[100:103]
	v_mfma_f32_16x16x32_f16 v[100:103], v[172:175], v[188:191], v[100:103]
	v_mfma_f32_16x16x32_f16 v[108:111], v[164:167], v[188:191], v[108:111]
	v_mfma_f32_16x16x32_f16 v[108:111], v[160:163], v[184:187], v[108:111]
	v_mfma_f32_16x16x32_f16 v[92:95], v[160:163], v[196:199], v[92:95]
	v_mfma_f32_16x16x32_f16 v[92:95], v[164:167], v[200:203], v[92:95]
	v_mfma_f32_16x16x32_f16 v[84:87], v[172:175], v[200:203], v[84:87]
	v_mfma_f32_16x16x32_f16 v[84:87], v[168:171], v[196:199], v[84:87]
	v_mfma_f32_16x16x32_f16 v[68:71], v[168:171], v[204:207], v[68:71]
	v_mfma_f32_16x16x32_f16 v[68:71], v[172:175], v[208:211], v[68:71]
	s_setprio 3
	s_barrier
	v_mfma_f32_16x16x32_f16 v[76:79], v[164:167], v[208:211], v[76:79]
	v_mfma_f32_16x16x32_f16 v[76:79], v[160:163], v[204:207], v[76:79]
	s_setprio 0
	s_add_i32 s44, s67, s53
	v_lshl_add_u64 v[136:137], v[136:137], 0, s[86:87]
	s_mov_b32 m0, s44
	ds_read_b128 v[176:179], v216 offset:49152
	ds_read_b128 v[180:183], v216 offset:50176
	ds_read_b128 v[184:187], v216 offset:51200
	ds_read_b128 v[188:191], v216 offset:52224
	ds_read_b128 v[196:199], v216 offset:53248
	ds_read_b128 v[200:203], v216 offset:54272
	ds_read_b128 v[204:207], v216 offset:55296
	ds_read_b128 v[208:211], v216 offset:56320
	global_load_lds_dwordx4 v[136:137], off
	s_add_i32 m0, s44, 0x2000
	s_add_u32 s42, s42, 0x80080
	v_lshl_add_u64 v[136:137], v[192:193], 0, s[86:87]
	s_addc_u32 s43, s43, 0
	s_add_i32 s44, s68, s53
	global_load_lds_dwordx4 v[136:137], off
	s_mov_b32 m0, s44
	v_lshl_add_u64 v[136:137], v[212:213], 0, s[86:87]
	global_load_lds_dwordx4 v138, s[42:43]
	s_add_i32 m0, s44, 0x2000
	s_nop 0
	global_load_lds_dwordx4 v134, s[42:43]
	s_mov_b32 m0, s59
	s_nop 0
	global_load_lds_dwordx4 v[136:137], off
	v_lshl_add_u64 v[136:137], v[214:215], 0, s[86:87]
	s_mov_b32 m0, s60
	s_nop 0
	global_load_lds_dwordx4 v[136:137], off
	s_waitcnt vmcnt(8)
	s_waitcnt lgkmcnt(0)
	s_barrier
	s_setprio 1
	s_waitcnt lgkmcnt(0)
	v_mfma_f32_16x16x32_f16 v[64:67], v[144:147], v[176:179], v[64:67]
	v_mfma_f32_16x16x32_f16 v[64:67], v[148:151], v[180:183], v[64:67]
	v_mfma_f32_16x16x32_f16 v[56:59], v[156:159], v[180:183], v[56:59]
	v_mfma_f32_16x16x32_f16 v[56:59], v[152:155], v[176:179], v[56:59]
	v_mfma_f32_16x16x32_f16 v[40:43], v[152:155], v[184:187], v[40:43]
	v_mfma_f32_16x16x32_f16 v[40:43], v[156:159], v[188:191], v[40:43]
	v_mfma_f32_16x16x32_f16 v[48:51], v[148:151], v[188:191], v[48:51]
	v_mfma_f32_16x16x32_f16 v[48:51], v[144:147], v[184:187], v[48:51]
	v_mfma_f32_16x16x32_f16 v[32:35], v[144:147], v[196:199], v[32:35]
	v_mfma_f32_16x16x32_f16 v[32:35], v[148:151], v[200:203], v[32:35]
	v_mfma_f32_16x16x32_f16 v[24:27], v[156:159], v[200:203], v[24:27]
	v_mfma_f32_16x16x32_f16 v[24:27], v[152:155], v[196:199], v[24:27]
	v_mfma_f32_16x16x32_f16 v[8:11], v[152:155], v[204:207], v[8:11]
	v_mfma_f32_16x16x32_f16 v[8:11], v[156:159], v[208:211], v[8:11]
	v_mfma_f32_16x16x32_f16 v[16:19], v[148:151], v[208:211], v[16:19]
	v_mfma_f32_16x16x32_f16 v[16:19], v[144:147], v[204:207], v[16:19]
	s_setprio 0
	s_setprio 1
	v_mfma_f32_16x16x32_f16 v[60:63], v[160:163], v[176:179], v[60:63]
	v_mfma_f32_16x16x32_f16 v[60:63], v[164:167], v[180:183], v[60:63]
	v_mfma_f32_16x16x32_f16 v[52:55], v[172:175], v[180:183], v[52:55]
	v_mfma_f32_16x16x32_f16 v[52:55], v[168:171], v[176:179], v[52:55]
	v_mfma_f32_16x16x32_f16 v[36:39], v[168:171], v[184:187], v[36:39]
	v_mfma_f32_16x16x32_f16 v[36:39], v[172:175], v[188:191], v[36:39]
	v_mfma_f32_16x16x32_f16 v[44:47], v[164:167], v[188:191], v[44:47]
	v_mfma_f32_16x16x32_f16 v[44:47], v[160:163], v[184:187], v[44:47]
	v_mfma_f32_16x16x32_f16 v[28:31], v[160:163], v[196:199], v[28:31]
	v_mfma_f32_16x16x32_f16 v[28:31], v[164:167], v[200:203], v[28:31]
	v_mfma_f32_16x16x32_f16 v[20:23], v[172:175], v[200:203], v[20:23]
	v_mfma_f32_16x16x32_f16 v[20:23], v[168:171], v[196:199], v[20:23]
	v_mfma_f32_16x16x32_f16 v[4:7], v[168:171], v[204:207], v[4:7]
	v_mfma_f32_16x16x32_f16 v[4:7], v[172:175], v[208:211], v[4:7]
	s_setprio 3
	s_barrier
	v_mfma_f32_16x16x32_f16 v[12:15], v[164:167], v[208:211], v[12:15]
	v_mfma_f32_16x16x32_f16 v[12:15], v[160:163], v[204:207], v[12:15]
	s_setprio 0
	s_add_i32 s11, s11, 2
	s_add_u32 s40, s40, 0x100
	s_addc_u32 s41, s41, 0
	s_cmp_gt_u32 s11, 29
	s_cbranch_scc0 .LBB0_2161
	s_andn2_b64 vcc, exec, s[26:27]
	s_cbranch_vccnz .LBB0_2164
	s_add_u32 s6, s28, 0x80080
	s_addc_u32 s7, s29, 0
	s_mov_b32 m0, s61
	v_lshl_add_u64 v[144:145], s[6:7], 0, v[2:3]
	v_lshl_add_u64 v[136:137], s[6:7], 0, v[132:133]
	global_load_lds_dwordx4 v[144:145], off
	s_mov_b32 m0, s62
	s_mov_b32 s47, s65
	global_load_lds_dwordx4 v[136:137], off
	s_mov_b32 s64, s10
	s_mov_b64 s[8:9], s[14:15]
	s_mov_b64 s[6:7], s[12:13]
	s_mov_b32 s63, s66

.LBB0_2269:
	s_add_i32 s51, 0, 0x10000
	s_add_i32 s71, 0, 0x14000
	v_add_u32_e32 v16, s51, v232
	v_add_u32_e32 v32, s71, v232
	ds_read_b128 v[4:7], v16
	ds_read_b128 v[8:11], v16 offset:1024
	ds_read_b128 v[12:15], v16 offset:2048
	ds_read_b128 v[16:19], v16 offset:3072
	ds_read_b128 v[20:23], v32
	ds_read_b128 v[24:27], v32 offset:1024
	ds_read_b128 v[28:31], v32 offset:2048
	ds_read_b128 v[32:35], v32 offset:3072
	v_add_u32_e32 v233, 0, v231
	ds_read_b128 v[36:39], v233
	ds_read_b128 v[40:43], v233 offset:1024
	ds_read_b128 v[44:47], v233 offset:2048
	ds_read_b128 v[48:51], v233 offset:3072
	ds_read_b128 v[52:55], v233 offset:4096
	ds_read_b128 v[56:59], v233 offset:5120
	ds_read_b128 v[60:63], v233 offset:6144
	ds_read_b128 v[64:67], v233 offset:7168
	s_waitcnt vmcnt(8)
	s_waitcnt lgkmcnt(0)
	s_barrier
	s_setprio 1
	s_waitcnt lgkmcnt(0)
	v_mfma_f32_16x16x32_bf16 v[68:71], v[4:7], v[36:39], 0
	v_mfma_f32_16x16x32_bf16 v[68:71], v[8:11], v[40:43], v[68:71]
	v_mfma_f32_16x16x32_bf16 v[72:75], v[12:15], v[36:39], 0
	v_mfma_f32_16x16x32_bf16 v[72:75], v[16:19], v[40:43], v[72:75]
	v_mfma_f32_16x16x32_bf16 v[80:83], v[12:15], v[44:47], 0
	v_mfma_f32_16x16x32_bf16 v[80:83], v[16:19], v[48:51], v[80:83]
	v_mfma_f32_16x16x32_bf16 v[76:79], v[4:7], v[44:47], 0
	v_mfma_f32_16x16x32_bf16 v[76:79], v[8:11], v[48:51], v[76:79]
	v_mfma_f32_16x16x32_bf16 v[84:87], v[4:7], v[52:55], 0
	v_mfma_f32_16x16x32_bf16 v[84:87], v[8:11], v[56:59], v[84:87]
	v_mfma_f32_16x16x32_bf16 v[88:91], v[12:15], v[52:55], 0
	v_mfma_f32_16x16x32_bf16 v[88:91], v[16:19], v[56:59], v[88:91]
	v_mfma_f32_16x16x32_bf16 v[96:99], v[12:15], v[60:63], 0
	v_mfma_f32_16x16x32_bf16 v[96:99], v[16:19], v[64:67], v[96:99]
	v_mfma_f32_16x16x32_bf16 v[92:95], v[4:7], v[60:63], 0
	v_mfma_f32_16x16x32_bf16 v[92:95], v[8:11], v[64:67], v[92:95]
	s_setprio 0
	s_setprio 1
	v_mfma_f32_16x16x32_bf16 v[100:103], v[20:23], v[36:39], 0
	v_mfma_f32_16x16x32_bf16 v[36:39], v[28:31], v[36:39], 0
	v_mfma_f32_16x16x32_bf16 v[104:107], v[20:23], v[44:47], 0
	v_mfma_f32_16x16x32_bf16 v[44:47], v[28:31], v[44:47], 0
	v_mfma_f32_16x16x32_bf16 v[108:111], v[20:23], v[52:55], 0
	v_mfma_f32_16x16x32_bf16 v[52:55], v[28:31], v[52:55], 0
	v_mfma_f32_16x16x32_bf16 v[112:115], v[20:23], v[60:63], 0
	v_mfma_f32_16x16x32_bf16 v[60:63], v[28:31], v[60:63], 0
	v_mfma_f32_16x16x32_bf16 v[100:103], v[24:27], v[40:43], v[100:103]
	v_mfma_f32_16x16x32_bf16 v[40:43], v[32:35], v[40:43], v[36:39]
	v_mfma_f32_16x16x32_bf16 v[104:107], v[24:27], v[48:51], v[104:107]
	v_mfma_f32_16x16x32_bf16 v[48:51], v[32:35], v[48:51], v[44:47]
	v_mfma_f32_16x16x32_bf16 v[108:111], v[24:27], v[56:59], v[108:111]
	v_mfma_f32_16x16x32_bf16 v[56:59], v[32:35], v[56:59], v[52:55]
	s_setprio 3
	s_barrier
	v_mfma_f32_16x16x32_bf16 v[112:115], v[24:27], v[64:67], v[112:115]
	v_mfma_f32_16x16x32_bf16 v[64:67], v[32:35], v[64:67], v[60:63]
	s_setprio 0
	v_lshl_add_u64 v[186:187], s[12:13], 0, v[2:3]
	s_add_i32 s51, s51, s38
	v_mov_b32_e32 v191, v3
	v_lshl_add_u64 v[134:135], v[186:187], 0, s[74:75]
	s_mov_b32 m0, s51
	v_lshl_add_u64 v[246:247], s[12:13], 0, v[190:191]
	ds_read_b128 v[36:39], v233 offset:16384
	ds_read_b128 v[44:47], v233 offset:17408
	ds_read_b128 v[52:55], v233 offset:18432
	ds_read_b128 v[60:63], v233 offset:19456
	ds_read_b128 v[116:119], v233 offset:20480
	ds_read_b128 v[120:123], v233 offset:21504
	ds_read_b128 v[124:127], v233 offset:22528
	ds_read_b128 v[128:131], v233 offset:23552
	global_load_lds_dwordx4 v[134:135], off
	v_lshl_add_u64 v[134:135], v[246:247], 0, s[74:75]
	s_add_i32 m0, s51, 0x2000
	s_add_i32 s51, s71, s38
	global_load_lds_dwordx4 v[134:135], off
	s_mov_b32 m0, s51
	v_mov_b32_e32 v133, v3
	global_load_lds_dwordx4 v2, s[16:17]
	s_add_i32 m0, s51, 0x2000
	v_lshl_add_u64 v[248:249], s[14:15], 0, v[132:133]
	v_mov_b32_e32 v189, v3
	global_load_lds_dwordx4 v190, s[16:17]
	v_lshl_add_u64 v[134:135], v[248:249], 0, s[74:75]
	s_mov_b32 m0, s56
	v_lshl_add_u64 v[250:251], s[14:15], 0, v[188:189]
	global_load_lds_dwordx4 v[134:135], off
	v_lshl_add_u64 v[134:135], v[250:251], 0, s[74:75]
	s_mov_b32 m0, s57
	s_nop 0
	global_load_lds_dwordx4 v[134:135], off
	s_waitcnt vmcnt(8)
	s_waitcnt lgkmcnt(0)
	s_barrier
	s_setprio 1
	s_waitcnt lgkmcnt(0)
	v_mfma_f32_16x16x32_bf16 v[134:137], v[4:7], v[36:39], 0
	v_mfma_f32_16x16x32_bf16 v[138:141], v[12:15], v[36:39], 0
	v_mfma_f32_16x16x32_bf16 v[142:145], v[4:7], v[52:55], 0
	v_mfma_f32_16x16x32_bf16 v[146:149], v[12:15], v[52:55], 0
	v_mfma_f32_16x16x32_bf16 v[150:153], v[4:7], v[116:119], 0
	v_mfma_f32_16x16x32_bf16 v[154:157], v[12:15], v[116:119], 0
	v_mfma_f32_16x16x32_bf16 v[4:7], v[4:7], v[124:127], 0
	v_mfma_f32_16x16x32_bf16 v[12:15], v[12:15], v[124:127], 0
	v_mfma_f32_16x16x32_bf16 v[134:137], v[8:11], v[44:47], v[134:137]
	v_mfma_f32_16x16x32_bf16 v[138:141], v[16:19], v[44:47], v[138:141]
	v_mfma_f32_16x16x32_bf16 v[142:145], v[8:11], v[60:63], v[142:145]
	v_mfma_f32_16x16x32_bf16 v[146:149], v[16:19], v[60:63], v[146:149]
	v_mfma_f32_16x16x32_bf16 v[150:153], v[8:11], v[120:123], v[150:153]
	v_mfma_f32_16x16x32_bf16 v[154:157], v[16:19], v[120:123], v[154:157]
	v_mfma_f32_16x16x32_bf16 v[158:161], v[8:11], v[128:131], v[4:7]
	v_mfma_f32_16x16x32_bf16 v[162:165], v[16:19], v[128:131], v[12:15]
	s_setprio 0
	s_setprio 1
	v_mfma_f32_16x16x32_bf16 v[4:7], v[20:23], v[36:39], 0
	v_mfma_f32_16x16x32_bf16 v[8:11], v[28:31], v[36:39], 0
	v_mfma_f32_16x16x32_bf16 v[12:15], v[20:23], v[52:55], 0
	v_mfma_f32_16x16x32_bf16 v[16:19], v[28:31], v[52:55], 0
	v_mfma_f32_16x16x32_bf16 v[36:39], v[20:23], v[116:119], 0
	v_mfma_f32_16x16x32_bf16 v[52:55], v[28:31], v[116:119], 0
	v_mfma_f32_16x16x32_bf16 v[20:23], v[20:23], v[124:127], 0
	v_mfma_f32_16x16x32_bf16 v[28:31], v[28:31], v[124:127], 0
	v_mfma_f32_16x16x32_bf16 v[116:119], v[24:27], v[44:47], v[4:7]
	v_mfma_f32_16x16x32_bf16 v[124:127], v[32:35], v[44:47], v[8:11]
	v_mfma_f32_16x16x32_bf16 v[174:177], v[24:27], v[120:123], v[36:39]
	v_mfma_f32_16x16x32_bf16 v[120:123], v[32:35], v[120:123], v[52:55]
	v_mfma_f32_16x16x32_bf16 v[178:181], v[24:27], v[128:131], v[20:23]
	v_mfma_f32_16x16x32_bf16 v[128:131], v[32:35], v[128:131], v[28:31]
	s_setprio 3
	s_barrier
	v_mfma_f32_16x16x32_bf16 v[166:169], v[24:27], v[60:63], v[12:15]
	v_mfma_f32_16x16x32_bf16 v[170:173], v[32:35], v[60:63], v[16:19]
	s_setprio 0
	s_add_i32 s51, 0, 0x18000
	v_add_u32_e32 v4, s51, v232
	s_add_i32 s71, 0, 0x1c000
	ds_read_b128 v[182:185], v4
	ds_read_b128 v[192:195], v4 offset:1024
	ds_read_b128 v[196:199], v4 offset:2048
	ds_read_b128 v[200:203], v4 offset:3072
	v_add_u32_e32 v4, s71, v232
	ds_read_b128 v[204:207], v4
	ds_read_b128 v[208:211], v4 offset:1024
	ds_read_b128 v[212:215], v4 offset:2048
	ds_read_b128 v[216:219], v4 offset:3072
	s_mov_b32 m0, s58
	ds_read_b128 v[44:47], v233 offset:32768
	ds_read_b128 v[52:55], v233 offset:33792
	ds_read_b128 v[60:63], v233 offset:34816
	ds_read_b128 v[220:223], v233 offset:35840
	ds_read_b128 v[224:227], v233 offset:36864
	ds_read_b128 v[234:237], v233 offset:37888
	ds_read_b128 v[238:241], v233 offset:38912
	ds_read_b128 v[242:245], v233 offset:39936
	global_load_lds_dwordx4 v132, s[26:27]
	s_mov_b32 m0, s59
	s_nop 0
	global_load_lds_dwordx4 v188, s[26:27]
	s_waitcnt vmcnt(8)
	s_waitcnt lgkmcnt(0)
	s_barrier
	s_setprio 1
	s_waitcnt lgkmcnt(0)
	v_mfma_f32_16x16x32_bf16 v[4:7], v[182:185], v[44:47], v[68:71]
	v_mfma_f32_16x16x32_bf16 v[8:11], v[196:199], v[44:47], v[72:75]
	v_mfma_f32_16x16x32_bf16 v[12:15], v[182:185], v[60:63], v[76:79]
	v_mfma_f32_16x16x32_bf16 v[16:19], v[196:199], v[60:63], v[80:83]
	v_mfma_f32_16x16x32_bf16 v[20:23], v[182:185], v[224:227], v[84:87]
	v_mfma_f32_16x16x32_bf16 v[24:27], v[196:199], v[224:227], v[88:91]
	v_mfma_f32_16x16x32_bf16 v[28:31], v[182:185], v[238:241], v[92:95]
	v_mfma_f32_16x16x32_bf16 v[32:35], v[196:199], v[238:241], v[96:99]
	v_mfma_f32_16x16x32_bf16 v[4:7], v[192:195], v[52:55], v[4:7]
	v_mfma_f32_16x16x32_bf16 v[8:11], v[200:203], v[52:55], v[8:11]
	v_mfma_f32_16x16x32_bf16 v[12:15], v[192:195], v[220:223], v[12:15]
	v_mfma_f32_16x16x32_bf16 v[16:19], v[200:203], v[220:223], v[16:19]
	v_mfma_f32_16x16x32_bf16 v[20:23], v[192:195], v[234:237], v[20:23]
	v_mfma_f32_16x16x32_bf16 v[24:27], v[200:203], v[234:237], v[24:27]
	v_mfma_f32_16x16x32_bf16 v[28:31], v[192:195], v[242:245], v[28:31]
	v_mfma_f32_16x16x32_bf16 v[32:35], v[200:203], v[242:245], v[32:35]
	s_setprio 0
	s_setprio 1
	v_mfma_f32_16x16x32_bf16 v[36:39], v[204:207], v[44:47], v[100:103]
	v_mfma_f32_16x16x32_bf16 v[40:43], v[212:215], v[44:47], v[40:43]
	v_mfma_f32_16x16x32_bf16 v[36:39], v[208:211], v[52:55], v[36:39]
	v_mfma_f32_16x16x32_bf16 v[40:43], v[216:219], v[52:55], v[40:43]
	v_mfma_f32_16x16x32_bf16 v[44:47], v[204:207], v[60:63], v[104:107]
	v_mfma_f32_16x16x32_bf16 v[48:51], v[212:215], v[60:63], v[48:51]
	v_mfma_f32_16x16x32_bf16 v[52:55], v[204:207], v[224:227], v[108:111]
	v_mfma_f32_16x16x32_bf16 v[56:59], v[212:215], v[224:227], v[56:59]
	v_mfma_f32_16x16x32_bf16 v[60:63], v[204:207], v[238:241], v[112:115]
	v_mfma_f32_16x16x32_bf16 v[64:67], v[212:215], v[238:241], v[64:67]
	v_mfma_f32_16x16x32_bf16 v[44:47], v[208:211], v[220:223], v[44:47]
	v_mfma_f32_16x16x32_bf16 v[48:51], v[216:219], v[220:223], v[48:51]
	v_mfma_f32_16x16x32_bf16 v[52:55], v[208:211], v[234:237], v[52:55]
	v_mfma_f32_16x16x32_bf16 v[56:59], v[216:219], v[234:237], v[56:59]
	s_setprio 3
	s_barrier
	v_mfma_f32_16x16x32_bf16 v[60:63], v[208:211], v[242:245], v[60:63]
	v_mfma_f32_16x16x32_bf16 v[64:67], v[216:219], v[242:245], v[64:67]
	s_setprio 0
	s_add_i32 s51, s51, s38
	v_lshl_add_u64 v[68:69], v[186:187], 0, s[24:25]
	s_mov_b32 m0, s51
	ds_read_b128 v[104:107], v233 offset:49152
	ds_read_b128 v[108:111], v233 offset:50176
	ds_read_b128 v[112:115], v233 offset:51200
	ds_read_b128 v[220:223], v233 offset:52224
	ds_read_b128 v[224:227], v233 offset:53248
	ds_read_b128 v[234:237], v233 offset:54272
	ds_read_b128 v[238:241], v233 offset:55296
	ds_read_b128 v[242:245], v233 offset:56320
	global_load_lds_dwordx4 v[68:69], off
	v_lshl_add_u64 v[68:69], v[246:247], 0, s[24:25]
	s_add_i32 m0, s51, 0x2000
	s_add_i32 s51, s71, s38
	global_load_lds_dwordx4 v[68:69], off
	s_mov_b32 m0, s51
	v_lshl_add_u64 v[68:69], v[248:249], 0, s[24:25]
	global_load_lds_dwordx4 v2, s[28:29]
	s_add_i32 m0, s51, 0x2000
	s_nop 0
	global_load_lds_dwordx4 v190, s[28:29]
	s_mov_b32 m0, s63
	s_nop 0
	global_load_lds_dwordx4 v[68:69], off
	v_lshl_add_u64 v[68:69], v[250:251], 0, s[24:25]
	s_mov_b32 m0, s64
	s_nop 0
	global_load_lds_dwordx4 v[68:69], off
	s_waitcnt vmcnt(8)
	s_waitcnt lgkmcnt(0)
	s_barrier
	s_setprio 1
	s_waitcnt lgkmcnt(0)
	v_mfma_f32_16x16x32_bf16 v[68:71], v[182:185], v[104:107], v[134:137]
	v_mfma_f32_16x16x32_bf16 v[72:75], v[196:199], v[104:107], v[138:141]
	v_mfma_f32_16x16x32_bf16 v[76:79], v[182:185], v[112:115], v[142:145]
	v_mfma_f32_16x16x32_bf16 v[80:83], v[196:199], v[112:115], v[146:149]
	v_mfma_f32_16x16x32_bf16 v[84:87], v[182:185], v[224:227], v[150:153]
	v_mfma_f32_16x16x32_bf16 v[88:91], v[196:199], v[224:227], v[154:157]
	v_mfma_f32_16x16x32_bf16 v[92:95], v[182:185], v[238:241], v[158:161]
	v_mfma_f32_16x16x32_bf16 v[96:99], v[196:199], v[238:241], v[162:165]
	v_mfma_f32_16x16x32_bf16 v[68:71], v[192:195], v[108:111], v[68:71]
	v_mfma_f32_16x16x32_bf16 v[72:75], v[200:203], v[108:111], v[72:75]
	v_mfma_f32_16x16x32_bf16 v[76:79], v[192:195], v[220:223], v[76:79]
	v_mfma_f32_16x16x32_bf16 v[80:83], v[200:203], v[220:223], v[80:83]
	v_mfma_f32_16x16x32_bf16 v[84:87], v[192:195], v[234:237], v[84:87]
	v_mfma_f32_16x16x32_bf16 v[88:91], v[200:203], v[234:237], v[88:91]
	v_mfma_f32_16x16x32_bf16 v[92:95], v[192:195], v[242:245], v[92:95]
	v_mfma_f32_16x16x32_bf16 v[96:99], v[200:203], v[242:245], v[96:99]
	s_setprio 0
	s_setprio 1
	v_mfma_f32_16x16x32_bf16 v[100:103], v[204:207], v[104:107], v[116:119]
	v_mfma_f32_16x16x32_bf16 v[104:107], v[212:215], v[104:107], v[124:127]
	v_mfma_f32_16x16x32_bf16 v[100:103], v[208:211], v[108:111], v[100:103]
	v_mfma_f32_16x16x32_bf16 v[104:107], v[216:219], v[108:111], v[104:107]
	v_mfma_f32_16x16x32_bf16 v[108:111], v[204:207], v[112:115], v[166:169]
	v_mfma_f32_16x16x32_bf16 v[112:115], v[212:215], v[112:115], v[170:173]
	v_mfma_f32_16x16x32_bf16 v[116:119], v[204:207], v[224:227], v[174:177]
	v_mfma_f32_16x16x32_bf16 v[120:123], v[212:215], v[224:227], v[120:123]
	v_mfma_f32_16x16x32_bf16 v[124:127], v[204:207], v[238:241], v[178:181]
	v_mfma_f32_16x16x32_bf16 v[128:131], v[212:215], v[238:241], v[128:131]
	v_mfma_f32_16x16x32_bf16 v[108:111], v[208:211], v[220:223], v[108:111]
	v_mfma_f32_16x16x32_bf16 v[112:115], v[216:219], v[220:223], v[112:115]
	v_mfma_f32_16x16x32_bf16 v[116:119], v[208:211], v[234:237], v[116:119]
	v_mfma_f32_16x16x32_bf16 v[120:123], v[216:219], v[234:237], v[120:123]
	s_setprio 3
	s_barrier
	v_mfma_f32_16x16x32_bf16 v[124:127], v[208:211], v[242:245], v[124:127]
	v_mfma_f32_16x16x32_bf16 v[128:131], v[216:219], v[242:245], v[128:131]
	s_setprio 0
	s_add_i32 s41, s41, 2
	s_cmp_ge_i32 s41, s40
	s_cbranch_scc0 .LBB0_2269
	v_mov_b32_e32 v192, v2
	s_branch .LBB0_2272

.LBB0_2273:
	s_add_u32 s12, s14, 0xfffc0080
	s_addc_u32 s13, s15, -1
	s_add_i32 s29, 0, 0x10000
	s_cmp_eq_u32 s28, 12
	s_cselect_b32 s17, s9, s13
	s_cselect_b32 s16, s8, s12
	s_cselect_b32 s13, s11, s27
	s_cselect_b32 s12, s10, s26
	s_add_i32 s51, 0, 0x14000
	v_add_u32_e32 v144, s29, v232
	v_add_u32_e32 v160, s51, v232
	s_waitcnt lgkmcnt(0)
	ds_read_b128 v[132:135], v144
	ds_read_b128 v[136:139], v144 offset:1024
	ds_read_b128 v[140:143], v144 offset:2048
	ds_read_b128 v[144:147], v144 offset:3072
	ds_read_b128 v[148:151], v160
	ds_read_b128 v[152:155], v160 offset:1024
	ds_read_b128 v[156:159], v160 offset:2048
	ds_read_b128 v[160:163], v160 offset:3072
	s_mov_b32 m0, s65
	v_add_u32_e32 v210, 0, v231
	ds_read_b128 v[164:167], v210
	ds_read_b128 v[168:171], v210 offset:1024
	ds_read_b128 v[172:175], v210 offset:2048
	ds_read_b128 v[176:179], v210 offset:3072
	ds_read_b128 v[180:183], v210 offset:4096
	ds_read_b128 v[184:187], v210 offset:5120
	ds_read_b128 v[194:197], v210 offset:6144
	ds_read_b128 v[198:201], v210 offset:7168
	global_load_lds_dwordx4 v2, s[14:15]
	s_mov_b32 m0, s66
	v_mov_b32_e32 v189, v3
	global_load_lds_dwordx4 v188, s[14:15]
	s_waitcnt vmcnt(8)
	s_waitcnt lgkmcnt(0)
	s_barrier
	s_setprio 1
	s_waitcnt lgkmcnt(0)
	v_mfma_f32_16x16x32_bf16 v[4:7], v[132:135], v[164:167], v[4:7]
	v_mfma_f32_16x16x32_bf16 v[4:7], v[136:139], v[168:171], v[4:7]
	v_mfma_f32_16x16x32_bf16 v[8:11], v[144:147], v[168:171], v[8:11]
	v_mfma_f32_16x16x32_bf16 v[8:11], v[140:143], v[164:167], v[8:11]
	v_mfma_f32_16x16x32_bf16 v[16:19], v[140:143], v[172:175], v[16:19]
	v_mfma_f32_16x16x32_bf16 v[16:19], v[144:147], v[176:179], v[16:19]
	v_mfma_f32_16x16x32_bf16 v[12:15], v[136:139], v[176:179], v[12:15]
	v_mfma_f32_16x16x32_bf16 v[12:15], v[132:135], v[172:175], v[12:15]
	v_mfma_f32_16x16x32_bf16 v[20:23], v[132:135], v[180:183], v[20:23]
	v_mfma_f32_16x16x32_bf16 v[20:23], v[136:139], v[184:187], v[20:23]
	v_mfma_f32_16x16x32_bf16 v[24:27], v[144:147], v[184:187], v[24:27]
	v_mfma_f32_16x16x32_bf16 v[24:27], v[140:143], v[180:183], v[24:27]
	v_mfma_f32_16x16x32_bf16 v[32:35], v[140:143], v[194:197], v[32:35]
	v_mfma_f32_16x16x32_bf16 v[32:35], v[144:147], v[198:201], v[32:35]
	v_mfma_f32_16x16x32_bf16 v[28:31], v[136:139], v[198:201], v[28:31]
	v_mfma_f32_16x16x32_bf16 v[28:31], v[132:135], v[194:197], v[28:31]
	s_setprio 0
	s_setprio 1
	v_mfma_f32_16x16x32_bf16 v[36:39], v[148:151], v[164:167], v[36:39]
	v_mfma_f32_16x16x32_bf16 v[36:39], v[152:155], v[168:171], v[36:39]
	v_mfma_f32_16x16x32_bf16 v[40:43], v[160:163], v[168:171], v[40:43]
	v_mfma_f32_16x16x32_bf16 v[40:43], v[156:159], v[164:167], v[40:43]
	v_mfma_f32_16x16x32_bf16 v[48:51], v[156:159], v[172:175], v[48:51]
	v_mfma_f32_16x16x32_bf16 v[48:51], v[160:163], v[176:179], v[48:51]
	v_mfma_f32_16x16x32_bf16 v[44:47], v[152:155], v[176:179], v[44:47]
	v_mfma_f32_16x16x32_bf16 v[44:47], v[148:151], v[172:175], v[44:47]
	v_mfma_f32_16x16x32_bf16 v[52:55], v[148:151], v[180:183], v[52:55]
	v_mfma_f32_16x16x32_bf16 v[52:55], v[152:155], v[184:187], v[52:55]
	v_mfma_f32_16x16x32_bf16 v[56:59], v[160:163], v[184:187], v[56:59]
	v_mfma_f32_16x16x32_bf16 v[56:59], v[156:159], v[180:183], v[56:59]
	v_mfma_f32_16x16x32_bf16 v[64:67], v[156:159], v[194:197], v[64:67]
	v_mfma_f32_16x16x32_bf16 v[64:67], v[160:163], v[198:201], v[64:67]
	s_setprio 3
	s_barrier
	v_mfma_f32_16x16x32_bf16 v[60:63], v[152:155], v[198:201], v[60:63]
	v_mfma_f32_16x16x32_bf16 v[60:63], v[148:151], v[194:197], v[60:63]
	s_setprio 0
	s_add_i32 s29, s29, s38
	s_mov_b32 m0, s29
	ds_read_b128 v[164:167], v210 offset:16384
	ds_read_b128 v[168:171], v210 offset:17408
	ds_read_b128 v[172:175], v210 offset:18432
	ds_read_b128 v[176:179], v210 offset:19456
	ds_read_b128 v[180:183], v210 offset:20480
	ds_read_b128 v[184:187], v210 offset:21504
	ds_read_b128 v[194:197], v210 offset:22528
	ds_read_b128 v[198:201], v210 offset:23552
	global_load_lds_dwordx4 v192, s[12:13]
	s_add_i32 m0, s29, 0x2000
	s_add_u32 s40, s12, 0x100000
	s_addc_u32 s41, s13, 0
	s_add_i32 s29, s51, s38
	global_load_lds_dwordx4 v190, s[12:13]
	s_mov_b32 m0, s29
	v_mov_b32_e32 v193, v3
	global_load_lds_dwordx4 v192, s[40:41]
	s_add_i32 m0, s29, 0x2000
	v_mov_b32_e32 v191, v3
	global_load_lds_dwordx4 v190, s[40:41]
	s_mov_b32 m0, s56
	v_lshl_add_u64 v[202:203], s[12:13], 0, v[192:193]
	global_load_lds_dwordx4 v2, s[16:17]
	s_mov_b32 m0, s57
	v_lshl_add_u64 v[204:205], s[12:13], 0, v[190:191]
	global_load_lds_dwordx4 v188, s[16:17]
	s_waitcnt vmcnt(8)
	s_waitcnt lgkmcnt(0)
	v_lshl_add_u64 v[206:207], s[16:17], 0, v[2:3]
	v_lshl_add_u64 v[208:209], s[16:17], 0, v[188:189]
	s_barrier
	s_setprio 1
	s_waitcnt lgkmcnt(0)
	v_mfma_f32_16x16x32_bf16 v[68:71], v[132:135], v[164:167], v[68:71]
	v_mfma_f32_16x16x32_bf16 v[68:71], v[136:139], v[168:171], v[68:71]
	v_mfma_f32_16x16x32_bf16 v[72:75], v[144:147], v[168:171], v[72:75]
	v_mfma_f32_16x16x32_bf16 v[72:75], v[140:143], v[164:167], v[72:75]
	v_mfma_f32_16x16x32_bf16 v[80:83], v[140:143], v[172:175], v[80:83]
	v_mfma_f32_16x16x32_bf16 v[80:83], v[144:147], v[176:179], v[80:83]
	v_mfma_f32_16x16x32_bf16 v[76:79], v[136:139], v[176:179], v[76:79]
	v_mfma_f32_16x16x32_bf16 v[76:79], v[132:135], v[172:175], v[76:79]
	v_mfma_f32_16x16x32_bf16 v[84:87], v[132:135], v[180:183], v[84:87]
	v_mfma_f32_16x16x32_bf16 v[84:87], v[136:139], v[184:187], v[84:87]
	v_mfma_f32_16x16x32_bf16 v[88:91], v[144:147], v[184:187], v[88:91]
	v_mfma_f32_16x16x32_bf16 v[88:91], v[140:143], v[180:183], v[88:91]
	v_mfma_f32_16x16x32_bf16 v[96:99], v[140:143], v[194:197], v[96:99]
	v_mfma_f32_16x16x32_bf16 v[96:99], v[144:147], v[198:201], v[96:99]
	v_mfma_f32_16x16x32_bf16 v[92:95], v[136:139], v[198:201], v[92:95]
	v_mfma_f32_16x16x32_bf16 v[92:95], v[132:135], v[194:197], v[92:95]
	s_setprio 0
	s_setprio 1
	v_mfma_f32_16x16x32_bf16 v[100:103], v[148:151], v[164:167], v[100:103]
	v_mfma_f32_16x16x32_bf16 v[100:103], v[152:155], v[168:171], v[100:103]
	v_mfma_f32_16x16x32_bf16 v[104:107], v[160:163], v[168:171], v[104:107]
	v_mfma_f32_16x16x32_bf16 v[104:107], v[156:159], v[164:167], v[104:107]
	v_mfma_f32_16x16x32_bf16 v[112:115], v[156:159], v[172:175], v[112:115]
	v_mfma_f32_16x16x32_bf16 v[112:115], v[160:163], v[176:179], v[112:115]
	v_mfma_f32_16x16x32_bf16 v[108:111], v[152:155], v[176:179], v[108:111]
	v_mfma_f32_16x16x32_bf16 v[108:111], v[148:151], v[172:175], v[108:111]
	v_mfma_f32_16x16x32_bf16 v[116:119], v[148:151], v[180:183], v[116:119]
	v_mfma_f32_16x16x32_bf16 v[116:119], v[152:155], v[184:187], v[116:119]
	v_mfma_f32_16x16x32_bf16 v[120:123], v[160:163], v[184:187], v[120:123]
	v_mfma_f32_16x16x32_bf16 v[120:123], v[156:159], v[180:183], v[120:123]
	v_mfma_f32_16x16x32_bf16 v[128:131], v[156:159], v[194:197], v[128:131]
	v_mfma_f32_16x16x32_bf16 v[128:131], v[160:163], v[198:201], v[128:131]
	s_setprio 3
	s_barrier
	v_mfma_f32_16x16x32_bf16 v[124:127], v[152:155], v[198:201], v[124:127]
	v_mfma_f32_16x16x32_bf16 v[124:127], v[148:151], v[194:197], v[124:127]
	s_setprio 0
	s_add_i32 s29, 0, 0x18000
	s_add_i32 s40, 0, 0x1c000
	v_add_u32_e32 v144, s29, v232
	v_add_u32_e32 v160, s40, v232
	ds_read_b128 v[132:135], v144
	ds_read_b128 v[136:139], v144 offset:1024
	ds_read_b128 v[140:143], v144 offset:2048
	ds_read_b128 v[144:147], v144 offset:3072
	ds_read_b128 v[148:151], v160
	ds_read_b128 v[152:155], v160 offset:1024
	ds_read_b128 v[156:159], v160 offset:2048
	ds_read_b128 v[160:163], v160 offset:3072
	s_add_u32 s16, s16, 0x40000
	s_addc_u32 s17, s17, 0
	s_mov_b32 m0, s58
	ds_read_b128 v[164:167], v210 offset:32768
	ds_read_b128 v[168:171], v210 offset:33792
	ds_read_b128 v[172:175], v210 offset:34816
	ds_read_b128 v[176:179], v210 offset:35840
	ds_read_b128 v[180:183], v210 offset:36864
	ds_read_b128 v[184:187], v210 offset:37888
	ds_read_b128 v[194:197], v210 offset:38912
	ds_read_b128 v[198:201], v210 offset:39936
	global_load_lds_dwordx4 v2, s[16:17]
	s_mov_b32 m0, s59
	s_nop 0
	global_load_lds_dwordx4 v188, s[16:17]
	s_waitcnt vmcnt(8)
	s_waitcnt lgkmcnt(0)
	s_barrier
	s_setprio 1
	s_waitcnt lgkmcnt(0)
	v_mfma_f32_16x16x32_bf16 v[4:7], v[132:135], v[164:167], v[4:7]
	v_mfma_f32_16x16x32_bf16 v[4:7], v[136:139], v[168:171], v[4:7]
	v_mfma_f32_16x16x32_bf16 v[8:11], v[144:147], v[168:171], v[8:11]
	v_mfma_f32_16x16x32_bf16 v[8:11], v[140:143], v[164:167], v[8:11]
	v_mfma_f32_16x16x32_bf16 v[16:19], v[140:143], v[172:175], v[16:19]
	v_mfma_f32_16x16x32_bf16 v[16:19], v[144:147], v[176:179], v[16:19]
	v_mfma_f32_16x16x32_bf16 v[12:15], v[136:139], v[176:179], v[12:15]
	v_mfma_f32_16x16x32_bf16 v[12:15], v[132:135], v[172:175], v[12:15]
	v_mfma_f32_16x16x32_bf16 v[20:23], v[132:135], v[180:183], v[20:23]
	v_mfma_f32_16x16x32_bf16 v[20:23], v[136:139], v[184:187], v[20:23]
	v_mfma_f32_16x16x32_bf16 v[24:27], v[144:147], v[184:187], v[24:27]
	v_mfma_f32_16x16x32_bf16 v[24:27], v[140:143], v[180:183], v[24:27]
	v_mfma_f32_16x16x32_bf16 v[32:35], v[140:143], v[194:197], v[32:35]
	v_mfma_f32_16x16x32_bf16 v[32:35], v[144:147], v[198:201], v[32:35]
	v_mfma_f32_16x16x32_bf16 v[28:31], v[136:139], v[198:201], v[28:31]
	v_mfma_f32_16x16x32_bf16 v[28:31], v[132:135], v[194:197], v[28:31]
	s_setprio 0
	s_setprio 1
	v_mfma_f32_16x16x32_bf16 v[36:39], v[148:151], v[164:167], v[36:39]
	v_mfma_f32_16x16x32_bf16 v[36:39], v[152:155], v[168:171], v[36:39]
	v_mfma_f32_16x16x32_bf16 v[40:43], v[160:163], v[168:171], v[40:43]
	v_mfma_f32_16x16x32_bf16 v[40:43], v[156:159], v[164:167], v[40:43]
	v_mfma_f32_16x16x32_bf16 v[48:51], v[156:159], v[172:175], v[48:51]
	v_mfma_f32_16x16x32_bf16 v[48:51], v[160:163], v[176:179], v[48:51]
	v_mfma_f32_16x16x32_bf16 v[44:47], v[152:155], v[176:179], v[44:47]
	v_mfma_f32_16x16x32_bf16 v[44:47], v[148:151], v[172:175], v[44:47]
	v_mfma_f32_16x16x32_bf16 v[52:55], v[148:151], v[180:183], v[52:55]
	v_mfma_f32_16x16x32_bf16 v[52:55], v[152:155], v[184:187], v[52:55]
	v_mfma_f32_16x16x32_bf16 v[56:59], v[160:163], v[184:187], v[56:59]
	v_mfma_f32_16x16x32_bf16 v[56:59], v[156:159], v[180:183], v[56:59]
	v_mfma_f32_16x16x32_bf16 v[64:67], v[156:159], v[194:197], v[64:67]
	v_mfma_f32_16x16x32_bf16 v[64:67], v[160:163], v[198:201], v[64:67]
	s_setprio 3
	s_barrier
	v_mfma_f32_16x16x32_bf16 v[60:63], v[152:155], v[198:201], v[60:63]
	v_mfma_f32_16x16x32_bf16 v[60:63], v[148:151], v[194:197], v[60:63]
	s_setprio 0
	s_add_i32 s16, s29, s38
	v_lshl_add_u64 v[202:203], v[202:203], 0, s[86:87]
	s_mov_b32 m0, s16
	ds_read_b128 v[164:167], v210 offset:49152
	ds_read_b128 v[168:171], v210 offset:50176
	ds_read_b128 v[172:175], v210 offset:51200
	ds_read_b128 v[176:179], v210 offset:52224
	ds_read_b128 v[180:183], v210 offset:53248
	ds_read_b128 v[184:187], v210 offset:54272
	ds_read_b128 v[194:197], v210 offset:55296
	ds_read_b128 v[198:201], v210 offset:56320
	global_load_lds_dwordx4 v[202:203], off
	s_add_i32 m0, s16, 0x2000
	s_add_u32 s12, s12, 0x100080
	v_lshl_add_u64 v[202:203], v[204:205], 0, s[86:87]
	s_addc_u32 s13, s13, 0
	s_add_i32 s16, s40, s38
	global_load_lds_dwordx4 v[202:203], off
	s_mov_b32 m0, s16
	v_lshl_add_u64 v[202:203], v[206:207], 0, s[86:87]
	global_load_lds_dwordx4 v192, s[12:13]
	s_add_i32 m0, s16, 0x2000
	s_nop 0
	global_load_lds_dwordx4 v190, s[12:13]
	s_mov_b32 m0, s63
	s_nop 0
	global_load_lds_dwordx4 v[202:203], off
	v_lshl_add_u64 v[202:203], v[208:209], 0, s[86:87]
	s_mov_b32 m0, s64
	s_nop 0
	global_load_lds_dwordx4 v[202:203], off
	s_waitcnt vmcnt(8)
	s_waitcnt lgkmcnt(0)
	s_barrier
	s_setprio 1
	s_waitcnt lgkmcnt(0)
	v_mfma_f32_16x16x32_bf16 v[68:71], v[132:135], v[164:167], v[68:71]
	v_mfma_f32_16x16x32_bf16 v[68:71], v[136:139], v[168:171], v[68:71]
	v_mfma_f32_16x16x32_bf16 v[72:75], v[144:147], v[168:171], v[72:75]
	v_mfma_f32_16x16x32_bf16 v[72:75], v[140:143], v[164:167], v[72:75]
	v_mfma_f32_16x16x32_bf16 v[80:83], v[140:143], v[172:175], v[80:83]
	v_mfma_f32_16x16x32_bf16 v[80:83], v[144:147], v[176:179], v[80:83]
	v_mfma_f32_16x16x32_bf16 v[76:79], v[136:139], v[176:179], v[76:79]
	v_mfma_f32_16x16x32_bf16 v[76:79], v[132:135], v[172:175], v[76:79]
	v_mfma_f32_16x16x32_bf16 v[84:87], v[132:135], v[180:183], v[84:87]
	v_mfma_f32_16x16x32_bf16 v[84:87], v[136:139], v[184:187], v[84:87]
	v_mfma_f32_16x16x32_bf16 v[88:91], v[144:147], v[184:187], v[88:91]
	v_mfma_f32_16x16x32_bf16 v[88:91], v[140:143], v[180:183], v[88:91]
	v_mfma_f32_16x16x32_bf16 v[96:99], v[140:143], v[194:197], v[96:99]
	v_mfma_f32_16x16x32_bf16 v[96:99], v[144:147], v[198:201], v[96:99]
	v_mfma_f32_16x16x32_bf16 v[92:95], v[136:139], v[198:201], v[92:95]
	v_mfma_f32_16x16x32_bf16 v[92:95], v[132:135], v[194:197], v[92:95]
	s_setprio 0
	s_setprio 1
	v_mfma_f32_16x16x32_bf16 v[100:103], v[148:151], v[164:167], v[100:103]
	v_mfma_f32_16x16x32_bf16 v[100:103], v[152:155], v[168:171], v[100:103]
	v_mfma_f32_16x16x32_bf16 v[104:107], v[160:163], v[168:171], v[104:107]
	v_mfma_f32_16x16x32_bf16 v[104:107], v[156:159], v[164:167], v[104:107]
	v_mfma_f32_16x16x32_bf16 v[112:115], v[156:159], v[172:175], v[112:115]
	v_mfma_f32_16x16x32_bf16 v[112:115], v[160:163], v[176:179], v[112:115]
	v_mfma_f32_16x16x32_bf16 v[108:111], v[152:155], v[176:179], v[108:111]
	v_mfma_f32_16x16x32_bf16 v[108:111], v[148:151], v[172:175], v[108:111]
	v_mfma_f32_16x16x32_bf16 v[116:119], v[148:151], v[180:183], v[116:119]
	v_mfma_f32_16x16x32_bf16 v[116:119], v[152:155], v[184:187], v[116:119]
	v_mfma_f32_16x16x32_bf16 v[120:123], v[160:163], v[184:187], v[120:123]
	v_mfma_f32_16x16x32_bf16 v[120:123], v[156:159], v[180:183], v[120:123]
	v_mfma_f32_16x16x32_bf16 v[128:131], v[156:159], v[194:197], v[128:131]
	v_mfma_f32_16x16x32_bf16 v[128:131], v[160:163], v[198:201], v[128:131]
	s_setprio 3
	s_barrier
	v_mfma_f32_16x16x32_bf16 v[124:127], v[152:155], v[198:201], v[124:127]
	v_mfma_f32_16x16x32_bf16 v[124:127], v[148:151], v[194:197], v[124:127]
	s_setprio 0
	s_add_i32 s28, s28, 2
	s_add_u32 s14, s14, 0x100
	s_addc_u32 s15, s15, 0
	s_add_u32 s26, s26, 0x100
	s_addc_u32 s27, s27, 0
	s_cmp_gt_u32 s28, 13
	s_cbranch_scc0 .LBB0_2273
	s_and_b64 vcc, exec, s[48:49]
	s_cbranch_vccz .LBB0_2276
	s_barrier
